# baseline (speedup 1.0000x reference)
; #define PG8_STAGE(bufoff, gbase, voff) do { _Pragma("unroll") for (int _i = 0; _i < 2; ++_i) \
;         __builtin_amdgcn_global_load_lds((const unsigned*)((const char*)(gbase) + (voff)[_i]), (PG8_LAS unsigned*)(lds + (bufoff) + ldsw + _i * 8192), 16, 0, 0); } while (0)
; #define PG8_LDA(dst, b, h) do { _Pragma("unroll") for (int m = 0; m < 4; ++m) _Pragma("unroll") for (int k = 0; k < 2; ++k) dst[m][k] = *(const PG8_LAS bf16x8*)(lds + PG8_SA(b, h) + aoff + m * 2048 + k * 1024); } while (0)
; #define PG8_LDB(dst, b, h) do { _Pragma("unroll") for (int n = 0; n < 2; ++n) _Pragma("unroll") for (int k = 0; k < 2; ++k) dst[n][k] = *(const PG8_LAS bf16x8*)(lds + PG8_SB(b, h) + boff + n * 2048 + k * 1024); } while (0)
; #define PG8_MMA(ai, bj, At, Bt) do { __builtin_amdgcn_s_setprio(1); _Pragma("unroll") for (int m = 0; m < 4; ++m) _Pragma("unroll") for (int n = 0; n < 2; ++n) _Pragma("unroll") for (int k = 0; k < 2; ++k) \
;         acc[ai][bj][m][n] = __builtin_amdgcn_mfma_f32_16x16x32_bf16(Bt[n][k], At[m][k], acc[ai][bj][m][n], 0, 0, 0); __builtin_amdgcn_s_setprio(0); } while (0)
; #define PG8_WAIT_V(n) asm volatile("s_waitcnt vmcnt(" #n ")" ::: "memory")
; #define PG8_WAIT_L(n) asm volatile("s_waitcnt lgkmcnt(" #n ")" ::: "memory")
; #define PG8_BAR __builtin_amdgcn_s_barrier()
; #define PG8_SCHED __builtin_amdgcn_sched_barrier(0)
; template <class Epi, class Sched, bool ALIGN_EPI = false, bool SP2 = false>
; __device__ __forceinline__ void gemm_phase(PG8_LAS unsigned char* lds, const Gemm g, const Sched& S, const Epi& E) {
;     ...
;             PG8_LDB(B0, 0, 0); PG8_LDB(B1, 0, 1); PG8_SCHED; PG8_LDA(At, 0, 0); PG8_STAGE(PG8_SA(1, 1), a1 + hstep, voffA);
;             PG8_WAIT_V(8); PG8_WAIT_L(0); PG8_BAR; PG8_MMA(0, 0, At, B0); PG8_MMA(0, 1, At, B1); PG8_BAR; PG8_SCHED;
;             PG8_LDA(At, 0, 1); PG8_STAGE(PG8_SB(0, 0), b2, voffB); PG8_STAGE(PG8_SB(0, 1), b2 + hstep, voffB); PG8_STAGE(PG8_SA(0, 0), a2, voffA);
;             PG8_WAIT_V(8); PG8_WAIT_L(0); PG8_BAR; PG8_MMA(1, 0, At, B0); PG8_MMA(1, 1, At, B1); PG8_BAR; PG8_SCHED;
.LBB0_121:
	ds_read_b128 v[148:151], v159
	ds_read_b128 v[168:171], v159 offset:1024
	ds_read_b128 v[172:175], v159 offset:2048
	ds_read_b128 v[176:179], v159 offset:3072
	ds_read_b128 v[180:183], v160
	ds_read_b128 v[184:187], v160 offset:1024
	ds_read_b128 v[188:191], v160 offset:2048
	ds_read_b128 v[192:195], v160 offset:3072
	s_add_i32 s46, s42, 2
	s_add_u32 s47, s6, 0x80
	s_addc_u32 s43, s7, 0
	s_cmp_eq_u32 s93, s42
	s_cselect_b32 s42, s38, s47
	s_cselect_b32 s43, s39, s43
	s_cselect_b32 s69, s41, vcc_lo
	s_cselect_b32 s68, s40, s0
	v_lshl_add_u64 v[152:153], s[6:7], 0, v[142:143]
	s_add_i32 m0, s64, 0xc000
	ds_read_b128 v[196:199], v161
	ds_read_b128 v[200:203], v161 offset:1024
	ds_read_b128 v[204:207], v161 offset:2048
	ds_read_b128 v[208:211], v161 offset:3072
	ds_read_b128 v[212:215], v161 offset:4096
	ds_read_b128 v[216:219], v161 offset:5120
	ds_read_b128 v[220:223], v161 offset:6144
	ds_read_b128 v[224:227], v161 offset:7168
	global_load_lds_dwordx4 v[152:153], off
	v_lshl_add_u64 v[152:153], s[6:7], 0, v[140:141]
	s_add_i32 m0, s64, 0xe000
	s_nop 0
	global_load_lds_dwordx4 v[152:153], off
	s_waitcnt vmcnt(8)
	s_waitcnt lgkmcnt(0)
	s_barrier
	s_setprio 1
	v_mfma_f32_16x16x32_bf16 v[126:129], v[148:151], v[196:199], v[126:129]
	v_mfma_f32_16x16x32_bf16 v[122:125], v[172:175], v[196:199], v[122:125]
	v_mfma_f32_16x16x32_bf16 v[110:113], v[148:151], v[204:207], v[110:113]
	v_mfma_f32_16x16x32_bf16 v[106:109], v[172:175], v[204:207], v[106:109]
	v_mfma_f32_16x16x32_bf16 v[94:97], v[148:151], v[212:215], v[94:97]
	v_mfma_f32_16x16x32_bf16 v[90:93], v[172:175], v[212:215], v[90:93]
	v_mfma_f32_16x16x32_bf16 v[78:81], v[148:151], v[220:223], v[78:81]
	v_mfma_f32_16x16x32_bf16 v[74:77], v[172:175], v[220:223], v[74:77]
	v_mfma_f32_16x16x32_bf16 v[126:129], v[168:171], v[200:203], v[126:129]
	v_mfma_f32_16x16x32_bf16 v[122:125], v[176:179], v[200:203], v[122:125]
	v_mfma_f32_16x16x32_bf16 v[110:113], v[168:171], v[208:211], v[110:113]
	v_mfma_f32_16x16x32_bf16 v[106:109], v[176:179], v[208:211], v[106:109]
	v_mfma_f32_16x16x32_bf16 v[94:97], v[168:171], v[216:219], v[94:97]
	v_mfma_f32_16x16x32_bf16 v[90:93], v[176:179], v[216:219], v[90:93]
	v_mfma_f32_16x16x32_bf16 v[78:81], v[168:171], v[224:227], v[78:81]
	v_mfma_f32_16x16x32_bf16 v[74:77], v[176:179], v[224:227], v[74:77]
	v_mfma_f32_16x16x32_bf16 v[118:121], v[180:183], v[196:199], v[118:121]
	v_mfma_f32_16x16x32_bf16 v[114:117], v[188:191], v[196:199], v[114:117]
	v_mfma_f32_16x16x32_bf16 v[102:105], v[180:183], v[204:207], v[102:105]
	v_mfma_f32_16x16x32_bf16 v[98:101], v[188:191], v[204:207], v[98:101]
	v_mfma_f32_16x16x32_bf16 v[86:89], v[180:183], v[212:215], v[86:89]
	v_mfma_f32_16x16x32_bf16 v[82:85], v[188:191], v[212:215], v[82:85]
	v_mfma_f32_16x16x32_bf16 v[70:73], v[180:183], v[220:223], v[70:73]
	v_mfma_f32_16x16x32_bf16 v[66:69], v[188:191], v[220:223], v[66:69]
	v_mfma_f32_16x16x32_bf16 v[118:121], v[184:187], v[200:203], v[118:121]
	v_mfma_f32_16x16x32_bf16 v[114:117], v[192:195], v[200:203], v[114:117]
	v_mfma_f32_16x16x32_bf16 v[102:105], v[184:187], v[208:211], v[102:105]
	v_mfma_f32_16x16x32_bf16 v[98:101], v[192:195], v[208:211], v[98:101]
	v_mfma_f32_16x16x32_bf16 v[86:89], v[184:187], v[216:219], v[86:89]
	v_mfma_f32_16x16x32_bf16 v[82:85], v[192:195], v[216:219], v[82:85]
	v_mfma_f32_16x16x32_bf16 v[70:73], v[184:187], v[224:227], v[70:73]
	v_mfma_f32_16x16x32_bf16 v[66:69], v[192:195], v[224:227], v[66:69]
	s_setprio 0
	s_barrier
	s_add_i32 s47, s97, s55
	v_lshl_add_u64 v[152:153], s[68:69], 0, v[132:133]
	s_mov_b32 m0, s47
	ds_read_b128 v[196:199], v161 offset:16384
	ds_read_b128 v[200:203], v161 offset:17408
	ds_read_b128 v[204:207], v161 offset:18432
	ds_read_b128 v[208:211], v161 offset:19456
	ds_read_b128 v[212:215], v161 offset:20480
	ds_read_b128 v[216:219], v161 offset:21504
	ds_read_b128 v[220:223], v161 offset:22528
	ds_read_b128 v[224:227], v161 offset:23552
	global_load_lds_dwordx4 v[152:153], off
	s_add_i32 m0, s47, 0x2000
	v_lshl_add_u64 v[228:229], s[68:69], 0, v[136:137]
	s_add_u32 s68, s68, s10
	s_addc_u32 s69, s69, s11
	s_add_i32 s47, s80, s55
	global_load_lds_dwordx4 v[228:229], off
	v_lshl_add_u64 v[230:231], s[68:69], 0, v[132:133]
	s_mov_b32 m0, s47
	v_lshl_add_u64 v[232:233], s[68:69], 0, v[136:137]
	global_load_lds_dwordx4 v[230:231], off
	s_add_i32 m0, s47, 0x2000
	v_lshl_add_u64 v[234:235], s[42:43], 0, v[130:131]
	global_load_lds_dwordx4 v[232:233], off
	s_mov_b32 m0, s64
	v_lshl_add_u64 v[236:237], s[42:43], 0, v[134:135]
	global_load_lds_dwordx4 v[234:235], off
	s_mov_b32 m0, s65
	s_nop 0
	global_load_lds_dwordx4 v[236:237], off
	s_waitcnt vmcnt(8)
	s_waitcnt lgkmcnt(0)
	s_barrier
; #define PG8_STAGE(bufoff, gbase, voff) do { _Pragma("unroll") for (int _i = 0; _i < 2; ++_i) \
;         __builtin_amdgcn_global_load_lds((const unsigned*)((const char*)(gbase) + (voff)[_i]), (PG8_LAS unsigned*)(lds + (bufoff) + ldsw + _i * 8192), 16, 0, 0); } while (0)
; #define PG8_LDA(dst, b, h) do { _Pragma("unroll") for (int m = 0; m < 4; ++m) _Pragma("unroll") for (int k = 0; k < 2; ++k) dst[m][k] = *(const PG8_LAS bf16x8*)(lds + PG8_SA(b, h) + aoff + m * 2048 + k * 1024); } while (0)
; #define PG8_LDB(dst, b, h) do { _Pragma("unroll") for (int n = 0; n < 2; ++n) _Pragma("unroll") for (int k = 0; k < 2; ++k) dst[n][k] = *(const PG8_LAS bf16x8*)(lds + PG8_SB(b, h) + boff + n * 2048 + k * 1024); } while (0)
; #define PG8_MMA(ai, bj, At, Bt) do { __builtin_amdgcn_s_setprio(1); _Pragma("unroll") for (int m = 0; m < 4; ++m) _Pragma("unroll") for (int n = 0; n < 2; ++n) _Pragma("unroll") for (int k = 0; k < 2; ++k) \
;         acc[ai][bj][m][n] = __builtin_amdgcn_mfma_f32_16x16x32_bf16(Bt[n][k], At[m][k], acc[ai][bj][m][n], 0, 0, 0); __builtin_amdgcn_s_setprio(0); } while (0)
; #define PG8_WAIT_V(n) asm volatile("s_waitcnt vmcnt(" #n ")" ::: "memory")
; #define PG8_WAIT_L(n) asm volatile("s_waitcnt lgkmcnt(" #n ")" ::: "memory")
; #define PG8_BAR __builtin_amdgcn_s_barrier()
; #define PG8_SCHED __builtin_amdgcn_sched_barrier(0)
; template <class Epi, class Sched, bool ALIGN_EPI = false, bool SP2 = false>
; __device__ __forceinline__ void gemm_phase(PG8_LAS unsigned char* lds, const Gemm g, const Sched& S, const Epi& E) {
;     ...
;             PG8_WAIT_V(8); PG8_WAIT_L(0); PG8_BAR; PG8_MMA(1, 0, At, B0); PG8_MMA(1, 1, At, B1); PG8_BAR; PG8_SCHED;
;             PG8_LDB(B0, 1, 0); PG8_LDB(B1, 1, 1); PG8_SCHED; PG8_LDA(At, 1, 0); PG8_STAGE(PG8_SA(0, 1), a2 + hstep, voffA);
;             PG8_WAIT_V(8); PG8_WAIT_L(0); PG8_BAR; PG8_MMA(0, 0, At, B0); PG8_MMA(0, 1, At, B1); PG8_BAR; PG8_SCHED;
	s_setprio 1
	v_mfma_f32_16x16x32_bf16 v[62:65], v[148:151], v[196:199], v[62:65]
	v_mfma_f32_16x16x32_bf16 v[58:61], v[172:175], v[196:199], v[58:61]
	v_mfma_f32_16x16x32_bf16 v[46:49], v[148:151], v[204:207], v[46:49]
	v_mfma_f32_16x16x32_bf16 v[42:45], v[172:175], v[204:207], v[42:45]
	v_mfma_f32_16x16x32_bf16 v[30:33], v[148:151], v[212:215], v[30:33]
	v_mfma_f32_16x16x32_bf16 v[26:29], v[172:175], v[212:215], v[26:29]
	v_mfma_f32_16x16x32_bf16 v[14:17], v[148:151], v[220:223], v[14:17]
	v_mfma_f32_16x16x32_bf16 v[10:13], v[172:175], v[220:223], v[10:13]
	v_mfma_f32_16x16x32_bf16 v[62:65], v[168:171], v[200:203], v[62:65]
	v_mfma_f32_16x16x32_bf16 v[58:61], v[176:179], v[200:203], v[58:61]
	v_mfma_f32_16x16x32_bf16 v[46:49], v[168:171], v[208:211], v[46:49]
	v_mfma_f32_16x16x32_bf16 v[42:45], v[176:179], v[208:211], v[42:45]
	v_mfma_f32_16x16x32_bf16 v[30:33], v[168:171], v[216:219], v[30:33]
	v_mfma_f32_16x16x32_bf16 v[26:29], v[176:179], v[216:219], v[26:29]
	v_mfma_f32_16x16x32_bf16 v[14:17], v[168:171], v[224:227], v[14:17]
	v_mfma_f32_16x16x32_bf16 v[10:13], v[176:179], v[224:227], v[10:13]
	v_mfma_f32_16x16x32_bf16 v[54:57], v[180:183], v[196:199], v[54:57]
	v_mfma_f32_16x16x32_bf16 v[50:53], v[188:191], v[196:199], v[50:53]
	v_mfma_f32_16x16x32_bf16 v[38:41], v[180:183], v[204:207], v[38:41]
	v_mfma_f32_16x16x32_bf16 v[34:37], v[188:191], v[204:207], v[34:37]
	v_mfma_f32_16x16x32_bf16 v[22:25], v[180:183], v[212:215], v[22:25]
	v_mfma_f32_16x16x32_bf16 v[18:21], v[188:191], v[212:215], v[18:21]
	v_mfma_f32_16x16x32_bf16 v[6:9], v[180:183], v[220:223], v[6:9]
	v_mfma_f32_16x16x32_bf16 v[2:5], v[188:191], v[220:223], v[2:5]
	v_mfma_f32_16x16x32_bf16 v[54:57], v[184:187], v[200:203], v[54:57]
	v_mfma_f32_16x16x32_bf16 v[50:53], v[192:195], v[200:203], v[50:53]
	v_mfma_f32_16x16x32_bf16 v[38:41], v[184:187], v[208:211], v[38:41]
	v_mfma_f32_16x16x32_bf16 v[34:37], v[192:195], v[208:211], v[34:37]
	v_mfma_f32_16x16x32_bf16 v[22:25], v[184:187], v[216:219], v[22:25]
	v_mfma_f32_16x16x32_bf16 v[18:21], v[192:195], v[216:219], v[18:21]
	v_mfma_f32_16x16x32_bf16 v[6:9], v[184:187], v[224:227], v[6:9]
	v_mfma_f32_16x16x32_bf16 v[2:5], v[192:195], v[224:227], v[2:5]
	s_setprio 0
	s_barrier
	s_add_i32 s47, 0, 0x18000
	v_add_u32_e32 v138, s47, v154
	s_add_i32 s68, 0, 0x1c000
	ds_read_b128 v[148:151], v138
	ds_read_b128 v[168:171], v138 offset:1024
	ds_read_b128 v[172:175], v138 offset:2048
	ds_read_b128 v[176:179], v138 offset:3072
	v_add_u32_e32 v138, s68, v154
	ds_read_b128 v[180:183], v138
	ds_read_b128 v[184:187], v138 offset:1024
	ds_read_b128 v[188:191], v138 offset:2048
	ds_read_b128 v[192:195], v138 offset:3072
	s_add_u32 s42, s42, s10
	s_addc_u32 s43, s43, s11
	s_mov_b32 m0, s66
	v_lshl_add_u64 v[238:239], s[42:43], 0, v[130:131]
	ds_read_b128 v[196:199], v161 offset:32768
	ds_read_b128 v[200:203], v161 offset:33792
	ds_read_b128 v[204:207], v161 offset:34816
	ds_read_b128 v[208:211], v161 offset:35840
	ds_read_b128 v[212:215], v161 offset:36864
	ds_read_b128 v[216:219], v161 offset:37888
	ds_read_b128 v[220:223], v161 offset:38912
	ds_read_b128 v[224:227], v161 offset:39936
	global_load_lds_dwordx4 v[238:239], off
	v_lshl_add_u64 v[238:239], s[42:43], 0, v[134:135]
	s_mov_b32 m0, s67
	s_nop 0
	global_load_lds_dwordx4 v[238:239], off
	s_waitcnt vmcnt(8)
	s_waitcnt lgkmcnt(0)
	s_barrier
	s_setprio 1
	v_mfma_f32_16x16x32_bf16 v[126:129], v[148:151], v[196:199], v[126:129]
	v_mfma_f32_16x16x32_bf16 v[122:125], v[172:175], v[196:199], v[122:125]
	v_mfma_f32_16x16x32_bf16 v[110:113], v[148:151], v[204:207], v[110:113]
	v_mfma_f32_16x16x32_bf16 v[106:109], v[172:175], v[204:207], v[106:109]
	v_mfma_f32_16x16x32_bf16 v[94:97], v[148:151], v[212:215], v[94:97]
	v_mfma_f32_16x16x32_bf16 v[90:93], v[172:175], v[212:215], v[90:93]
	v_mfma_f32_16x16x32_bf16 v[78:81], v[148:151], v[220:223], v[78:81]
	v_mfma_f32_16x16x32_bf16 v[74:77], v[172:175], v[220:223], v[74:77]
	v_mfma_f32_16x16x32_bf16 v[126:129], v[168:171], v[200:203], v[126:129]
	v_mfma_f32_16x16x32_bf16 v[122:125], v[176:179], v[200:203], v[122:125]
	v_mfma_f32_16x16x32_bf16 v[110:113], v[168:171], v[208:211], v[110:113]
	v_mfma_f32_16x16x32_bf16 v[106:109], v[176:179], v[208:211], v[106:109]
	v_mfma_f32_16x16x32_bf16 v[94:97], v[168:171], v[216:219], v[94:97]
	v_mfma_f32_16x16x32_bf16 v[90:93], v[176:179], v[216:219], v[90:93]
	v_mfma_f32_16x16x32_bf16 v[78:81], v[168:171], v[224:227], v[78:81]
	v_mfma_f32_16x16x32_bf16 v[74:77], v[176:179], v[224:227], v[74:77]
	v_mfma_f32_16x16x32_bf16 v[118:121], v[180:183], v[196:199], v[118:121]
	v_mfma_f32_16x16x32_bf16 v[114:117], v[188:191], v[196:199], v[114:117]
	v_mfma_f32_16x16x32_bf16 v[102:105], v[180:183], v[204:207], v[102:105]
	v_mfma_f32_16x16x32_bf16 v[98:101], v[188:191], v[204:207], v[98:101]
	v_mfma_f32_16x16x32_bf16 v[86:89], v[180:183], v[212:215], v[86:89]
	v_mfma_f32_16x16x32_bf16 v[82:85], v[188:191], v[212:215], v[82:85]
	v_mfma_f32_16x16x32_bf16 v[70:73], v[180:183], v[220:223], v[70:73]
	v_mfma_f32_16x16x32_bf16 v[66:69], v[188:191], v[220:223], v[66:69]
	v_mfma_f32_16x16x32_bf16 v[118:121], v[184:187], v[200:203], v[118:121]
	v_mfma_f32_16x16x32_bf16 v[114:117], v[192:195], v[200:203], v[114:117]
	v_mfma_f32_16x16x32_bf16 v[102:105], v[184:187], v[208:211], v[102:105]
	v_mfma_f32_16x16x32_bf16 v[98:101], v[192:195], v[208:211], v[98:101]
	v_mfma_f32_16x16x32_bf16 v[86:89], v[184:187], v[216:219], v[86:89]
	v_mfma_f32_16x16x32_bf16 v[82:85], v[192:195], v[216:219], v[82:85]
	v_mfma_f32_16x16x32_bf16 v[70:73], v[184:187], v[224:227], v[70:73]
	v_mfma_f32_16x16x32_bf16 v[66:69], v[192:195], v[224:227], v[66:69]
	s_setprio 0
	s_barrier
; #define PG8_STAGE(bufoff, gbase, voff) do { _Pragma("unroll") for (int _i = 0; _i < 2; ++_i) \
;         __builtin_amdgcn_global_load_lds((const unsigned*)((const char*)(gbase) + (voff)[_i]), (PG8_LAS unsigned*)(lds + (bufoff) + ldsw + _i * 8192), 16, 0, 0); } while (0)
; #define PG8_LDA(dst, b, h) do { _Pragma("unroll") for (int m = 0; m < 4; ++m) _Pragma("unroll") for (int k = 0; k < 2; ++k) dst[m][k] = *(const PG8_LAS bf16x8*)(lds + PG8_SA(b, h) + aoff + m * 2048 + k * 1024); } while (0)
; #define PG8_MMA(ai, bj, At, Bt) do { __builtin_amdgcn_s_setprio(1); _Pragma("unroll") for (int m = 0; m < 4; ++m) _Pragma("unroll") for (int n = 0; n < 2; ++n) _Pragma("unroll") for (int k = 0; k < 2; ++k) \
;         acc[ai][bj][m][n] = __builtin_amdgcn_mfma_f32_16x16x32_bf16(Bt[n][k], At[m][k], acc[ai][bj][m][n], 0, 0, 0); __builtin_amdgcn_s_setprio(0); } while (0)
; #define PG8_WAIT_V(n) asm volatile("s_waitcnt vmcnt(" #n ")" ::: "memory")
; #define PG8_WAIT_L(n) asm volatile("s_waitcnt lgkmcnt(" #n ")" ::: "memory")
; #define PG8_BAR __builtin_amdgcn_s_barrier()
; #define PG8_SCHED __builtin_amdgcn_sched_barrier(0)
; template <class Epi, class Sched, bool ALIGN_EPI = false, bool SP2 = false>
; __device__ __forceinline__ void gemm_phase(PG8_LAS unsigned char* lds, const Gemm g, const Sched& S, const Epi& E) {
;     ...
;         for (int t = 0; t < nt; t += 2) {
;             const bool last = (t == nt - 2);
;             const char* a1 = cA + (size_t)(t + 1) * kstep;
;             const char* a2 = last ? nA : cA + (size_t)(t + 2) * kstep; const char* b2 = last ? nB : cB + (size_t)(t + 2) * kstep;
;     ...
;             PG8_LDA(At, 1, 1); PG8_STAGE(PG8_SB(1, 0), b3, voffB); PG8_STAGE(PG8_SB(1, 1), b3 + hstep, voffB); PG8_STAGE(PG8_SA(1, 0), a3, voffA);
;             PG8_WAIT_V(8); PG8_WAIT_L(0); PG8_BAR; PG8_MMA(1, 0, At, B0); PG8_MMA(1, 1, At, B1); PG8_BAR; PG8_SCHED;
	s_add_i32 s42, s47, s55
	v_lshl_add_u64 v[152:153], v[152:153], 0, s[30:31]
	s_mov_b32 m0, s42
	ds_read_b128 v[196:199], v161 offset:49152
	ds_read_b128 v[200:203], v161 offset:50176
	ds_read_b128 v[204:207], v161 offset:51200
	ds_read_b128 v[208:211], v161 offset:52224
	ds_read_b128 v[212:215], v161 offset:53248
	ds_read_b128 v[216:219], v161 offset:54272
	ds_read_b128 v[220:223], v161 offset:55296
	ds_read_b128 v[224:227], v161 offset:56320
	global_load_lds_dwordx4 v[152:153], off
	v_lshl_add_u64 v[152:153], v[228:229], 0, s[30:31]
	s_add_i32 m0, s42, 0x2000
	s_add_i32 s42, s68, s55
	global_load_lds_dwordx4 v[152:153], off
	v_lshl_add_u64 v[152:153], v[230:231], 0, s[30:31]
	s_mov_b32 m0, s42
	s_nop 0
	global_load_lds_dwordx4 v[152:153], off
	v_lshl_add_u64 v[152:153], v[232:233], 0, s[30:31]
	s_add_i32 m0, s42, 0x2000
	s_nop 0
	global_load_lds_dwordx4 v[152:153], off
	v_lshl_add_u64 v[152:153], v[234:235], 0, s[30:31]
	s_mov_b32 m0, s89
	s_nop 0
	global_load_lds_dwordx4 v[152:153], off
	v_lshl_add_u64 v[152:153], v[236:237], 0, s[30:31]
	s_mov_b32 m0, s90
	s_nop 0
	global_load_lds_dwordx4 v[152:153], off
	s_waitcnt vmcnt(8)
	s_waitcnt lgkmcnt(0)
	s_barrier
	s_setprio 1
	v_mfma_f32_16x16x32_bf16 v[62:65], v[148:151], v[196:199], v[62:65]
	v_mfma_f32_16x16x32_bf16 v[58:61], v[172:175], v[196:199], v[58:61]
	v_mfma_f32_16x16x32_bf16 v[46:49], v[148:151], v[204:207], v[46:49]
	v_mfma_f32_16x16x32_bf16 v[42:45], v[172:175], v[204:207], v[42:45]
	v_mfma_f32_16x16x32_bf16 v[30:33], v[148:151], v[212:215], v[30:33]
	v_mfma_f32_16x16x32_bf16 v[26:29], v[172:175], v[212:215], v[26:29]
	v_mfma_f32_16x16x32_bf16 v[14:17], v[148:151], v[220:223], v[14:17]
	v_mfma_f32_16x16x32_bf16 v[10:13], v[172:175], v[220:223], v[10:13]
	v_mfma_f32_16x16x32_bf16 v[62:65], v[168:171], v[200:203], v[62:65]
	v_mfma_f32_16x16x32_bf16 v[58:61], v[176:179], v[200:203], v[58:61]
	v_mfma_f32_16x16x32_bf16 v[46:49], v[168:171], v[208:211], v[46:49]
	v_mfma_f32_16x16x32_bf16 v[42:45], v[176:179], v[208:211], v[42:45]
	v_mfma_f32_16x16x32_bf16 v[30:33], v[168:171], v[216:219], v[30:33]
	v_mfma_f32_16x16x32_bf16 v[26:29], v[176:179], v[216:219], v[26:29]
	v_mfma_f32_16x16x32_bf16 v[14:17], v[168:171], v[224:227], v[14:17]
	v_mfma_f32_16x16x32_bf16 v[10:13], v[176:179], v[224:227], v[10:13]
	v_mfma_f32_16x16x32_bf16 v[54:57], v[180:183], v[196:199], v[54:57]
	v_mfma_f32_16x16x32_bf16 v[50:53], v[188:191], v[196:199], v[50:53]
	v_mfma_f32_16x16x32_bf16 v[38:41], v[180:183], v[204:207], v[38:41]
	v_mfma_f32_16x16x32_bf16 v[34:37], v[188:191], v[204:207], v[34:37]
	v_mfma_f32_16x16x32_bf16 v[22:25], v[180:183], v[212:215], v[22:25]
	v_mfma_f32_16x16x32_bf16 v[18:21], v[188:191], v[212:215], v[18:21]
	v_mfma_f32_16x16x32_bf16 v[6:9], v[180:183], v[220:223], v[6:9]
	v_mfma_f32_16x16x32_bf16 v[2:5], v[188:191], v[220:223], v[2:5]
	v_mfma_f32_16x16x32_bf16 v[54:57], v[184:187], v[200:203], v[54:57]
	v_mfma_f32_16x16x32_bf16 v[50:53], v[192:195], v[200:203], v[50:53]
	v_mfma_f32_16x16x32_bf16 v[38:41], v[184:187], v[208:211], v[38:41]
	v_mfma_f32_16x16x32_bf16 v[34:37], v[192:195], v[208:211], v[34:37]
	v_mfma_f32_16x16x32_bf16 v[22:25], v[184:187], v[216:219], v[22:25]
	v_mfma_f32_16x16x32_bf16 v[18:21], v[192:195], v[216:219], v[18:21]
	v_mfma_f32_16x16x32_bf16 v[6:9], v[184:187], v[224:227], v[6:9]
	v_mfma_f32_16x16x32_bf16 v[2:5], v[192:195], v[224:227], v[2:5]
	s_setprio 0
	s_add_u32 s0, s0, 0x100
	s_addc_u32 vcc_lo, vcc_lo, 0
	s_add_u32 s6, s6, 0x100
	s_addc_u32 s7, s7, 0
	s_cmp_ge_i32 s46, s91
	s_mov_b32 s42, s46
	s_barrier
	s_cbranch_scc0 .LBB0_121

; #define PG8_STAGE(bufoff, gbase, voff) do { _Pragma("unroll") for (int _i = 0; _i < 2; ++_i) \
;         __builtin_amdgcn_global_load_lds((const unsigned*)((const char*)(gbase) + (voff)[_i]), (PG8_LAS unsigned*)(lds + (bufoff) + ldsw + _i * 8192), 16, 0, 0); } while (0)
; #define PG8_LDA(dst, b, h) do { _Pragma("unroll") for (int m = 0; m < 4; ++m) _Pragma("unroll") for (int k = 0; k < 2; ++k) dst[m][k] = *(const PG8_LAS bf16x8*)(lds + PG8_SA(b, h) + aoff + m * 2048 + k * 1024); } while (0)
; #define PG8_LDB(dst, b, h) do { _Pragma("unroll") for (int n = 0; n < 2; ++n) _Pragma("unroll") for (int k = 0; k < 2; ++k) dst[n][k] = *(const PG8_LAS bf16x8*)(lds + PG8_SB(b, h) + boff + n * 2048 + k * 1024); } while (0)
; #define PG8_MMA(ai, bj, At, Bt) do { __builtin_amdgcn_s_setprio(1); _Pragma("unroll") for (int m = 0; m < 4; ++m) _Pragma("unroll") for (int n = 0; n < 2; ++n) _Pragma("unroll") for (int k = 0; k < 2; ++k) \
;         acc[ai][bj][m][n] = __builtin_amdgcn_mfma_f32_16x16x32_bf16(Bt[n][k], At[m][k], acc[ai][bj][m][n], 0, 0, 0); __builtin_amdgcn_s_setprio(0); } while (0)
; #define PG8_WAIT_V(n) asm volatile("s_waitcnt vmcnt(" #n ")" ::: "memory")
; #define PG8_WAIT_L(n) asm volatile("s_waitcnt lgkmcnt(" #n ")" ::: "memory")
; #define PG8_BAR __builtin_amdgcn_s_barrier()
; #define PG8_SCHED __builtin_amdgcn_sched_barrier(0)
; template <class Epi, class Sched, bool ALIGN_EPI = false, bool SP2 = false>
; __device__ __forceinline__ void gemm_phase(PG8_LAS unsigned char* lds, const Gemm g, const Sched& S, const Epi& E) {
;     ...
;             PG8_LDB(B0, 0, 0); PG8_LDB(B1, 0, 1); PG8_SCHED; PG8_LDA(At, 0, 0); PG8_STAGE(PG8_SA(1, 1), a1 + hstep, voffA);
;             PG8_WAIT_V(8); PG8_WAIT_L(0); PG8_BAR; PG8_MMA(0, 0, At, B0); PG8_MMA(0, 1, At, B1); PG8_BAR; PG8_SCHED;
;             PG8_LDA(At, 0, 1); PG8_STAGE(PG8_SB(0, 0), b2, voffB); PG8_STAGE(PG8_SB(0, 1), b2 + hstep, voffB); PG8_STAGE(PG8_SA(0, 0), a2, voffA);
;             PG8_WAIT_V(8); PG8_WAIT_L(0); PG8_BAR; PG8_MMA(1, 0, At, B0); PG8_MMA(1, 1, At, B1); PG8_BAR; PG8_SCHED;
.LBB0_497:
	ds_read_b128 v[146:149], v152
	ds_read_b128 v[156:159], v152 offset:1024
	ds_read_b128 v[160:163], v152 offset:2048
	ds_read_b128 v[164:167], v152 offset:3072
	ds_read_b128 v[168:171], v153
	ds_read_b128 v[172:175], v153 offset:1024
	ds_read_b128 v[176:179], v153 offset:2048
	ds_read_b128 v[180:183], v153 offset:3072
	s_add_i32 s60, s34, 2
	s_add_u32 s61, s30, 0x80
	s_addc_u32 s35, s31, 0
	s_cmp_eq_u32 s44, s34
	s_cselect_b32 s34, s6, s61
	s_cselect_b32 s35, s7, s35
	s_cselect_b32 s63, s29, s59
	s_cselect_b32 s62, s28, s58
	v_lshl_add_u64 v[216:217], s[30:31], 0, v[140:141]
	s_add_i32 m0, s39, 0xc000
	ds_read_b128 v[184:187], v154
	ds_read_b128 v[188:191], v154 offset:1024
	ds_read_b128 v[192:195], v154 offset:2048
	ds_read_b128 v[196:199], v154 offset:3072
	ds_read_b128 v[200:203], v154 offset:4096
	ds_read_b128 v[204:207], v154 offset:5120
	ds_read_b128 v[208:211], v154 offset:6144
	ds_read_b128 v[212:215], v154 offset:7168
	global_load_lds_dwordx4 v[216:217], off
	v_lshl_add_u64 v[216:217], s[30:31], 0, v[138:139]
	s_add_i32 m0, s39, 0xe000
	s_nop 0
	global_load_lds_dwordx4 v[216:217], off
	s_waitcnt vmcnt(8)
	s_waitcnt lgkmcnt(0)
	s_barrier
	s_setprio 1
	v_mfma_f32_16x16x32_bf16 v[126:129], v[146:149], v[184:187], v[126:129]
	v_mfma_f32_16x16x32_bf16 v[122:125], v[160:163], v[184:187], v[122:125]
	v_mfma_f32_16x16x32_bf16 v[110:113], v[146:149], v[192:195], v[110:113]
	v_mfma_f32_16x16x32_bf16 v[106:109], v[160:163], v[192:195], v[106:109]
	v_mfma_f32_16x16x32_bf16 v[94:97], v[146:149], v[200:203], v[94:97]
	v_mfma_f32_16x16x32_bf16 v[90:93], v[160:163], v[200:203], v[90:93]
	v_mfma_f32_16x16x32_bf16 v[78:81], v[146:149], v[208:211], v[78:81]
	v_mfma_f32_16x16x32_bf16 v[74:77], v[160:163], v[208:211], v[74:77]
	v_mfma_f32_16x16x32_bf16 v[126:129], v[156:159], v[188:191], v[126:129]
	v_mfma_f32_16x16x32_bf16 v[122:125], v[164:167], v[188:191], v[122:125]
	v_mfma_f32_16x16x32_bf16 v[110:113], v[156:159], v[196:199], v[110:113]
	v_mfma_f32_16x16x32_bf16 v[106:109], v[164:167], v[196:199], v[106:109]
	v_mfma_f32_16x16x32_bf16 v[94:97], v[156:159], v[204:207], v[94:97]
	v_mfma_f32_16x16x32_bf16 v[90:93], v[164:167], v[204:207], v[90:93]
	v_mfma_f32_16x16x32_bf16 v[78:81], v[156:159], v[212:215], v[78:81]
	v_mfma_f32_16x16x32_bf16 v[74:77], v[164:167], v[212:215], v[74:77]
	v_mfma_f32_16x16x32_bf16 v[118:121], v[168:171], v[184:187], v[118:121]
	v_mfma_f32_16x16x32_bf16 v[114:117], v[176:179], v[184:187], v[114:117]
	v_mfma_f32_16x16x32_bf16 v[102:105], v[168:171], v[192:195], v[102:105]
	v_mfma_f32_16x16x32_bf16 v[98:101], v[176:179], v[192:195], v[98:101]
	v_mfma_f32_16x16x32_bf16 v[86:89], v[168:171], v[200:203], v[86:89]
	v_mfma_f32_16x16x32_bf16 v[82:85], v[176:179], v[200:203], v[82:85]
	v_mfma_f32_16x16x32_bf16 v[70:73], v[168:171], v[208:211], v[70:73]
	v_mfma_f32_16x16x32_bf16 v[66:69], v[176:179], v[208:211], v[66:69]
	v_mfma_f32_16x16x32_bf16 v[118:121], v[172:175], v[188:191], v[118:121]
	v_mfma_f32_16x16x32_bf16 v[114:117], v[180:183], v[188:191], v[114:117]
	v_mfma_f32_16x16x32_bf16 v[102:105], v[172:175], v[196:199], v[102:105]
	v_mfma_f32_16x16x32_bf16 v[98:101], v[180:183], v[196:199], v[98:101]
	v_mfma_f32_16x16x32_bf16 v[86:89], v[172:175], v[204:207], v[86:89]
	v_mfma_f32_16x16x32_bf16 v[82:85], v[180:183], v[204:207], v[82:85]
	v_mfma_f32_16x16x32_bf16 v[70:73], v[172:175], v[212:215], v[70:73]
	v_mfma_f32_16x16x32_bf16 v[66:69], v[180:183], v[212:215], v[66:69]
	s_setprio 0
	s_barrier
	s_add_i32 s61, s54, s38
	v_lshl_add_u64 v[216:217], s[62:63], 0, v[132:133]
	s_mov_b32 m0, s61
	ds_read_b128 v[184:187], v154 offset:16384
	ds_read_b128 v[188:191], v154 offset:17408
	ds_read_b128 v[192:195], v154 offset:18432
	ds_read_b128 v[196:199], v154 offset:19456
	ds_read_b128 v[200:203], v154 offset:20480
	ds_read_b128 v[204:207], v154 offset:21504
	ds_read_b128 v[208:211], v154 offset:22528
	ds_read_b128 v[212:215], v154 offset:23552
	global_load_lds_dwordx4 v[216:217], off
	s_add_i32 m0, s61, 0x2000
	v_lshl_add_u64 v[218:219], s[62:63], 0, v[136:137]
	s_add_u32 s62, s62, s12
	s_addc_u32 s63, s63, s13
	s_add_i32 s61, s55, s38
	global_load_lds_dwordx4 v[218:219], off
	v_lshl_add_u64 v[220:221], s[62:63], 0, v[132:133]
	s_mov_b32 m0, s61
	v_lshl_add_u64 v[222:223], s[62:63], 0, v[136:137]
	global_load_lds_dwordx4 v[220:221], off
	s_add_i32 m0, s61, 0x2000
	v_lshl_add_u64 v[224:225], s[34:35], 0, v[130:131]
	global_load_lds_dwordx4 v[222:223], off
	s_mov_b32 m0, s39
	v_lshl_add_u64 v[226:227], s[34:35], 0, v[134:135]
	global_load_lds_dwordx4 v[224:225], off
	s_mov_b32 m0, s40
	s_nop 0
	global_load_lds_dwordx4 v[226:227], off
	s_waitcnt vmcnt(8)
	s_waitcnt lgkmcnt(0)
	s_barrier
; #define PG8_STAGE(bufoff, gbase, voff) do { _Pragma("unroll") for (int _i = 0; _i < 2; ++_i) \
;         __builtin_amdgcn_global_load_lds((const unsigned*)((const char*)(gbase) + (voff)[_i]), (PG8_LAS unsigned*)(lds + (bufoff) + ldsw + _i * 8192), 16, 0, 0); } while (0)
; #define PG8_LDA(dst, b, h) do { _Pragma("unroll") for (int m = 0; m < 4; ++m) _Pragma("unroll") for (int k = 0; k < 2; ++k) dst[m][k] = *(const PG8_LAS bf16x8*)(lds + PG8_SA(b, h) + aoff + m * 2048 + k * 1024); } while (0)
; #define PG8_LDB(dst, b, h) do { _Pragma("unroll") for (int n = 0; n < 2; ++n) _Pragma("unroll") for (int k = 0; k < 2; ++k) dst[n][k] = *(const PG8_LAS bf16x8*)(lds + PG8_SB(b, h) + boff + n * 2048 + k * 1024); } while (0)
; #define PG8_MMA(ai, bj, At, Bt) do { __builtin_amdgcn_s_setprio(1); _Pragma("unroll") for (int m = 0; m < 4; ++m) _Pragma("unroll") for (int n = 0; n < 2; ++n) _Pragma("unroll") for (int k = 0; k < 2; ++k) \
;         acc[ai][bj][m][n] = __builtin_amdgcn_mfma_f32_16x16x32_bf16(Bt[n][k], At[m][k], acc[ai][bj][m][n], 0, 0, 0); __builtin_amdgcn_s_setprio(0); } while (0)
; #define PG8_WAIT_V(n) asm volatile("s_waitcnt vmcnt(" #n ")" ::: "memory")
; #define PG8_WAIT_L(n) asm volatile("s_waitcnt lgkmcnt(" #n ")" ::: "memory")
; #define PG8_BAR __builtin_amdgcn_s_barrier()
; #define PG8_SCHED __builtin_amdgcn_sched_barrier(0)
; template <class Epi, class Sched, bool ALIGN_EPI = false, bool SP2 = false>
; __device__ __forceinline__ void gemm_phase(PG8_LAS unsigned char* lds, const Gemm g, const Sched& S, const Epi& E) {
;     ...
;             PG8_WAIT_V(8); PG8_WAIT_L(0); PG8_BAR; PG8_MMA(1, 0, At, B0); PG8_MMA(1, 1, At, B1); PG8_BAR; PG8_SCHED;
;             PG8_LDB(B0, 1, 0); PG8_LDB(B1, 1, 1); PG8_SCHED; PG8_LDA(At, 1, 0); PG8_STAGE(PG8_SA(0, 1), a2 + hstep, voffA);
;             PG8_WAIT_V(8); PG8_WAIT_L(0); PG8_BAR; PG8_MMA(0, 0, At, B0); PG8_MMA(0, 1, At, B1); PG8_BAR; PG8_SCHED;
	s_setprio 1
	v_mfma_f32_16x16x32_bf16 v[62:65], v[146:149], v[184:187], v[62:65]
	v_mfma_f32_16x16x32_bf16 v[58:61], v[160:163], v[184:187], v[58:61]
	v_mfma_f32_16x16x32_bf16 v[46:49], v[146:149], v[192:195], v[46:49]
	v_mfma_f32_16x16x32_bf16 v[42:45], v[160:163], v[192:195], v[42:45]
	v_mfma_f32_16x16x32_bf16 v[30:33], v[146:149], v[200:203], v[30:33]
	v_mfma_f32_16x16x32_bf16 v[26:29], v[160:163], v[200:203], v[26:29]
	v_mfma_f32_16x16x32_bf16 v[14:17], v[146:149], v[208:211], v[14:17]
	v_mfma_f32_16x16x32_bf16 v[10:13], v[160:163], v[208:211], v[10:13]
	v_mfma_f32_16x16x32_bf16 v[62:65], v[156:159], v[188:191], v[62:65]
	v_mfma_f32_16x16x32_bf16 v[58:61], v[164:167], v[188:191], v[58:61]
	v_mfma_f32_16x16x32_bf16 v[46:49], v[156:159], v[196:199], v[46:49]
	v_mfma_f32_16x16x32_bf16 v[42:45], v[164:167], v[196:199], v[42:45]
	v_mfma_f32_16x16x32_bf16 v[30:33], v[156:159], v[204:207], v[30:33]
	v_mfma_f32_16x16x32_bf16 v[26:29], v[164:167], v[204:207], v[26:29]
	v_mfma_f32_16x16x32_bf16 v[14:17], v[156:159], v[212:215], v[14:17]
	v_mfma_f32_16x16x32_bf16 v[10:13], v[164:167], v[212:215], v[10:13]
	v_mfma_f32_16x16x32_bf16 v[54:57], v[168:171], v[184:187], v[54:57]
	v_mfma_f32_16x16x32_bf16 v[50:53], v[176:179], v[184:187], v[50:53]
	v_mfma_f32_16x16x32_bf16 v[38:41], v[168:171], v[192:195], v[38:41]
	v_mfma_f32_16x16x32_bf16 v[34:37], v[176:179], v[192:195], v[34:37]
	v_mfma_f32_16x16x32_bf16 v[22:25], v[168:171], v[200:203], v[22:25]
	v_mfma_f32_16x16x32_bf16 v[18:21], v[176:179], v[200:203], v[18:21]
	v_mfma_f32_16x16x32_bf16 v[6:9], v[168:171], v[208:211], v[6:9]
	v_mfma_f32_16x16x32_bf16 v[2:5], v[176:179], v[208:211], v[2:5]
	v_mfma_f32_16x16x32_bf16 v[54:57], v[172:175], v[188:191], v[54:57]
	v_mfma_f32_16x16x32_bf16 v[50:53], v[180:183], v[188:191], v[50:53]
	v_mfma_f32_16x16x32_bf16 v[38:41], v[172:175], v[196:199], v[38:41]
	v_mfma_f32_16x16x32_bf16 v[34:37], v[180:183], v[196:199], v[34:37]
	v_mfma_f32_16x16x32_bf16 v[22:25], v[172:175], v[204:207], v[22:25]
	v_mfma_f32_16x16x32_bf16 v[18:21], v[180:183], v[204:207], v[18:21]
	v_mfma_f32_16x16x32_bf16 v[6:9], v[172:175], v[212:215], v[6:9]
	v_mfma_f32_16x16x32_bf16 v[2:5], v[180:183], v[212:215], v[2:5]
	s_setprio 0
	s_barrier
	s_add_i32 s61, 0, 0x18000
	v_add_u32_e32 v155, s61, v150
	s_add_i32 s62, 0, 0x1c000
	ds_read_b128 v[146:149], v155
	ds_read_b128 v[156:159], v155 offset:1024
	ds_read_b128 v[160:163], v155 offset:2048
	ds_read_b128 v[164:167], v155 offset:3072
	v_add_u32_e32 v155, s62, v150
	ds_read_b128 v[168:171], v155
	ds_read_b128 v[172:175], v155 offset:1024
	ds_read_b128 v[176:179], v155 offset:2048
	ds_read_b128 v[180:183], v155 offset:3072
	s_add_u32 s34, s34, s12
	s_addc_u32 s35, s35, s13
	s_mov_b32 m0, s41
	v_lshl_add_u64 v[228:229], s[34:35], 0, v[130:131]
	ds_read_b128 v[184:187], v154 offset:32768
	ds_read_b128 v[188:191], v154 offset:33792
	ds_read_b128 v[192:195], v154 offset:34816
	ds_read_b128 v[196:199], v154 offset:35840
	ds_read_b128 v[200:203], v154 offset:36864
	ds_read_b128 v[204:207], v154 offset:37888
	ds_read_b128 v[208:211], v154 offset:38912
	ds_read_b128 v[212:215], v154 offset:39936
	global_load_lds_dwordx4 v[228:229], off
	v_lshl_add_u64 v[228:229], s[34:35], 0, v[134:135]
	s_mov_b32 m0, s42
	s_nop 0
	global_load_lds_dwordx4 v[228:229], off
	s_waitcnt vmcnt(8)
	s_waitcnt lgkmcnt(0)
	s_barrier
	s_setprio 1
	v_mfma_f32_16x16x32_bf16 v[126:129], v[146:149], v[184:187], v[126:129]
	v_mfma_f32_16x16x32_bf16 v[122:125], v[160:163], v[184:187], v[122:125]
	v_mfma_f32_16x16x32_bf16 v[110:113], v[146:149], v[192:195], v[110:113]
	v_mfma_f32_16x16x32_bf16 v[106:109], v[160:163], v[192:195], v[106:109]
	v_mfma_f32_16x16x32_bf16 v[94:97], v[146:149], v[200:203], v[94:97]
	v_mfma_f32_16x16x32_bf16 v[90:93], v[160:163], v[200:203], v[90:93]
	v_mfma_f32_16x16x32_bf16 v[78:81], v[146:149], v[208:211], v[78:81]
	v_mfma_f32_16x16x32_bf16 v[74:77], v[160:163], v[208:211], v[74:77]
	v_mfma_f32_16x16x32_bf16 v[126:129], v[156:159], v[188:191], v[126:129]
	v_mfma_f32_16x16x32_bf16 v[122:125], v[164:167], v[188:191], v[122:125]
	v_mfma_f32_16x16x32_bf16 v[110:113], v[156:159], v[196:199], v[110:113]
	v_mfma_f32_16x16x32_bf16 v[106:109], v[164:167], v[196:199], v[106:109]
	v_mfma_f32_16x16x32_bf16 v[94:97], v[156:159], v[204:207], v[94:97]
	v_mfma_f32_16x16x32_bf16 v[90:93], v[164:167], v[204:207], v[90:93]
	v_mfma_f32_16x16x32_bf16 v[78:81], v[156:159], v[212:215], v[78:81]
	v_mfma_f32_16x16x32_bf16 v[74:77], v[164:167], v[212:215], v[74:77]
	v_mfma_f32_16x16x32_bf16 v[118:121], v[168:171], v[184:187], v[118:121]
	v_mfma_f32_16x16x32_bf16 v[114:117], v[176:179], v[184:187], v[114:117]
	v_mfma_f32_16x16x32_bf16 v[102:105], v[168:171], v[192:195], v[102:105]
	v_mfma_f32_16x16x32_bf16 v[98:101], v[176:179], v[192:195], v[98:101]
	v_mfma_f32_16x16x32_bf16 v[86:89], v[168:171], v[200:203], v[86:89]
	v_mfma_f32_16x16x32_bf16 v[82:85], v[176:179], v[200:203], v[82:85]
	v_mfma_f32_16x16x32_bf16 v[70:73], v[168:171], v[208:211], v[70:73]
	v_mfma_f32_16x16x32_bf16 v[66:69], v[176:179], v[208:211], v[66:69]
	v_mfma_f32_16x16x32_bf16 v[118:121], v[172:175], v[188:191], v[118:121]
	v_mfma_f32_16x16x32_bf16 v[114:117], v[180:183], v[188:191], v[114:117]
	v_mfma_f32_16x16x32_bf16 v[102:105], v[172:175], v[196:199], v[102:105]
	v_mfma_f32_16x16x32_bf16 v[98:101], v[180:183], v[196:199], v[98:101]
	v_mfma_f32_16x16x32_bf16 v[86:89], v[172:175], v[204:207], v[86:89]
	v_mfma_f32_16x16x32_bf16 v[82:85], v[180:183], v[204:207], v[82:85]
	v_mfma_f32_16x16x32_bf16 v[70:73], v[172:175], v[212:215], v[70:73]
	v_mfma_f32_16x16x32_bf16 v[66:69], v[180:183], v[212:215], v[66:69]
	s_setprio 0
	s_barrier
; #define PG8_STAGE(bufoff, gbase, voff) do { _Pragma("unroll") for (int _i = 0; _i < 2; ++_i) \
;         __builtin_amdgcn_global_load_lds((const unsigned*)((const char*)(gbase) + (voff)[_i]), (PG8_LAS unsigned*)(lds + (bufoff) + ldsw + _i * 8192), 16, 0, 0); } while (0)
; #define PG8_LDA(dst, b, h) do { _Pragma("unroll") for (int m = 0; m < 4; ++m) _Pragma("unroll") for (int k = 0; k < 2; ++k) dst[m][k] = *(const PG8_LAS bf16x8*)(lds + PG8_SA(b, h) + aoff + m * 2048 + k * 1024); } while (0)
; #define PG8_MMA(ai, bj, At, Bt) do { __builtin_amdgcn_s_setprio(1); _Pragma("unroll") for (int m = 0; m < 4; ++m) _Pragma("unroll") for (int n = 0; n < 2; ++n) _Pragma("unroll") for (int k = 0; k < 2; ++k) \
;         acc[ai][bj][m][n] = __builtin_amdgcn_mfma_f32_16x16x32_bf16(Bt[n][k], At[m][k], acc[ai][bj][m][n], 0, 0, 0); __builtin_amdgcn_s_setprio(0); } while (0)
; #define PG8_WAIT_V(n) asm volatile("s_waitcnt vmcnt(" #n ")" ::: "memory")
; #define PG8_WAIT_L(n) asm volatile("s_waitcnt lgkmcnt(" #n ")" ::: "memory")
; #define PG8_BAR __builtin_amdgcn_s_barrier()
; #define PG8_SCHED __builtin_amdgcn_sched_barrier(0)
; template <class Epi, class Sched, bool ALIGN_EPI = false, bool SP2 = false>
; __device__ __forceinline__ void gemm_phase(PG8_LAS unsigned char* lds, const Gemm g, const Sched& S, const Epi& E) {
;     ...
;         for (int t = 0; t < nt; t += 2) {
;             const bool last = (t == nt - 2);
;             const char* a1 = cA + (size_t)(t + 1) * kstep;
;             const char* a2 = last ? nA : cA + (size_t)(t + 2) * kstep; const char* b2 = last ? nB : cB + (size_t)(t + 2) * kstep;
;     ...
;             PG8_LDA(At, 1, 1); PG8_STAGE(PG8_SB(1, 0), b3, voffB); PG8_STAGE(PG8_SB(1, 1), b3 + hstep, voffB); PG8_STAGE(PG8_SA(1, 0), a3, voffA);
;             PG8_WAIT_V(8); PG8_WAIT_L(0); PG8_BAR; PG8_MMA(1, 0, At, B0); PG8_MMA(1, 1, At, B1); PG8_BAR; PG8_SCHED;
	s_add_i32 s34, s61, s38
	v_lshl_add_u64 v[216:217], v[216:217], 0, s[20:21]
	s_mov_b32 m0, s34
	ds_read_b128 v[184:187], v154 offset:49152
	ds_read_b128 v[188:191], v154 offset:50176
	ds_read_b128 v[192:195], v154 offset:51200
	ds_read_b128 v[196:199], v154 offset:52224
	ds_read_b128 v[200:203], v154 offset:53248
	ds_read_b128 v[204:207], v154 offset:54272
	ds_read_b128 v[208:211], v154 offset:55296
	ds_read_b128 v[212:215], v154 offset:56320
	global_load_lds_dwordx4 v[216:217], off
	v_lshl_add_u64 v[216:217], v[218:219], 0, s[20:21]
	s_add_i32 m0, s34, 0x2000
	s_add_i32 s34, s62, s38
	global_load_lds_dwordx4 v[216:217], off
	v_lshl_add_u64 v[216:217], v[220:221], 0, s[20:21]
	s_mov_b32 m0, s34
	s_nop 0
	global_load_lds_dwordx4 v[216:217], off
	v_lshl_add_u64 v[216:217], v[222:223], 0, s[20:21]
	s_add_i32 m0, s34, 0x2000
	s_nop 0
	global_load_lds_dwordx4 v[216:217], off
	v_lshl_add_u64 v[216:217], v[224:225], 0, s[20:21]
	s_mov_b32 m0, s46
	s_nop 0
	global_load_lds_dwordx4 v[216:217], off
	v_lshl_add_u64 v[216:217], v[226:227], 0, s[20:21]
	s_mov_b32 m0, s47
	s_nop 0
	global_load_lds_dwordx4 v[216:217], off
	s_waitcnt vmcnt(8)
	s_waitcnt lgkmcnt(0)
	s_barrier
	s_setprio 1
	v_mfma_f32_16x16x32_bf16 v[62:65], v[146:149], v[184:187], v[62:65]
	v_mfma_f32_16x16x32_bf16 v[58:61], v[160:163], v[184:187], v[58:61]
	v_mfma_f32_16x16x32_bf16 v[46:49], v[146:149], v[192:195], v[46:49]
	v_mfma_f32_16x16x32_bf16 v[42:45], v[160:163], v[192:195], v[42:45]
	v_mfma_f32_16x16x32_bf16 v[30:33], v[146:149], v[200:203], v[30:33]
	v_mfma_f32_16x16x32_bf16 v[26:29], v[160:163], v[200:203], v[26:29]
	v_mfma_f32_16x16x32_bf16 v[14:17], v[146:149], v[208:211], v[14:17]
	v_mfma_f32_16x16x32_bf16 v[10:13], v[160:163], v[208:211], v[10:13]
	v_mfma_f32_16x16x32_bf16 v[62:65], v[156:159], v[188:191], v[62:65]
	v_mfma_f32_16x16x32_bf16 v[58:61], v[164:167], v[188:191], v[58:61]
	v_mfma_f32_16x16x32_bf16 v[46:49], v[156:159], v[196:199], v[46:49]
	v_mfma_f32_16x16x32_bf16 v[42:45], v[164:167], v[196:199], v[42:45]
	v_mfma_f32_16x16x32_bf16 v[30:33], v[156:159], v[204:207], v[30:33]
	v_mfma_f32_16x16x32_bf16 v[26:29], v[164:167], v[204:207], v[26:29]
	v_mfma_f32_16x16x32_bf16 v[14:17], v[156:159], v[212:215], v[14:17]
	v_mfma_f32_16x16x32_bf16 v[10:13], v[164:167], v[212:215], v[10:13]
	v_mfma_f32_16x16x32_bf16 v[54:57], v[168:171], v[184:187], v[54:57]
	v_mfma_f32_16x16x32_bf16 v[50:53], v[176:179], v[184:187], v[50:53]
	v_mfma_f32_16x16x32_bf16 v[38:41], v[168:171], v[192:195], v[38:41]
	v_mfma_f32_16x16x32_bf16 v[34:37], v[176:179], v[192:195], v[34:37]
	v_mfma_f32_16x16x32_bf16 v[22:25], v[168:171], v[200:203], v[22:25]
	v_mfma_f32_16x16x32_bf16 v[18:21], v[176:179], v[200:203], v[18:21]
	v_mfma_f32_16x16x32_bf16 v[6:9], v[168:171], v[208:211], v[6:9]
	v_mfma_f32_16x16x32_bf16 v[2:5], v[176:179], v[208:211], v[2:5]
	v_mfma_f32_16x16x32_bf16 v[54:57], v[172:175], v[188:191], v[54:57]
	v_mfma_f32_16x16x32_bf16 v[50:53], v[180:183], v[188:191], v[50:53]
	v_mfma_f32_16x16x32_bf16 v[38:41], v[172:175], v[196:199], v[38:41]
	v_mfma_f32_16x16x32_bf16 v[34:37], v[180:183], v[196:199], v[34:37]
	v_mfma_f32_16x16x32_bf16 v[22:25], v[172:175], v[204:207], v[22:25]
	v_mfma_f32_16x16x32_bf16 v[18:21], v[180:183], v[204:207], v[18:21]
	v_mfma_f32_16x16x32_bf16 v[6:9], v[172:175], v[212:215], v[6:9]
	v_mfma_f32_16x16x32_bf16 v[2:5], v[180:183], v[212:215], v[2:5]
	s_setprio 0
	s_add_u32 s58, s58, 0x100
	s_addc_u32 s59, s59, 0
	s_add_u32 s30, s30, 0x100
	s_addc_u32 s31, s31, 0
	s_cmp_ge_i32 s60, s52
	s_mov_b32 s34, s60
	s_barrier
	s_cbranch_scc0 .LBB0_497

; #define PG8_STAGE(bufoff, gbase, voff) do { _Pragma("unroll") for (int _i = 0; _i < 2; ++_i) \
;         __builtin_amdgcn_global_load_lds((const unsigned*)((const char*)(gbase) + (voff)[_i]), (PG8_LAS unsigned*)(lds + (bufoff) + ldsw + _i * 8192), 16, 0, 0); } while (0)
; #define PG8_LDA(dst, b, h) do { _Pragma("unroll") for (int m = 0; m < 4; ++m) _Pragma("unroll") for (int k = 0; k < 2; ++k) dst[m][k] = *(const PG8_LAS bf16x8*)(lds + PG8_SA(b, h) + aoff + m * 2048 + k * 1024); } while (0)
; #define PG8_LDB(dst, b, h) do { _Pragma("unroll") for (int n = 0; n < 2; ++n) _Pragma("unroll") for (int k = 0; k < 2; ++k) dst[n][k] = *(const PG8_LAS bf16x8*)(lds + PG8_SB(b, h) + boff + n * 2048 + k * 1024); } while (0)
; #define PG8_MMA(ai, bj, At, Bt) do { __builtin_amdgcn_s_setprio(1); _Pragma("unroll") for (int m = 0; m < 4; ++m) _Pragma("unroll") for (int n = 0; n < 2; ++n) _Pragma("unroll") for (int k = 0; k < 2; ++k) \
;         acc[ai][bj][m][n] = __builtin_amdgcn_mfma_f32_16x16x32_bf16(Bt[n][k], At[m][k], acc[ai][bj][m][n], 0, 0, 0); __builtin_amdgcn_s_setprio(0); } while (0)
; #define PG8_WAIT_V(n) asm volatile("s_waitcnt vmcnt(" #n ")" ::: "memory")
; #define PG8_WAIT_L(n) asm volatile("s_waitcnt lgkmcnt(" #n ")" ::: "memory")
; #define PG8_BAR __builtin_amdgcn_s_barrier()
; #define PG8_SCHED __builtin_amdgcn_sched_barrier(0)
; template <class Epi, class Sched, bool ALIGN_EPI = false, bool SP2 = false>
; __device__ __forceinline__ void gemm_phase(PG8_LAS unsigned char* lds, const Gemm g, const Sched& S, const Epi& E) {
;     ...
;             PG8_LDB(B0, 0, 0); PG8_LDB(B1, 0, 1); PG8_SCHED; PG8_LDA(At, 0, 0); PG8_STAGE(PG8_SA(1, 1), a1 + hstep, voffA);
;             PG8_WAIT_V(8); PG8_WAIT_L(0); PG8_BAR; PG8_MMA(0, 0, At, B0); PG8_MMA(0, 1, At, B1); PG8_BAR; PG8_SCHED;
;             PG8_LDA(At, 0, 1); PG8_STAGE(PG8_SB(0, 0), b2, voffB); PG8_STAGE(PG8_SB(0, 1), b2 + hstep, voffB); PG8_STAGE(PG8_SA(0, 0), a2, voffA);
;             PG8_WAIT_V(8); PG8_WAIT_L(0); PG8_BAR; PG8_MMA(1, 0, At, B0); PG8_MMA(1, 1, At, B1); PG8_BAR; PG8_SCHED;
.LBB0_582:
	ds_read_b128 v[152:155], v148
	ds_read_b128 v[156:159], v148 offset:1024
	ds_read_b128 v[160:163], v148 offset:2048
	ds_read_b128 v[164:167], v148 offset:3072
	ds_read_b128 v[168:171], v149
	ds_read_b128 v[172:175], v149 offset:1024
	ds_read_b128 v[176:179], v149 offset:2048
	ds_read_b128 v[180:183], v149 offset:3072
	s_add_i32 s60, s30, 2
	s_add_u32 s61, s28, 0x80
	s_addc_u32 s31, s29, 0
	s_cmp_eq_u32 s45, s30
	s_cselect_b32 s30, s6, s61
	s_cselect_b32 s31, s7, s31
	s_cselect_b32 s63, s25, s59
	s_cselect_b32 s62, s24, s58
	v_lshl_add_u64 v[216:217], s[28:29], 0, v[140:141]
	s_add_i32 m0, s0, 0xc000
	ds_read_b128 v[184:187], v150
	ds_read_b128 v[188:191], v150 offset:1024
	ds_read_b128 v[192:195], v150 offset:2048
	ds_read_b128 v[196:199], v150 offset:3072
	ds_read_b128 v[200:203], v150 offset:4096
	ds_read_b128 v[204:207], v150 offset:5120
	ds_read_b128 v[208:211], v150 offset:6144
	ds_read_b128 v[212:215], v150 offset:7168
	global_load_lds_dwordx4 v[216:217], off
	v_lshl_add_u64 v[216:217], s[28:29], 0, v[138:139]
	s_add_i32 m0, s0, 0xe000
	s_nop 0
	global_load_lds_dwordx4 v[216:217], off
	s_waitcnt vmcnt(8)
	s_waitcnt lgkmcnt(0)
	s_barrier
	s_setprio 1
	v_mfma_f32_16x16x32_bf16 v[122:125], v[152:155], v[184:187], v[122:125]
	v_mfma_f32_16x16x32_bf16 v[126:129], v[160:163], v[184:187], v[126:129]
	v_mfma_f32_16x16x32_bf16 v[110:113], v[152:155], v[192:195], v[110:113]
	v_mfma_f32_16x16x32_bf16 v[106:109], v[160:163], v[192:195], v[106:109]
	v_mfma_f32_16x16x32_bf16 v[94:97], v[152:155], v[200:203], v[94:97]
	v_mfma_f32_16x16x32_bf16 v[90:93], v[160:163], v[200:203], v[90:93]
	v_mfma_f32_16x16x32_bf16 v[78:81], v[152:155], v[208:211], v[78:81]
	v_mfma_f32_16x16x32_bf16 v[74:77], v[160:163], v[208:211], v[74:77]
	v_mfma_f32_16x16x32_bf16 v[122:125], v[156:159], v[188:191], v[122:125]
	v_mfma_f32_16x16x32_bf16 v[126:129], v[164:167], v[188:191], v[126:129]
	v_mfma_f32_16x16x32_bf16 v[110:113], v[156:159], v[196:199], v[110:113]
	v_mfma_f32_16x16x32_bf16 v[106:109], v[164:167], v[196:199], v[106:109]
	v_mfma_f32_16x16x32_bf16 v[94:97], v[156:159], v[204:207], v[94:97]
	v_mfma_f32_16x16x32_bf16 v[90:93], v[164:167], v[204:207], v[90:93]
	v_mfma_f32_16x16x32_bf16 v[78:81], v[156:159], v[212:215], v[78:81]
	v_mfma_f32_16x16x32_bf16 v[74:77], v[164:167], v[212:215], v[74:77]
	v_mfma_f32_16x16x32_bf16 v[118:121], v[168:171], v[184:187], v[118:121]
	v_mfma_f32_16x16x32_bf16 v[114:117], v[176:179], v[184:187], v[114:117]
	v_mfma_f32_16x16x32_bf16 v[102:105], v[168:171], v[192:195], v[102:105]
	v_mfma_f32_16x16x32_bf16 v[98:101], v[176:179], v[192:195], v[98:101]
	v_mfma_f32_16x16x32_bf16 v[86:89], v[168:171], v[200:203], v[86:89]
	v_mfma_f32_16x16x32_bf16 v[82:85], v[176:179], v[200:203], v[82:85]
	v_mfma_f32_16x16x32_bf16 v[70:73], v[168:171], v[208:211], v[70:73]
	v_mfma_f32_16x16x32_bf16 v[66:69], v[176:179], v[208:211], v[66:69]
	v_mfma_f32_16x16x32_bf16 v[118:121], v[172:175], v[188:191], v[118:121]
	v_mfma_f32_16x16x32_bf16 v[114:117], v[180:183], v[188:191], v[114:117]
	v_mfma_f32_16x16x32_bf16 v[102:105], v[172:175], v[196:199], v[102:105]
	v_mfma_f32_16x16x32_bf16 v[98:101], v[180:183], v[196:199], v[98:101]
	v_mfma_f32_16x16x32_bf16 v[86:89], v[172:175], v[204:207], v[86:89]
	v_mfma_f32_16x16x32_bf16 v[82:85], v[180:183], v[204:207], v[82:85]
	v_mfma_f32_16x16x32_bf16 v[70:73], v[172:175], v[212:215], v[70:73]
	v_mfma_f32_16x16x32_bf16 v[66:69], v[180:183], v[212:215], v[66:69]
	s_setprio 0
	s_barrier
	s_add_i32 s61, s52, s38
	v_lshl_add_u64 v[216:217], s[62:63], 0, v[132:133]
	s_mov_b32 m0, s61
	ds_read_b128 v[184:187], v150 offset:16384
	ds_read_b128 v[188:191], v150 offset:17408
	ds_read_b128 v[192:195], v150 offset:18432
	ds_read_b128 v[196:199], v150 offset:19456
	ds_read_b128 v[200:203], v150 offset:20480
	ds_read_b128 v[204:207], v150 offset:21504
	ds_read_b128 v[208:211], v150 offset:22528
	ds_read_b128 v[212:215], v150 offset:23552
	global_load_lds_dwordx4 v[216:217], off
	s_add_i32 m0, s61, 0x2000
	v_lshl_add_u64 v[218:219], s[62:63], 0, v[136:137]
	s_add_u32 s62, s62, s10
	s_addc_u32 s63, s63, s11
	s_add_i32 s61, s53, s38
	global_load_lds_dwordx4 v[218:219], off
	v_lshl_add_u64 v[220:221], s[62:63], 0, v[132:133]
	s_mov_b32 m0, s61
	v_lshl_add_u64 v[222:223], s[62:63], 0, v[136:137]
	global_load_lds_dwordx4 v[220:221], off
	s_add_i32 m0, s61, 0x2000
	v_lshl_add_u64 v[224:225], s[30:31], 0, v[130:131]
	global_load_lds_dwordx4 v[222:223], off
	s_mov_b32 m0, s0
	v_lshl_add_u64 v[226:227], s[30:31], 0, v[134:135]
	global_load_lds_dwordx4 v[224:225], off
	s_mov_b32 m0, s1
	s_nop 0
	global_load_lds_dwordx4 v[226:227], off
	s_waitcnt vmcnt(8)
	s_waitcnt lgkmcnt(0)
	s_barrier
; #define PG8_STAGE(bufoff, gbase, voff) do { _Pragma("unroll") for (int _i = 0; _i < 2; ++_i) \
;         __builtin_amdgcn_global_load_lds((const unsigned*)((const char*)(gbase) + (voff)[_i]), (PG8_LAS unsigned*)(lds + (bufoff) + ldsw + _i * 8192), 16, 0, 0); } while (0)
; #define PG8_LDA(dst, b, h) do { _Pragma("unroll") for (int m = 0; m < 4; ++m) _Pragma("unroll") for (int k = 0; k < 2; ++k) dst[m][k] = *(const PG8_LAS bf16x8*)(lds + PG8_SA(b, h) + aoff + m * 2048 + k * 1024); } while (0)
; #define PG8_LDB(dst, b, h) do { _Pragma("unroll") for (int n = 0; n < 2; ++n) _Pragma("unroll") for (int k = 0; k < 2; ++k) dst[n][k] = *(const PG8_LAS bf16x8*)(lds + PG8_SB(b, h) + boff + n * 2048 + k * 1024); } while (0)
; #define PG8_MMA(ai, bj, At, Bt) do { __builtin_amdgcn_s_setprio(1); _Pragma("unroll") for (int m = 0; m < 4; ++m) _Pragma("unroll") for (int n = 0; n < 2; ++n) _Pragma("unroll") for (int k = 0; k < 2; ++k) \
;         acc[ai][bj][m][n] = __builtin_amdgcn_mfma_f32_16x16x32_bf16(Bt[n][k], At[m][k], acc[ai][bj][m][n], 0, 0, 0); __builtin_amdgcn_s_setprio(0); } while (0)
; #define PG8_WAIT_V(n) asm volatile("s_waitcnt vmcnt(" #n ")" ::: "memory")
; #define PG8_WAIT_L(n) asm volatile("s_waitcnt lgkmcnt(" #n ")" ::: "memory")
; #define PG8_BAR __builtin_amdgcn_s_barrier()
; #define PG8_SCHED __builtin_amdgcn_sched_barrier(0)
; template <class Epi, class Sched, bool ALIGN_EPI = false, bool SP2 = false>
; __device__ __forceinline__ void gemm_phase(PG8_LAS unsigned char* lds, const Gemm g, const Sched& S, const Epi& E) {
;     ...
;             PG8_WAIT_V(8); PG8_WAIT_L(0); PG8_BAR; PG8_MMA(1, 0, At, B0); PG8_MMA(1, 1, At, B1); PG8_BAR; PG8_SCHED;
;             PG8_LDB(B0, 1, 0); PG8_LDB(B1, 1, 1); PG8_SCHED; PG8_LDA(At, 1, 0); PG8_STAGE(PG8_SA(0, 1), a2 + hstep, voffA);
;             PG8_WAIT_V(8); PG8_WAIT_L(0); PG8_BAR; PG8_MMA(0, 0, At, B0); PG8_MMA(0, 1, At, B1); PG8_BAR; PG8_SCHED;
	s_setprio 1
	v_mfma_f32_16x16x32_bf16 v[62:65], v[152:155], v[184:187], v[62:65]
	v_mfma_f32_16x16x32_bf16 v[58:61], v[160:163], v[184:187], v[58:61]
	v_mfma_f32_16x16x32_bf16 v[46:49], v[152:155], v[192:195], v[46:49]
	v_mfma_f32_16x16x32_bf16 v[42:45], v[160:163], v[192:195], v[42:45]
	v_mfma_f32_16x16x32_bf16 v[30:33], v[152:155], v[200:203], v[30:33]
	v_mfma_f32_16x16x32_bf16 v[26:29], v[160:163], v[200:203], v[26:29]
	v_mfma_f32_16x16x32_bf16 v[14:17], v[152:155], v[208:211], v[14:17]
	v_mfma_f32_16x16x32_bf16 v[10:13], v[160:163], v[208:211], v[10:13]
	v_mfma_f32_16x16x32_bf16 v[62:65], v[156:159], v[188:191], v[62:65]
	v_mfma_f32_16x16x32_bf16 v[58:61], v[164:167], v[188:191], v[58:61]
	v_mfma_f32_16x16x32_bf16 v[46:49], v[156:159], v[196:199], v[46:49]
	v_mfma_f32_16x16x32_bf16 v[42:45], v[164:167], v[196:199], v[42:45]
	v_mfma_f32_16x16x32_bf16 v[30:33], v[156:159], v[204:207], v[30:33]
	v_mfma_f32_16x16x32_bf16 v[26:29], v[164:167], v[204:207], v[26:29]
	v_mfma_f32_16x16x32_bf16 v[14:17], v[156:159], v[212:215], v[14:17]
	v_mfma_f32_16x16x32_bf16 v[10:13], v[164:167], v[212:215], v[10:13]
	v_mfma_f32_16x16x32_bf16 v[54:57], v[168:171], v[184:187], v[54:57]
	v_mfma_f32_16x16x32_bf16 v[50:53], v[176:179], v[184:187], v[50:53]
	v_mfma_f32_16x16x32_bf16 v[38:41], v[168:171], v[192:195], v[38:41]
	v_mfma_f32_16x16x32_bf16 v[34:37], v[176:179], v[192:195], v[34:37]
	v_mfma_f32_16x16x32_bf16 v[22:25], v[168:171], v[200:203], v[22:25]
	v_mfma_f32_16x16x32_bf16 v[18:21], v[176:179], v[200:203], v[18:21]
	v_mfma_f32_16x16x32_bf16 v[6:9], v[168:171], v[208:211], v[6:9]
	v_mfma_f32_16x16x32_bf16 v[2:5], v[176:179], v[208:211], v[2:5]
	v_mfma_f32_16x16x32_bf16 v[54:57], v[172:175], v[188:191], v[54:57]
	v_mfma_f32_16x16x32_bf16 v[50:53], v[180:183], v[188:191], v[50:53]
	v_mfma_f32_16x16x32_bf16 v[38:41], v[172:175], v[196:199], v[38:41]
	v_mfma_f32_16x16x32_bf16 v[34:37], v[180:183], v[196:199], v[34:37]
	v_mfma_f32_16x16x32_bf16 v[22:25], v[172:175], v[204:207], v[22:25]
	v_mfma_f32_16x16x32_bf16 v[18:21], v[180:183], v[204:207], v[18:21]
	v_mfma_f32_16x16x32_bf16 v[6:9], v[172:175], v[212:215], v[6:9]
	v_mfma_f32_16x16x32_bf16 v[2:5], v[180:183], v[212:215], v[2:5]
	s_setprio 0
	s_barrier
	s_add_i32 s61, 0, 0x18000
	v_add_u32_e32 v151, s61, v146
	s_add_i32 s62, 0, 0x1c000
	ds_read_b128 v[152:155], v151
	ds_read_b128 v[156:159], v151 offset:1024
	ds_read_b128 v[160:163], v151 offset:2048
	ds_read_b128 v[164:167], v151 offset:3072
	v_add_u32_e32 v151, s62, v146
	ds_read_b128 v[168:171], v151
	ds_read_b128 v[172:175], v151 offset:1024
	ds_read_b128 v[176:179], v151 offset:2048
	ds_read_b128 v[180:183], v151 offset:3072
	s_add_u32 s30, s30, s10
	s_addc_u32 s31, s31, s11
	s_mov_b32 m0, s39
	v_lshl_add_u64 v[228:229], s[30:31], 0, v[130:131]
	ds_read_b128 v[184:187], v150 offset:32768
	ds_read_b128 v[188:191], v150 offset:33792
	ds_read_b128 v[192:195], v150 offset:34816
	ds_read_b128 v[196:199], v150 offset:35840
	ds_read_b128 v[200:203], v150 offset:36864
	ds_read_b128 v[204:207], v150 offset:37888
	ds_read_b128 v[208:211], v150 offset:38912
	ds_read_b128 v[212:215], v150 offset:39936
	global_load_lds_dwordx4 v[228:229], off
	v_lshl_add_u64 v[228:229], s[30:31], 0, v[134:135]
	s_mov_b32 m0, s40
	s_nop 0
	global_load_lds_dwordx4 v[228:229], off
	s_waitcnt vmcnt(8)
	s_waitcnt lgkmcnt(0)
	s_barrier
	s_setprio 1
	v_mfma_f32_16x16x32_bf16 v[122:125], v[152:155], v[184:187], v[122:125]
	v_mfma_f32_16x16x32_bf16 v[126:129], v[160:163], v[184:187], v[126:129]
	v_mfma_f32_16x16x32_bf16 v[110:113], v[152:155], v[192:195], v[110:113]
	v_mfma_f32_16x16x32_bf16 v[106:109], v[160:163], v[192:195], v[106:109]
	v_mfma_f32_16x16x32_bf16 v[94:97], v[152:155], v[200:203], v[94:97]
	v_mfma_f32_16x16x32_bf16 v[90:93], v[160:163], v[200:203], v[90:93]
	v_mfma_f32_16x16x32_bf16 v[78:81], v[152:155], v[208:211], v[78:81]
	v_mfma_f32_16x16x32_bf16 v[74:77], v[160:163], v[208:211], v[74:77]
	v_mfma_f32_16x16x32_bf16 v[122:125], v[156:159], v[188:191], v[122:125]
	v_mfma_f32_16x16x32_bf16 v[126:129], v[164:167], v[188:191], v[126:129]
	v_mfma_f32_16x16x32_bf16 v[110:113], v[156:159], v[196:199], v[110:113]
	v_mfma_f32_16x16x32_bf16 v[106:109], v[164:167], v[196:199], v[106:109]
	v_mfma_f32_16x16x32_bf16 v[94:97], v[156:159], v[204:207], v[94:97]
	v_mfma_f32_16x16x32_bf16 v[90:93], v[164:167], v[204:207], v[90:93]
	v_mfma_f32_16x16x32_bf16 v[78:81], v[156:159], v[212:215], v[78:81]
	v_mfma_f32_16x16x32_bf16 v[74:77], v[164:167], v[212:215], v[74:77]
	v_mfma_f32_16x16x32_bf16 v[118:121], v[168:171], v[184:187], v[118:121]
	v_mfma_f32_16x16x32_bf16 v[114:117], v[176:179], v[184:187], v[114:117]
	v_mfma_f32_16x16x32_bf16 v[102:105], v[168:171], v[192:195], v[102:105]
	v_mfma_f32_16x16x32_bf16 v[98:101], v[176:179], v[192:195], v[98:101]
	v_mfma_f32_16x16x32_bf16 v[86:89], v[168:171], v[200:203], v[86:89]
	v_mfma_f32_16x16x32_bf16 v[82:85], v[176:179], v[200:203], v[82:85]
	v_mfma_f32_16x16x32_bf16 v[70:73], v[168:171], v[208:211], v[70:73]
	v_mfma_f32_16x16x32_bf16 v[66:69], v[176:179], v[208:211], v[66:69]
	v_mfma_f32_16x16x32_bf16 v[118:121], v[172:175], v[188:191], v[118:121]
	v_mfma_f32_16x16x32_bf16 v[114:117], v[180:183], v[188:191], v[114:117]
	v_mfma_f32_16x16x32_bf16 v[102:105], v[172:175], v[196:199], v[102:105]
	v_mfma_f32_16x16x32_bf16 v[98:101], v[180:183], v[196:199], v[98:101]
	v_mfma_f32_16x16x32_bf16 v[86:89], v[172:175], v[204:207], v[86:89]
	v_mfma_f32_16x16x32_bf16 v[82:85], v[180:183], v[204:207], v[82:85]
	v_mfma_f32_16x16x32_bf16 v[70:73], v[172:175], v[212:215], v[70:73]
	v_mfma_f32_16x16x32_bf16 v[66:69], v[180:183], v[212:215], v[66:69]
	s_setprio 0
	s_barrier
; #define PG8_STAGE(bufoff, gbase, voff) do { _Pragma("unroll") for (int _i = 0; _i < 2; ++_i) \
;         __builtin_amdgcn_global_load_lds((const unsigned*)((const char*)(gbase) + (voff)[_i]), (PG8_LAS unsigned*)(lds + (bufoff) + ldsw + _i * 8192), 16, 0, 0); } while (0)
; #define PG8_LDA(dst, b, h) do { _Pragma("unroll") for (int m = 0; m < 4; ++m) _Pragma("unroll") for (int k = 0; k < 2; ++k) dst[m][k] = *(const PG8_LAS bf16x8*)(lds + PG8_SA(b, h) + aoff + m * 2048 + k * 1024); } while (0)
; #define PG8_MMA(ai, bj, At, Bt) do { __builtin_amdgcn_s_setprio(1); _Pragma("unroll") for (int m = 0; m < 4; ++m) _Pragma("unroll") for (int n = 0; n < 2; ++n) _Pragma("unroll") for (int k = 0; k < 2; ++k) \
;         acc[ai][bj][m][n] = __builtin_amdgcn_mfma_f32_16x16x32_bf16(Bt[n][k], At[m][k], acc[ai][bj][m][n], 0, 0, 0); __builtin_amdgcn_s_setprio(0); } while (0)
; #define PG8_WAIT_V(n) asm volatile("s_waitcnt vmcnt(" #n ")" ::: "memory")
; #define PG8_WAIT_L(n) asm volatile("s_waitcnt lgkmcnt(" #n ")" ::: "memory")
; #define PG8_BAR __builtin_amdgcn_s_barrier()
; #define PG8_SCHED __builtin_amdgcn_sched_barrier(0)
; template <class Epi, class Sched, bool ALIGN_EPI = false, bool SP2 = false>
; __device__ __forceinline__ void gemm_phase(PG8_LAS unsigned char* lds, const Gemm g, const Sched& S, const Epi& E) {
;     ...
;         for (int t = 0; t < nt; t += 2) {
;             const bool last = (t == nt - 2);
;             const char* a1 = cA + (size_t)(t + 1) * kstep;
;             const char* a2 = last ? nA : cA + (size_t)(t + 2) * kstep; const char* b2 = last ? nB : cB + (size_t)(t + 2) * kstep;
;     ...
;             PG8_LDA(At, 1, 1); PG8_STAGE(PG8_SB(1, 0), b3, voffB); PG8_STAGE(PG8_SB(1, 1), b3 + hstep, voffB); PG8_STAGE(PG8_SA(1, 0), a3, voffA);
;             PG8_WAIT_V(8); PG8_WAIT_L(0); PG8_BAR; PG8_MMA(1, 0, At, B0); PG8_MMA(1, 1, At, B1); PG8_BAR; PG8_SCHED;
	s_add_i32 s30, s61, s38
	v_lshl_add_u64 v[216:217], v[216:217], 0, s[18:19]
	s_mov_b32 m0, s30
	ds_read_b128 v[184:187], v150 offset:49152
	ds_read_b128 v[188:191], v150 offset:50176
	ds_read_b128 v[192:195], v150 offset:51200
	ds_read_b128 v[196:199], v150 offset:52224
	ds_read_b128 v[200:203], v150 offset:53248
	ds_read_b128 v[204:207], v150 offset:54272
	ds_read_b128 v[208:211], v150 offset:55296
	ds_read_b128 v[212:215], v150 offset:56320
	global_load_lds_dwordx4 v[216:217], off
	v_lshl_add_u64 v[216:217], v[218:219], 0, s[18:19]
	s_add_i32 m0, s30, 0x2000
	s_add_i32 s30, s62, s38
	global_load_lds_dwordx4 v[216:217], off
	v_lshl_add_u64 v[216:217], v[220:221], 0, s[18:19]
	s_mov_b32 m0, s30
	s_nop 0
	global_load_lds_dwordx4 v[216:217], off
	v_lshl_add_u64 v[216:217], v[222:223], 0, s[18:19]
	s_add_i32 m0, s30, 0x2000
	s_nop 0
	global_load_lds_dwordx4 v[216:217], off
	v_lshl_add_u64 v[216:217], v[224:225], 0, s[18:19]
	s_mov_b32 m0, s42
	s_nop 0
	global_load_lds_dwordx4 v[216:217], off
	v_lshl_add_u64 v[216:217], v[226:227], 0, s[18:19]
	s_mov_b32 m0, s43
	s_nop 0
	global_load_lds_dwordx4 v[216:217], off
	s_waitcnt vmcnt(8)
	s_waitcnt lgkmcnt(0)
	s_barrier
	s_setprio 1
	v_mfma_f32_16x16x32_bf16 v[62:65], v[152:155], v[184:187], v[62:65]
	v_mfma_f32_16x16x32_bf16 v[58:61], v[160:163], v[184:187], v[58:61]
	v_mfma_f32_16x16x32_bf16 v[46:49], v[152:155], v[192:195], v[46:49]
	v_mfma_f32_16x16x32_bf16 v[42:45], v[160:163], v[192:195], v[42:45]
	v_mfma_f32_16x16x32_bf16 v[30:33], v[152:155], v[200:203], v[30:33]
	v_mfma_f32_16x16x32_bf16 v[26:29], v[160:163], v[200:203], v[26:29]
	v_mfma_f32_16x16x32_bf16 v[14:17], v[152:155], v[208:211], v[14:17]
	v_mfma_f32_16x16x32_bf16 v[10:13], v[160:163], v[208:211], v[10:13]
	v_mfma_f32_16x16x32_bf16 v[62:65], v[156:159], v[188:191], v[62:65]
	v_mfma_f32_16x16x32_bf16 v[58:61], v[164:167], v[188:191], v[58:61]
	v_mfma_f32_16x16x32_bf16 v[46:49], v[156:159], v[196:199], v[46:49]
	v_mfma_f32_16x16x32_bf16 v[42:45], v[164:167], v[196:199], v[42:45]
	v_mfma_f32_16x16x32_bf16 v[30:33], v[156:159], v[204:207], v[30:33]
	v_mfma_f32_16x16x32_bf16 v[26:29], v[164:167], v[204:207], v[26:29]
	v_mfma_f32_16x16x32_bf16 v[14:17], v[156:159], v[212:215], v[14:17]
	v_mfma_f32_16x16x32_bf16 v[10:13], v[164:167], v[212:215], v[10:13]
	v_mfma_f32_16x16x32_bf16 v[54:57], v[168:171], v[184:187], v[54:57]
	v_mfma_f32_16x16x32_bf16 v[50:53], v[176:179], v[184:187], v[50:53]
	v_mfma_f32_16x16x32_bf16 v[38:41], v[168:171], v[192:195], v[38:41]
	v_mfma_f32_16x16x32_bf16 v[34:37], v[176:179], v[192:195], v[34:37]
	v_mfma_f32_16x16x32_bf16 v[22:25], v[168:171], v[200:203], v[22:25]
	v_mfma_f32_16x16x32_bf16 v[18:21], v[176:179], v[200:203], v[18:21]
	v_mfma_f32_16x16x32_bf16 v[6:9], v[168:171], v[208:211], v[6:9]
	v_mfma_f32_16x16x32_bf16 v[2:5], v[176:179], v[208:211], v[2:5]
	v_mfma_f32_16x16x32_bf16 v[54:57], v[172:175], v[188:191], v[54:57]
	v_mfma_f32_16x16x32_bf16 v[50:53], v[180:183], v[188:191], v[50:53]
	v_mfma_f32_16x16x32_bf16 v[38:41], v[172:175], v[196:199], v[38:41]
	v_mfma_f32_16x16x32_bf16 v[34:37], v[180:183], v[196:199], v[34:37]
	v_mfma_f32_16x16x32_bf16 v[22:25], v[172:175], v[204:207], v[22:25]
	v_mfma_f32_16x16x32_bf16 v[18:21], v[180:183], v[204:207], v[18:21]
	v_mfma_f32_16x16x32_bf16 v[6:9], v[172:175], v[212:215], v[6:9]
	v_mfma_f32_16x16x32_bf16 v[2:5], v[180:183], v[212:215], v[2:5]
	s_setprio 0
	s_add_u32 s58, s58, 0x100
	s_addc_u32 s59, s59, 0
	s_add_u32 s28, s28, 0x100
	s_addc_u32 s29, s29, 0
	s_cmp_ge_i32 s60, s44
	s_mov_b32 s30, s60
	s_barrier
	s_cbranch_scc0 .LBB0_582

; #define PG8_STAGE(bufoff, gbase, voff) do { _Pragma("unroll") for (int _i = 0; _i < 2; ++_i) \
;         __builtin_amdgcn_global_load_lds((const unsigned*)((const char*)(gbase) + (voff)[_i]), (PG8_LAS unsigned*)(lds + (bufoff) + ldsw + _i * 8192), 16, 0, 0); } while (0)
; #define PG8_LDA(dst, b, h) do { _Pragma("unroll") for (int m = 0; m < 4; ++m) _Pragma("unroll") for (int k = 0; k < 2; ++k) dst[m][k] = *(const PG8_LAS bf16x8*)(lds + PG8_SA(b, h) + aoff + m * 2048 + k * 1024); } while (0)
; #define PG8_LDB(dst, b, h) do { _Pragma("unroll") for (int n = 0; n < 2; ++n) _Pragma("unroll") for (int k = 0; k < 2; ++k) dst[n][k] = *(const PG8_LAS bf16x8*)(lds + PG8_SB(b, h) + boff + n * 2048 + k * 1024); } while (0)
; #define PG8_MMA(ai, bj, At, Bt) do { __builtin_amdgcn_s_setprio(1); _Pragma("unroll") for (int m = 0; m < 4; ++m) _Pragma("unroll") for (int n = 0; n < 2; ++n) _Pragma("unroll") for (int k = 0; k < 2; ++k) \
;         acc[ai][bj][m][n] = __builtin_amdgcn_mfma_f32_16x16x32_bf16(Bt[n][k], At[m][k], acc[ai][bj][m][n], 0, 0, 0); __builtin_amdgcn_s_setprio(0); } while (0)
; #define PG8_WAIT_V(n) asm volatile("s_waitcnt vmcnt(" #n ")" ::: "memory")
; #define PG8_WAIT_L(n) asm volatile("s_waitcnt lgkmcnt(" #n ")" ::: "memory")
; #define PG8_BAR __builtin_amdgcn_s_barrier()
; #define PG8_SCHED __builtin_amdgcn_sched_barrier(0)
; template <class Epi, class Sched, bool ALIGN_EPI = false, bool SP2 = false>
; __device__ __forceinline__ void gemm_phase(PG8_LAS unsigned char* lds, const Gemm g, const Sched& S, const Epi& E) {
;     ...
;             PG8_LDB(B0, 0, 0); PG8_LDB(B1, 0, 1); PG8_SCHED; PG8_LDA(At, 0, 0); PG8_STAGE(PG8_SA(1, 1), a1 + hstep, voffA);
;             PG8_WAIT_V(8); PG8_WAIT_L(0); PG8_BAR; PG8_MMA(0, 0, At, B0); PG8_MMA(0, 1, At, B1); PG8_BAR; PG8_SCHED;
;             PG8_LDA(At, 0, 1); PG8_STAGE(PG8_SB(0, 0), b2, voffB); PG8_STAGE(PG8_SB(0, 1), b2 + hstep, voffB); PG8_STAGE(PG8_SA(0, 0), a2, voffA);
;             PG8_WAIT_V(8); PG8_WAIT_L(0); PG8_BAR; PG8_MMA(1, 0, At, B0); PG8_MMA(1, 1, At, B1); PG8_BAR; PG8_SCHED;
.LBB0_749:
	ds_read_b128 v[152:155], v148
	ds_read_b128 v[156:159], v148 offset:1024
	ds_read_b128 v[160:163], v148 offset:2048
	ds_read_b128 v[164:167], v148 offset:3072
	ds_read_b128 v[168:171], v149
	ds_read_b128 v[172:175], v149 offset:1024
	ds_read_b128 v[176:179], v149 offset:2048
	ds_read_b128 v[180:183], v149 offset:3072
	s_add_i32 s60, s30, 2
	s_add_u32 s61, s28, 0x80
	s_addc_u32 s31, s29, 0
	s_cmp_eq_u32 s48, s30
	s_cselect_b32 s30, s6, s61
	s_cselect_b32 s31, s7, s31
	s_cselect_b32 s63, s25, s59
	s_cselect_b32 s62, s24, s58
	v_lshl_add_u64 v[216:217], s[28:29], 0, v[140:141]
	s_add_i32 m0, s40, 0xc000
	ds_read_b128 v[184:187], v150
	ds_read_b128 v[188:191], v150 offset:1024
	ds_read_b128 v[192:195], v150 offset:2048
	ds_read_b128 v[196:199], v150 offset:3072
	ds_read_b128 v[200:203], v150 offset:4096
	ds_read_b128 v[204:207], v150 offset:5120
	ds_read_b128 v[208:211], v150 offset:6144
	ds_read_b128 v[212:215], v150 offset:7168
	global_load_lds_dwordx4 v[216:217], off
	v_lshl_add_u64 v[216:217], s[28:29], 0, v[138:139]
	s_add_i32 m0, s40, 0xe000
	s_nop 0
	global_load_lds_dwordx4 v[216:217], off
	s_waitcnt vmcnt(8)
	s_waitcnt lgkmcnt(0)
	s_barrier
	s_setprio 1
	v_mfma_f32_16x16x32_bf16 v[122:125], v[152:155], v[184:187], v[122:125]
	v_mfma_f32_16x16x32_bf16 v[118:121], v[160:163], v[184:187], v[118:121]
	v_mfma_f32_16x16x32_bf16 v[110:113], v[152:155], v[192:195], v[110:113]
	v_mfma_f32_16x16x32_bf16 v[102:105], v[160:163], v[192:195], v[102:105]
	v_mfma_f32_16x16x32_bf16 v[94:97], v[152:155], v[200:203], v[94:97]
	v_mfma_f32_16x16x32_bf16 v[86:89], v[160:163], v[200:203], v[86:89]
	v_mfma_f32_16x16x32_bf16 v[78:81], v[152:155], v[208:211], v[78:81]
	v_mfma_f32_16x16x32_bf16 v[70:73], v[160:163], v[208:211], v[70:73]
	v_mfma_f32_16x16x32_bf16 v[122:125], v[156:159], v[188:191], v[122:125]
	v_mfma_f32_16x16x32_bf16 v[118:121], v[164:167], v[188:191], v[118:121]
	v_mfma_f32_16x16x32_bf16 v[110:113], v[156:159], v[196:199], v[110:113]
	v_mfma_f32_16x16x32_bf16 v[102:105], v[164:167], v[196:199], v[102:105]
	v_mfma_f32_16x16x32_bf16 v[94:97], v[156:159], v[204:207], v[94:97]
	v_mfma_f32_16x16x32_bf16 v[86:89], v[164:167], v[204:207], v[86:89]
	v_mfma_f32_16x16x32_bf16 v[78:81], v[156:159], v[212:215], v[78:81]
	v_mfma_f32_16x16x32_bf16 v[70:73], v[164:167], v[212:215], v[70:73]
	v_mfma_f32_16x16x32_bf16 v[126:129], v[168:171], v[184:187], v[126:129]
	v_mfma_f32_16x16x32_bf16 v[114:117], v[176:179], v[184:187], v[114:117]
	v_mfma_f32_16x16x32_bf16 v[106:109], v[168:171], v[192:195], v[106:109]
	v_mfma_f32_16x16x32_bf16 v[98:101], v[176:179], v[192:195], v[98:101]
	v_mfma_f32_16x16x32_bf16 v[90:93], v[168:171], v[200:203], v[90:93]
	v_mfma_f32_16x16x32_bf16 v[82:85], v[176:179], v[200:203], v[82:85]
	v_mfma_f32_16x16x32_bf16 v[74:77], v[168:171], v[208:211], v[74:77]
	v_mfma_f32_16x16x32_bf16 v[66:69], v[176:179], v[208:211], v[66:69]
	v_mfma_f32_16x16x32_bf16 v[126:129], v[172:175], v[188:191], v[126:129]
	v_mfma_f32_16x16x32_bf16 v[114:117], v[180:183], v[188:191], v[114:117]
	v_mfma_f32_16x16x32_bf16 v[106:109], v[172:175], v[196:199], v[106:109]
	v_mfma_f32_16x16x32_bf16 v[98:101], v[180:183], v[196:199], v[98:101]
	v_mfma_f32_16x16x32_bf16 v[90:93], v[172:175], v[204:207], v[90:93]
	v_mfma_f32_16x16x32_bf16 v[82:85], v[180:183], v[204:207], v[82:85]
	v_mfma_f32_16x16x32_bf16 v[74:77], v[172:175], v[212:215], v[74:77]
	v_mfma_f32_16x16x32_bf16 v[66:69], v[180:183], v[212:215], v[66:69]
	s_setprio 0
	s_barrier
	s_add_i32 s61, s53, s37
	v_lshl_add_u64 v[216:217], s[62:63], 0, v[134:135]
	s_mov_b32 m0, s61
	ds_read_b128 v[184:187], v150 offset:16384
	ds_read_b128 v[188:191], v150 offset:17408
	ds_read_b128 v[192:195], v150 offset:18432
	ds_read_b128 v[196:199], v150 offset:19456
	ds_read_b128 v[200:203], v150 offset:20480
	ds_read_b128 v[204:207], v150 offset:21504
	ds_read_b128 v[208:211], v150 offset:22528
	ds_read_b128 v[212:215], v150 offset:23552
	global_load_lds_dwordx4 v[216:217], off
	s_add_i32 m0, s61, 0x2000
	v_lshl_add_u64 v[218:219], s[62:63], 0, v[130:131]
	s_add_u32 s62, s62, s10
	s_addc_u32 s63, s63, s11
	s_add_i32 s61, s54, s37
	global_load_lds_dwordx4 v[218:219], off
	v_lshl_add_u64 v[220:221], s[62:63], 0, v[134:135]
	s_mov_b32 m0, s61
	v_lshl_add_u64 v[222:223], s[62:63], 0, v[130:131]
	global_load_lds_dwordx4 v[220:221], off
	s_add_i32 m0, s61, 0x2000
	v_lshl_add_u64 v[224:225], s[30:31], 0, v[136:137]
	global_load_lds_dwordx4 v[222:223], off
	s_mov_b32 m0, s40
	v_lshl_add_u64 v[226:227], s[30:31], 0, v[132:133]
	global_load_lds_dwordx4 v[224:225], off
	s_mov_b32 m0, s41
	s_nop 0
	global_load_lds_dwordx4 v[226:227], off
	s_waitcnt vmcnt(8)
	s_waitcnt lgkmcnt(0)
	s_barrier
; #define PG8_STAGE(bufoff, gbase, voff) do { _Pragma("unroll") for (int _i = 0; _i < 2; ++_i) \
;         __builtin_amdgcn_global_load_lds((const unsigned*)((const char*)(gbase) + (voff)[_i]), (PG8_LAS unsigned*)(lds + (bufoff) + ldsw + _i * 8192), 16, 0, 0); } while (0)
; #define PG8_LDA(dst, b, h) do { _Pragma("unroll") for (int m = 0; m < 4; ++m) _Pragma("unroll") for (int k = 0; k < 2; ++k) dst[m][k] = *(const PG8_LAS bf16x8*)(lds + PG8_SA(b, h) + aoff + m * 2048 + k * 1024); } while (0)
; #define PG8_LDB(dst, b, h) do { _Pragma("unroll") for (int n = 0; n < 2; ++n) _Pragma("unroll") for (int k = 0; k < 2; ++k) dst[n][k] = *(const PG8_LAS bf16x8*)(lds + PG8_SB(b, h) + boff + n * 2048 + k * 1024); } while (0)
; #define PG8_MMA(ai, bj, At, Bt) do { __builtin_amdgcn_s_setprio(1); _Pragma("unroll") for (int m = 0; m < 4; ++m) _Pragma("unroll") for (int n = 0; n < 2; ++n) _Pragma("unroll") for (int k = 0; k < 2; ++k) \
;         acc[ai][bj][m][n] = __builtin_amdgcn_mfma_f32_16x16x32_bf16(Bt[n][k], At[m][k], acc[ai][bj][m][n], 0, 0, 0); __builtin_amdgcn_s_setprio(0); } while (0)
; #define PG8_WAIT_V(n) asm volatile("s_waitcnt vmcnt(" #n ")" ::: "memory")
; #define PG8_WAIT_L(n) asm volatile("s_waitcnt lgkmcnt(" #n ")" ::: "memory")
; #define PG8_BAR __builtin_amdgcn_s_barrier()
; #define PG8_SCHED __builtin_amdgcn_sched_barrier(0)
; template <class Epi, class Sched, bool ALIGN_EPI = false, bool SP2 = false>
; __device__ __forceinline__ void gemm_phase(PG8_LAS unsigned char* lds, const Gemm g, const Sched& S, const Epi& E) {
;     ...
;             PG8_WAIT_V(8); PG8_WAIT_L(0); PG8_BAR; PG8_MMA(1, 0, At, B0); PG8_MMA(1, 1, At, B1); PG8_BAR; PG8_SCHED;
;             PG8_LDB(B0, 1, 0); PG8_LDB(B1, 1, 1); PG8_SCHED; PG8_LDA(At, 1, 0); PG8_STAGE(PG8_SA(0, 1), a2 + hstep, voffA);
;             PG8_WAIT_V(8); PG8_WAIT_L(0); PG8_BAR; PG8_MMA(0, 0, At, B0); PG8_MMA(0, 1, At, B1); PG8_BAR; PG8_SCHED;
	s_setprio 1
	v_mfma_f32_16x16x32_bf16 v[62:65], v[152:155], v[184:187], v[62:65]
	v_mfma_f32_16x16x32_bf16 v[54:57], v[160:163], v[184:187], v[54:57]
	v_mfma_f32_16x16x32_bf16 v[46:49], v[152:155], v[192:195], v[46:49]
	v_mfma_f32_16x16x32_bf16 v[38:41], v[160:163], v[192:195], v[38:41]
	v_mfma_f32_16x16x32_bf16 v[30:33], v[152:155], v[200:203], v[30:33]
	v_mfma_f32_16x16x32_bf16 v[22:25], v[160:163], v[200:203], v[22:25]
	v_mfma_f32_16x16x32_bf16 v[14:17], v[152:155], v[208:211], v[14:17]
	v_mfma_f32_16x16x32_bf16 v[6:9], v[160:163], v[208:211], v[6:9]
	v_mfma_f32_16x16x32_bf16 v[62:65], v[156:159], v[188:191], v[62:65]
	v_mfma_f32_16x16x32_bf16 v[54:57], v[164:167], v[188:191], v[54:57]
	v_mfma_f32_16x16x32_bf16 v[46:49], v[156:159], v[196:199], v[46:49]
	v_mfma_f32_16x16x32_bf16 v[38:41], v[164:167], v[196:199], v[38:41]
	v_mfma_f32_16x16x32_bf16 v[30:33], v[156:159], v[204:207], v[30:33]
	v_mfma_f32_16x16x32_bf16 v[22:25], v[164:167], v[204:207], v[22:25]
	v_mfma_f32_16x16x32_bf16 v[14:17], v[156:159], v[212:215], v[14:17]
	v_mfma_f32_16x16x32_bf16 v[6:9], v[164:167], v[212:215], v[6:9]
	v_mfma_f32_16x16x32_bf16 v[58:61], v[168:171], v[184:187], v[58:61]
	v_mfma_f32_16x16x32_bf16 v[50:53], v[176:179], v[184:187], v[50:53]
	v_mfma_f32_16x16x32_bf16 v[42:45], v[168:171], v[192:195], v[42:45]
	v_mfma_f32_16x16x32_bf16 v[34:37], v[176:179], v[192:195], v[34:37]
	v_mfma_f32_16x16x32_bf16 v[26:29], v[168:171], v[200:203], v[26:29]
	v_mfma_f32_16x16x32_bf16 v[18:21], v[176:179], v[200:203], v[18:21]
	v_mfma_f32_16x16x32_bf16 v[10:13], v[168:171], v[208:211], v[10:13]
	v_mfma_f32_16x16x32_bf16 v[2:5], v[176:179], v[208:211], v[2:5]
	v_mfma_f32_16x16x32_bf16 v[58:61], v[172:175], v[188:191], v[58:61]
	v_mfma_f32_16x16x32_bf16 v[50:53], v[180:183], v[188:191], v[50:53]
	v_mfma_f32_16x16x32_bf16 v[42:45], v[172:175], v[196:199], v[42:45]
	v_mfma_f32_16x16x32_bf16 v[34:37], v[180:183], v[196:199], v[34:37]
	v_mfma_f32_16x16x32_bf16 v[26:29], v[172:175], v[204:207], v[26:29]
	v_mfma_f32_16x16x32_bf16 v[18:21], v[180:183], v[204:207], v[18:21]
	v_mfma_f32_16x16x32_bf16 v[10:13], v[172:175], v[212:215], v[10:13]
	v_mfma_f32_16x16x32_bf16 v[2:5], v[180:183], v[212:215], v[2:5]
	s_setprio 0
	s_barrier
	s_add_i32 s61, 0, 0x18000
	v_add_u32_e32 v151, s61, v146
	s_add_i32 s62, 0, 0x1c000
	ds_read_b128 v[152:155], v151
	ds_read_b128 v[156:159], v151 offset:1024
	ds_read_b128 v[160:163], v151 offset:2048
	ds_read_b128 v[164:167], v151 offset:3072
	v_add_u32_e32 v151, s62, v146
	ds_read_b128 v[168:171], v151
	ds_read_b128 v[172:175], v151 offset:1024
	ds_read_b128 v[176:179], v151 offset:2048
	ds_read_b128 v[180:183], v151 offset:3072
	s_add_u32 s30, s30, s10
	s_addc_u32 s31, s31, s11
	s_mov_b32 m0, s42
	v_lshl_add_u64 v[228:229], s[30:31], 0, v[136:137]
	ds_read_b128 v[184:187], v150 offset:32768
	ds_read_b128 v[188:191], v150 offset:33792
	ds_read_b128 v[192:195], v150 offset:34816
	ds_read_b128 v[196:199], v150 offset:35840
	ds_read_b128 v[200:203], v150 offset:36864
	ds_read_b128 v[204:207], v150 offset:37888
	ds_read_b128 v[208:211], v150 offset:38912
	ds_read_b128 v[212:215], v150 offset:39936
	global_load_lds_dwordx4 v[228:229], off
	v_lshl_add_u64 v[228:229], s[30:31], 0, v[132:133]
	s_mov_b32 m0, s43
	s_nop 0
	global_load_lds_dwordx4 v[228:229], off
	s_waitcnt vmcnt(8)
	s_waitcnt lgkmcnt(0)
	s_barrier
	s_setprio 1
	v_mfma_f32_16x16x32_bf16 v[122:125], v[152:155], v[184:187], v[122:125]
	v_mfma_f32_16x16x32_bf16 v[118:121], v[160:163], v[184:187], v[118:121]
	v_mfma_f32_16x16x32_bf16 v[110:113], v[152:155], v[192:195], v[110:113]
	v_mfma_f32_16x16x32_bf16 v[102:105], v[160:163], v[192:195], v[102:105]
	v_mfma_f32_16x16x32_bf16 v[94:97], v[152:155], v[200:203], v[94:97]
	v_mfma_f32_16x16x32_bf16 v[86:89], v[160:163], v[200:203], v[86:89]
	v_mfma_f32_16x16x32_bf16 v[78:81], v[152:155], v[208:211], v[78:81]
	v_mfma_f32_16x16x32_bf16 v[70:73], v[160:163], v[208:211], v[70:73]
	v_mfma_f32_16x16x32_bf16 v[122:125], v[156:159], v[188:191], v[122:125]
	v_mfma_f32_16x16x32_bf16 v[118:121], v[164:167], v[188:191], v[118:121]
	v_mfma_f32_16x16x32_bf16 v[110:113], v[156:159], v[196:199], v[110:113]
	v_mfma_f32_16x16x32_bf16 v[102:105], v[164:167], v[196:199], v[102:105]
	v_mfma_f32_16x16x32_bf16 v[94:97], v[156:159], v[204:207], v[94:97]
	v_mfma_f32_16x16x32_bf16 v[86:89], v[164:167], v[204:207], v[86:89]
	v_mfma_f32_16x16x32_bf16 v[78:81], v[156:159], v[212:215], v[78:81]
	v_mfma_f32_16x16x32_bf16 v[70:73], v[164:167], v[212:215], v[70:73]
	v_mfma_f32_16x16x32_bf16 v[126:129], v[168:171], v[184:187], v[126:129]
	v_mfma_f32_16x16x32_bf16 v[114:117], v[176:179], v[184:187], v[114:117]
	v_mfma_f32_16x16x32_bf16 v[106:109], v[168:171], v[192:195], v[106:109]
	v_mfma_f32_16x16x32_bf16 v[98:101], v[176:179], v[192:195], v[98:101]
	v_mfma_f32_16x16x32_bf16 v[90:93], v[168:171], v[200:203], v[90:93]
	v_mfma_f32_16x16x32_bf16 v[82:85], v[176:179], v[200:203], v[82:85]
	v_mfma_f32_16x16x32_bf16 v[74:77], v[168:171], v[208:211], v[74:77]
	v_mfma_f32_16x16x32_bf16 v[66:69], v[176:179], v[208:211], v[66:69]
	v_mfma_f32_16x16x32_bf16 v[126:129], v[172:175], v[188:191], v[126:129]
	v_mfma_f32_16x16x32_bf16 v[114:117], v[180:183], v[188:191], v[114:117]
	v_mfma_f32_16x16x32_bf16 v[106:109], v[172:175], v[196:199], v[106:109]
	v_mfma_f32_16x16x32_bf16 v[98:101], v[180:183], v[196:199], v[98:101]
	v_mfma_f32_16x16x32_bf16 v[90:93], v[172:175], v[204:207], v[90:93]
	v_mfma_f32_16x16x32_bf16 v[82:85], v[180:183], v[204:207], v[82:85]
	v_mfma_f32_16x16x32_bf16 v[74:77], v[172:175], v[212:215], v[74:77]
	v_mfma_f32_16x16x32_bf16 v[66:69], v[180:183], v[212:215], v[66:69]
	s_setprio 0
	s_barrier
; #define PG8_STAGE(bufoff, gbase, voff) do { _Pragma("unroll") for (int _i = 0; _i < 2; ++_i) \
;         __builtin_amdgcn_global_load_lds((const unsigned*)((const char*)(gbase) + (voff)[_i]), (PG8_LAS unsigned*)(lds + (bufoff) + ldsw + _i * 8192), 16, 0, 0); } while (0)
; #define PG8_LDA(dst, b, h) do { _Pragma("unroll") for (int m = 0; m < 4; ++m) _Pragma("unroll") for (int k = 0; k < 2; ++k) dst[m][k] = *(const PG8_LAS bf16x8*)(lds + PG8_SA(b, h) + aoff + m * 2048 + k * 1024); } while (0)
; #define PG8_MMA(ai, bj, At, Bt) do { __builtin_amdgcn_s_setprio(1); _Pragma("unroll") for (int m = 0; m < 4; ++m) _Pragma("unroll") for (int n = 0; n < 2; ++n) _Pragma("unroll") for (int k = 0; k < 2; ++k) \
;         acc[ai][bj][m][n] = __builtin_amdgcn_mfma_f32_16x16x32_bf16(Bt[n][k], At[m][k], acc[ai][bj][m][n], 0, 0, 0); __builtin_amdgcn_s_setprio(0); } while (0)
; #define PG8_WAIT_V(n) asm volatile("s_waitcnt vmcnt(" #n ")" ::: "memory")
; #define PG8_WAIT_L(n) asm volatile("s_waitcnt lgkmcnt(" #n ")" ::: "memory")
; #define PG8_BAR __builtin_amdgcn_s_barrier()
; #define PG8_SCHED __builtin_amdgcn_sched_barrier(0)
; template <class Epi, class Sched, bool ALIGN_EPI = false, bool SP2 = false>
; __device__ __forceinline__ void gemm_phase(PG8_LAS unsigned char* lds, const Gemm g, const Sched& S, const Epi& E) {
;     ...
;         for (int t = 0; t < nt; t += 2) {
;             const bool last = (t == nt - 2);
;             const char* a1 = cA + (size_t)(t + 1) * kstep;
;             const char* a2 = last ? nA : cA + (size_t)(t + 2) * kstep; const char* b2 = last ? nB : cB + (size_t)(t + 2) * kstep;
;     ...
;             PG8_LDA(At, 1, 1); PG8_STAGE(PG8_SB(1, 0), b3, voffB); PG8_STAGE(PG8_SB(1, 1), b3 + hstep, voffB); PG8_STAGE(PG8_SA(1, 0), a3, voffA);
;             PG8_WAIT_V(8); PG8_WAIT_L(0); PG8_BAR; PG8_MMA(1, 0, At, B0); PG8_MMA(1, 1, At, B1); PG8_BAR; PG8_SCHED;
	s_add_i32 s30, s61, s37
	v_lshl_add_u64 v[216:217], v[216:217], 0, s[18:19]
	s_mov_b32 m0, s30
	ds_read_b128 v[184:187], v150 offset:49152
	ds_read_b128 v[188:191], v150 offset:50176
	ds_read_b128 v[192:195], v150 offset:51200
	ds_read_b128 v[196:199], v150 offset:52224
	ds_read_b128 v[200:203], v150 offset:53248
	ds_read_b128 v[204:207], v150 offset:54272
	ds_read_b128 v[208:211], v150 offset:55296
	ds_read_b128 v[212:215], v150 offset:56320
	global_load_lds_dwordx4 v[216:217], off
	v_lshl_add_u64 v[216:217], v[218:219], 0, s[18:19]
	s_add_i32 m0, s30, 0x2000
	s_add_i32 s30, s62, s37
	global_load_lds_dwordx4 v[216:217], off
	v_lshl_add_u64 v[216:217], v[220:221], 0, s[18:19]
	s_mov_b32 m0, s30
	s_nop 0
	global_load_lds_dwordx4 v[216:217], off
	v_lshl_add_u64 v[216:217], v[222:223], 0, s[18:19]
	s_add_i32 m0, s30, 0x2000
	s_nop 0
	global_load_lds_dwordx4 v[216:217], off
	v_lshl_add_u64 v[216:217], v[224:225], 0, s[18:19]
	s_mov_b32 m0, s45
	s_nop 0
	global_load_lds_dwordx4 v[216:217], off
	v_lshl_add_u64 v[216:217], v[226:227], 0, s[18:19]
	s_mov_b32 m0, s46
	s_nop 0
	global_load_lds_dwordx4 v[216:217], off
	s_waitcnt vmcnt(8)
	s_waitcnt lgkmcnt(0)
	s_barrier
	s_setprio 1
	v_mfma_f32_16x16x32_bf16 v[62:65], v[152:155], v[184:187], v[62:65]
	v_mfma_f32_16x16x32_bf16 v[54:57], v[160:163], v[184:187], v[54:57]
	v_mfma_f32_16x16x32_bf16 v[46:49], v[152:155], v[192:195], v[46:49]
	v_mfma_f32_16x16x32_bf16 v[38:41], v[160:163], v[192:195], v[38:41]
	v_mfma_f32_16x16x32_bf16 v[30:33], v[152:155], v[200:203], v[30:33]
	v_mfma_f32_16x16x32_bf16 v[22:25], v[160:163], v[200:203], v[22:25]
	v_mfma_f32_16x16x32_bf16 v[14:17], v[152:155], v[208:211], v[14:17]
	v_mfma_f32_16x16x32_bf16 v[6:9], v[160:163], v[208:211], v[6:9]
	v_mfma_f32_16x16x32_bf16 v[62:65], v[156:159], v[188:191], v[62:65]
	v_mfma_f32_16x16x32_bf16 v[54:57], v[164:167], v[188:191], v[54:57]
	v_mfma_f32_16x16x32_bf16 v[46:49], v[156:159], v[196:199], v[46:49]
	v_mfma_f32_16x16x32_bf16 v[38:41], v[164:167], v[196:199], v[38:41]
	v_mfma_f32_16x16x32_bf16 v[30:33], v[156:159], v[204:207], v[30:33]
	v_mfma_f32_16x16x32_bf16 v[22:25], v[164:167], v[204:207], v[22:25]
	v_mfma_f32_16x16x32_bf16 v[14:17], v[156:159], v[212:215], v[14:17]
	v_mfma_f32_16x16x32_bf16 v[6:9], v[164:167], v[212:215], v[6:9]
	v_mfma_f32_16x16x32_bf16 v[58:61], v[168:171], v[184:187], v[58:61]
	v_mfma_f32_16x16x32_bf16 v[50:53], v[176:179], v[184:187], v[50:53]
	v_mfma_f32_16x16x32_bf16 v[42:45], v[168:171], v[192:195], v[42:45]
	v_mfma_f32_16x16x32_bf16 v[34:37], v[176:179], v[192:195], v[34:37]
	v_mfma_f32_16x16x32_bf16 v[26:29], v[168:171], v[200:203], v[26:29]
	v_mfma_f32_16x16x32_bf16 v[18:21], v[176:179], v[200:203], v[18:21]
	v_mfma_f32_16x16x32_bf16 v[10:13], v[168:171], v[208:211], v[10:13]
	v_mfma_f32_16x16x32_bf16 v[2:5], v[176:179], v[208:211], v[2:5]
	v_mfma_f32_16x16x32_bf16 v[58:61], v[172:175], v[188:191], v[58:61]
	v_mfma_f32_16x16x32_bf16 v[50:53], v[180:183], v[188:191], v[50:53]
	v_mfma_f32_16x16x32_bf16 v[42:45], v[172:175], v[196:199], v[42:45]
	v_mfma_f32_16x16x32_bf16 v[34:37], v[180:183], v[196:199], v[34:37]
	v_mfma_f32_16x16x32_bf16 v[26:29], v[172:175], v[204:207], v[26:29]
	v_mfma_f32_16x16x32_bf16 v[18:21], v[180:183], v[204:207], v[18:21]
	v_mfma_f32_16x16x32_bf16 v[10:13], v[172:175], v[212:215], v[10:13]
	v_mfma_f32_16x16x32_bf16 v[2:5], v[180:183], v[212:215], v[2:5]
	s_setprio 0
	s_add_u32 s58, s58, 0x100
	s_addc_u32 s59, s59, 0
	s_add_u32 s28, s28, 0x100
	s_addc_u32 s29, s29, 0
	s_cmp_ge_i32 s60, s47
	s_mov_b32 s30, s60
	s_barrier
	s_cbranch_scc0 .LBB0_749

; #define PG8_STAGE(bufoff, gbase, voff) do { _Pragma("unroll") for (int _i = 0; _i < 2; ++_i) \
;         __builtin_amdgcn_global_load_lds((const unsigned*)((const char*)(gbase) + (voff)[_i]), (PG8_LAS unsigned*)(lds + (bufoff) + ldsw + _i * 8192), 16, 0, 0); } while (0)
; #define PG8_LDA(dst, b, h) do { _Pragma("unroll") for (int m = 0; m < 4; ++m) _Pragma("unroll") for (int k = 0; k < 2; ++k) dst[m][k] = *(const PG8_LAS bf16x8*)(lds + PG8_SA(b, h) + aoff + m * 2048 + k * 1024); } while (0)
; #define PG8_LDB(dst, b, h) do { _Pragma("unroll") for (int n = 0; n < 2; ++n) _Pragma("unroll") for (int k = 0; k < 2; ++k) dst[n][k] = *(const PG8_LAS bf16x8*)(lds + PG8_SB(b, h) + boff + n * 2048 + k * 1024); } while (0)
; #define PG8_MMA(ai, bj, At, Bt) do { __builtin_amdgcn_s_setprio(1); _Pragma("unroll") for (int m = 0; m < 4; ++m) _Pragma("unroll") for (int n = 0; n < 2; ++n) _Pragma("unroll") for (int k = 0; k < 2; ++k) \
;         acc[ai][bj][m][n] = __builtin_amdgcn_mfma_f32_16x16x32_bf16(Bt[n][k], At[m][k], acc[ai][bj][m][n], 0, 0, 0); __builtin_amdgcn_s_setprio(0); } while (0)
; #define PG8_WAIT_V(n) asm volatile("s_waitcnt vmcnt(" #n ")" ::: "memory")
; #define PG8_WAIT_L(n) asm volatile("s_waitcnt lgkmcnt(" #n ")" ::: "memory")
; #define PG8_BAR __builtin_amdgcn_s_barrier()
; #define PG8_SCHED __builtin_amdgcn_sched_barrier(0)
; template <class Epi, class Sched, bool ALIGN_EPI = false, bool SP2 = false>
; __device__ __forceinline__ void gemm_phase(PG8_LAS unsigned char* lds, const Gemm g, const Sched& S, const Epi& E) {
;     ...
;             PG8_LDB(B0, 0, 0); PG8_LDB(B1, 0, 1); PG8_SCHED; PG8_LDA(At, 0, 0); PG8_STAGE(PG8_SA(1, 1), a1 + hstep, voffA);
;             PG8_WAIT_V(8); PG8_WAIT_L(0); PG8_BAR; PG8_MMA(0, 0, At, B0); PG8_MMA(0, 1, At, B1); PG8_BAR; PG8_SCHED;
;             PG8_LDA(At, 0, 1); PG8_STAGE(PG8_SB(0, 0), b2, voffB); PG8_STAGE(PG8_SB(0, 1), b2 + hstep, voffB); PG8_STAGE(PG8_SA(0, 0), a2, voffA);
;             PG8_WAIT_V(8); PG8_WAIT_L(0); PG8_BAR; PG8_MMA(1, 0, At, B0); PG8_MMA(1, 1, At, B1); PG8_BAR; PG8_SCHED;
.LBB0_834:
	ds_read_b128 v[152:155], v148
	ds_read_b128 v[156:159], v148 offset:1024
	ds_read_b128 v[160:163], v148 offset:2048
	ds_read_b128 v[164:167], v148 offset:3072
	ds_read_b128 v[168:171], v149
	ds_read_b128 v[172:175], v149 offset:1024
	ds_read_b128 v[176:179], v149 offset:2048
	ds_read_b128 v[180:183], v149 offset:3072
	s_add_i32 s58, s30, 2
	s_add_u32 s59, s28, 0x80
	s_addc_u32 s31, s29, 0
	s_cmp_eq_u32 s45, s30
	s_cselect_b32 s30, s6, s59
	s_cselect_b32 s31, s7, s31
	s_cselect_b32 s61, s25, s57
	s_cselect_b32 s60, s24, s56
	v_lshl_add_u64 v[216:217], s[28:29], 0, v[140:141]
	s_add_i32 m0, s0, 0xc000
	ds_read_b128 v[184:187], v150
	ds_read_b128 v[188:191], v150 offset:1024
	ds_read_b128 v[192:195], v150 offset:2048
	ds_read_b128 v[196:199], v150 offset:3072
	ds_read_b128 v[200:203], v150 offset:4096
	ds_read_b128 v[204:207], v150 offset:5120
	ds_read_b128 v[208:211], v150 offset:6144
	ds_read_b128 v[212:215], v150 offset:7168
	global_load_lds_dwordx4 v[216:217], off
	v_lshl_add_u64 v[216:217], s[28:29], 0, v[138:139]
	s_add_i32 m0, s0, 0xe000
	s_nop 0
	global_load_lds_dwordx4 v[216:217], off
	s_waitcnt vmcnt(8)
	s_waitcnt lgkmcnt(0)
	s_barrier
	s_setprio 1
	v_mfma_f32_16x16x32_bf16 v[122:125], v[152:155], v[184:187], v[122:125]
	v_mfma_f32_16x16x32_bf16 v[126:129], v[160:163], v[184:187], v[126:129]
	v_mfma_f32_16x16x32_bf16 v[110:113], v[152:155], v[192:195], v[110:113]
	v_mfma_f32_16x16x32_bf16 v[106:109], v[160:163], v[192:195], v[106:109]
	v_mfma_f32_16x16x32_bf16 v[94:97], v[152:155], v[200:203], v[94:97]
	v_mfma_f32_16x16x32_bf16 v[90:93], v[160:163], v[200:203], v[90:93]
	v_mfma_f32_16x16x32_bf16 v[78:81], v[152:155], v[208:211], v[78:81]
	v_mfma_f32_16x16x32_bf16 v[74:77], v[160:163], v[208:211], v[74:77]
	v_mfma_f32_16x16x32_bf16 v[122:125], v[156:159], v[188:191], v[122:125]
	v_mfma_f32_16x16x32_bf16 v[126:129], v[164:167], v[188:191], v[126:129]
	v_mfma_f32_16x16x32_bf16 v[110:113], v[156:159], v[196:199], v[110:113]
	v_mfma_f32_16x16x32_bf16 v[106:109], v[164:167], v[196:199], v[106:109]
	v_mfma_f32_16x16x32_bf16 v[94:97], v[156:159], v[204:207], v[94:97]
	v_mfma_f32_16x16x32_bf16 v[90:93], v[164:167], v[204:207], v[90:93]
	v_mfma_f32_16x16x32_bf16 v[78:81], v[156:159], v[212:215], v[78:81]
	v_mfma_f32_16x16x32_bf16 v[74:77], v[164:167], v[212:215], v[74:77]
	v_mfma_f32_16x16x32_bf16 v[118:121], v[168:171], v[184:187], v[118:121]
	v_mfma_f32_16x16x32_bf16 v[114:117], v[176:179], v[184:187], v[114:117]
	v_mfma_f32_16x16x32_bf16 v[102:105], v[168:171], v[192:195], v[102:105]
	v_mfma_f32_16x16x32_bf16 v[98:101], v[176:179], v[192:195], v[98:101]
	v_mfma_f32_16x16x32_bf16 v[86:89], v[168:171], v[200:203], v[86:89]
	v_mfma_f32_16x16x32_bf16 v[82:85], v[176:179], v[200:203], v[82:85]
	v_mfma_f32_16x16x32_bf16 v[70:73], v[168:171], v[208:211], v[70:73]
	v_mfma_f32_16x16x32_bf16 v[66:69], v[176:179], v[208:211], v[66:69]
	v_mfma_f32_16x16x32_bf16 v[118:121], v[172:175], v[188:191], v[118:121]
	v_mfma_f32_16x16x32_bf16 v[114:117], v[180:183], v[188:191], v[114:117]
	v_mfma_f32_16x16x32_bf16 v[102:105], v[172:175], v[196:199], v[102:105]
	v_mfma_f32_16x16x32_bf16 v[98:101], v[180:183], v[196:199], v[98:101]
	v_mfma_f32_16x16x32_bf16 v[86:89], v[172:175], v[204:207], v[86:89]
	v_mfma_f32_16x16x32_bf16 v[82:85], v[180:183], v[204:207], v[82:85]
	v_mfma_f32_16x16x32_bf16 v[70:73], v[172:175], v[212:215], v[70:73]
	v_mfma_f32_16x16x32_bf16 v[66:69], v[180:183], v[212:215], v[66:69]
	s_setprio 0
	s_barrier
	s_add_i32 s59, s48, s38
	v_lshl_add_u64 v[216:217], s[60:61], 0, v[132:133]
	s_mov_b32 m0, s59
	ds_read_b128 v[184:187], v150 offset:16384
	ds_read_b128 v[188:191], v150 offset:17408
	ds_read_b128 v[192:195], v150 offset:18432
	ds_read_b128 v[196:199], v150 offset:19456
	ds_read_b128 v[200:203], v150 offset:20480
	ds_read_b128 v[204:207], v150 offset:21504
	ds_read_b128 v[208:211], v150 offset:22528
	ds_read_b128 v[212:215], v150 offset:23552
	global_load_lds_dwordx4 v[216:217], off
	s_add_i32 m0, s59, 0x2000
	v_lshl_add_u64 v[218:219], s[60:61], 0, v[136:137]
	s_add_u32 s60, s60, s10
	s_addc_u32 s61, s61, s11
	s_add_i32 s59, s49, s38
	global_load_lds_dwordx4 v[218:219], off
	v_lshl_add_u64 v[220:221], s[60:61], 0, v[132:133]
	s_mov_b32 m0, s59
	v_lshl_add_u64 v[222:223], s[60:61], 0, v[136:137]
	global_load_lds_dwordx4 v[220:221], off
	s_add_i32 m0, s59, 0x2000
	v_lshl_add_u64 v[224:225], s[30:31], 0, v[130:131]
	global_load_lds_dwordx4 v[222:223], off
	s_mov_b32 m0, s0
	v_lshl_add_u64 v[226:227], s[30:31], 0, v[134:135]
	global_load_lds_dwordx4 v[224:225], off
	s_mov_b32 m0, s1
	s_nop 0
	global_load_lds_dwordx4 v[226:227], off
	s_waitcnt vmcnt(8)
	s_waitcnt lgkmcnt(0)
	s_barrier
; #define PG8_STAGE(bufoff, gbase, voff) do { _Pragma("unroll") for (int _i = 0; _i < 2; ++_i) \
;         __builtin_amdgcn_global_load_lds((const unsigned*)((const char*)(gbase) + (voff)[_i]), (PG8_LAS unsigned*)(lds + (bufoff) + ldsw + _i * 8192), 16, 0, 0); } while (0)
; #define PG8_LDA(dst, b, h) do { _Pragma("unroll") for (int m = 0; m < 4; ++m) _Pragma("unroll") for (int k = 0; k < 2; ++k) dst[m][k] = *(const PG8_LAS bf16x8*)(lds + PG8_SA(b, h) + aoff + m * 2048 + k * 1024); } while (0)
; #define PG8_LDB(dst, b, h) do { _Pragma("unroll") for (int n = 0; n < 2; ++n) _Pragma("unroll") for (int k = 0; k < 2; ++k) dst[n][k] = *(const PG8_LAS bf16x8*)(lds + PG8_SB(b, h) + boff + n * 2048 + k * 1024); } while (0)
; #define PG8_MMA(ai, bj, At, Bt) do { __builtin_amdgcn_s_setprio(1); _Pragma("unroll") for (int m = 0; m < 4; ++m) _Pragma("unroll") for (int n = 0; n < 2; ++n) _Pragma("unroll") for (int k = 0; k < 2; ++k) \
;         acc[ai][bj][m][n] = __builtin_amdgcn_mfma_f32_16x16x32_bf16(Bt[n][k], At[m][k], acc[ai][bj][m][n], 0, 0, 0); __builtin_amdgcn_s_setprio(0); } while (0)
; #define PG8_WAIT_V(n) asm volatile("s_waitcnt vmcnt(" #n ")" ::: "memory")
; #define PG8_WAIT_L(n) asm volatile("s_waitcnt lgkmcnt(" #n ")" ::: "memory")
; #define PG8_BAR __builtin_amdgcn_s_barrier()
; #define PG8_SCHED __builtin_amdgcn_sched_barrier(0)
; template <class Epi, class Sched, bool ALIGN_EPI = false, bool SP2 = false>
; __device__ __forceinline__ void gemm_phase(PG8_LAS unsigned char* lds, const Gemm g, const Sched& S, const Epi& E) {
;     ...
;             PG8_WAIT_V(8); PG8_WAIT_L(0); PG8_BAR; PG8_MMA(1, 0, At, B0); PG8_MMA(1, 1, At, B1); PG8_BAR; PG8_SCHED;
;             PG8_LDB(B0, 1, 0); PG8_LDB(B1, 1, 1); PG8_SCHED; PG8_LDA(At, 1, 0); PG8_STAGE(PG8_SA(0, 1), a2 + hstep, voffA);
;             PG8_WAIT_V(8); PG8_WAIT_L(0); PG8_BAR; PG8_MMA(0, 0, At, B0); PG8_MMA(0, 1, At, B1); PG8_BAR; PG8_SCHED;
	s_setprio 1
	v_mfma_f32_16x16x32_bf16 v[62:65], v[152:155], v[184:187], v[62:65]
	v_mfma_f32_16x16x32_bf16 v[58:61], v[160:163], v[184:187], v[58:61]
	v_mfma_f32_16x16x32_bf16 v[46:49], v[152:155], v[192:195], v[46:49]
	v_mfma_f32_16x16x32_bf16 v[42:45], v[160:163], v[192:195], v[42:45]
	v_mfma_f32_16x16x32_bf16 v[30:33], v[152:155], v[200:203], v[30:33]
	v_mfma_f32_16x16x32_bf16 v[26:29], v[160:163], v[200:203], v[26:29]
	v_mfma_f32_16x16x32_bf16 v[14:17], v[152:155], v[208:211], v[14:17]
	v_mfma_f32_16x16x32_bf16 v[10:13], v[160:163], v[208:211], v[10:13]
	v_mfma_f32_16x16x32_bf16 v[62:65], v[156:159], v[188:191], v[62:65]
	v_mfma_f32_16x16x32_bf16 v[58:61], v[164:167], v[188:191], v[58:61]
	v_mfma_f32_16x16x32_bf16 v[46:49], v[156:159], v[196:199], v[46:49]
	v_mfma_f32_16x16x32_bf16 v[42:45], v[164:167], v[196:199], v[42:45]
	v_mfma_f32_16x16x32_bf16 v[30:33], v[156:159], v[204:207], v[30:33]
	v_mfma_f32_16x16x32_bf16 v[26:29], v[164:167], v[204:207], v[26:29]
	v_mfma_f32_16x16x32_bf16 v[14:17], v[156:159], v[212:215], v[14:17]
	v_mfma_f32_16x16x32_bf16 v[10:13], v[164:167], v[212:215], v[10:13]
	v_mfma_f32_16x16x32_bf16 v[54:57], v[168:171], v[184:187], v[54:57]
	v_mfma_f32_16x16x32_bf16 v[50:53], v[176:179], v[184:187], v[50:53]
	v_mfma_f32_16x16x32_bf16 v[38:41], v[168:171], v[192:195], v[38:41]
	v_mfma_f32_16x16x32_bf16 v[34:37], v[176:179], v[192:195], v[34:37]
	v_mfma_f32_16x16x32_bf16 v[22:25], v[168:171], v[200:203], v[22:25]
	v_mfma_f32_16x16x32_bf16 v[18:21], v[176:179], v[200:203], v[18:21]
	v_mfma_f32_16x16x32_bf16 v[6:9], v[168:171], v[208:211], v[6:9]
	v_mfma_f32_16x16x32_bf16 v[2:5], v[176:179], v[208:211], v[2:5]
	v_mfma_f32_16x16x32_bf16 v[54:57], v[172:175], v[188:191], v[54:57]
	v_mfma_f32_16x16x32_bf16 v[50:53], v[180:183], v[188:191], v[50:53]
	v_mfma_f32_16x16x32_bf16 v[38:41], v[172:175], v[196:199], v[38:41]
	v_mfma_f32_16x16x32_bf16 v[34:37], v[180:183], v[196:199], v[34:37]
	v_mfma_f32_16x16x32_bf16 v[22:25], v[172:175], v[204:207], v[22:25]
	v_mfma_f32_16x16x32_bf16 v[18:21], v[180:183], v[204:207], v[18:21]
	v_mfma_f32_16x16x32_bf16 v[6:9], v[172:175], v[212:215], v[6:9]
	v_mfma_f32_16x16x32_bf16 v[2:5], v[180:183], v[212:215], v[2:5]
	s_setprio 0
	s_barrier
	s_add_i32 s59, 0, 0x18000
	v_add_u32_e32 v151, s59, v146
	s_add_i32 s60, 0, 0x1c000
	ds_read_b128 v[152:155], v151
	ds_read_b128 v[156:159], v151 offset:1024
	ds_read_b128 v[160:163], v151 offset:2048
	ds_read_b128 v[164:167], v151 offset:3072
	v_add_u32_e32 v151, s60, v146
	ds_read_b128 v[168:171], v151
	ds_read_b128 v[172:175], v151 offset:1024
	ds_read_b128 v[176:179], v151 offset:2048
	ds_read_b128 v[180:183], v151 offset:3072
	s_add_u32 s30, s30, s10
	s_addc_u32 s31, s31, s11
	s_mov_b32 m0, s39
	v_lshl_add_u64 v[228:229], s[30:31], 0, v[130:131]
	ds_read_b128 v[184:187], v150 offset:32768
	ds_read_b128 v[188:191], v150 offset:33792
	ds_read_b128 v[192:195], v150 offset:34816
	ds_read_b128 v[196:199], v150 offset:35840
	ds_read_b128 v[200:203], v150 offset:36864
	ds_read_b128 v[204:207], v150 offset:37888
	ds_read_b128 v[208:211], v150 offset:38912
	ds_read_b128 v[212:215], v150 offset:39936
	global_load_lds_dwordx4 v[228:229], off
	v_lshl_add_u64 v[228:229], s[30:31], 0, v[134:135]
	s_mov_b32 m0, s40
	s_nop 0
	global_load_lds_dwordx4 v[228:229], off
	s_waitcnt vmcnt(8)
	s_waitcnt lgkmcnt(0)
	s_barrier
	s_setprio 1
	v_mfma_f32_16x16x32_bf16 v[122:125], v[152:155], v[184:187], v[122:125]
	v_mfma_f32_16x16x32_bf16 v[126:129], v[160:163], v[184:187], v[126:129]
	v_mfma_f32_16x16x32_bf16 v[110:113], v[152:155], v[192:195], v[110:113]
	v_mfma_f32_16x16x32_bf16 v[106:109], v[160:163], v[192:195], v[106:109]
	v_mfma_f32_16x16x32_bf16 v[94:97], v[152:155], v[200:203], v[94:97]
	v_mfma_f32_16x16x32_bf16 v[90:93], v[160:163], v[200:203], v[90:93]
	v_mfma_f32_16x16x32_bf16 v[78:81], v[152:155], v[208:211], v[78:81]
	v_mfma_f32_16x16x32_bf16 v[74:77], v[160:163], v[208:211], v[74:77]
	v_mfma_f32_16x16x32_bf16 v[122:125], v[156:159], v[188:191], v[122:125]
	v_mfma_f32_16x16x32_bf16 v[126:129], v[164:167], v[188:191], v[126:129]
	v_mfma_f32_16x16x32_bf16 v[110:113], v[156:159], v[196:199], v[110:113]
	v_mfma_f32_16x16x32_bf16 v[106:109], v[164:167], v[196:199], v[106:109]
	v_mfma_f32_16x16x32_bf16 v[94:97], v[156:159], v[204:207], v[94:97]
	v_mfma_f32_16x16x32_bf16 v[90:93], v[164:167], v[204:207], v[90:93]
	v_mfma_f32_16x16x32_bf16 v[78:81], v[156:159], v[212:215], v[78:81]
	v_mfma_f32_16x16x32_bf16 v[74:77], v[164:167], v[212:215], v[74:77]
	v_mfma_f32_16x16x32_bf16 v[118:121], v[168:171], v[184:187], v[118:121]
	v_mfma_f32_16x16x32_bf16 v[114:117], v[176:179], v[184:187], v[114:117]
	v_mfma_f32_16x16x32_bf16 v[102:105], v[168:171], v[192:195], v[102:105]
	v_mfma_f32_16x16x32_bf16 v[98:101], v[176:179], v[192:195], v[98:101]
	v_mfma_f32_16x16x32_bf16 v[86:89], v[168:171], v[200:203], v[86:89]
	v_mfma_f32_16x16x32_bf16 v[82:85], v[176:179], v[200:203], v[82:85]
	v_mfma_f32_16x16x32_bf16 v[70:73], v[168:171], v[208:211], v[70:73]
	v_mfma_f32_16x16x32_bf16 v[66:69], v[176:179], v[208:211], v[66:69]
	v_mfma_f32_16x16x32_bf16 v[118:121], v[172:175], v[188:191], v[118:121]
	v_mfma_f32_16x16x32_bf16 v[114:117], v[180:183], v[188:191], v[114:117]
	v_mfma_f32_16x16x32_bf16 v[102:105], v[172:175], v[196:199], v[102:105]
	v_mfma_f32_16x16x32_bf16 v[98:101], v[180:183], v[196:199], v[98:101]
	v_mfma_f32_16x16x32_bf16 v[86:89], v[172:175], v[204:207], v[86:89]
	v_mfma_f32_16x16x32_bf16 v[82:85], v[180:183], v[204:207], v[82:85]
	v_mfma_f32_16x16x32_bf16 v[70:73], v[172:175], v[212:215], v[70:73]
	v_mfma_f32_16x16x32_bf16 v[66:69], v[180:183], v[212:215], v[66:69]
	s_setprio 0
	s_barrier
; #define PG8_STAGE(bufoff, gbase, voff) do { _Pragma("unroll") for (int _i = 0; _i < 2; ++_i) \
;         __builtin_amdgcn_global_load_lds((const unsigned*)((const char*)(gbase) + (voff)[_i]), (PG8_LAS unsigned*)(lds + (bufoff) + ldsw + _i * 8192), 16, 0, 0); } while (0)
; #define PG8_LDA(dst, b, h) do { _Pragma("unroll") for (int m = 0; m < 4; ++m) _Pragma("unroll") for (int k = 0; k < 2; ++k) dst[m][k] = *(const PG8_LAS bf16x8*)(lds + PG8_SA(b, h) + aoff + m * 2048 + k * 1024); } while (0)
; #define PG8_MMA(ai, bj, At, Bt) do { __builtin_amdgcn_s_setprio(1); _Pragma("unroll") for (int m = 0; m < 4; ++m) _Pragma("unroll") for (int n = 0; n < 2; ++n) _Pragma("unroll") for (int k = 0; k < 2; ++k) \
;         acc[ai][bj][m][n] = __builtin_amdgcn_mfma_f32_16x16x32_bf16(Bt[n][k], At[m][k], acc[ai][bj][m][n], 0, 0, 0); __builtin_amdgcn_s_setprio(0); } while (0)
; #define PG8_WAIT_V(n) asm volatile("s_waitcnt vmcnt(" #n ")" ::: "memory")
; #define PG8_WAIT_L(n) asm volatile("s_waitcnt lgkmcnt(" #n ")" ::: "memory")
; #define PG8_BAR __builtin_amdgcn_s_barrier()
; #define PG8_SCHED __builtin_amdgcn_sched_barrier(0)
; template <class Epi, class Sched, bool ALIGN_EPI = false, bool SP2 = false>
; __device__ __forceinline__ void gemm_phase(PG8_LAS unsigned char* lds, const Gemm g, const Sched& S, const Epi& E) {
;     ...
;         for (int t = 0; t < nt; t += 2) {
;             const bool last = (t == nt - 2);
;             const char* a1 = cA + (size_t)(t + 1) * kstep;
;             const char* a2 = last ? nA : cA + (size_t)(t + 2) * kstep; const char* b2 = last ? nB : cB + (size_t)(t + 2) * kstep;
;     ...
;             PG8_LDA(At, 1, 1); PG8_STAGE(PG8_SB(1, 0), b3, voffB); PG8_STAGE(PG8_SB(1, 1), b3 + hstep, voffB); PG8_STAGE(PG8_SA(1, 0), a3, voffA);
;             PG8_WAIT_V(8); PG8_WAIT_L(0); PG8_BAR; PG8_MMA(1, 0, At, B0); PG8_MMA(1, 1, At, B1); PG8_BAR; PG8_SCHED;
	s_add_i32 s30, s59, s38
	v_lshl_add_u64 v[216:217], v[216:217], 0, s[18:19]
	s_mov_b32 m0, s30
	ds_read_b128 v[184:187], v150 offset:49152
	ds_read_b128 v[188:191], v150 offset:50176
	ds_read_b128 v[192:195], v150 offset:51200
	ds_read_b128 v[196:199], v150 offset:52224
	ds_read_b128 v[200:203], v150 offset:53248
	ds_read_b128 v[204:207], v150 offset:54272
	ds_read_b128 v[208:211], v150 offset:55296
	ds_read_b128 v[212:215], v150 offset:56320
	global_load_lds_dwordx4 v[216:217], off
	v_lshl_add_u64 v[216:217], v[218:219], 0, s[18:19]
	s_add_i32 m0, s30, 0x2000
	s_add_i32 s30, s60, s38
	global_load_lds_dwordx4 v[216:217], off
	v_lshl_add_u64 v[216:217], v[220:221], 0, s[18:19]
	s_mov_b32 m0, s30
	s_nop 0
	global_load_lds_dwordx4 v[216:217], off
	v_lshl_add_u64 v[216:217], v[222:223], 0, s[18:19]
	s_add_i32 m0, s30, 0x2000
	s_nop 0
	global_load_lds_dwordx4 v[216:217], off
	v_lshl_add_u64 v[216:217], v[224:225], 0, s[18:19]
	s_mov_b32 m0, s42
	s_nop 0
	global_load_lds_dwordx4 v[216:217], off
	v_lshl_add_u64 v[216:217], v[226:227], 0, s[18:19]
	s_mov_b32 m0, s43
	s_nop 0
	global_load_lds_dwordx4 v[216:217], off
	s_waitcnt vmcnt(8)
	s_waitcnt lgkmcnt(0)
	s_barrier
	s_setprio 1
	v_mfma_f32_16x16x32_bf16 v[62:65], v[152:155], v[184:187], v[62:65]
	v_mfma_f32_16x16x32_bf16 v[58:61], v[160:163], v[184:187], v[58:61]
	v_mfma_f32_16x16x32_bf16 v[46:49], v[152:155], v[192:195], v[46:49]
	v_mfma_f32_16x16x32_bf16 v[42:45], v[160:163], v[192:195], v[42:45]
	v_mfma_f32_16x16x32_bf16 v[30:33], v[152:155], v[200:203], v[30:33]
	v_mfma_f32_16x16x32_bf16 v[26:29], v[160:163], v[200:203], v[26:29]
	v_mfma_f32_16x16x32_bf16 v[14:17], v[152:155], v[208:211], v[14:17]
	v_mfma_f32_16x16x32_bf16 v[10:13], v[160:163], v[208:211], v[10:13]
	v_mfma_f32_16x16x32_bf16 v[62:65], v[156:159], v[188:191], v[62:65]
	v_mfma_f32_16x16x32_bf16 v[58:61], v[164:167], v[188:191], v[58:61]
	v_mfma_f32_16x16x32_bf16 v[46:49], v[156:159], v[196:199], v[46:49]
	v_mfma_f32_16x16x32_bf16 v[42:45], v[164:167], v[196:199], v[42:45]
	v_mfma_f32_16x16x32_bf16 v[30:33], v[156:159], v[204:207], v[30:33]
	v_mfma_f32_16x16x32_bf16 v[26:29], v[164:167], v[204:207], v[26:29]
	v_mfma_f32_16x16x32_bf16 v[14:17], v[156:159], v[212:215], v[14:17]
	v_mfma_f32_16x16x32_bf16 v[10:13], v[164:167], v[212:215], v[10:13]
	v_mfma_f32_16x16x32_bf16 v[54:57], v[168:171], v[184:187], v[54:57]
	v_mfma_f32_16x16x32_bf16 v[50:53], v[176:179], v[184:187], v[50:53]
	v_mfma_f32_16x16x32_bf16 v[38:41], v[168:171], v[192:195], v[38:41]
	v_mfma_f32_16x16x32_bf16 v[34:37], v[176:179], v[192:195], v[34:37]
	v_mfma_f32_16x16x32_bf16 v[22:25], v[168:171], v[200:203], v[22:25]
	v_mfma_f32_16x16x32_bf16 v[18:21], v[176:179], v[200:203], v[18:21]
	v_mfma_f32_16x16x32_bf16 v[6:9], v[168:171], v[208:211], v[6:9]
	v_mfma_f32_16x16x32_bf16 v[2:5], v[176:179], v[208:211], v[2:5]
	v_mfma_f32_16x16x32_bf16 v[54:57], v[172:175], v[188:191], v[54:57]
	v_mfma_f32_16x16x32_bf16 v[50:53], v[180:183], v[188:191], v[50:53]
	v_mfma_f32_16x16x32_bf16 v[38:41], v[172:175], v[196:199], v[38:41]
	v_mfma_f32_16x16x32_bf16 v[34:37], v[180:183], v[196:199], v[34:37]
	v_mfma_f32_16x16x32_bf16 v[22:25], v[172:175], v[204:207], v[22:25]
	v_mfma_f32_16x16x32_bf16 v[18:21], v[180:183], v[204:207], v[18:21]
	v_mfma_f32_16x16x32_bf16 v[6:9], v[172:175], v[212:215], v[6:9]
	v_mfma_f32_16x16x32_bf16 v[2:5], v[180:183], v[212:215], v[2:5]
	s_setprio 0
	s_add_u32 s56, s56, 0x100
	s_addc_u32 s57, s57, 0
	s_add_u32 s28, s28, 0x100
	s_addc_u32 s29, s29, 0
	s_cmp_ge_i32 s58, s44
	s_mov_b32 s30, s58
	s_barrier
	s_cbranch_scc0 .LBB0_834

; #define PG8_STAGE(bufoff, gbase, voff) do { _Pragma("unroll") for (int _i = 0; _i < 2; ++_i) \
;         __builtin_amdgcn_global_load_lds((const unsigned*)((const char*)(gbase) + (voff)[_i]), (PG8_LAS unsigned*)(lds + (bufoff) + ldsw + _i * 8192), 16, 0, 0); } while (0)
; #define PG8_LDA(dst, b, h) do { _Pragma("unroll") for (int m = 0; m < 4; ++m) _Pragma("unroll") for (int k = 0; k < 2; ++k) dst[m][k] = *(const PG8_LAS bf16x8*)(lds + PG8_SA(b, h) + aoff + m * 2048 + k * 1024); } while (0)
; #define PG8_LDB(dst, b, h) do { _Pragma("unroll") for (int n = 0; n < 2; ++n) _Pragma("unroll") for (int k = 0; k < 2; ++k) dst[n][k] = *(const PG8_LAS bf16x8*)(lds + PG8_SB(b, h) + boff + n * 2048 + k * 1024); } while (0)
; #define PG8_MMA(ai, bj, At, Bt) do { __builtin_amdgcn_s_setprio(1); _Pragma("unroll") for (int m = 0; m < 4; ++m) _Pragma("unroll") for (int n = 0; n < 2; ++n) _Pragma("unroll") for (int k = 0; k < 2; ++k) \
;         acc[ai][bj][m][n] = __builtin_amdgcn_mfma_f32_16x16x32_bf16(Bt[n][k], At[m][k], acc[ai][bj][m][n], 0, 0, 0); __builtin_amdgcn_s_setprio(0); } while (0)
; #define PG8_WAIT_V(n) asm volatile("s_waitcnt vmcnt(" #n ")" ::: "memory")
; #define PG8_WAIT_L(n) asm volatile("s_waitcnt lgkmcnt(" #n ")" ::: "memory")
; #define PG8_BAR __builtin_amdgcn_s_barrier()
; #define PG8_SCHED __builtin_amdgcn_sched_barrier(0)
; template <class Epi, class Sched, bool ALIGN_EPI = false, bool SP2 = false>
; __device__ __forceinline__ void gemm_phase(PG8_LAS unsigned char* lds, const Gemm g, const Sched& S, const Epi& E) {
;     ...
;             PG8_LDB(B0, 0, 0); PG8_LDB(B1, 0, 1); PG8_SCHED; PG8_LDA(At, 0, 0); PG8_STAGE(PG8_SA(1, 1), a1 + hstep, voffA);
;             PG8_WAIT_V(8); PG8_WAIT_L(0); PG8_BAR; PG8_MMA(0, 0, At, B0); PG8_MMA(0, 1, At, B1); PG8_BAR; PG8_SCHED;
;             PG8_LDA(At, 0, 1); PG8_STAGE(PG8_SB(0, 0), b2, voffB); PG8_STAGE(PG8_SB(0, 1), b2 + hstep, voffB); PG8_STAGE(PG8_SA(0, 0), a2, voffA);
;             PG8_WAIT_V(8); PG8_WAIT_L(0); PG8_BAR; PG8_MMA(1, 0, At, B0); PG8_MMA(1, 1, At, B1); PG8_BAR; PG8_SCHED;
.LBB0_1154:
	ds_read_b128 v[130:133], v160
	ds_read_b128 v[134:137], v160 offset:1024
	ds_read_b128 v[164:167], v160 offset:2048
	ds_read_b128 v[168:171], v160 offset:3072
	ds_read_b128 v[172:175], v161
	ds_read_b128 v[176:179], v161 offset:1024
	ds_read_b128 v[180:183], v161 offset:2048
	ds_read_b128 v[184:187], v161 offset:3072
	s_add_i32 s81, s36, 2
	s_add_u32 s70, s34, 0x80
	s_addc_u32 s37, s35, 0
	s_cmp_eq_u32 s55, s36
	s_cselect_b32 s36, s4, s70
	s_cselect_b32 s37, s5, s37
	s_cselect_b32 s71, s31, s80
	s_cselect_b32 s70, s30, s45
	v_lshl_add_u64 v[158:159], s[34:35], 0, v[152:153]
	s_add_i32 m0, s42, 0xc000
	ds_read_b128 v[188:191], v162
	ds_read_b128 v[192:195], v162 offset:1024
	ds_read_b128 v[196:199], v162 offset:2048
	ds_read_b128 v[200:203], v162 offset:3072
	ds_read_b128 v[204:207], v162 offset:4096
	ds_read_b128 v[208:211], v162 offset:5120
	ds_read_b128 v[212:215], v162 offset:6144
	ds_read_b128 v[216:219], v162 offset:7168
	global_load_lds_dwordx4 v[158:159], off
	v_lshl_add_u64 v[158:159], s[34:35], 0, v[150:151]
	s_add_i32 m0, s42, 0xe000
	s_nop 0
	global_load_lds_dwordx4 v[158:159], off
	s_waitcnt vmcnt(8)
	s_waitcnt lgkmcnt(0)
	s_barrier
	s_setprio 1
	v_mfma_f32_16x16x32_bf16 v[126:129], v[130:133], v[188:191], v[126:129]
	v_mfma_f32_16x16x32_bf16 v[122:125], v[164:167], v[188:191], v[122:125]
	v_mfma_f32_16x16x32_bf16 v[110:113], v[130:133], v[196:199], v[110:113]
	v_mfma_f32_16x16x32_bf16 v[106:109], v[164:167], v[196:199], v[106:109]
	v_mfma_f32_16x16x32_bf16 v[94:97], v[130:133], v[204:207], v[94:97]
	v_mfma_f32_16x16x32_bf16 v[90:93], v[164:167], v[204:207], v[90:93]
	v_mfma_f32_16x16x32_bf16 v[78:81], v[130:133], v[212:215], v[78:81]
	v_mfma_f32_16x16x32_bf16 v[74:77], v[164:167], v[212:215], v[74:77]
	v_mfma_f32_16x16x32_bf16 v[126:129], v[134:137], v[192:195], v[126:129]
	v_mfma_f32_16x16x32_bf16 v[122:125], v[168:171], v[192:195], v[122:125]
	v_mfma_f32_16x16x32_bf16 v[110:113], v[134:137], v[200:203], v[110:113]
	v_mfma_f32_16x16x32_bf16 v[106:109], v[168:171], v[200:203], v[106:109]
	v_mfma_f32_16x16x32_bf16 v[94:97], v[134:137], v[208:211], v[94:97]
	v_mfma_f32_16x16x32_bf16 v[90:93], v[168:171], v[208:211], v[90:93]
	v_mfma_f32_16x16x32_bf16 v[78:81], v[134:137], v[216:219], v[78:81]
	v_mfma_f32_16x16x32_bf16 v[74:77], v[168:171], v[216:219], v[74:77]
	v_mfma_f32_16x16x32_bf16 v[118:121], v[172:175], v[188:191], v[118:121]
	v_mfma_f32_16x16x32_bf16 v[114:117], v[180:183], v[188:191], v[114:117]
	v_mfma_f32_16x16x32_bf16 v[102:105], v[172:175], v[196:199], v[102:105]
	v_mfma_f32_16x16x32_bf16 v[98:101], v[180:183], v[196:199], v[98:101]
	v_mfma_f32_16x16x32_bf16 v[86:89], v[172:175], v[204:207], v[86:89]
	v_mfma_f32_16x16x32_bf16 v[82:85], v[180:183], v[204:207], v[82:85]
	v_mfma_f32_16x16x32_bf16 v[70:73], v[172:175], v[212:215], v[70:73]
	v_mfma_f32_16x16x32_bf16 v[66:69], v[180:183], v[212:215], v[66:69]
	v_mfma_f32_16x16x32_bf16 v[118:121], v[176:179], v[192:195], v[118:121]
	v_mfma_f32_16x16x32_bf16 v[114:117], v[184:187], v[192:195], v[114:117]
	v_mfma_f32_16x16x32_bf16 v[102:105], v[176:179], v[200:203], v[102:105]
	v_mfma_f32_16x16x32_bf16 v[98:101], v[184:187], v[200:203], v[98:101]
	v_mfma_f32_16x16x32_bf16 v[86:89], v[176:179], v[208:211], v[86:89]
	v_mfma_f32_16x16x32_bf16 v[82:85], v[184:187], v[208:211], v[82:85]
	v_mfma_f32_16x16x32_bf16 v[70:73], v[176:179], v[216:219], v[70:73]
	v_mfma_f32_16x16x32_bf16 v[66:69], v[184:187], v[216:219], v[66:69]
	s_setprio 0
	s_barrier
	s_add_i32 s72, s69, s41
	v_lshl_add_u64 v[158:159], s[70:71], 0, v[140:141]
	s_mov_b32 m0, s72
	ds_read_b128 v[188:191], v162 offset:16384
	ds_read_b128 v[192:195], v162 offset:17408
	ds_read_b128 v[196:199], v162 offset:18432
	ds_read_b128 v[200:203], v162 offset:19456
	ds_read_b128 v[204:207], v162 offset:20480
	ds_read_b128 v[208:211], v162 offset:21504
	ds_read_b128 v[212:215], v162 offset:22528
	ds_read_b128 v[216:219], v162 offset:23552
	global_load_lds_dwordx4 v[158:159], off
	s_add_i32 m0, s72, 0x2000
	v_lshl_add_u64 v[220:221], s[70:71], 0, v[144:145]
	s_add_u32 s70, s70, s8
	s_addc_u32 s71, s71, s9
	s_add_i32 s72, s86, s41
	global_load_lds_dwordx4 v[220:221], off
	v_lshl_add_u64 v[222:223], s[70:71], 0, v[140:141]
	s_mov_b32 m0, s72
	v_lshl_add_u64 v[224:225], s[70:71], 0, v[144:145]
	global_load_lds_dwordx4 v[222:223], off
	s_add_i32 m0, s72, 0x2000
	v_lshl_add_u64 v[226:227], s[36:37], 0, v[138:139]
	global_load_lds_dwordx4 v[224:225], off
	s_mov_b32 m0, s42
	v_lshl_add_u64 v[228:229], s[36:37], 0, v[142:143]
	global_load_lds_dwordx4 v[226:227], off
	s_mov_b32 m0, s46
	s_nop 0
	global_load_lds_dwordx4 v[228:229], off
	s_waitcnt vmcnt(8)
	s_waitcnt lgkmcnt(0)
	s_barrier
; #define PG8_STAGE(bufoff, gbase, voff) do { _Pragma("unroll") for (int _i = 0; _i < 2; ++_i) \
;         __builtin_amdgcn_global_load_lds((const unsigned*)((const char*)(gbase) + (voff)[_i]), (PG8_LAS unsigned*)(lds + (bufoff) + ldsw + _i * 8192), 16, 0, 0); } while (0)
; #define PG8_LDA(dst, b, h) do { _Pragma("unroll") for (int m = 0; m < 4; ++m) _Pragma("unroll") for (int k = 0; k < 2; ++k) dst[m][k] = *(const PG8_LAS bf16x8*)(lds + PG8_SA(b, h) + aoff + m * 2048 + k * 1024); } while (0)
; #define PG8_LDB(dst, b, h) do { _Pragma("unroll") for (int n = 0; n < 2; ++n) _Pragma("unroll") for (int k = 0; k < 2; ++k) dst[n][k] = *(const PG8_LAS bf16x8*)(lds + PG8_SB(b, h) + boff + n * 2048 + k * 1024); } while (0)
; #define PG8_MMA(ai, bj, At, Bt) do { __builtin_amdgcn_s_setprio(1); _Pragma("unroll") for (int m = 0; m < 4; ++m) _Pragma("unroll") for (int n = 0; n < 2; ++n) _Pragma("unroll") for (int k = 0; k < 2; ++k) \
;         acc[ai][bj][m][n] = __builtin_amdgcn_mfma_f32_16x16x32_bf16(Bt[n][k], At[m][k], acc[ai][bj][m][n], 0, 0, 0); __builtin_amdgcn_s_setprio(0); } while (0)
; #define PG8_WAIT_V(n) asm volatile("s_waitcnt vmcnt(" #n ")" ::: "memory")
; #define PG8_WAIT_L(n) asm volatile("s_waitcnt lgkmcnt(" #n ")" ::: "memory")
; #define PG8_BAR __builtin_amdgcn_s_barrier()
; #define PG8_SCHED __builtin_amdgcn_sched_barrier(0)
; template <class Epi, class Sched, bool ALIGN_EPI = false, bool SP2 = false>
; __device__ __forceinline__ void gemm_phase(PG8_LAS unsigned char* lds, const Gemm g, const Sched& S, const Epi& E) {
;     ...
;             PG8_WAIT_V(8); PG8_WAIT_L(0); PG8_BAR; PG8_MMA(1, 0, At, B0); PG8_MMA(1, 1, At, B1); PG8_BAR; PG8_SCHED;
;             PG8_LDB(B0, 1, 0); PG8_LDB(B1, 1, 1); PG8_SCHED; PG8_LDA(At, 1, 0); PG8_STAGE(PG8_SA(0, 1), a2 + hstep, voffA);
;             PG8_WAIT_V(8); PG8_WAIT_L(0); PG8_BAR; PG8_MMA(0, 0, At, B0); PG8_MMA(0, 1, At, B1); PG8_BAR; PG8_SCHED;
	s_setprio 1
	v_mfma_f32_16x16x32_bf16 v[62:65], v[130:133], v[188:191], v[62:65]
	v_mfma_f32_16x16x32_bf16 v[58:61], v[164:167], v[188:191], v[58:61]
	v_mfma_f32_16x16x32_bf16 v[46:49], v[130:133], v[196:199], v[46:49]
	v_mfma_f32_16x16x32_bf16 v[42:45], v[164:167], v[196:199], v[42:45]
	v_mfma_f32_16x16x32_bf16 v[30:33], v[130:133], v[204:207], v[30:33]
	v_mfma_f32_16x16x32_bf16 v[26:29], v[164:167], v[204:207], v[26:29]
	v_mfma_f32_16x16x32_bf16 v[14:17], v[130:133], v[212:215], v[14:17]
	v_mfma_f32_16x16x32_bf16 v[10:13], v[164:167], v[212:215], v[10:13]
	v_mfma_f32_16x16x32_bf16 v[62:65], v[134:137], v[192:195], v[62:65]
	v_mfma_f32_16x16x32_bf16 v[58:61], v[168:171], v[192:195], v[58:61]
	v_mfma_f32_16x16x32_bf16 v[46:49], v[134:137], v[200:203], v[46:49]
	v_mfma_f32_16x16x32_bf16 v[42:45], v[168:171], v[200:203], v[42:45]
	v_mfma_f32_16x16x32_bf16 v[30:33], v[134:137], v[208:211], v[30:33]
	v_mfma_f32_16x16x32_bf16 v[26:29], v[168:171], v[208:211], v[26:29]
	v_mfma_f32_16x16x32_bf16 v[14:17], v[134:137], v[216:219], v[14:17]
	v_mfma_f32_16x16x32_bf16 v[10:13], v[168:171], v[216:219], v[10:13]
	v_mfma_f32_16x16x32_bf16 v[54:57], v[172:175], v[188:191], v[54:57]
	v_mfma_f32_16x16x32_bf16 v[50:53], v[180:183], v[188:191], v[50:53]
	v_mfma_f32_16x16x32_bf16 v[38:41], v[172:175], v[196:199], v[38:41]
	v_mfma_f32_16x16x32_bf16 v[34:37], v[180:183], v[196:199], v[34:37]
	v_mfma_f32_16x16x32_bf16 v[22:25], v[172:175], v[204:207], v[22:25]
	v_mfma_f32_16x16x32_bf16 v[18:21], v[180:183], v[204:207], v[18:21]
	v_mfma_f32_16x16x32_bf16 v[6:9], v[172:175], v[212:215], v[6:9]
	v_mfma_f32_16x16x32_bf16 v[2:5], v[180:183], v[212:215], v[2:5]
	v_mfma_f32_16x16x32_bf16 v[54:57], v[176:179], v[192:195], v[54:57]
	v_mfma_f32_16x16x32_bf16 v[50:53], v[184:187], v[192:195], v[50:53]
	v_mfma_f32_16x16x32_bf16 v[38:41], v[176:179], v[200:203], v[38:41]
	v_mfma_f32_16x16x32_bf16 v[34:37], v[184:187], v[200:203], v[34:37]
	v_mfma_f32_16x16x32_bf16 v[22:25], v[176:179], v[208:211], v[22:25]
	v_mfma_f32_16x16x32_bf16 v[18:21], v[184:187], v[208:211], v[18:21]
	v_mfma_f32_16x16x32_bf16 v[6:9], v[176:179], v[216:219], v[6:9]
	v_mfma_f32_16x16x32_bf16 v[2:5], v[184:187], v[216:219], v[2:5]
	s_setprio 0
	s_barrier
	s_add_i32 s70, 0, 0x18000
	v_add_u32_e32 v146, s70, v149
	s_add_i32 s71, 0, 0x1c000
	ds_read_b128 v[130:133], v146
	ds_read_b128 v[134:137], v146 offset:1024
	ds_read_b128 v[164:167], v146 offset:2048
	ds_read_b128 v[168:171], v146 offset:3072
	v_add_u32_e32 v146, s71, v149
	ds_read_b128 v[172:175], v146
	ds_read_b128 v[176:179], v146 offset:1024
	ds_read_b128 v[180:183], v146 offset:2048
	ds_read_b128 v[184:187], v146 offset:3072
	s_add_u32 s36, s36, s8
	s_addc_u32 s37, s37, s9
	s_mov_b32 m0, s47
	v_lshl_add_u64 v[230:231], s[36:37], 0, v[138:139]
	ds_read_b128 v[188:191], v162 offset:32768
	ds_read_b128 v[192:195], v162 offset:33792
	ds_read_b128 v[196:199], v162 offset:34816
	ds_read_b128 v[200:203], v162 offset:35840
	ds_read_b128 v[204:207], v162 offset:36864
	ds_read_b128 v[208:211], v162 offset:37888
	ds_read_b128 v[212:215], v162 offset:38912
	ds_read_b128 v[216:219], v162 offset:39936
	global_load_lds_dwordx4 v[230:231], off
	v_lshl_add_u64 v[230:231], s[36:37], 0, v[142:143]
	s_mov_b32 m0, s48
	s_nop 0
	global_load_lds_dwordx4 v[230:231], off
	s_waitcnt vmcnt(8)
	s_waitcnt lgkmcnt(0)
	s_barrier
	s_setprio 1
	v_mfma_f32_16x16x32_bf16 v[126:129], v[130:133], v[188:191], v[126:129]
	v_mfma_f32_16x16x32_bf16 v[122:125], v[164:167], v[188:191], v[122:125]
	v_mfma_f32_16x16x32_bf16 v[110:113], v[130:133], v[196:199], v[110:113]
	v_mfma_f32_16x16x32_bf16 v[106:109], v[164:167], v[196:199], v[106:109]
	v_mfma_f32_16x16x32_bf16 v[94:97], v[130:133], v[204:207], v[94:97]
	v_mfma_f32_16x16x32_bf16 v[90:93], v[164:167], v[204:207], v[90:93]
	v_mfma_f32_16x16x32_bf16 v[78:81], v[130:133], v[212:215], v[78:81]
	v_mfma_f32_16x16x32_bf16 v[74:77], v[164:167], v[212:215], v[74:77]
	v_mfma_f32_16x16x32_bf16 v[126:129], v[134:137], v[192:195], v[126:129]
	v_mfma_f32_16x16x32_bf16 v[122:125], v[168:171], v[192:195], v[122:125]
	v_mfma_f32_16x16x32_bf16 v[110:113], v[134:137], v[200:203], v[110:113]
	v_mfma_f32_16x16x32_bf16 v[106:109], v[168:171], v[200:203], v[106:109]
	v_mfma_f32_16x16x32_bf16 v[94:97], v[134:137], v[208:211], v[94:97]
	v_mfma_f32_16x16x32_bf16 v[90:93], v[168:171], v[208:211], v[90:93]
	v_mfma_f32_16x16x32_bf16 v[78:81], v[134:137], v[216:219], v[78:81]
	v_mfma_f32_16x16x32_bf16 v[74:77], v[168:171], v[216:219], v[74:77]
	v_mfma_f32_16x16x32_bf16 v[118:121], v[172:175], v[188:191], v[118:121]
	v_mfma_f32_16x16x32_bf16 v[114:117], v[180:183], v[188:191], v[114:117]
	v_mfma_f32_16x16x32_bf16 v[102:105], v[172:175], v[196:199], v[102:105]
	v_mfma_f32_16x16x32_bf16 v[98:101], v[180:183], v[196:199], v[98:101]
	v_mfma_f32_16x16x32_bf16 v[86:89], v[172:175], v[204:207], v[86:89]
	v_mfma_f32_16x16x32_bf16 v[82:85], v[180:183], v[204:207], v[82:85]
	v_mfma_f32_16x16x32_bf16 v[70:73], v[172:175], v[212:215], v[70:73]
	v_mfma_f32_16x16x32_bf16 v[66:69], v[180:183], v[212:215], v[66:69]
	v_mfma_f32_16x16x32_bf16 v[118:121], v[176:179], v[192:195], v[118:121]
	v_mfma_f32_16x16x32_bf16 v[114:117], v[184:187], v[192:195], v[114:117]
	v_mfma_f32_16x16x32_bf16 v[102:105], v[176:179], v[200:203], v[102:105]
	v_mfma_f32_16x16x32_bf16 v[98:101], v[184:187], v[200:203], v[98:101]
	v_mfma_f32_16x16x32_bf16 v[86:89], v[176:179], v[208:211], v[86:89]
	v_mfma_f32_16x16x32_bf16 v[82:85], v[184:187], v[208:211], v[82:85]
	v_mfma_f32_16x16x32_bf16 v[70:73], v[176:179], v[216:219], v[70:73]
	v_mfma_f32_16x16x32_bf16 v[66:69], v[184:187], v[216:219], v[66:69]
	s_setprio 0
	s_barrier
; #define PG8_STAGE(bufoff, gbase, voff) do { _Pragma("unroll") for (int _i = 0; _i < 2; ++_i) \
;         __builtin_amdgcn_global_load_lds((const unsigned*)((const char*)(gbase) + (voff)[_i]), (PG8_LAS unsigned*)(lds + (bufoff) + ldsw + _i * 8192), 16, 0, 0); } while (0)
; #define PG8_LDA(dst, b, h) do { _Pragma("unroll") for (int m = 0; m < 4; ++m) _Pragma("unroll") for (int k = 0; k < 2; ++k) dst[m][k] = *(const PG8_LAS bf16x8*)(lds + PG8_SA(b, h) + aoff + m * 2048 + k * 1024); } while (0)
; #define PG8_MMA(ai, bj, At, Bt) do { __builtin_amdgcn_s_setprio(1); _Pragma("unroll") for (int m = 0; m < 4; ++m) _Pragma("unroll") for (int n = 0; n < 2; ++n) _Pragma("unroll") for (int k = 0; k < 2; ++k) \
;         acc[ai][bj][m][n] = __builtin_amdgcn_mfma_f32_16x16x32_bf16(Bt[n][k], At[m][k], acc[ai][bj][m][n], 0, 0, 0); __builtin_amdgcn_s_setprio(0); } while (0)
; #define PG8_WAIT_V(n) asm volatile("s_waitcnt vmcnt(" #n ")" ::: "memory")
; #define PG8_WAIT_L(n) asm volatile("s_waitcnt lgkmcnt(" #n ")" ::: "memory")
; #define PG8_BAR __builtin_amdgcn_s_barrier()
; #define PG8_SCHED __builtin_amdgcn_sched_barrier(0)
; template <class Epi, class Sched, bool ALIGN_EPI = false, bool SP2 = false>
; __device__ __forceinline__ void gemm_phase(PG8_LAS unsigned char* lds, const Gemm g, const Sched& S, const Epi& E) {
;     ...
;         for (int t = 0; t < nt; t += 2) {
;             const bool last = (t == nt - 2);
;             const char* a1 = cA + (size_t)(t + 1) * kstep;
;             const char* a2 = last ? nA : cA + (size_t)(t + 2) * kstep; const char* b2 = last ? nB : cB + (size_t)(t + 2) * kstep;
;     ...
;             PG8_LDA(At, 1, 1); PG8_STAGE(PG8_SB(1, 0), b3, voffB); PG8_STAGE(PG8_SB(1, 1), b3 + hstep, voffB); PG8_STAGE(PG8_SA(1, 0), a3, voffA);
;             PG8_WAIT_V(8); PG8_WAIT_L(0); PG8_BAR; PG8_MMA(1, 0, At, B0); PG8_MMA(1, 1, At, B1); PG8_BAR; PG8_SCHED;
	s_add_i32 s36, s70, s41
	v_lshl_add_u64 v[158:159], v[158:159], 0, s[24:25]
	s_mov_b32 m0, s36
	ds_read_b128 v[188:191], v162 offset:49152
	ds_read_b128 v[192:195], v162 offset:50176
	ds_read_b128 v[196:199], v162 offset:51200
	ds_read_b128 v[200:203], v162 offset:52224
	ds_read_b128 v[204:207], v162 offset:53248
	ds_read_b128 v[208:211], v162 offset:54272
	ds_read_b128 v[212:215], v162 offset:55296
	ds_read_b128 v[216:219], v162 offset:56320
	global_load_lds_dwordx4 v[158:159], off
	v_lshl_add_u64 v[158:159], v[220:221], 0, s[24:25]
	s_add_i32 m0, s36, 0x2000
	s_add_i32 s36, s71, s41
	global_load_lds_dwordx4 v[158:159], off
	v_lshl_add_u64 v[158:159], v[222:223], 0, s[24:25]
	s_mov_b32 m0, s36
	s_nop 0
	global_load_lds_dwordx4 v[158:159], off
	v_lshl_add_u64 v[158:159], v[224:225], 0, s[24:25]
	s_add_i32 m0, s36, 0x2000
	s_nop 0
	global_load_lds_dwordx4 v[158:159], off
	v_lshl_add_u64 v[158:159], v[226:227], 0, s[24:25]
	s_mov_b32 m0, s52
	s_nop 0
	global_load_lds_dwordx4 v[158:159], off
	v_lshl_add_u64 v[158:159], v[228:229], 0, s[24:25]
	s_mov_b32 m0, s53
	s_nop 0
	global_load_lds_dwordx4 v[158:159], off
	s_waitcnt vmcnt(8)
	s_waitcnt lgkmcnt(0)
	s_barrier
	s_setprio 1
	v_mfma_f32_16x16x32_bf16 v[62:65], v[130:133], v[188:191], v[62:65]
	v_mfma_f32_16x16x32_bf16 v[58:61], v[164:167], v[188:191], v[58:61]
	v_mfma_f32_16x16x32_bf16 v[46:49], v[130:133], v[196:199], v[46:49]
	v_mfma_f32_16x16x32_bf16 v[42:45], v[164:167], v[196:199], v[42:45]
	v_mfma_f32_16x16x32_bf16 v[30:33], v[130:133], v[204:207], v[30:33]
	v_mfma_f32_16x16x32_bf16 v[26:29], v[164:167], v[204:207], v[26:29]
	v_mfma_f32_16x16x32_bf16 v[14:17], v[130:133], v[212:215], v[14:17]
	v_mfma_f32_16x16x32_bf16 v[10:13], v[164:167], v[212:215], v[10:13]
	v_mfma_f32_16x16x32_bf16 v[62:65], v[134:137], v[192:195], v[62:65]
	v_mfma_f32_16x16x32_bf16 v[58:61], v[168:171], v[192:195], v[58:61]
	v_mfma_f32_16x16x32_bf16 v[46:49], v[134:137], v[200:203], v[46:49]
	v_mfma_f32_16x16x32_bf16 v[42:45], v[168:171], v[200:203], v[42:45]
	v_mfma_f32_16x16x32_bf16 v[30:33], v[134:137], v[208:211], v[30:33]
	v_mfma_f32_16x16x32_bf16 v[26:29], v[168:171], v[208:211], v[26:29]
	v_mfma_f32_16x16x32_bf16 v[14:17], v[134:137], v[216:219], v[14:17]
	v_mfma_f32_16x16x32_bf16 v[10:13], v[168:171], v[216:219], v[10:13]
	v_mfma_f32_16x16x32_bf16 v[54:57], v[172:175], v[188:191], v[54:57]
	v_mfma_f32_16x16x32_bf16 v[50:53], v[180:183], v[188:191], v[50:53]
	v_mfma_f32_16x16x32_bf16 v[38:41], v[172:175], v[196:199], v[38:41]
	v_mfma_f32_16x16x32_bf16 v[34:37], v[180:183], v[196:199], v[34:37]
	v_mfma_f32_16x16x32_bf16 v[22:25], v[172:175], v[204:207], v[22:25]
	v_mfma_f32_16x16x32_bf16 v[18:21], v[180:183], v[204:207], v[18:21]
	v_mfma_f32_16x16x32_bf16 v[6:9], v[172:175], v[212:215], v[6:9]
	v_mfma_f32_16x16x32_bf16 v[2:5], v[180:183], v[212:215], v[2:5]
	v_mfma_f32_16x16x32_bf16 v[54:57], v[176:179], v[192:195], v[54:57]
	v_mfma_f32_16x16x32_bf16 v[50:53], v[184:187], v[192:195], v[50:53]
	v_mfma_f32_16x16x32_bf16 v[38:41], v[176:179], v[200:203], v[38:41]
	v_mfma_f32_16x16x32_bf16 v[34:37], v[184:187], v[200:203], v[34:37]
	v_mfma_f32_16x16x32_bf16 v[22:25], v[176:179], v[208:211], v[22:25]
	v_mfma_f32_16x16x32_bf16 v[18:21], v[184:187], v[208:211], v[18:21]
	v_mfma_f32_16x16x32_bf16 v[6:9], v[176:179], v[216:219], v[6:9]
	v_mfma_f32_16x16x32_bf16 v[2:5], v[184:187], v[216:219], v[2:5]
	s_setprio 0
	s_add_u32 s45, s45, 0x100
	s_addc_u32 s80, s80, 0
	s_add_u32 s34, s34, 0x100
	s_addc_u32 s35, s35, 0
	s_cmp_ge_i32 s81, s54
	s_mov_b32 s36, s81
	s_barrier
	s_cbranch_scc0 .LBB0_1154

; #define PG8_STAGE(bufoff, gbase, voff) do { _Pragma("unroll") for (int _i = 0; _i < 2; ++_i) \
;         __builtin_amdgcn_global_load_lds((const unsigned*)((const char*)(gbase) + (voff)[_i]), (PG8_LAS unsigned*)(lds + (bufoff) + ldsw + _i * 8192), 16, 0, 0); } while (0)
; #define PG8_LDA(dst, b, h) do { _Pragma("unroll") for (int m = 0; m < 4; ++m) _Pragma("unroll") for (int k = 0; k < 2; ++k) dst[m][k] = *(const PG8_LAS bf16x8*)(lds + PG8_SA(b, h) + aoff + m * 2048 + k * 1024); } while (0)
; #define PG8_LDB(dst, b, h) do { _Pragma("unroll") for (int n = 0; n < 2; ++n) _Pragma("unroll") for (int k = 0; k < 2; ++k) dst[n][k] = *(const PG8_LAS bf16x8*)(lds + PG8_SB(b, h) + boff + n * 2048 + k * 1024); } while (0)
; #define PG8_MMA(ai, bj, At, Bt) do { __builtin_amdgcn_s_setprio(1); _Pragma("unroll") for (int m = 0; m < 4; ++m) _Pragma("unroll") for (int n = 0; n < 2; ++n) _Pragma("unroll") for (int k = 0; k < 2; ++k) \
;         acc[ai][bj][m][n] = __builtin_amdgcn_mfma_f32_16x16x32_bf16(Bt[n][k], At[m][k], acc[ai][bj][m][n], 0, 0, 0); __builtin_amdgcn_s_setprio(0); } while (0)
; #define PG8_WAIT_V(n) asm volatile("s_waitcnt vmcnt(" #n ")" ::: "memory")
; #define PG8_WAIT_L(n) asm volatile("s_waitcnt lgkmcnt(" #n ")" ::: "memory")
; #define PG8_BAR __builtin_amdgcn_s_barrier()
; #define PG8_SCHED __builtin_amdgcn_sched_barrier(0)
; template <class Epi, class Sched, bool ALIGN_EPI = false, bool SP2 = false>
; __device__ __forceinline__ void gemm_phase(PG8_LAS unsigned char* lds, const Gemm g, const Sched& S, const Epi& E) {
;     ...
;             PG8_LDB(B0, 0, 0); PG8_LDB(B1, 0, 1); PG8_SCHED; PG8_LDA(At, 0, 0); PG8_STAGE(PG8_SA(1, 1), a1 + hstep, voffA);
;             PG8_WAIT_V(8); PG8_WAIT_L(0); PG8_BAR; PG8_MMA(0, 0, At, B0); PG8_MMA(0, 1, At, B1); PG8_BAR; PG8_SCHED;
;             PG8_LDA(At, 0, 1); PG8_STAGE(PG8_SB(0, 0), b2, voffB); PG8_STAGE(PG8_SB(0, 1), b2 + hstep, voffB); PG8_STAGE(PG8_SA(0, 0), a2, voffA);
;             PG8_WAIT_V(8); PG8_WAIT_L(0); PG8_BAR; PG8_MMA(1, 0, At, B0); PG8_MMA(1, 1, At, B1); PG8_BAR; PG8_SCHED;
.LBB0_1375:
	ds_read_b128 v[166:169], v162
	ds_read_b128 v[170:173], v162 offset:1024
	ds_read_b128 v[174:177], v162 offset:2048
	ds_read_b128 v[178:181], v162 offset:3072
	ds_read_b128 v[182:185], v163
	ds_read_b128 v[186:189], v163 offset:1024
	ds_read_b128 v[190:193], v163 offset:2048
	ds_read_b128 v[194:197], v163 offset:3072
	s_add_i32 s87, s36, 2
	s_add_u32 s70, s34, 0x80
	s_addc_u32 s37, s35, 0
	s_cmp_eq_u32 s52, s36
	s_cselect_b32 s36, s4, s70
	s_cselect_b32 s37, s5, s37
	s_cselect_b32 s71, s31, s86
	s_cselect_b32 s70, s30, s81
	v_lshl_add_u64 v[230:231], s[34:35], 0, v[140:141]
	s_add_i32 m0, s42, 0xc000
	ds_read_b128 v[198:201], v164
	ds_read_b128 v[202:205], v164 offset:1024
	ds_read_b128 v[206:209], v164 offset:2048
	ds_read_b128 v[210:213], v164 offset:3072
	ds_read_b128 v[214:217], v164 offset:4096
	ds_read_b128 v[218:221], v164 offset:5120
	ds_read_b128 v[222:225], v164 offset:6144
	ds_read_b128 v[226:229], v164 offset:7168
	global_load_lds_dwordx4 v[230:231], off
	v_lshl_add_u64 v[230:231], s[34:35], 0, v[138:139]
	s_add_i32 m0, s42, 0xe000
	s_nop 0
	global_load_lds_dwordx4 v[230:231], off
	s_waitcnt vmcnt(8)
	s_waitcnt lgkmcnt(0)
	s_barrier
	s_setprio 1
	v_mfma_f32_16x16x32_bf16 v[122:125], v[166:169], v[198:201], v[122:125]
	v_mfma_f32_16x16x32_bf16 v[126:129], v[174:177], v[198:201], v[126:129]
	v_mfma_f32_16x16x32_bf16 v[110:113], v[166:169], v[206:209], v[110:113]
	v_mfma_f32_16x16x32_bf16 v[106:109], v[174:177], v[206:209], v[106:109]
	v_mfma_f32_16x16x32_bf16 v[94:97], v[166:169], v[214:217], v[94:97]
	v_mfma_f32_16x16x32_bf16 v[90:93], v[174:177], v[214:217], v[90:93]
	v_mfma_f32_16x16x32_bf16 v[78:81], v[166:169], v[222:225], v[78:81]
	v_mfma_f32_16x16x32_bf16 v[74:77], v[174:177], v[222:225], v[74:77]
	v_mfma_f32_16x16x32_bf16 v[122:125], v[170:173], v[202:205], v[122:125]
	v_mfma_f32_16x16x32_bf16 v[126:129], v[178:181], v[202:205], v[126:129]
	v_mfma_f32_16x16x32_bf16 v[110:113], v[170:173], v[210:213], v[110:113]
	v_mfma_f32_16x16x32_bf16 v[106:109], v[178:181], v[210:213], v[106:109]
	v_mfma_f32_16x16x32_bf16 v[94:97], v[170:173], v[218:221], v[94:97]
	v_mfma_f32_16x16x32_bf16 v[90:93], v[178:181], v[218:221], v[90:93]
	v_mfma_f32_16x16x32_bf16 v[78:81], v[170:173], v[226:229], v[78:81]
	v_mfma_f32_16x16x32_bf16 v[74:77], v[178:181], v[226:229], v[74:77]
	v_mfma_f32_16x16x32_bf16 v[118:121], v[182:185], v[198:201], v[118:121]
	v_mfma_f32_16x16x32_bf16 v[114:117], v[190:193], v[198:201], v[114:117]
	v_mfma_f32_16x16x32_bf16 v[102:105], v[182:185], v[206:209], v[102:105]
	v_mfma_f32_16x16x32_bf16 v[98:101], v[190:193], v[206:209], v[98:101]
	v_mfma_f32_16x16x32_bf16 v[86:89], v[182:185], v[214:217], v[86:89]
	v_mfma_f32_16x16x32_bf16 v[82:85], v[190:193], v[214:217], v[82:85]
	v_mfma_f32_16x16x32_bf16 v[70:73], v[182:185], v[222:225], v[70:73]
	v_mfma_f32_16x16x32_bf16 v[66:69], v[190:193], v[222:225], v[66:69]
	v_mfma_f32_16x16x32_bf16 v[118:121], v[186:189], v[202:205], v[118:121]
	v_mfma_f32_16x16x32_bf16 v[114:117], v[194:197], v[202:205], v[114:117]
	v_mfma_f32_16x16x32_bf16 v[102:105], v[186:189], v[210:213], v[102:105]
	v_mfma_f32_16x16x32_bf16 v[98:101], v[194:197], v[210:213], v[98:101]
	v_mfma_f32_16x16x32_bf16 v[86:89], v[186:189], v[218:221], v[86:89]
	v_mfma_f32_16x16x32_bf16 v[82:85], v[194:197], v[218:221], v[82:85]
	v_mfma_f32_16x16x32_bf16 v[70:73], v[186:189], v[226:229], v[70:73]
	v_mfma_f32_16x16x32_bf16 v[66:69], v[194:197], v[226:229], v[66:69]
	s_setprio 0
	s_barrier
	s_add_i32 s72, s55, s41
	v_lshl_add_u64 v[230:231], s[70:71], 0, v[132:133]
	s_mov_b32 m0, s72
	ds_read_b128 v[198:201], v164 offset:16384
	ds_read_b128 v[202:205], v164 offset:17408
	ds_read_b128 v[206:209], v164 offset:18432
	ds_read_b128 v[210:213], v164 offset:19456
	ds_read_b128 v[214:217], v164 offset:20480
	ds_read_b128 v[218:221], v164 offset:21504
	ds_read_b128 v[222:225], v164 offset:22528
	ds_read_b128 v[226:229], v164 offset:23552
	global_load_lds_dwordx4 v[230:231], off
	s_add_i32 m0, s72, 0x2000
	v_lshl_add_u64 v[232:233], s[70:71], 0, v[136:137]
	s_add_u32 s70, s70, s14
	s_addc_u32 s71, s71, s15
	s_add_i32 s72, s56, s41
	global_load_lds_dwordx4 v[232:233], off
	v_lshl_add_u64 v[234:235], s[70:71], 0, v[132:133]
	s_mov_b32 m0, s72
	v_lshl_add_u64 v[236:237], s[70:71], 0, v[136:137]
	global_load_lds_dwordx4 v[234:235], off
	s_add_i32 m0, s72, 0x2000
	v_lshl_add_u64 v[238:239], s[36:37], 0, v[130:131]
	global_load_lds_dwordx4 v[236:237], off
	s_mov_b32 m0, s42
	v_lshl_add_u64 v[240:241], s[36:37], 0, v[134:135]
	global_load_lds_dwordx4 v[238:239], off
	s_mov_b32 m0, s43
	s_nop 0
	global_load_lds_dwordx4 v[240:241], off
	s_waitcnt vmcnt(8)
	s_waitcnt lgkmcnt(0)
	s_barrier
; #define PG8_STAGE(bufoff, gbase, voff) do { _Pragma("unroll") for (int _i = 0; _i < 2; ++_i) \
;         __builtin_amdgcn_global_load_lds((const unsigned*)((const char*)(gbase) + (voff)[_i]), (PG8_LAS unsigned*)(lds + (bufoff) + ldsw + _i * 8192), 16, 0, 0); } while (0)
; #define PG8_LDA(dst, b, h) do { _Pragma("unroll") for (int m = 0; m < 4; ++m) _Pragma("unroll") for (int k = 0; k < 2; ++k) dst[m][k] = *(const PG8_LAS bf16x8*)(lds + PG8_SA(b, h) + aoff + m * 2048 + k * 1024); } while (0)
; #define PG8_LDB(dst, b, h) do { _Pragma("unroll") for (int n = 0; n < 2; ++n) _Pragma("unroll") for (int k = 0; k < 2; ++k) dst[n][k] = *(const PG8_LAS bf16x8*)(lds + PG8_SB(b, h) + boff + n * 2048 + k * 1024); } while (0)
; #define PG8_MMA(ai, bj, At, Bt) do { __builtin_amdgcn_s_setprio(1); _Pragma("unroll") for (int m = 0; m < 4; ++m) _Pragma("unroll") for (int n = 0; n < 2; ++n) _Pragma("unroll") for (int k = 0; k < 2; ++k) \
;         acc[ai][bj][m][n] = __builtin_amdgcn_mfma_f32_16x16x32_bf16(Bt[n][k], At[m][k], acc[ai][bj][m][n], 0, 0, 0); __builtin_amdgcn_s_setprio(0); } while (0)
; #define PG8_WAIT_V(n) asm volatile("s_waitcnt vmcnt(" #n ")" ::: "memory")
; #define PG8_WAIT_L(n) asm volatile("s_waitcnt lgkmcnt(" #n ")" ::: "memory")
; #define PG8_BAR __builtin_amdgcn_s_barrier()
; #define PG8_SCHED __builtin_amdgcn_sched_barrier(0)
; template <class Epi, class Sched, bool ALIGN_EPI = false, bool SP2 = false>
; __device__ __forceinline__ void gemm_phase(PG8_LAS unsigned char* lds, const Gemm g, const Sched& S, const Epi& E) {
;     ...
;             PG8_WAIT_V(8); PG8_WAIT_L(0); PG8_BAR; PG8_MMA(1, 0, At, B0); PG8_MMA(1, 1, At, B1); PG8_BAR; PG8_SCHED;
;             PG8_LDB(B0, 1, 0); PG8_LDB(B1, 1, 1); PG8_SCHED; PG8_LDA(At, 1, 0); PG8_STAGE(PG8_SA(0, 1), a2 + hstep, voffA);
;             PG8_WAIT_V(8); PG8_WAIT_L(0); PG8_BAR; PG8_MMA(0, 0, At, B0); PG8_MMA(0, 1, At, B1); PG8_BAR; PG8_SCHED;
	s_setprio 1
	v_mfma_f32_16x16x32_bf16 v[62:65], v[166:169], v[198:201], v[62:65]
	v_mfma_f32_16x16x32_bf16 v[58:61], v[174:177], v[198:201], v[58:61]
	v_mfma_f32_16x16x32_bf16 v[46:49], v[166:169], v[206:209], v[46:49]
	v_mfma_f32_16x16x32_bf16 v[42:45], v[174:177], v[206:209], v[42:45]
	v_mfma_f32_16x16x32_bf16 v[30:33], v[166:169], v[214:217], v[30:33]
	v_mfma_f32_16x16x32_bf16 v[26:29], v[174:177], v[214:217], v[26:29]
	v_mfma_f32_16x16x32_bf16 v[14:17], v[166:169], v[222:225], v[14:17]
	v_mfma_f32_16x16x32_bf16 v[10:13], v[174:177], v[222:225], v[10:13]
	v_mfma_f32_16x16x32_bf16 v[62:65], v[170:173], v[202:205], v[62:65]
	v_mfma_f32_16x16x32_bf16 v[58:61], v[178:181], v[202:205], v[58:61]
	v_mfma_f32_16x16x32_bf16 v[46:49], v[170:173], v[210:213], v[46:49]
	v_mfma_f32_16x16x32_bf16 v[42:45], v[178:181], v[210:213], v[42:45]
	v_mfma_f32_16x16x32_bf16 v[30:33], v[170:173], v[218:221], v[30:33]
	v_mfma_f32_16x16x32_bf16 v[26:29], v[178:181], v[218:221], v[26:29]
	v_mfma_f32_16x16x32_bf16 v[14:17], v[170:173], v[226:229], v[14:17]
	v_mfma_f32_16x16x32_bf16 v[10:13], v[178:181], v[226:229], v[10:13]
	v_mfma_f32_16x16x32_bf16 v[54:57], v[182:185], v[198:201], v[54:57]
	v_mfma_f32_16x16x32_bf16 v[50:53], v[190:193], v[198:201], v[50:53]
	v_mfma_f32_16x16x32_bf16 v[38:41], v[182:185], v[206:209], v[38:41]
	v_mfma_f32_16x16x32_bf16 v[34:37], v[190:193], v[206:209], v[34:37]
	v_mfma_f32_16x16x32_bf16 v[22:25], v[182:185], v[214:217], v[22:25]
	v_mfma_f32_16x16x32_bf16 v[18:21], v[190:193], v[214:217], v[18:21]
	v_mfma_f32_16x16x32_bf16 v[6:9], v[182:185], v[222:225], v[6:9]
	v_mfma_f32_16x16x32_bf16 v[2:5], v[190:193], v[222:225], v[2:5]
	v_mfma_f32_16x16x32_bf16 v[54:57], v[186:189], v[202:205], v[54:57]
	v_mfma_f32_16x16x32_bf16 v[50:53], v[194:197], v[202:205], v[50:53]
	v_mfma_f32_16x16x32_bf16 v[38:41], v[186:189], v[210:213], v[38:41]
	v_mfma_f32_16x16x32_bf16 v[34:37], v[194:197], v[210:213], v[34:37]
	v_mfma_f32_16x16x32_bf16 v[22:25], v[186:189], v[218:221], v[22:25]
	v_mfma_f32_16x16x32_bf16 v[18:21], v[194:197], v[218:221], v[18:21]
	v_mfma_f32_16x16x32_bf16 v[6:9], v[186:189], v[226:229], v[6:9]
	v_mfma_f32_16x16x32_bf16 v[2:5], v[194:197], v[226:229], v[2:5]
	s_setprio 0
	s_barrier
	s_add_i32 s70, 0, 0x18000
	v_add_u32_e32 v165, s70, v160
	s_add_i32 s71, 0, 0x1c000
	ds_read_b128 v[166:169], v165
	ds_read_b128 v[170:173], v165 offset:1024
	ds_read_b128 v[174:177], v165 offset:2048
	ds_read_b128 v[178:181], v165 offset:3072
	v_add_u32_e32 v165, s71, v160
	ds_read_b128 v[182:185], v165
	ds_read_b128 v[186:189], v165 offset:1024
	ds_read_b128 v[190:193], v165 offset:2048
	ds_read_b128 v[194:197], v165 offset:3072
	s_add_u32 s36, s36, s14
	s_addc_u32 s37, s37, s15
	s_mov_b32 m0, s44
	v_lshl_add_u64 v[242:243], s[36:37], 0, v[130:131]
	ds_read_b128 v[198:201], v164 offset:32768
	ds_read_b128 v[202:205], v164 offset:33792
	ds_read_b128 v[206:209], v164 offset:34816
	ds_read_b128 v[210:213], v164 offset:35840
	ds_read_b128 v[214:217], v164 offset:36864
	ds_read_b128 v[218:221], v164 offset:37888
	ds_read_b128 v[222:225], v164 offset:38912
	ds_read_b128 v[226:229], v164 offset:39936
	global_load_lds_dwordx4 v[242:243], off
	v_lshl_add_u64 v[242:243], s[36:37], 0, v[134:135]
	s_mov_b32 m0, s45
	s_nop 0
	global_load_lds_dwordx4 v[242:243], off
	s_waitcnt vmcnt(8)
	s_waitcnt lgkmcnt(0)
	s_barrier
	s_setprio 1
	v_mfma_f32_16x16x32_bf16 v[122:125], v[166:169], v[198:201], v[122:125]
	v_mfma_f32_16x16x32_bf16 v[126:129], v[174:177], v[198:201], v[126:129]
	v_mfma_f32_16x16x32_bf16 v[110:113], v[166:169], v[206:209], v[110:113]
	v_mfma_f32_16x16x32_bf16 v[106:109], v[174:177], v[206:209], v[106:109]
	v_mfma_f32_16x16x32_bf16 v[94:97], v[166:169], v[214:217], v[94:97]
	v_mfma_f32_16x16x32_bf16 v[90:93], v[174:177], v[214:217], v[90:93]
	v_mfma_f32_16x16x32_bf16 v[78:81], v[166:169], v[222:225], v[78:81]
	v_mfma_f32_16x16x32_bf16 v[74:77], v[174:177], v[222:225], v[74:77]
	v_mfma_f32_16x16x32_bf16 v[122:125], v[170:173], v[202:205], v[122:125]
	v_mfma_f32_16x16x32_bf16 v[126:129], v[178:181], v[202:205], v[126:129]
	v_mfma_f32_16x16x32_bf16 v[110:113], v[170:173], v[210:213], v[110:113]
	v_mfma_f32_16x16x32_bf16 v[106:109], v[178:181], v[210:213], v[106:109]
	v_mfma_f32_16x16x32_bf16 v[94:97], v[170:173], v[218:221], v[94:97]
	v_mfma_f32_16x16x32_bf16 v[90:93], v[178:181], v[218:221], v[90:93]
	v_mfma_f32_16x16x32_bf16 v[78:81], v[170:173], v[226:229], v[78:81]
	v_mfma_f32_16x16x32_bf16 v[74:77], v[178:181], v[226:229], v[74:77]
	v_mfma_f32_16x16x32_bf16 v[118:121], v[182:185], v[198:201], v[118:121]
	v_mfma_f32_16x16x32_bf16 v[114:117], v[190:193], v[198:201], v[114:117]
	v_mfma_f32_16x16x32_bf16 v[102:105], v[182:185], v[206:209], v[102:105]
	v_mfma_f32_16x16x32_bf16 v[98:101], v[190:193], v[206:209], v[98:101]
	v_mfma_f32_16x16x32_bf16 v[86:89], v[182:185], v[214:217], v[86:89]
	v_mfma_f32_16x16x32_bf16 v[82:85], v[190:193], v[214:217], v[82:85]
	v_mfma_f32_16x16x32_bf16 v[70:73], v[182:185], v[222:225], v[70:73]
	v_mfma_f32_16x16x32_bf16 v[66:69], v[190:193], v[222:225], v[66:69]
	v_mfma_f32_16x16x32_bf16 v[118:121], v[186:189], v[202:205], v[118:121]
	v_mfma_f32_16x16x32_bf16 v[114:117], v[194:197], v[202:205], v[114:117]
	v_mfma_f32_16x16x32_bf16 v[102:105], v[186:189], v[210:213], v[102:105]
	v_mfma_f32_16x16x32_bf16 v[98:101], v[194:197], v[210:213], v[98:101]
	v_mfma_f32_16x16x32_bf16 v[86:89], v[186:189], v[218:221], v[86:89]
	v_mfma_f32_16x16x32_bf16 v[82:85], v[194:197], v[218:221], v[82:85]
	v_mfma_f32_16x16x32_bf16 v[70:73], v[186:189], v[226:229], v[70:73]
	v_mfma_f32_16x16x32_bf16 v[66:69], v[194:197], v[226:229], v[66:69]
	s_setprio 0
	s_barrier
; #define PG8_STAGE(bufoff, gbase, voff) do { _Pragma("unroll") for (int _i = 0; _i < 2; ++_i) \
;         __builtin_amdgcn_global_load_lds((const unsigned*)((const char*)(gbase) + (voff)[_i]), (PG8_LAS unsigned*)(lds + (bufoff) + ldsw + _i * 8192), 16, 0, 0); } while (0)
; #define PG8_LDA(dst, b, h) do { _Pragma("unroll") for (int m = 0; m < 4; ++m) _Pragma("unroll") for (int k = 0; k < 2; ++k) dst[m][k] = *(const PG8_LAS bf16x8*)(lds + PG8_SA(b, h) + aoff + m * 2048 + k * 1024); } while (0)
; #define PG8_MMA(ai, bj, At, Bt) do { __builtin_amdgcn_s_setprio(1); _Pragma("unroll") for (int m = 0; m < 4; ++m) _Pragma("unroll") for (int n = 0; n < 2; ++n) _Pragma("unroll") for (int k = 0; k < 2; ++k) \
;         acc[ai][bj][m][n] = __builtin_amdgcn_mfma_f32_16x16x32_bf16(Bt[n][k], At[m][k], acc[ai][bj][m][n], 0, 0, 0); __builtin_amdgcn_s_setprio(0); } while (0)
; #define PG8_WAIT_V(n) asm volatile("s_waitcnt vmcnt(" #n ")" ::: "memory")
; #define PG8_WAIT_L(n) asm volatile("s_waitcnt lgkmcnt(" #n ")" ::: "memory")
; #define PG8_BAR __builtin_amdgcn_s_barrier()
; #define PG8_SCHED __builtin_amdgcn_sched_barrier(0)
; template <class Epi, class Sched, bool ALIGN_EPI = false, bool SP2 = false>
; __device__ __forceinline__ void gemm_phase(PG8_LAS unsigned char* lds, const Gemm g, const Sched& S, const Epi& E) {
;     ...
;         for (int t = 0; t < nt; t += 2) {
;             const bool last = (t == nt - 2);
;             const char* a1 = cA + (size_t)(t + 1) * kstep;
;             const char* a2 = last ? nA : cA + (size_t)(t + 2) * kstep; const char* b2 = last ? nB : cB + (size_t)(t + 2) * kstep;
;     ...
;             PG8_LDA(At, 1, 1); PG8_STAGE(PG8_SB(1, 0), b3, voffB); PG8_STAGE(PG8_SB(1, 1), b3 + hstep, voffB); PG8_STAGE(PG8_SA(1, 0), a3, voffA);
;             PG8_WAIT_V(8); PG8_WAIT_L(0); PG8_BAR; PG8_MMA(1, 0, At, B0); PG8_MMA(1, 1, At, B1); PG8_BAR; PG8_SCHED;
	s_add_i32 s36, s70, s41
	v_lshl_add_u64 v[230:231], v[230:231], 0, s[24:25]
	s_mov_b32 m0, s36
	ds_read_b128 v[198:201], v164 offset:49152
	ds_read_b128 v[202:205], v164 offset:50176
	ds_read_b128 v[206:209], v164 offset:51200
	ds_read_b128 v[210:213], v164 offset:52224
	ds_read_b128 v[214:217], v164 offset:53248
	ds_read_b128 v[218:221], v164 offset:54272
	ds_read_b128 v[222:225], v164 offset:55296
	ds_read_b128 v[226:229], v164 offset:56320
	global_load_lds_dwordx4 v[230:231], off
	v_lshl_add_u64 v[230:231], v[232:233], 0, s[24:25]
	s_add_i32 m0, s36, 0x2000
	s_add_i32 s36, s71, s41
	global_load_lds_dwordx4 v[230:231], off
	v_lshl_add_u64 v[230:231], v[234:235], 0, s[24:25]
	s_mov_b32 m0, s36
	s_nop 0
	global_load_lds_dwordx4 v[230:231], off
	v_lshl_add_u64 v[230:231], v[236:237], 0, s[24:25]
	s_add_i32 m0, s36, 0x2000
	s_nop 0
	global_load_lds_dwordx4 v[230:231], off
	v_lshl_add_u64 v[230:231], v[238:239], 0, s[24:25]
	s_mov_b32 m0, s47
	s_nop 0
	global_load_lds_dwordx4 v[230:231], off
	v_lshl_add_u64 v[230:231], v[240:241], 0, s[24:25]
	s_mov_b32 m0, s48
	s_nop 0
	global_load_lds_dwordx4 v[230:231], off
	s_waitcnt vmcnt(8)
	s_waitcnt lgkmcnt(0)
	s_barrier
	s_setprio 1
	v_mfma_f32_16x16x32_bf16 v[62:65], v[166:169], v[198:201], v[62:65]
	v_mfma_f32_16x16x32_bf16 v[58:61], v[174:177], v[198:201], v[58:61]
	v_mfma_f32_16x16x32_bf16 v[46:49], v[166:169], v[206:209], v[46:49]
	v_mfma_f32_16x16x32_bf16 v[42:45], v[174:177], v[206:209], v[42:45]
	v_mfma_f32_16x16x32_bf16 v[30:33], v[166:169], v[214:217], v[30:33]
	v_mfma_f32_16x16x32_bf16 v[26:29], v[174:177], v[214:217], v[26:29]
	v_mfma_f32_16x16x32_bf16 v[14:17], v[166:169], v[222:225], v[14:17]
	v_mfma_f32_16x16x32_bf16 v[10:13], v[174:177], v[222:225], v[10:13]
	v_mfma_f32_16x16x32_bf16 v[62:65], v[170:173], v[202:205], v[62:65]
	v_mfma_f32_16x16x32_bf16 v[58:61], v[178:181], v[202:205], v[58:61]
	v_mfma_f32_16x16x32_bf16 v[46:49], v[170:173], v[210:213], v[46:49]
	v_mfma_f32_16x16x32_bf16 v[42:45], v[178:181], v[210:213], v[42:45]
	v_mfma_f32_16x16x32_bf16 v[30:33], v[170:173], v[218:221], v[30:33]
	v_mfma_f32_16x16x32_bf16 v[26:29], v[178:181], v[218:221], v[26:29]
	v_mfma_f32_16x16x32_bf16 v[14:17], v[170:173], v[226:229], v[14:17]
	v_mfma_f32_16x16x32_bf16 v[10:13], v[178:181], v[226:229], v[10:13]
	v_mfma_f32_16x16x32_bf16 v[54:57], v[182:185], v[198:201], v[54:57]
	v_mfma_f32_16x16x32_bf16 v[50:53], v[190:193], v[198:201], v[50:53]
	v_mfma_f32_16x16x32_bf16 v[38:41], v[182:185], v[206:209], v[38:41]
	v_mfma_f32_16x16x32_bf16 v[34:37], v[190:193], v[206:209], v[34:37]
	v_mfma_f32_16x16x32_bf16 v[22:25], v[182:185], v[214:217], v[22:25]
	v_mfma_f32_16x16x32_bf16 v[18:21], v[190:193], v[214:217], v[18:21]
	v_mfma_f32_16x16x32_bf16 v[6:9], v[182:185], v[222:225], v[6:9]
	v_mfma_f32_16x16x32_bf16 v[2:5], v[190:193], v[222:225], v[2:5]
	v_mfma_f32_16x16x32_bf16 v[54:57], v[186:189], v[202:205], v[54:57]
	v_mfma_f32_16x16x32_bf16 v[50:53], v[194:197], v[202:205], v[50:53]
	v_mfma_f32_16x16x32_bf16 v[38:41], v[186:189], v[210:213], v[38:41]
	v_mfma_f32_16x16x32_bf16 v[34:37], v[194:197], v[210:213], v[34:37]
	v_mfma_f32_16x16x32_bf16 v[22:25], v[186:189], v[218:221], v[22:25]
	v_mfma_f32_16x16x32_bf16 v[18:21], v[194:197], v[218:221], v[18:21]
	v_mfma_f32_16x16x32_bf16 v[6:9], v[186:189], v[226:229], v[6:9]
	v_mfma_f32_16x16x32_bf16 v[2:5], v[194:197], v[226:229], v[2:5]
	s_setprio 0
	s_add_u32 s81, s81, 0x100
	s_addc_u32 s86, s86, 0
	s_add_u32 s34, s34, 0x100
	s_addc_u32 s35, s35, 0
	s_cmp_ge_i32 s87, s49
	s_mov_b32 s36, s87
	s_barrier
	s_cbranch_scc0 .LBB0_1375

; #define PG8_STAGE(bufoff, gbase, voff) do { _Pragma("unroll") for (int _i = 0; _i < 2; ++_i) \
;         __builtin_amdgcn_global_load_lds((const unsigned*)((const char*)(gbase) + (voff)[_i]), (PG8_LAS unsigned*)(lds + (bufoff) + ldsw + _i * 8192), 16, 0, 0); } while (0)
; #define PG8_LDA(dst, b, h) do { _Pragma("unroll") for (int m = 0; m < 4; ++m) _Pragma("unroll") for (int k = 0; k < 2; ++k) dst[m][k] = *(const PG8_LAS bf16x8*)(lds + PG8_SA(b, h) + aoff + m * 2048 + k * 1024); } while (0)
; #define PG8_LDB(dst, b, h) do { _Pragma("unroll") for (int n = 0; n < 2; ++n) _Pragma("unroll") for (int k = 0; k < 2; ++k) dst[n][k] = *(const PG8_LAS bf16x8*)(lds + PG8_SB(b, h) + boff + n * 2048 + k * 1024); } while (0)
; #define PG8_MMA(ai, bj, At, Bt) do { __builtin_amdgcn_s_setprio(1); _Pragma("unroll") for (int m = 0; m < 4; ++m) _Pragma("unroll") for (int n = 0; n < 2; ++n) _Pragma("unroll") for (int k = 0; k < 2; ++k) \
;         acc[ai][bj][m][n] = __builtin_amdgcn_mfma_f32_16x16x32_bf16(Bt[n][k], At[m][k], acc[ai][bj][m][n], 0, 0, 0); __builtin_amdgcn_s_setprio(0); } while (0)
; #define PG8_WAIT_V(n) asm volatile("s_waitcnt vmcnt(" #n ")" ::: "memory")
; #define PG8_WAIT_L(n) asm volatile("s_waitcnt lgkmcnt(" #n ")" ::: "memory")
; template <class Epi, class Sched, bool ALIGN_EPI = false, bool SP2 = false>
; __device__ __forceinline__ void gemm_phase(PG8_LAS unsigned char* lds, const Gemm g, const Sched& S, const Epi& E) {
;     ...
;             const bool last = (t == nt - 2);
;             const char* a1 = cA + (size_t)(t + 1) * kstep;
;             const char* a2 = last ? nA : cA + (size_t)(t + 2) * kstep; const char* b2 = last ? nB : cB + (size_t)(t + 2) * kstep;
;             const char* a3 = a2 + kstep; const char* b3 = b2 + kstep;
;             if (last && has_next) S.a_ready(nxt);
;             if constexpr (SP2) {
;             PG8_LDB(B0, 0, 0); PG8_LDB(B1, 0, 1); PG8_SCHED; PG8_LDA(At, 0, 0); PG8_STAGE(PG8_SA(1, 1), a1 + hstep, voffA);
;             PG8_WAIT_V(8); PG8_WAIT_L(0); PG8_BAR; PG8_MMA(0, 0, At, B0); PG8_MMA(0, 1, At, B1); PG8_BAR; PG8_SCHED;
;             PG8_LDA(At, 0, 1); PG8_STAGE(PG8_SB(0, 0), b2, voffB); PG8_STAGE(PG8_SB(0, 1), b2 + hstep, voffB); PG8_STAGE(PG8_SA(0, 0), a2, voffA);
;             PG8_WAIT_V(8); PG8_WAIT_L(0); PG8_BAR; PG8_MMA(1, 0, At, B0); PG8_MMA(1, 1, At, B1); PG8_BAR; PG8_SCHED;
.LBB0_1404:
	ds_read_b128 v[166:169], v162
	ds_read_b128 v[170:173], v162 offset:1024
	ds_read_b128 v[174:177], v162 offset:2048
	ds_read_b128 v[178:181], v162 offset:3072
	ds_read_b128 v[182:185], v163
	ds_read_b128 v[186:189], v163 offset:1024
	ds_read_b128 v[190:193], v163 offset:2048
	ds_read_b128 v[194:197], v163 offset:3072
	s_add_i32 s86, s34, 2
	s_add_u32 s70, s30, 0x80
	s_addc_u32 s35, s31, 0
	s_cmp_eq_u32 s49, s34
	s_cselect_b32 s34, s6, s70
	s_cselect_b32 s35, s7, s35
	s_cselect_b32 s71, s29, s81
	s_cselect_b32 s70, s28, s80
	v_lshl_add_u64 v[230:231], s[30:31], 0, v[140:141]
	s_add_i32 m0, s41, 0xc000
	ds_read_b128 v[198:201], v164
	ds_read_b128 v[202:205], v164 offset:1024
	ds_read_b128 v[206:209], v164 offset:2048
	ds_read_b128 v[210:213], v164 offset:3072
	ds_read_b128 v[214:217], v164 offset:4096
	ds_read_b128 v[218:221], v164 offset:5120
	ds_read_b128 v[222:225], v164 offset:6144
	ds_read_b128 v[226:229], v164 offset:7168
	global_load_lds_dwordx4 v[230:231], off
	v_lshl_add_u64 v[230:231], s[30:31], 0, v[138:139]
	s_add_i32 m0, s41, 0xe000
	s_nop 0
	global_load_lds_dwordx4 v[230:231], off
	s_waitcnt vmcnt(8)
	s_waitcnt lgkmcnt(0)
	s_barrier
	s_setprio 1
	v_mfma_f32_16x16x32_bf16 v[122:125], v[166:169], v[198:201], v[122:125]
	v_mfma_f32_16x16x32_bf16 v[126:129], v[174:177], v[198:201], v[126:129]
	v_mfma_f32_16x16x32_bf16 v[110:113], v[166:169], v[206:209], v[110:113]
	v_mfma_f32_16x16x32_bf16 v[106:109], v[174:177], v[206:209], v[106:109]
	v_mfma_f32_16x16x32_bf16 v[94:97], v[166:169], v[214:217], v[94:97]
	v_mfma_f32_16x16x32_bf16 v[90:93], v[174:177], v[214:217], v[90:93]
	v_mfma_f32_16x16x32_bf16 v[78:81], v[166:169], v[222:225], v[78:81]
	v_mfma_f32_16x16x32_bf16 v[74:77], v[174:177], v[222:225], v[74:77]
	v_mfma_f32_16x16x32_bf16 v[122:125], v[170:173], v[202:205], v[122:125]
	v_mfma_f32_16x16x32_bf16 v[126:129], v[178:181], v[202:205], v[126:129]
	v_mfma_f32_16x16x32_bf16 v[110:113], v[170:173], v[210:213], v[110:113]
	v_mfma_f32_16x16x32_bf16 v[106:109], v[178:181], v[210:213], v[106:109]
	v_mfma_f32_16x16x32_bf16 v[94:97], v[170:173], v[218:221], v[94:97]
	v_mfma_f32_16x16x32_bf16 v[90:93], v[178:181], v[218:221], v[90:93]
	v_mfma_f32_16x16x32_bf16 v[78:81], v[170:173], v[226:229], v[78:81]
	v_mfma_f32_16x16x32_bf16 v[74:77], v[178:181], v[226:229], v[74:77]
	v_mfma_f32_16x16x32_bf16 v[118:121], v[182:185], v[198:201], v[118:121]
	v_mfma_f32_16x16x32_bf16 v[114:117], v[190:193], v[198:201], v[114:117]
	v_mfma_f32_16x16x32_bf16 v[102:105], v[182:185], v[206:209], v[102:105]
	v_mfma_f32_16x16x32_bf16 v[98:101], v[190:193], v[206:209], v[98:101]
	v_mfma_f32_16x16x32_bf16 v[86:89], v[182:185], v[214:217], v[86:89]
	v_mfma_f32_16x16x32_bf16 v[82:85], v[190:193], v[214:217], v[82:85]
	v_mfma_f32_16x16x32_bf16 v[70:73], v[182:185], v[222:225], v[70:73]
	v_mfma_f32_16x16x32_bf16 v[66:69], v[190:193], v[222:225], v[66:69]
	v_mfma_f32_16x16x32_bf16 v[118:121], v[186:189], v[202:205], v[118:121]
	v_mfma_f32_16x16x32_bf16 v[114:117], v[194:197], v[202:205], v[114:117]
	v_mfma_f32_16x16x32_bf16 v[102:105], v[186:189], v[210:213], v[102:105]
	v_mfma_f32_16x16x32_bf16 v[98:101], v[194:197], v[210:213], v[98:101]
	v_mfma_f32_16x16x32_bf16 v[86:89], v[186:189], v[218:221], v[86:89]
	v_mfma_f32_16x16x32_bf16 v[82:85], v[194:197], v[218:221], v[82:85]
	v_mfma_f32_16x16x32_bf16 v[70:73], v[186:189], v[226:229], v[70:73]
	v_mfma_f32_16x16x32_bf16 v[66:69], v[194:197], v[226:229], v[66:69]
	s_setprio 0
	s_barrier
	s_add_i32 s72, s54, s40
	v_lshl_add_u64 v[230:231], s[70:71], 0, v[132:133]
	s_mov_b32 m0, s72
	ds_read_b128 v[198:201], v164 offset:16384
	ds_read_b128 v[202:205], v164 offset:17408
	ds_read_b128 v[206:209], v164 offset:18432
	ds_read_b128 v[210:213], v164 offset:19456
	ds_read_b128 v[214:217], v164 offset:20480
	ds_read_b128 v[218:221], v164 offset:21504
	ds_read_b128 v[222:225], v164 offset:22528
	ds_read_b128 v[226:229], v164 offset:23552
	global_load_lds_dwordx4 v[230:231], off
	s_add_i32 m0, s72, 0x2000
	v_lshl_add_u64 v[232:233], s[70:71], 0, v[136:137]
	s_add_u32 s70, s70, s12
	s_addc_u32 s71, s71, s13
	s_add_i32 s72, s55, s40
	global_load_lds_dwordx4 v[232:233], off
	v_lshl_add_u64 v[234:235], s[70:71], 0, v[132:133]
	s_mov_b32 m0, s72
	v_lshl_add_u64 v[236:237], s[70:71], 0, v[136:137]
	global_load_lds_dwordx4 v[234:235], off
	s_add_i32 m0, s72, 0x2000
	v_lshl_add_u64 v[238:239], s[34:35], 0, v[130:131]
	global_load_lds_dwordx4 v[236:237], off
	s_mov_b32 m0, s41
	v_lshl_add_u64 v[240:241], s[34:35], 0, v[134:135]
	global_load_lds_dwordx4 v[238:239], off
	s_mov_b32 m0, s42
	s_nop 0
	global_load_lds_dwordx4 v[240:241], off
	s_waitcnt vmcnt(8)
	s_waitcnt lgkmcnt(0)
	s_barrier
; #define PG8_STAGE(bufoff, gbase, voff) do { _Pragma("unroll") for (int _i = 0; _i < 2; ++_i) \
;         __builtin_amdgcn_global_load_lds((const unsigned*)((const char*)(gbase) + (voff)[_i]), (PG8_LAS unsigned*)(lds + (bufoff) + ldsw + _i * 8192), 16, 0, 0); } while (0)
; #define PG8_LDA(dst, b, h) do { _Pragma("unroll") for (int m = 0; m < 4; ++m) _Pragma("unroll") for (int k = 0; k < 2; ++k) dst[m][k] = *(const PG8_LAS bf16x8*)(lds + PG8_SA(b, h) + aoff + m * 2048 + k * 1024); } while (0)
; #define PG8_LDB(dst, b, h) do { _Pragma("unroll") for (int n = 0; n < 2; ++n) _Pragma("unroll") for (int k = 0; k < 2; ++k) dst[n][k] = *(const PG8_LAS bf16x8*)(lds + PG8_SB(b, h) + boff + n * 2048 + k * 1024); } while (0)
; #define PG8_MMA(ai, bj, At, Bt) do { __builtin_amdgcn_s_setprio(1); _Pragma("unroll") for (int m = 0; m < 4; ++m) _Pragma("unroll") for (int n = 0; n < 2; ++n) _Pragma("unroll") for (int k = 0; k < 2; ++k) \
;         acc[ai][bj][m][n] = __builtin_amdgcn_mfma_f32_16x16x32_bf16(Bt[n][k], At[m][k], acc[ai][bj][m][n], 0, 0, 0); __builtin_amdgcn_s_setprio(0); } while (0)
; #define PG8_WAIT_V(n) asm volatile("s_waitcnt vmcnt(" #n ")" ::: "memory")
; #define PG8_WAIT_L(n) asm volatile("s_waitcnt lgkmcnt(" #n ")" ::: "memory")
; #define PG8_BAR __builtin_amdgcn_s_barrier()
; #define PG8_SCHED __builtin_amdgcn_sched_barrier(0)
; template <class Epi, class Sched, bool ALIGN_EPI = false, bool SP2 = false>
; __device__ __forceinline__ void gemm_phase(PG8_LAS unsigned char* lds, const Gemm g, const Sched& S, const Epi& E) {
;     ...
;             PG8_WAIT_V(8); PG8_WAIT_L(0); PG8_BAR; PG8_MMA(1, 0, At, B0); PG8_MMA(1, 1, At, B1); PG8_BAR; PG8_SCHED;
;             PG8_LDB(B0, 1, 0); PG8_LDB(B1, 1, 1); PG8_SCHED; PG8_LDA(At, 1, 0); PG8_STAGE(PG8_SA(0, 1), a2 + hstep, voffA);
;             PG8_WAIT_V(8); PG8_WAIT_L(0); PG8_BAR; PG8_MMA(0, 0, At, B0); PG8_MMA(0, 1, At, B1); PG8_BAR; PG8_SCHED;
	s_setprio 1
	v_mfma_f32_16x16x32_bf16 v[62:65], v[166:169], v[198:201], v[62:65]
	v_mfma_f32_16x16x32_bf16 v[58:61], v[174:177], v[198:201], v[58:61]
	v_mfma_f32_16x16x32_bf16 v[46:49], v[166:169], v[206:209], v[46:49]
	v_mfma_f32_16x16x32_bf16 v[42:45], v[174:177], v[206:209], v[42:45]
	v_mfma_f32_16x16x32_bf16 v[30:33], v[166:169], v[214:217], v[30:33]
	v_mfma_f32_16x16x32_bf16 v[26:29], v[174:177], v[214:217], v[26:29]
	v_mfma_f32_16x16x32_bf16 v[14:17], v[166:169], v[222:225], v[14:17]
	v_mfma_f32_16x16x32_bf16 v[10:13], v[174:177], v[222:225], v[10:13]
	v_mfma_f32_16x16x32_bf16 v[62:65], v[170:173], v[202:205], v[62:65]
	v_mfma_f32_16x16x32_bf16 v[58:61], v[178:181], v[202:205], v[58:61]
	v_mfma_f32_16x16x32_bf16 v[46:49], v[170:173], v[210:213], v[46:49]
	v_mfma_f32_16x16x32_bf16 v[42:45], v[178:181], v[210:213], v[42:45]
	v_mfma_f32_16x16x32_bf16 v[30:33], v[170:173], v[218:221], v[30:33]
	v_mfma_f32_16x16x32_bf16 v[26:29], v[178:181], v[218:221], v[26:29]
	v_mfma_f32_16x16x32_bf16 v[14:17], v[170:173], v[226:229], v[14:17]
	v_mfma_f32_16x16x32_bf16 v[10:13], v[178:181], v[226:229], v[10:13]
	v_mfma_f32_16x16x32_bf16 v[54:57], v[182:185], v[198:201], v[54:57]
	v_mfma_f32_16x16x32_bf16 v[50:53], v[190:193], v[198:201], v[50:53]
	v_mfma_f32_16x16x32_bf16 v[38:41], v[182:185], v[206:209], v[38:41]
	v_mfma_f32_16x16x32_bf16 v[34:37], v[190:193], v[206:209], v[34:37]
	v_mfma_f32_16x16x32_bf16 v[22:25], v[182:185], v[214:217], v[22:25]
	v_mfma_f32_16x16x32_bf16 v[18:21], v[190:193], v[214:217], v[18:21]
	v_mfma_f32_16x16x32_bf16 v[6:9], v[182:185], v[222:225], v[6:9]
	v_mfma_f32_16x16x32_bf16 v[2:5], v[190:193], v[222:225], v[2:5]
	v_mfma_f32_16x16x32_bf16 v[54:57], v[186:189], v[202:205], v[54:57]
	v_mfma_f32_16x16x32_bf16 v[50:53], v[194:197], v[202:205], v[50:53]
	v_mfma_f32_16x16x32_bf16 v[38:41], v[186:189], v[210:213], v[38:41]
	v_mfma_f32_16x16x32_bf16 v[34:37], v[194:197], v[210:213], v[34:37]
	v_mfma_f32_16x16x32_bf16 v[22:25], v[186:189], v[218:221], v[22:25]
	v_mfma_f32_16x16x32_bf16 v[18:21], v[194:197], v[218:221], v[18:21]
	v_mfma_f32_16x16x32_bf16 v[6:9], v[186:189], v[226:229], v[6:9]
	v_mfma_f32_16x16x32_bf16 v[2:5], v[194:197], v[226:229], v[2:5]
	s_setprio 0
	s_barrier
	s_add_i32 s70, 0, 0x18000
	v_add_u32_e32 v165, s70, v160
	s_add_i32 s71, 0, 0x1c000
	ds_read_b128 v[166:169], v165
	ds_read_b128 v[170:173], v165 offset:1024
	ds_read_b128 v[174:177], v165 offset:2048
	ds_read_b128 v[178:181], v165 offset:3072
	v_add_u32_e32 v165, s71, v160
	ds_read_b128 v[182:185], v165
	ds_read_b128 v[186:189], v165 offset:1024
	ds_read_b128 v[190:193], v165 offset:2048
	ds_read_b128 v[194:197], v165 offset:3072
	s_add_u32 s34, s34, s12
	s_addc_u32 s35, s35, s13
	s_mov_b32 m0, s43
	v_lshl_add_u64 v[242:243], s[34:35], 0, v[130:131]
	ds_read_b128 v[198:201], v164 offset:32768
	ds_read_b128 v[202:205], v164 offset:33792
	ds_read_b128 v[206:209], v164 offset:34816
	ds_read_b128 v[210:213], v164 offset:35840
	ds_read_b128 v[214:217], v164 offset:36864
	ds_read_b128 v[218:221], v164 offset:37888
	ds_read_b128 v[222:225], v164 offset:38912
	ds_read_b128 v[226:229], v164 offset:39936
	global_load_lds_dwordx4 v[242:243], off
	v_lshl_add_u64 v[242:243], s[34:35], 0, v[134:135]
	s_mov_b32 m0, s44
	s_nop 0
	global_load_lds_dwordx4 v[242:243], off
	s_waitcnt vmcnt(8)
	s_waitcnt lgkmcnt(0)
	s_barrier
	s_setprio 1
	v_mfma_f32_16x16x32_bf16 v[122:125], v[166:169], v[198:201], v[122:125]
	v_mfma_f32_16x16x32_bf16 v[126:129], v[174:177], v[198:201], v[126:129]
	v_mfma_f32_16x16x32_bf16 v[110:113], v[166:169], v[206:209], v[110:113]
	v_mfma_f32_16x16x32_bf16 v[106:109], v[174:177], v[206:209], v[106:109]
	v_mfma_f32_16x16x32_bf16 v[94:97], v[166:169], v[214:217], v[94:97]
	v_mfma_f32_16x16x32_bf16 v[90:93], v[174:177], v[214:217], v[90:93]
	v_mfma_f32_16x16x32_bf16 v[78:81], v[166:169], v[222:225], v[78:81]
	v_mfma_f32_16x16x32_bf16 v[74:77], v[174:177], v[222:225], v[74:77]
	v_mfma_f32_16x16x32_bf16 v[122:125], v[170:173], v[202:205], v[122:125]
	v_mfma_f32_16x16x32_bf16 v[126:129], v[178:181], v[202:205], v[126:129]
	v_mfma_f32_16x16x32_bf16 v[110:113], v[170:173], v[210:213], v[110:113]
	v_mfma_f32_16x16x32_bf16 v[106:109], v[178:181], v[210:213], v[106:109]
	v_mfma_f32_16x16x32_bf16 v[94:97], v[170:173], v[218:221], v[94:97]
	v_mfma_f32_16x16x32_bf16 v[90:93], v[178:181], v[218:221], v[90:93]
	v_mfma_f32_16x16x32_bf16 v[78:81], v[170:173], v[226:229], v[78:81]
	v_mfma_f32_16x16x32_bf16 v[74:77], v[178:181], v[226:229], v[74:77]
	v_mfma_f32_16x16x32_bf16 v[118:121], v[182:185], v[198:201], v[118:121]
	v_mfma_f32_16x16x32_bf16 v[114:117], v[190:193], v[198:201], v[114:117]
	v_mfma_f32_16x16x32_bf16 v[102:105], v[182:185], v[206:209], v[102:105]
	v_mfma_f32_16x16x32_bf16 v[98:101], v[190:193], v[206:209], v[98:101]
	v_mfma_f32_16x16x32_bf16 v[86:89], v[182:185], v[214:217], v[86:89]
	v_mfma_f32_16x16x32_bf16 v[82:85], v[190:193], v[214:217], v[82:85]
	v_mfma_f32_16x16x32_bf16 v[70:73], v[182:185], v[222:225], v[70:73]
	v_mfma_f32_16x16x32_bf16 v[66:69], v[190:193], v[222:225], v[66:69]
	v_mfma_f32_16x16x32_bf16 v[118:121], v[186:189], v[202:205], v[118:121]
	v_mfma_f32_16x16x32_bf16 v[114:117], v[194:197], v[202:205], v[114:117]
	v_mfma_f32_16x16x32_bf16 v[102:105], v[186:189], v[210:213], v[102:105]
	v_mfma_f32_16x16x32_bf16 v[98:101], v[194:197], v[210:213], v[98:101]
	v_mfma_f32_16x16x32_bf16 v[86:89], v[186:189], v[218:221], v[86:89]
	v_mfma_f32_16x16x32_bf16 v[82:85], v[194:197], v[218:221], v[82:85]
	v_mfma_f32_16x16x32_bf16 v[70:73], v[186:189], v[226:229], v[70:73]
	v_mfma_f32_16x16x32_bf16 v[66:69], v[194:197], v[226:229], v[66:69]
	s_setprio 0
	s_barrier
; #define PG8_STAGE(bufoff, gbase, voff) do { _Pragma("unroll") for (int _i = 0; _i < 2; ++_i) \
;         __builtin_amdgcn_global_load_lds((const unsigned*)((const char*)(gbase) + (voff)[_i]), (PG8_LAS unsigned*)(lds + (bufoff) + ldsw + _i * 8192), 16, 0, 0); } while (0)
; #define PG8_LDA(dst, b, h) do { _Pragma("unroll") for (int m = 0; m < 4; ++m) _Pragma("unroll") for (int k = 0; k < 2; ++k) dst[m][k] = *(const PG8_LAS bf16x8*)(lds + PG8_SA(b, h) + aoff + m * 2048 + k * 1024); } while (0)
; #define PG8_MMA(ai, bj, At, Bt) do { __builtin_amdgcn_s_setprio(1); _Pragma("unroll") for (int m = 0; m < 4; ++m) _Pragma("unroll") for (int n = 0; n < 2; ++n) _Pragma("unroll") for (int k = 0; k < 2; ++k) \
;         acc[ai][bj][m][n] = __builtin_amdgcn_mfma_f32_16x16x32_bf16(Bt[n][k], At[m][k], acc[ai][bj][m][n], 0, 0, 0); __builtin_amdgcn_s_setprio(0); } while (0)
; #define PG8_WAIT_V(n) asm volatile("s_waitcnt vmcnt(" #n ")" ::: "memory")
; #define PG8_WAIT_L(n) asm volatile("s_waitcnt lgkmcnt(" #n ")" ::: "memory")
; #define PG8_BAR __builtin_amdgcn_s_barrier()
; #define PG8_SCHED __builtin_amdgcn_sched_barrier(0)
; template <class Epi, class Sched, bool ALIGN_EPI = false, bool SP2 = false>
; __device__ __forceinline__ void gemm_phase(PG8_LAS unsigned char* lds, const Gemm g, const Sched& S, const Epi& E) {
;     ...
;         for (int t = 0; t < nt; t += 2) {
;             const bool last = (t == nt - 2);
;             const char* a1 = cA + (size_t)(t + 1) * kstep;
;             const char* a2 = last ? nA : cA + (size_t)(t + 2) * kstep; const char* b2 = last ? nB : cB + (size_t)(t + 2) * kstep;
;             const char* a3 = a2 + kstep; const char* b3 = b2 + kstep;
;     ...
;             PG8_LDA(At, 1, 1); PG8_STAGE(PG8_SB(1, 0), b3, voffB); PG8_STAGE(PG8_SB(1, 1), b3 + hstep, voffB); PG8_STAGE(PG8_SA(1, 0), a3, voffA);
;             PG8_WAIT_V(8); PG8_WAIT_L(0); PG8_BAR; PG8_MMA(1, 0, At, B0); PG8_MMA(1, 1, At, B1); PG8_BAR; PG8_SCHED;
	s_add_i32 s34, s70, s40
	v_lshl_add_u64 v[230:231], v[230:231], 0, s[22:23]
	s_mov_b32 m0, s34
	ds_read_b128 v[198:201], v164 offset:49152
	ds_read_b128 v[202:205], v164 offset:50176
	ds_read_b128 v[206:209], v164 offset:51200
	ds_read_b128 v[210:213], v164 offset:52224
	ds_read_b128 v[214:217], v164 offset:53248
	ds_read_b128 v[218:221], v164 offset:54272
	ds_read_b128 v[222:225], v164 offset:55296
	ds_read_b128 v[226:229], v164 offset:56320
	global_load_lds_dwordx4 v[230:231], off
	v_lshl_add_u64 v[230:231], v[232:233], 0, s[22:23]
	s_add_i32 m0, s34, 0x2000
	s_add_i32 s34, s71, s40
	global_load_lds_dwordx4 v[230:231], off
	v_lshl_add_u64 v[230:231], v[234:235], 0, s[22:23]
	s_mov_b32 m0, s34
	s_nop 0
	global_load_lds_dwordx4 v[230:231], off
	v_lshl_add_u64 v[230:231], v[236:237], 0, s[22:23]
	s_add_i32 m0, s34, 0x2000
	s_nop 0
	global_load_lds_dwordx4 v[230:231], off
	v_lshl_add_u64 v[230:231], v[238:239], 0, s[22:23]
	s_mov_b32 m0, s46
	s_nop 0
	global_load_lds_dwordx4 v[230:231], off
	v_lshl_add_u64 v[230:231], v[240:241], 0, s[22:23]
	s_mov_b32 m0, s47
	s_nop 0
	global_load_lds_dwordx4 v[230:231], off
	s_waitcnt vmcnt(8)
	s_waitcnt lgkmcnt(0)
	s_barrier
	s_setprio 1
	v_mfma_f32_16x16x32_bf16 v[62:65], v[166:169], v[198:201], v[62:65]
	v_mfma_f32_16x16x32_bf16 v[58:61], v[174:177], v[198:201], v[58:61]
	v_mfma_f32_16x16x32_bf16 v[46:49], v[166:169], v[206:209], v[46:49]
	v_mfma_f32_16x16x32_bf16 v[42:45], v[174:177], v[206:209], v[42:45]
	v_mfma_f32_16x16x32_bf16 v[30:33], v[166:169], v[214:217], v[30:33]
	v_mfma_f32_16x16x32_bf16 v[26:29], v[174:177], v[214:217], v[26:29]
	v_mfma_f32_16x16x32_bf16 v[14:17], v[166:169], v[222:225], v[14:17]
	v_mfma_f32_16x16x32_bf16 v[10:13], v[174:177], v[222:225], v[10:13]
	v_mfma_f32_16x16x32_bf16 v[62:65], v[170:173], v[202:205], v[62:65]
	v_mfma_f32_16x16x32_bf16 v[58:61], v[178:181], v[202:205], v[58:61]
	v_mfma_f32_16x16x32_bf16 v[46:49], v[170:173], v[210:213], v[46:49]
	v_mfma_f32_16x16x32_bf16 v[42:45], v[178:181], v[210:213], v[42:45]
	v_mfma_f32_16x16x32_bf16 v[30:33], v[170:173], v[218:221], v[30:33]
	v_mfma_f32_16x16x32_bf16 v[26:29], v[178:181], v[218:221], v[26:29]
	v_mfma_f32_16x16x32_bf16 v[14:17], v[170:173], v[226:229], v[14:17]
	v_mfma_f32_16x16x32_bf16 v[10:13], v[178:181], v[226:229], v[10:13]
	v_mfma_f32_16x16x32_bf16 v[54:57], v[182:185], v[198:201], v[54:57]
	v_mfma_f32_16x16x32_bf16 v[50:53], v[190:193], v[198:201], v[50:53]
	v_mfma_f32_16x16x32_bf16 v[38:41], v[182:185], v[206:209], v[38:41]
	v_mfma_f32_16x16x32_bf16 v[34:37], v[190:193], v[206:209], v[34:37]
	v_mfma_f32_16x16x32_bf16 v[22:25], v[182:185], v[214:217], v[22:25]
	v_mfma_f32_16x16x32_bf16 v[18:21], v[190:193], v[214:217], v[18:21]
	v_mfma_f32_16x16x32_bf16 v[6:9], v[182:185], v[222:225], v[6:9]
	v_mfma_f32_16x16x32_bf16 v[2:5], v[190:193], v[222:225], v[2:5]
	v_mfma_f32_16x16x32_bf16 v[54:57], v[186:189], v[202:205], v[54:57]
	v_mfma_f32_16x16x32_bf16 v[50:53], v[194:197], v[202:205], v[50:53]
	v_mfma_f32_16x16x32_bf16 v[38:41], v[186:189], v[210:213], v[38:41]
	v_mfma_f32_16x16x32_bf16 v[34:37], v[194:197], v[210:213], v[34:37]
	v_mfma_f32_16x16x32_bf16 v[22:25], v[186:189], v[218:221], v[22:25]
	v_mfma_f32_16x16x32_bf16 v[18:21], v[194:197], v[218:221], v[18:21]
	v_mfma_f32_16x16x32_bf16 v[6:9], v[186:189], v[226:229], v[6:9]
	v_mfma_f32_16x16x32_bf16 v[2:5], v[194:197], v[226:229], v[2:5]
	s_setprio 0
	s_add_u32 s80, s80, 0x100
	s_addc_u32 s81, s81, 0
	s_add_u32 s30, s30, 0x100
	s_addc_u32 s31, s31, 0
	s_cmp_ge_i32 s86, s48
	s_mov_b32 s34, s86
	s_barrier
	s_cbranch_scc0 .LBB0_1404

; #define PG8_STAGE(bufoff, gbase, voff) do { _Pragma("unroll") for (int _i = 0; _i < 2; ++_i) \
;         __builtin_amdgcn_global_load_lds((const unsigned*)((const char*)(gbase) + (voff)[_i]), (PG8_LAS unsigned*)(lds + (bufoff) + ldsw + _i * 8192), 16, 0, 0); } while (0)
; #define PG8_LDA(dst, b, h) do { _Pragma("unroll") for (int m = 0; m < 4; ++m) _Pragma("unroll") for (int k = 0; k < 2; ++k) dst[m][k] = *(const PG8_LAS bf16x8*)(lds + PG8_SA(b, h) + aoff + m * 2048 + k * 1024); } while (0)
; #define PG8_LDB(dst, b, h) do { _Pragma("unroll") for (int n = 0; n < 2; ++n) _Pragma("unroll") for (int k = 0; k < 2; ++k) dst[n][k] = *(const PG8_LAS bf16x8*)(lds + PG8_SB(b, h) + boff + n * 2048 + k * 1024); } while (0)
; #define PG8_MMA(ai, bj, At, Bt) do { __builtin_amdgcn_s_setprio(1); _Pragma("unroll") for (int m = 0; m < 4; ++m) _Pragma("unroll") for (int n = 0; n < 2; ++n) _Pragma("unroll") for (int k = 0; k < 2; ++k) \
;         acc[ai][bj][m][n] = __builtin_amdgcn_mfma_f32_16x16x32_bf16(Bt[n][k], At[m][k], acc[ai][bj][m][n], 0, 0, 0); __builtin_amdgcn_s_setprio(0); } while (0)
; #define PG8_WAIT_V(n) asm volatile("s_waitcnt vmcnt(" #n ")" ::: "memory")
; #define PG8_WAIT_L(n) asm volatile("s_waitcnt lgkmcnt(" #n ")" ::: "memory")
; template <class Epi, class Sched, bool ALIGN_EPI = false, bool SP2 = false>
; __device__ __forceinline__ void gemm_phase(PG8_LAS unsigned char* lds, const Gemm g, const Sched& S, const Epi& E) {
;     ...
;             const bool last = (t == nt - 2);
;             const char* a1 = cA + (size_t)(t + 1) * kstep;
;             const char* a2 = last ? nA : cA + (size_t)(t + 2) * kstep; const char* b2 = last ? nB : cB + (size_t)(t + 2) * kstep;
;             const char* a3 = a2 + kstep; const char* b3 = b2 + kstep;
;             if (last && has_next) S.a_ready(nxt);
;             if constexpr (SP2) {
;             PG8_LDB(B0, 0, 0); PG8_LDB(B1, 0, 1); PG8_SCHED; PG8_LDA(At, 0, 0); PG8_STAGE(PG8_SA(1, 1), a1 + hstep, voffA);
;             PG8_WAIT_V(8); PG8_WAIT_L(0); PG8_BAR; PG8_MMA(0, 0, At, B0); PG8_MMA(0, 1, At, B1); PG8_BAR; PG8_SCHED;
;             PG8_LDA(At, 0, 1); PG8_STAGE(PG8_SB(0, 0), b2, voffB); PG8_STAGE(PG8_SB(0, 1), b2 + hstep, voffB); PG8_STAGE(PG8_SA(0, 0), a2, voffA);
;             PG8_WAIT_V(8); PG8_WAIT_L(0); PG8_BAR; PG8_MMA(1, 0, At, B0); PG8_MMA(1, 1, At, B1); PG8_BAR; PG8_SCHED;
.LBB0_1433:
	ds_read_b128 v[156:159], v1
	ds_read_b128 v[160:163], v1 offset:1024
	ds_read_b128 v[164:167], v1 offset:2048
	ds_read_b128 v[168:171], v1 offset:3072
	ds_read_b128 v[172:175], v146
	ds_read_b128 v[176:179], v146 offset:1024
	ds_read_b128 v[180:183], v146 offset:2048
	ds_read_b128 v[184:187], v146 offset:3072
	s_add_i32 s80, s30, 2
	s_add_u32 s70, s28, 0x80
	s_addc_u32 s31, s29, 0
	s_cmp_eq_u32 s47, s30
	s_cselect_b32 s30, s4, s70
	s_cselect_b32 s31, s5, s31
	s_cselect_b32 s71, s27, s69
	s_cselect_b32 s70, s26, s68
	v_lshl_add_u64 v[152:153], s[28:29], 0, v[140:141]
	s_add_i32 m0, s39, 0xc000
	ds_read_b128 v[188:191], v147
	ds_read_b128 v[192:195], v147 offset:1024
	ds_read_b128 v[196:199], v147 offset:2048
	ds_read_b128 v[200:203], v147 offset:3072
	ds_read_b128 v[204:207], v147 offset:4096
	ds_read_b128 v[208:211], v147 offset:5120
	ds_read_b128 v[212:215], v147 offset:6144
	ds_read_b128 v[216:219], v147 offset:7168
	global_load_lds_dwordx4 v[152:153], off
	v_lshl_add_u64 v[152:153], s[28:29], 0, v[138:139]
	s_add_i32 m0, s39, 0xe000
	s_nop 0
	global_load_lds_dwordx4 v[152:153], off
	s_waitcnt vmcnt(8)
	s_waitcnt lgkmcnt(0)
	s_barrier
	s_setprio 1
	v_mfma_f32_16x16x32_bf16 v[122:125], v[156:159], v[188:191], v[122:125]
	v_mfma_f32_16x16x32_bf16 v[126:129], v[164:167], v[188:191], v[126:129]
	v_mfma_f32_16x16x32_bf16 v[110:113], v[156:159], v[196:199], v[110:113]
	v_mfma_f32_16x16x32_bf16 v[106:109], v[164:167], v[196:199], v[106:109]
	v_mfma_f32_16x16x32_bf16 v[94:97], v[156:159], v[204:207], v[94:97]
	v_mfma_f32_16x16x32_bf16 v[90:93], v[164:167], v[204:207], v[90:93]
	v_mfma_f32_16x16x32_bf16 v[78:81], v[156:159], v[212:215], v[78:81]
	v_mfma_f32_16x16x32_bf16 v[74:77], v[164:167], v[212:215], v[74:77]
	v_mfma_f32_16x16x32_bf16 v[122:125], v[160:163], v[192:195], v[122:125]
	v_mfma_f32_16x16x32_bf16 v[126:129], v[168:171], v[192:195], v[126:129]
	v_mfma_f32_16x16x32_bf16 v[110:113], v[160:163], v[200:203], v[110:113]
	v_mfma_f32_16x16x32_bf16 v[106:109], v[168:171], v[200:203], v[106:109]
	v_mfma_f32_16x16x32_bf16 v[94:97], v[160:163], v[208:211], v[94:97]
	v_mfma_f32_16x16x32_bf16 v[90:93], v[168:171], v[208:211], v[90:93]
	v_mfma_f32_16x16x32_bf16 v[78:81], v[160:163], v[216:219], v[78:81]
	v_mfma_f32_16x16x32_bf16 v[74:77], v[168:171], v[216:219], v[74:77]
	v_mfma_f32_16x16x32_bf16 v[118:121], v[172:175], v[188:191], v[118:121]
	v_mfma_f32_16x16x32_bf16 v[114:117], v[180:183], v[188:191], v[114:117]
	v_mfma_f32_16x16x32_bf16 v[102:105], v[172:175], v[196:199], v[102:105]
	v_mfma_f32_16x16x32_bf16 v[98:101], v[180:183], v[196:199], v[98:101]
	v_mfma_f32_16x16x32_bf16 v[86:89], v[172:175], v[204:207], v[86:89]
	v_mfma_f32_16x16x32_bf16 v[82:85], v[180:183], v[204:207], v[82:85]
	v_mfma_f32_16x16x32_bf16 v[70:73], v[172:175], v[212:215], v[70:73]
	v_mfma_f32_16x16x32_bf16 v[66:69], v[180:183], v[212:215], v[66:69]
	v_mfma_f32_16x16x32_bf16 v[118:121], v[176:179], v[192:195], v[118:121]
	v_mfma_f32_16x16x32_bf16 v[114:117], v[184:187], v[192:195], v[114:117]
	v_mfma_f32_16x16x32_bf16 v[102:105], v[176:179], v[200:203], v[102:105]
	v_mfma_f32_16x16x32_bf16 v[98:101], v[184:187], v[200:203], v[98:101]
	v_mfma_f32_16x16x32_bf16 v[86:89], v[176:179], v[208:211], v[86:89]
	v_mfma_f32_16x16x32_bf16 v[82:85], v[184:187], v[208:211], v[82:85]
	v_mfma_f32_16x16x32_bf16 v[70:73], v[176:179], v[216:219], v[70:73]
	v_mfma_f32_16x16x32_bf16 v[66:69], v[184:187], v[216:219], v[66:69]
	s_setprio 0
	s_barrier
	s_add_i32 s72, s52, s38
	v_lshl_add_u64 v[152:153], s[70:71], 0, v[132:133]
	s_mov_b32 m0, s72
	ds_read_b128 v[188:191], v147 offset:16384
	ds_read_b128 v[192:195], v147 offset:17408
	ds_read_b128 v[196:199], v147 offset:18432
	ds_read_b128 v[200:203], v147 offset:19456
	ds_read_b128 v[204:207], v147 offset:20480
	ds_read_b128 v[208:211], v147 offset:21504
	ds_read_b128 v[212:215], v147 offset:22528
	ds_read_b128 v[216:219], v147 offset:23552
	global_load_lds_dwordx4 v[152:153], off
	s_add_i32 m0, s72, 0x2000
	v_lshl_add_u64 v[220:221], s[70:71], 0, v[136:137]
	s_add_u32 s70, s70, s6
	s_addc_u32 s71, s71, s7
	s_add_i32 s72, s53, s38
	global_load_lds_dwordx4 v[220:221], off
	v_lshl_add_u64 v[222:223], s[70:71], 0, v[132:133]
	s_mov_b32 m0, s72
	v_lshl_add_u64 v[224:225], s[70:71], 0, v[136:137]
	global_load_lds_dwordx4 v[222:223], off
	s_add_i32 m0, s72, 0x2000
	v_lshl_add_u64 v[226:227], s[30:31], 0, v[130:131]
	global_load_lds_dwordx4 v[224:225], off
	s_mov_b32 m0, s39
	v_lshl_add_u64 v[228:229], s[30:31], 0, v[134:135]
	global_load_lds_dwordx4 v[226:227], off
	s_mov_b32 m0, s40
	s_nop 0
	global_load_lds_dwordx4 v[228:229], off
	s_waitcnt vmcnt(8)
	s_waitcnt lgkmcnt(0)
	s_barrier
; #define PG8_STAGE(bufoff, gbase, voff) do { _Pragma("unroll") for (int _i = 0; _i < 2; ++_i) \
;         __builtin_amdgcn_global_load_lds((const unsigned*)((const char*)(gbase) + (voff)[_i]), (PG8_LAS unsigned*)(lds + (bufoff) + ldsw + _i * 8192), 16, 0, 0); } while (0)
; #define PG8_LDA(dst, b, h) do { _Pragma("unroll") for (int m = 0; m < 4; ++m) _Pragma("unroll") for (int k = 0; k < 2; ++k) dst[m][k] = *(const PG8_LAS bf16x8*)(lds + PG8_SA(b, h) + aoff + m * 2048 + k * 1024); } while (0)
; #define PG8_LDB(dst, b, h) do { _Pragma("unroll") for (int n = 0; n < 2; ++n) _Pragma("unroll") for (int k = 0; k < 2; ++k) dst[n][k] = *(const PG8_LAS bf16x8*)(lds + PG8_SB(b, h) + boff + n * 2048 + k * 1024); } while (0)
; #define PG8_MMA(ai, bj, At, Bt) do { __builtin_amdgcn_s_setprio(1); _Pragma("unroll") for (int m = 0; m < 4; ++m) _Pragma("unroll") for (int n = 0; n < 2; ++n) _Pragma("unroll") for (int k = 0; k < 2; ++k) \
;         acc[ai][bj][m][n] = __builtin_amdgcn_mfma_f32_16x16x32_bf16(Bt[n][k], At[m][k], acc[ai][bj][m][n], 0, 0, 0); __builtin_amdgcn_s_setprio(0); } while (0)
; #define PG8_WAIT_V(n) asm volatile("s_waitcnt vmcnt(" #n ")" ::: "memory")
; #define PG8_WAIT_L(n) asm volatile("s_waitcnt lgkmcnt(" #n ")" ::: "memory")
; #define PG8_BAR __builtin_amdgcn_s_barrier()
; #define PG8_SCHED __builtin_amdgcn_sched_barrier(0)
; template <class Epi, class Sched, bool ALIGN_EPI = false, bool SP2 = false>
; __device__ __forceinline__ void gemm_phase(PG8_LAS unsigned char* lds, const Gemm g, const Sched& S, const Epi& E) {
;     ...
;             PG8_WAIT_V(8); PG8_WAIT_L(0); PG8_BAR; PG8_MMA(1, 0, At, B0); PG8_MMA(1, 1, At, B1); PG8_BAR; PG8_SCHED;
;             PG8_LDB(B0, 1, 0); PG8_LDB(B1, 1, 1); PG8_SCHED; PG8_LDA(At, 1, 0); PG8_STAGE(PG8_SA(0, 1), a2 + hstep, voffA);
;             PG8_WAIT_V(8); PG8_WAIT_L(0); PG8_BAR; PG8_MMA(0, 0, At, B0); PG8_MMA(0, 1, At, B1); PG8_BAR; PG8_SCHED;
	s_setprio 1
	v_mfma_f32_16x16x32_bf16 v[62:65], v[156:159], v[188:191], v[62:65]
	v_mfma_f32_16x16x32_bf16 v[58:61], v[164:167], v[188:191], v[58:61]
	v_mfma_f32_16x16x32_bf16 v[46:49], v[156:159], v[196:199], v[46:49]
	v_mfma_f32_16x16x32_bf16 v[42:45], v[164:167], v[196:199], v[42:45]
	v_mfma_f32_16x16x32_bf16 v[30:33], v[156:159], v[204:207], v[30:33]
	v_mfma_f32_16x16x32_bf16 v[26:29], v[164:167], v[204:207], v[26:29]
	v_mfma_f32_16x16x32_bf16 v[14:17], v[156:159], v[212:215], v[14:17]
	v_mfma_f32_16x16x32_bf16 v[10:13], v[164:167], v[212:215], v[10:13]
	v_mfma_f32_16x16x32_bf16 v[62:65], v[160:163], v[192:195], v[62:65]
	v_mfma_f32_16x16x32_bf16 v[58:61], v[168:171], v[192:195], v[58:61]
	v_mfma_f32_16x16x32_bf16 v[46:49], v[160:163], v[200:203], v[46:49]
	v_mfma_f32_16x16x32_bf16 v[42:45], v[168:171], v[200:203], v[42:45]
	v_mfma_f32_16x16x32_bf16 v[30:33], v[160:163], v[208:211], v[30:33]
	v_mfma_f32_16x16x32_bf16 v[26:29], v[168:171], v[208:211], v[26:29]
	v_mfma_f32_16x16x32_bf16 v[14:17], v[160:163], v[216:219], v[14:17]
	v_mfma_f32_16x16x32_bf16 v[10:13], v[168:171], v[216:219], v[10:13]
	v_mfma_f32_16x16x32_bf16 v[54:57], v[172:175], v[188:191], v[54:57]
	v_mfma_f32_16x16x32_bf16 v[50:53], v[180:183], v[188:191], v[50:53]
	v_mfma_f32_16x16x32_bf16 v[38:41], v[172:175], v[196:199], v[38:41]
	v_mfma_f32_16x16x32_bf16 v[34:37], v[180:183], v[196:199], v[34:37]
	v_mfma_f32_16x16x32_bf16 v[22:25], v[172:175], v[204:207], v[22:25]
	v_mfma_f32_16x16x32_bf16 v[18:21], v[180:183], v[204:207], v[18:21]
	v_mfma_f32_16x16x32_bf16 v[6:9], v[172:175], v[212:215], v[6:9]
	v_mfma_f32_16x16x32_bf16 v[2:5], v[180:183], v[212:215], v[2:5]
	v_mfma_f32_16x16x32_bf16 v[54:57], v[176:179], v[192:195], v[54:57]
	v_mfma_f32_16x16x32_bf16 v[50:53], v[184:187], v[192:195], v[50:53]
	v_mfma_f32_16x16x32_bf16 v[38:41], v[176:179], v[200:203], v[38:41]
	v_mfma_f32_16x16x32_bf16 v[34:37], v[184:187], v[200:203], v[34:37]
	v_mfma_f32_16x16x32_bf16 v[22:25], v[176:179], v[208:211], v[22:25]
	v_mfma_f32_16x16x32_bf16 v[18:21], v[184:187], v[208:211], v[18:21]
	v_mfma_f32_16x16x32_bf16 v[6:9], v[176:179], v[216:219], v[6:9]
	v_mfma_f32_16x16x32_bf16 v[2:5], v[184:187], v[216:219], v[2:5]
	s_setprio 0
	s_barrier
	s_add_i32 s70, 0, 0x18000
	v_add_u32_e32 v148, s70, v150
	s_add_i32 s71, 0, 0x1c000
	ds_read_b128 v[156:159], v148
	ds_read_b128 v[160:163], v148 offset:1024
	ds_read_b128 v[164:167], v148 offset:2048
	ds_read_b128 v[168:171], v148 offset:3072
	v_add_u32_e32 v148, s71, v150
	ds_read_b128 v[172:175], v148
	ds_read_b128 v[176:179], v148 offset:1024
	ds_read_b128 v[180:183], v148 offset:2048
	ds_read_b128 v[184:187], v148 offset:3072
	s_add_u32 s30, s30, s6
	s_addc_u32 s31, s31, s7
	s_mov_b32 m0, s41
	v_lshl_add_u64 v[230:231], s[30:31], 0, v[130:131]
	ds_read_b128 v[188:191], v147 offset:32768
	ds_read_b128 v[192:195], v147 offset:33792
	ds_read_b128 v[196:199], v147 offset:34816
	ds_read_b128 v[200:203], v147 offset:35840
	ds_read_b128 v[204:207], v147 offset:36864
	ds_read_b128 v[208:211], v147 offset:37888
	ds_read_b128 v[212:215], v147 offset:38912
	ds_read_b128 v[216:219], v147 offset:39936
	global_load_lds_dwordx4 v[230:231], off
	v_lshl_add_u64 v[230:231], s[30:31], 0, v[134:135]
	s_mov_b32 m0, s42
	s_nop 0
	global_load_lds_dwordx4 v[230:231], off
	s_waitcnt vmcnt(8)
	s_waitcnt lgkmcnt(0)
	s_barrier
	s_setprio 1
	v_mfma_f32_16x16x32_bf16 v[122:125], v[156:159], v[188:191], v[122:125]
	v_mfma_f32_16x16x32_bf16 v[126:129], v[164:167], v[188:191], v[126:129]
	v_mfma_f32_16x16x32_bf16 v[110:113], v[156:159], v[196:199], v[110:113]
	v_mfma_f32_16x16x32_bf16 v[106:109], v[164:167], v[196:199], v[106:109]
	v_mfma_f32_16x16x32_bf16 v[94:97], v[156:159], v[204:207], v[94:97]
	v_mfma_f32_16x16x32_bf16 v[90:93], v[164:167], v[204:207], v[90:93]
	v_mfma_f32_16x16x32_bf16 v[78:81], v[156:159], v[212:215], v[78:81]
	v_mfma_f32_16x16x32_bf16 v[74:77], v[164:167], v[212:215], v[74:77]
	v_mfma_f32_16x16x32_bf16 v[122:125], v[160:163], v[192:195], v[122:125]
	v_mfma_f32_16x16x32_bf16 v[126:129], v[168:171], v[192:195], v[126:129]
	v_mfma_f32_16x16x32_bf16 v[110:113], v[160:163], v[200:203], v[110:113]
	v_mfma_f32_16x16x32_bf16 v[106:109], v[168:171], v[200:203], v[106:109]
	v_mfma_f32_16x16x32_bf16 v[94:97], v[160:163], v[208:211], v[94:97]
	v_mfma_f32_16x16x32_bf16 v[90:93], v[168:171], v[208:211], v[90:93]
	v_mfma_f32_16x16x32_bf16 v[78:81], v[160:163], v[216:219], v[78:81]
	v_mfma_f32_16x16x32_bf16 v[74:77], v[168:171], v[216:219], v[74:77]
	v_mfma_f32_16x16x32_bf16 v[118:121], v[172:175], v[188:191], v[118:121]
	v_mfma_f32_16x16x32_bf16 v[114:117], v[180:183], v[188:191], v[114:117]
	v_mfma_f32_16x16x32_bf16 v[102:105], v[172:175], v[196:199], v[102:105]
	v_mfma_f32_16x16x32_bf16 v[98:101], v[180:183], v[196:199], v[98:101]
	v_mfma_f32_16x16x32_bf16 v[86:89], v[172:175], v[204:207], v[86:89]
	v_mfma_f32_16x16x32_bf16 v[82:85], v[180:183], v[204:207], v[82:85]
	v_mfma_f32_16x16x32_bf16 v[70:73], v[172:175], v[212:215], v[70:73]
	v_mfma_f32_16x16x32_bf16 v[66:69], v[180:183], v[212:215], v[66:69]
	v_mfma_f32_16x16x32_bf16 v[118:121], v[176:179], v[192:195], v[118:121]
	v_mfma_f32_16x16x32_bf16 v[114:117], v[184:187], v[192:195], v[114:117]
	v_mfma_f32_16x16x32_bf16 v[102:105], v[176:179], v[200:203], v[102:105]
	v_mfma_f32_16x16x32_bf16 v[98:101], v[184:187], v[200:203], v[98:101]
	v_mfma_f32_16x16x32_bf16 v[86:89], v[176:179], v[208:211], v[86:89]
	v_mfma_f32_16x16x32_bf16 v[82:85], v[184:187], v[208:211], v[82:85]
	v_mfma_f32_16x16x32_bf16 v[70:73], v[176:179], v[216:219], v[70:73]
	v_mfma_f32_16x16x32_bf16 v[66:69], v[184:187], v[216:219], v[66:69]
	s_setprio 0
	s_barrier
; #define PG8_STAGE(bufoff, gbase, voff) do { _Pragma("unroll") for (int _i = 0; _i < 2; ++_i) \
;         __builtin_amdgcn_global_load_lds((const unsigned*)((const char*)(gbase) + (voff)[_i]), (PG8_LAS unsigned*)(lds + (bufoff) + ldsw + _i * 8192), 16, 0, 0); } while (0)
; #define PG8_LDA(dst, b, h) do { _Pragma("unroll") for (int m = 0; m < 4; ++m) _Pragma("unroll") for (int k = 0; k < 2; ++k) dst[m][k] = *(const PG8_LAS bf16x8*)(lds + PG8_SA(b, h) + aoff + m * 2048 + k * 1024); } while (0)
; #define PG8_MMA(ai, bj, At, Bt) do { __builtin_amdgcn_s_setprio(1); _Pragma("unroll") for (int m = 0; m < 4; ++m) _Pragma("unroll") for (int n = 0; n < 2; ++n) _Pragma("unroll") for (int k = 0; k < 2; ++k) \
;         acc[ai][bj][m][n] = __builtin_amdgcn_mfma_f32_16x16x32_bf16(Bt[n][k], At[m][k], acc[ai][bj][m][n], 0, 0, 0); __builtin_amdgcn_s_setprio(0); } while (0)
; #define PG8_WAIT_V(n) asm volatile("s_waitcnt vmcnt(" #n ")" ::: "memory")
; #define PG8_WAIT_L(n) asm volatile("s_waitcnt lgkmcnt(" #n ")" ::: "memory")
; #define PG8_BAR __builtin_amdgcn_s_barrier()
; #define PG8_SCHED __builtin_amdgcn_sched_barrier(0)
; template <class Epi, class Sched, bool ALIGN_EPI = false, bool SP2 = false>
; __device__ __forceinline__ void gemm_phase(PG8_LAS unsigned char* lds, const Gemm g, const Sched& S, const Epi& E) {
;     ...
;         for (int t = 0; t < nt; t += 2) {
;             const bool last = (t == nt - 2);
;             const char* a1 = cA + (size_t)(t + 1) * kstep;
;             const char* a2 = last ? nA : cA + (size_t)(t + 2) * kstep; const char* b2 = last ? nB : cB + (size_t)(t + 2) * kstep;
;             const char* a3 = a2 + kstep; const char* b3 = b2 + kstep;
;     ...
;             PG8_LDA(At, 1, 1); PG8_STAGE(PG8_SB(1, 0), b3, voffB); PG8_STAGE(PG8_SB(1, 1), b3 + hstep, voffB); PG8_STAGE(PG8_SA(1, 0), a3, voffA);
;             PG8_WAIT_V(8); PG8_WAIT_L(0); PG8_BAR; PG8_MMA(1, 0, At, B0); PG8_MMA(1, 1, At, B1); PG8_BAR; PG8_SCHED;
	s_add_i32 s30, s70, s38
	v_lshl_add_u64 v[152:153], v[152:153], 0, s[20:21]
	s_mov_b32 m0, s30
	ds_read_b128 v[188:191], v147 offset:49152
	ds_read_b128 v[192:195], v147 offset:50176
	ds_read_b128 v[196:199], v147 offset:51200
	ds_read_b128 v[200:203], v147 offset:52224
	ds_read_b128 v[204:207], v147 offset:53248
	ds_read_b128 v[208:211], v147 offset:54272
	ds_read_b128 v[212:215], v147 offset:55296
	ds_read_b128 v[216:219], v147 offset:56320
	global_load_lds_dwordx4 v[152:153], off
	v_lshl_add_u64 v[152:153], v[220:221], 0, s[20:21]
	s_add_i32 m0, s30, 0x2000
	s_add_i32 s30, s71, s38
	global_load_lds_dwordx4 v[152:153], off
	v_lshl_add_u64 v[152:153], v[222:223], 0, s[20:21]
	s_mov_b32 m0, s30
	s_nop 0
	global_load_lds_dwordx4 v[152:153], off
	v_lshl_add_u64 v[152:153], v[224:225], 0, s[20:21]
	s_add_i32 m0, s30, 0x2000
	s_nop 0
	global_load_lds_dwordx4 v[152:153], off
	v_lshl_add_u64 v[152:153], v[226:227], 0, s[20:21]
	s_mov_b32 m0, s44
	s_nop 0
	global_load_lds_dwordx4 v[152:153], off
	v_lshl_add_u64 v[152:153], v[228:229], 0, s[20:21]
	s_mov_b32 m0, s45
	s_nop 0
	global_load_lds_dwordx4 v[152:153], off
	s_waitcnt vmcnt(8)
	s_waitcnt lgkmcnt(0)
	s_barrier
	s_setprio 1
	v_mfma_f32_16x16x32_bf16 v[62:65], v[156:159], v[188:191], v[62:65]
	v_mfma_f32_16x16x32_bf16 v[58:61], v[164:167], v[188:191], v[58:61]
	v_mfma_f32_16x16x32_bf16 v[46:49], v[156:159], v[196:199], v[46:49]
	v_mfma_f32_16x16x32_bf16 v[42:45], v[164:167], v[196:199], v[42:45]
	v_mfma_f32_16x16x32_bf16 v[30:33], v[156:159], v[204:207], v[30:33]
	v_mfma_f32_16x16x32_bf16 v[26:29], v[164:167], v[204:207], v[26:29]
	v_mfma_f32_16x16x32_bf16 v[14:17], v[156:159], v[212:215], v[14:17]
	v_mfma_f32_16x16x32_bf16 v[10:13], v[164:167], v[212:215], v[10:13]
	v_mfma_f32_16x16x32_bf16 v[62:65], v[160:163], v[192:195], v[62:65]
	v_mfma_f32_16x16x32_bf16 v[58:61], v[168:171], v[192:195], v[58:61]
	v_mfma_f32_16x16x32_bf16 v[46:49], v[160:163], v[200:203], v[46:49]
	v_mfma_f32_16x16x32_bf16 v[42:45], v[168:171], v[200:203], v[42:45]
	v_mfma_f32_16x16x32_bf16 v[30:33], v[160:163], v[208:211], v[30:33]
	v_mfma_f32_16x16x32_bf16 v[26:29], v[168:171], v[208:211], v[26:29]
	v_mfma_f32_16x16x32_bf16 v[14:17], v[160:163], v[216:219], v[14:17]
	v_mfma_f32_16x16x32_bf16 v[10:13], v[168:171], v[216:219], v[10:13]
	v_mfma_f32_16x16x32_bf16 v[54:57], v[172:175], v[188:191], v[54:57]
	v_mfma_f32_16x16x32_bf16 v[50:53], v[180:183], v[188:191], v[50:53]
	v_mfma_f32_16x16x32_bf16 v[38:41], v[172:175], v[196:199], v[38:41]
	v_mfma_f32_16x16x32_bf16 v[34:37], v[180:183], v[196:199], v[34:37]
	v_mfma_f32_16x16x32_bf16 v[22:25], v[172:175], v[204:207], v[22:25]
	v_mfma_f32_16x16x32_bf16 v[18:21], v[180:183], v[204:207], v[18:21]
	v_mfma_f32_16x16x32_bf16 v[6:9], v[172:175], v[212:215], v[6:9]
	v_mfma_f32_16x16x32_bf16 v[2:5], v[180:183], v[212:215], v[2:5]
	v_mfma_f32_16x16x32_bf16 v[54:57], v[176:179], v[192:195], v[54:57]
	v_mfma_f32_16x16x32_bf16 v[50:53], v[184:187], v[192:195], v[50:53]
	v_mfma_f32_16x16x32_bf16 v[38:41], v[176:179], v[200:203], v[38:41]
	v_mfma_f32_16x16x32_bf16 v[34:37], v[184:187], v[200:203], v[34:37]
	v_mfma_f32_16x16x32_bf16 v[22:25], v[176:179], v[208:211], v[22:25]
	v_mfma_f32_16x16x32_bf16 v[18:21], v[184:187], v[208:211], v[18:21]
	v_mfma_f32_16x16x32_bf16 v[6:9], v[176:179], v[216:219], v[6:9]
	v_mfma_f32_16x16x32_bf16 v[2:5], v[184:187], v[216:219], v[2:5]
	s_setprio 0
	s_add_u32 s68, s68, 0x100
	s_addc_u32 s69, s69, 0
	s_add_u32 s28, s28, 0x100
	s_addc_u32 s29, s29, 0
	s_cmp_ge_i32 s80, s46
	s_mov_b32 s30, s80
	s_barrier
	s_cbranch_scc0 .LBB0_1433

; #define PG8_STAGE(bufoff, gbase, voff) do { _Pragma("unroll") for (int _i = 0; _i < 2; ++_i) \
;         __builtin_amdgcn_global_load_lds((const unsigned*)((const char*)(gbase) + (voff)[_i]), (PG8_LAS unsigned*)(lds + (bufoff) + ldsw + _i * 8192), 16, 0, 0); } while (0)
; #define PG8_LDA(dst, b, h) do { _Pragma("unroll") for (int m = 0; m < 4; ++m) _Pragma("unroll") for (int k = 0; k < 2; ++k) dst[m][k] = *(const PG8_LAS bf16x8*)(lds + PG8_SA(b, h) + aoff + m * 2048 + k * 1024); } while (0)
; #define PG8_LDB(dst, b, h) do { _Pragma("unroll") for (int n = 0; n < 2; ++n) _Pragma("unroll") for (int k = 0; k < 2; ++k) dst[n][k] = *(const PG8_LAS bf16x8*)(lds + PG8_SB(b, h) + boff + n * 2048 + k * 1024); } while (0)
; #define PG8_MMA(ai, bj, At, Bt) do { __builtin_amdgcn_s_setprio(1); _Pragma("unroll") for (int m = 0; m < 4; ++m) _Pragma("unroll") for (int n = 0; n < 2; ++n) _Pragma("unroll") for (int k = 0; k < 2; ++k) \
;         acc[ai][bj][m][n] = __builtin_amdgcn_mfma_f32_16x16x32_bf16(Bt[n][k], At[m][k], acc[ai][bj][m][n], 0, 0, 0); __builtin_amdgcn_s_setprio(0); } while (0)
; #define PG8_WAIT_V(n) asm volatile("s_waitcnt vmcnt(" #n ")" ::: "memory")
; #define PG8_WAIT_L(n) asm volatile("s_waitcnt lgkmcnt(" #n ")" ::: "memory")
; template <class Epi, class Sched, bool ALIGN_EPI = false, bool SP2 = false>
; __device__ __forceinline__ void gemm_phase(PG8_LAS unsigned char* lds, const Gemm g, const Sched& S, const Epi& E) {
;     ...
;             const bool last = (t == nt - 2);
;             const char* a1 = cA + (size_t)(t + 1) * kstep;
;             const char* a2 = last ? nA : cA + (size_t)(t + 2) * kstep; const char* b2 = last ? nB : cB + (size_t)(t + 2) * kstep;
;             const char* a3 = a2 + kstep; const char* b3 = b2 + kstep;
;             if (last && has_next) S.a_ready(nxt);
;             if constexpr (SP2) {
;             PG8_LDB(B0, 0, 0); PG8_LDB(B1, 0, 1); PG8_SCHED; PG8_LDA(At, 0, 0); PG8_STAGE(PG8_SA(1, 1), a1 + hstep, voffA);
;             PG8_WAIT_V(8); PG8_WAIT_L(0); PG8_BAR; PG8_MMA(0, 0, At, B0); PG8_MMA(0, 1, At, B1); PG8_BAR; PG8_SCHED;
;             PG8_LDA(At, 0, 1); PG8_STAGE(PG8_SB(0, 0), b2, voffB); PG8_STAGE(PG8_SB(0, 1), b2 + hstep, voffB); PG8_STAGE(PG8_SA(0, 0), a2, voffA);
;             PG8_WAIT_V(8); PG8_WAIT_L(0); PG8_BAR; PG8_MMA(1, 0, At, B0); PG8_MMA(1, 1, At, B1); PG8_BAR; PG8_SCHED;
.LBB0_1518:
	ds_read_b128 v[146:149], v168
	ds_read_b128 v[172:175], v168 offset:1024
	ds_read_b128 v[176:179], v168 offset:2048
	ds_read_b128 v[180:183], v168 offset:3072
	ds_read_b128 v[184:187], v169
	ds_read_b128 v[188:191], v169 offset:1024
	ds_read_b128 v[192:195], v169 offset:2048
	ds_read_b128 v[196:199], v169 offset:3072
	s_add_i32 s88, s38, 2
	s_add_u32 s70, s36, 0x80
	s_addc_u32 s39, s37, 0
	s_cmp_eq_u32 s53, s38
	s_cselect_b32 s38, s4, s70
	s_cselect_b32 s39, s5, s39
	s_cselect_b32 s71, s35, s87
	s_cselect_b32 s70, s34, s86
	v_lshl_add_u64 v[150:151], s[36:37], 0, v[140:141]
	s_add_i32 m0, s43, 0xc000
	ds_read_b128 v[200:203], v170
	ds_read_b128 v[204:207], v170 offset:1024
	ds_read_b128 v[208:211], v170 offset:2048
	ds_read_b128 v[212:215], v170 offset:3072
	ds_read_b128 v[216:219], v170 offset:4096
	ds_read_b128 v[220:223], v170 offset:5120
	ds_read_b128 v[224:227], v170 offset:6144
	ds_read_b128 v[228:231], v170 offset:7168
	global_load_lds_dwordx4 v[150:151], off
	v_lshl_add_u64 v[150:151], s[36:37], 0, v[138:139]
	s_add_i32 m0, s43, 0xe000
	s_nop 0
	global_load_lds_dwordx4 v[150:151], off
	s_waitcnt vmcnt(8)
	s_waitcnt lgkmcnt(0)
	s_barrier
	s_setprio 1
	v_mfma_f32_16x16x32_bf16 v[122:125], v[146:149], v[200:203], v[122:125]
	v_mfma_f32_16x16x32_bf16 v[126:129], v[176:179], v[200:203], v[126:129]
	v_mfma_f32_16x16x32_bf16 v[110:113], v[146:149], v[208:211], v[110:113]
	v_mfma_f32_16x16x32_bf16 v[106:109], v[176:179], v[208:211], v[106:109]
	v_mfma_f32_16x16x32_bf16 v[94:97], v[146:149], v[216:219], v[94:97]
	v_mfma_f32_16x16x32_bf16 v[90:93], v[176:179], v[216:219], v[90:93]
	v_mfma_f32_16x16x32_bf16 v[78:81], v[146:149], v[224:227], v[78:81]
	v_mfma_f32_16x16x32_bf16 v[74:77], v[176:179], v[224:227], v[74:77]
	v_mfma_f32_16x16x32_bf16 v[122:125], v[172:175], v[204:207], v[122:125]
	v_mfma_f32_16x16x32_bf16 v[126:129], v[180:183], v[204:207], v[126:129]
	v_mfma_f32_16x16x32_bf16 v[110:113], v[172:175], v[212:215], v[110:113]
	v_mfma_f32_16x16x32_bf16 v[106:109], v[180:183], v[212:215], v[106:109]
	v_mfma_f32_16x16x32_bf16 v[94:97], v[172:175], v[220:223], v[94:97]
	v_mfma_f32_16x16x32_bf16 v[90:93], v[180:183], v[220:223], v[90:93]
	v_mfma_f32_16x16x32_bf16 v[78:81], v[172:175], v[228:231], v[78:81]
	v_mfma_f32_16x16x32_bf16 v[74:77], v[180:183], v[228:231], v[74:77]
	v_mfma_f32_16x16x32_bf16 v[118:121], v[184:187], v[200:203], v[118:121]
	v_mfma_f32_16x16x32_bf16 v[114:117], v[192:195], v[200:203], v[114:117]
	v_mfma_f32_16x16x32_bf16 v[102:105], v[184:187], v[208:211], v[102:105]
	v_mfma_f32_16x16x32_bf16 v[98:101], v[192:195], v[208:211], v[98:101]
	v_mfma_f32_16x16x32_bf16 v[86:89], v[184:187], v[216:219], v[86:89]
	v_mfma_f32_16x16x32_bf16 v[82:85], v[192:195], v[216:219], v[82:85]
	v_mfma_f32_16x16x32_bf16 v[70:73], v[184:187], v[224:227], v[70:73]
	v_mfma_f32_16x16x32_bf16 v[66:69], v[192:195], v[224:227], v[66:69]
	v_mfma_f32_16x16x32_bf16 v[118:121], v[188:191], v[204:207], v[118:121]
	v_mfma_f32_16x16x32_bf16 v[114:117], v[196:199], v[204:207], v[114:117]
	v_mfma_f32_16x16x32_bf16 v[102:105], v[188:191], v[212:215], v[102:105]
	v_mfma_f32_16x16x32_bf16 v[98:101], v[196:199], v[212:215], v[98:101]
	v_mfma_f32_16x16x32_bf16 v[86:89], v[188:191], v[220:223], v[86:89]
	v_mfma_f32_16x16x32_bf16 v[82:85], v[196:199], v[220:223], v[82:85]
	v_mfma_f32_16x16x32_bf16 v[70:73], v[188:191], v[228:231], v[70:73]
	v_mfma_f32_16x16x32_bf16 v[66:69], v[196:199], v[228:231], v[66:69]
	s_setprio 0
	s_barrier
	s_add_i32 s72, s56, s42
	v_lshl_add_u64 v[150:151], s[70:71], 0, v[132:133]
	s_mov_b32 m0, s72
	ds_read_b128 v[200:203], v170 offset:16384
	ds_read_b128 v[204:207], v170 offset:17408
	ds_read_b128 v[208:211], v170 offset:18432
	ds_read_b128 v[212:215], v170 offset:19456
	ds_read_b128 v[216:219], v170 offset:20480
	ds_read_b128 v[220:223], v170 offset:21504
	ds_read_b128 v[224:227], v170 offset:22528
	ds_read_b128 v[228:231], v170 offset:23552
	global_load_lds_dwordx4 v[150:151], off
	s_add_i32 m0, s72, 0x2000
	v_lshl_add_u64 v[232:233], s[70:71], 0, v[136:137]
	s_add_u32 s70, s70, s14
	s_addc_u32 s71, s71, s15
	s_add_i32 s72, s57, s42
	global_load_lds_dwordx4 v[232:233], off
	v_lshl_add_u64 v[234:235], s[70:71], 0, v[132:133]
	s_mov_b32 m0, s72
	v_lshl_add_u64 v[236:237], s[70:71], 0, v[136:137]
	global_load_lds_dwordx4 v[234:235], off
	s_add_i32 m0, s72, 0x2000
	v_lshl_add_u64 v[238:239], s[38:39], 0, v[130:131]
	global_load_lds_dwordx4 v[236:237], off
	s_mov_b32 m0, s43
	v_lshl_add_u64 v[240:241], s[38:39], 0, v[134:135]
	global_load_lds_dwordx4 v[238:239], off
	s_mov_b32 m0, s44
	s_nop 0
	global_load_lds_dwordx4 v[240:241], off
	s_waitcnt vmcnt(8)
	s_waitcnt lgkmcnt(0)
	s_barrier
; #define PG8_STAGE(bufoff, gbase, voff) do { _Pragma("unroll") for (int _i = 0; _i < 2; ++_i) \
;         __builtin_amdgcn_global_load_lds((const unsigned*)((const char*)(gbase) + (voff)[_i]), (PG8_LAS unsigned*)(lds + (bufoff) + ldsw + _i * 8192), 16, 0, 0); } while (0)
; #define PG8_LDA(dst, b, h) do { _Pragma("unroll") for (int m = 0; m < 4; ++m) _Pragma("unroll") for (int k = 0; k < 2; ++k) dst[m][k] = *(const PG8_LAS bf16x8*)(lds + PG8_SA(b, h) + aoff + m * 2048 + k * 1024); } while (0)
; #define PG8_LDB(dst, b, h) do { _Pragma("unroll") for (int n = 0; n < 2; ++n) _Pragma("unroll") for (int k = 0; k < 2; ++k) dst[n][k] = *(const PG8_LAS bf16x8*)(lds + PG8_SB(b, h) + boff + n * 2048 + k * 1024); } while (0)
; #define PG8_MMA(ai, bj, At, Bt) do { __builtin_amdgcn_s_setprio(1); _Pragma("unroll") for (int m = 0; m < 4; ++m) _Pragma("unroll") for (int n = 0; n < 2; ++n) _Pragma("unroll") for (int k = 0; k < 2; ++k) \
;         acc[ai][bj][m][n] = __builtin_amdgcn_mfma_f32_16x16x32_bf16(Bt[n][k], At[m][k], acc[ai][bj][m][n], 0, 0, 0); __builtin_amdgcn_s_setprio(0); } while (0)
; #define PG8_WAIT_V(n) asm volatile("s_waitcnt vmcnt(" #n ")" ::: "memory")
; #define PG8_WAIT_L(n) asm volatile("s_waitcnt lgkmcnt(" #n ")" ::: "memory")
; #define PG8_BAR __builtin_amdgcn_s_barrier()
; #define PG8_SCHED __builtin_amdgcn_sched_barrier(0)
; template <class Epi, class Sched, bool ALIGN_EPI = false, bool SP2 = false>
; __device__ __forceinline__ void gemm_phase(PG8_LAS unsigned char* lds, const Gemm g, const Sched& S, const Epi& E) {
;     ...
;             PG8_WAIT_V(8); PG8_WAIT_L(0); PG8_BAR; PG8_MMA(1, 0, At, B0); PG8_MMA(1, 1, At, B1); PG8_BAR; PG8_SCHED;
;             PG8_LDB(B0, 1, 0); PG8_LDB(B1, 1, 1); PG8_SCHED; PG8_LDA(At, 1, 0); PG8_STAGE(PG8_SA(0, 1), a2 + hstep, voffA);
;             PG8_WAIT_V(8); PG8_WAIT_L(0); PG8_BAR; PG8_MMA(0, 0, At, B0); PG8_MMA(0, 1, At, B1); PG8_BAR; PG8_SCHED;
	s_setprio 1
	v_mfma_f32_16x16x32_bf16 v[62:65], v[146:149], v[200:203], v[62:65]
	v_mfma_f32_16x16x32_bf16 v[58:61], v[176:179], v[200:203], v[58:61]
	v_mfma_f32_16x16x32_bf16 v[46:49], v[146:149], v[208:211], v[46:49]
	v_mfma_f32_16x16x32_bf16 v[42:45], v[176:179], v[208:211], v[42:45]
	v_mfma_f32_16x16x32_bf16 v[30:33], v[146:149], v[216:219], v[30:33]
	v_mfma_f32_16x16x32_bf16 v[26:29], v[176:179], v[216:219], v[26:29]
	v_mfma_f32_16x16x32_bf16 v[14:17], v[146:149], v[224:227], v[14:17]
	v_mfma_f32_16x16x32_bf16 v[10:13], v[176:179], v[224:227], v[10:13]
	v_mfma_f32_16x16x32_bf16 v[62:65], v[172:175], v[204:207], v[62:65]
	v_mfma_f32_16x16x32_bf16 v[58:61], v[180:183], v[204:207], v[58:61]
	v_mfma_f32_16x16x32_bf16 v[46:49], v[172:175], v[212:215], v[46:49]
	v_mfma_f32_16x16x32_bf16 v[42:45], v[180:183], v[212:215], v[42:45]
	v_mfma_f32_16x16x32_bf16 v[30:33], v[172:175], v[220:223], v[30:33]
	v_mfma_f32_16x16x32_bf16 v[26:29], v[180:183], v[220:223], v[26:29]
	v_mfma_f32_16x16x32_bf16 v[14:17], v[172:175], v[228:231], v[14:17]
	v_mfma_f32_16x16x32_bf16 v[10:13], v[180:183], v[228:231], v[10:13]
	v_mfma_f32_16x16x32_bf16 v[54:57], v[184:187], v[200:203], v[54:57]
	v_mfma_f32_16x16x32_bf16 v[50:53], v[192:195], v[200:203], v[50:53]
	v_mfma_f32_16x16x32_bf16 v[38:41], v[184:187], v[208:211], v[38:41]
	v_mfma_f32_16x16x32_bf16 v[34:37], v[192:195], v[208:211], v[34:37]
	v_mfma_f32_16x16x32_bf16 v[22:25], v[184:187], v[216:219], v[22:25]
	v_mfma_f32_16x16x32_bf16 v[18:21], v[192:195], v[216:219], v[18:21]
	v_mfma_f32_16x16x32_bf16 v[6:9], v[184:187], v[224:227], v[6:9]
	v_mfma_f32_16x16x32_bf16 v[2:5], v[192:195], v[224:227], v[2:5]
	v_mfma_f32_16x16x32_bf16 v[54:57], v[188:191], v[204:207], v[54:57]
	v_mfma_f32_16x16x32_bf16 v[50:53], v[196:199], v[204:207], v[50:53]
	v_mfma_f32_16x16x32_bf16 v[38:41], v[188:191], v[212:215], v[38:41]
	v_mfma_f32_16x16x32_bf16 v[34:37], v[196:199], v[212:215], v[34:37]
	v_mfma_f32_16x16x32_bf16 v[22:25], v[188:191], v[220:223], v[22:25]
	v_mfma_f32_16x16x32_bf16 v[18:21], v[196:199], v[220:223], v[18:21]
	v_mfma_f32_16x16x32_bf16 v[6:9], v[188:191], v[228:231], v[6:9]
	v_mfma_f32_16x16x32_bf16 v[2:5], v[196:199], v[228:231], v[2:5]
	s_setprio 0
	s_barrier
	s_add_i32 s70, 0, 0x18000
	v_add_u32_e32 v171, s70, v166
	s_add_i32 s71, 0, 0x1c000
	ds_read_b128 v[146:149], v171
	ds_read_b128 v[172:175], v171 offset:1024
	ds_read_b128 v[176:179], v171 offset:2048
	ds_read_b128 v[180:183], v171 offset:3072
	v_add_u32_e32 v171, s71, v166
	ds_read_b128 v[184:187], v171
	ds_read_b128 v[188:191], v171 offset:1024
	ds_read_b128 v[192:195], v171 offset:2048
	ds_read_b128 v[196:199], v171 offset:3072
	s_add_u32 s38, s38, s14
	s_addc_u32 s39, s39, s15
	s_mov_b32 m0, s45
	v_lshl_add_u64 v[242:243], s[38:39], 0, v[130:131]
	ds_read_b128 v[200:203], v170 offset:32768
	ds_read_b128 v[204:207], v170 offset:33792
	ds_read_b128 v[208:211], v170 offset:34816
	ds_read_b128 v[212:215], v170 offset:35840
	ds_read_b128 v[216:219], v170 offset:36864
	ds_read_b128 v[220:223], v170 offset:37888
	ds_read_b128 v[224:227], v170 offset:38912
	ds_read_b128 v[228:231], v170 offset:39936
	global_load_lds_dwordx4 v[242:243], off
	v_lshl_add_u64 v[242:243], s[38:39], 0, v[134:135]
	s_mov_b32 m0, s46
	s_nop 0
	global_load_lds_dwordx4 v[242:243], off
	s_waitcnt vmcnt(8)
	s_waitcnt lgkmcnt(0)
	s_barrier
	s_setprio 1
	v_mfma_f32_16x16x32_bf16 v[122:125], v[146:149], v[200:203], v[122:125]
	v_mfma_f32_16x16x32_bf16 v[126:129], v[176:179], v[200:203], v[126:129]
	v_mfma_f32_16x16x32_bf16 v[110:113], v[146:149], v[208:211], v[110:113]
	v_mfma_f32_16x16x32_bf16 v[106:109], v[176:179], v[208:211], v[106:109]
	v_mfma_f32_16x16x32_bf16 v[94:97], v[146:149], v[216:219], v[94:97]
	v_mfma_f32_16x16x32_bf16 v[90:93], v[176:179], v[216:219], v[90:93]
	v_mfma_f32_16x16x32_bf16 v[78:81], v[146:149], v[224:227], v[78:81]
	v_mfma_f32_16x16x32_bf16 v[74:77], v[176:179], v[224:227], v[74:77]
	v_mfma_f32_16x16x32_bf16 v[122:125], v[172:175], v[204:207], v[122:125]
	v_mfma_f32_16x16x32_bf16 v[126:129], v[180:183], v[204:207], v[126:129]
	v_mfma_f32_16x16x32_bf16 v[110:113], v[172:175], v[212:215], v[110:113]
	v_mfma_f32_16x16x32_bf16 v[106:109], v[180:183], v[212:215], v[106:109]
	v_mfma_f32_16x16x32_bf16 v[94:97], v[172:175], v[220:223], v[94:97]
	v_mfma_f32_16x16x32_bf16 v[90:93], v[180:183], v[220:223], v[90:93]
	v_mfma_f32_16x16x32_bf16 v[78:81], v[172:175], v[228:231], v[78:81]
	v_mfma_f32_16x16x32_bf16 v[74:77], v[180:183], v[228:231], v[74:77]
	v_mfma_f32_16x16x32_bf16 v[118:121], v[184:187], v[200:203], v[118:121]
	v_mfma_f32_16x16x32_bf16 v[114:117], v[192:195], v[200:203], v[114:117]
	v_mfma_f32_16x16x32_bf16 v[102:105], v[184:187], v[208:211], v[102:105]
	v_mfma_f32_16x16x32_bf16 v[98:101], v[192:195], v[208:211], v[98:101]
	v_mfma_f32_16x16x32_bf16 v[86:89], v[184:187], v[216:219], v[86:89]
	v_mfma_f32_16x16x32_bf16 v[82:85], v[192:195], v[216:219], v[82:85]
	v_mfma_f32_16x16x32_bf16 v[70:73], v[184:187], v[224:227], v[70:73]
	v_mfma_f32_16x16x32_bf16 v[66:69], v[192:195], v[224:227], v[66:69]
	v_mfma_f32_16x16x32_bf16 v[118:121], v[188:191], v[204:207], v[118:121]
	v_mfma_f32_16x16x32_bf16 v[114:117], v[196:199], v[204:207], v[114:117]
	v_mfma_f32_16x16x32_bf16 v[102:105], v[188:191], v[212:215], v[102:105]
	v_mfma_f32_16x16x32_bf16 v[98:101], v[196:199], v[212:215], v[98:101]
	v_mfma_f32_16x16x32_bf16 v[86:89], v[188:191], v[220:223], v[86:89]
	v_mfma_f32_16x16x32_bf16 v[82:85], v[196:199], v[220:223], v[82:85]
	v_mfma_f32_16x16x32_bf16 v[70:73], v[188:191], v[228:231], v[70:73]
	v_mfma_f32_16x16x32_bf16 v[66:69], v[196:199], v[228:231], v[66:69]
	s_setprio 0
	s_barrier
; #define PG8_STAGE(bufoff, gbase, voff) do { _Pragma("unroll") for (int _i = 0; _i < 2; ++_i) \
;         __builtin_amdgcn_global_load_lds((const unsigned*)((const char*)(gbase) + (voff)[_i]), (PG8_LAS unsigned*)(lds + (bufoff) + ldsw + _i * 8192), 16, 0, 0); } while (0)
; #define PG8_LDA(dst, b, h) do { _Pragma("unroll") for (int m = 0; m < 4; ++m) _Pragma("unroll") for (int k = 0; k < 2; ++k) dst[m][k] = *(const PG8_LAS bf16x8*)(lds + PG8_SA(b, h) + aoff + m * 2048 + k * 1024); } while (0)
; #define PG8_MMA(ai, bj, At, Bt) do { __builtin_amdgcn_s_setprio(1); _Pragma("unroll") for (int m = 0; m < 4; ++m) _Pragma("unroll") for (int n = 0; n < 2; ++n) _Pragma("unroll") for (int k = 0; k < 2; ++k) \
;         acc[ai][bj][m][n] = __builtin_amdgcn_mfma_f32_16x16x32_bf16(Bt[n][k], At[m][k], acc[ai][bj][m][n], 0, 0, 0); __builtin_amdgcn_s_setprio(0); } while (0)
; #define PG8_WAIT_V(n) asm volatile("s_waitcnt vmcnt(" #n ")" ::: "memory")
; #define PG8_WAIT_L(n) asm volatile("s_waitcnt lgkmcnt(" #n ")" ::: "memory")
; #define PG8_BAR __builtin_amdgcn_s_barrier()
; #define PG8_SCHED __builtin_amdgcn_sched_barrier(0)
; template <class Epi, class Sched, bool ALIGN_EPI = false, bool SP2 = false>
; __device__ __forceinline__ void gemm_phase(PG8_LAS unsigned char* lds, const Gemm g, const Sched& S, const Epi& E) {
;     ...
;         for (int t = 0; t < nt; t += 2) {
;             const bool last = (t == nt - 2);
;             const char* a1 = cA + (size_t)(t + 1) * kstep;
;             const char* a2 = last ? nA : cA + (size_t)(t + 2) * kstep; const char* b2 = last ? nB : cB + (size_t)(t + 2) * kstep;
;             const char* a3 = a2 + kstep; const char* b3 = b2 + kstep;
;     ...
;             PG8_LDA(At, 1, 1); PG8_STAGE(PG8_SB(1, 0), b3, voffB); PG8_STAGE(PG8_SB(1, 1), b3 + hstep, voffB); PG8_STAGE(PG8_SA(1, 0), a3, voffA);
;             PG8_WAIT_V(8); PG8_WAIT_L(0); PG8_BAR; PG8_MMA(1, 0, At, B0); PG8_MMA(1, 1, At, B1); PG8_BAR; PG8_SCHED;
	s_add_i32 s38, s70, s42
	v_lshl_add_u64 v[150:151], v[150:151], 0, s[24:25]
	s_mov_b32 m0, s38
	ds_read_b128 v[200:203], v170 offset:49152
	ds_read_b128 v[204:207], v170 offset:50176
	ds_read_b128 v[208:211], v170 offset:51200
	ds_read_b128 v[212:215], v170 offset:52224
	ds_read_b128 v[216:219], v170 offset:53248
	ds_read_b128 v[220:223], v170 offset:54272
	ds_read_b128 v[224:227], v170 offset:55296
	ds_read_b128 v[228:231], v170 offset:56320
	global_load_lds_dwordx4 v[150:151], off
	v_lshl_add_u64 v[150:151], v[232:233], 0, s[24:25]
	s_add_i32 m0, s38, 0x2000
	s_add_i32 s38, s71, s42
	global_load_lds_dwordx4 v[150:151], off
	v_lshl_add_u64 v[150:151], v[234:235], 0, s[24:25]
	s_mov_b32 m0, s38
	s_nop 0
	global_load_lds_dwordx4 v[150:151], off
	v_lshl_add_u64 v[150:151], v[236:237], 0, s[24:25]
	s_add_i32 m0, s38, 0x2000
	s_nop 0
	global_load_lds_dwordx4 v[150:151], off
	v_lshl_add_u64 v[150:151], v[238:239], 0, s[24:25]
	s_mov_b32 m0, s48
	s_nop 0
	global_load_lds_dwordx4 v[150:151], off
	v_lshl_add_u64 v[150:151], v[240:241], 0, s[24:25]
	s_mov_b32 m0, s49
	s_nop 0
	global_load_lds_dwordx4 v[150:151], off
	s_waitcnt vmcnt(8)
	s_waitcnt lgkmcnt(0)
	s_barrier
	s_setprio 1
	v_mfma_f32_16x16x32_bf16 v[62:65], v[146:149], v[200:203], v[62:65]
	v_mfma_f32_16x16x32_bf16 v[58:61], v[176:179], v[200:203], v[58:61]
	v_mfma_f32_16x16x32_bf16 v[46:49], v[146:149], v[208:211], v[46:49]
	v_mfma_f32_16x16x32_bf16 v[42:45], v[176:179], v[208:211], v[42:45]
	v_mfma_f32_16x16x32_bf16 v[30:33], v[146:149], v[216:219], v[30:33]
	v_mfma_f32_16x16x32_bf16 v[26:29], v[176:179], v[216:219], v[26:29]
	v_mfma_f32_16x16x32_bf16 v[14:17], v[146:149], v[224:227], v[14:17]
	v_mfma_f32_16x16x32_bf16 v[10:13], v[176:179], v[224:227], v[10:13]
	v_mfma_f32_16x16x32_bf16 v[62:65], v[172:175], v[204:207], v[62:65]
	v_mfma_f32_16x16x32_bf16 v[58:61], v[180:183], v[204:207], v[58:61]
	v_mfma_f32_16x16x32_bf16 v[46:49], v[172:175], v[212:215], v[46:49]
	v_mfma_f32_16x16x32_bf16 v[42:45], v[180:183], v[212:215], v[42:45]
	v_mfma_f32_16x16x32_bf16 v[30:33], v[172:175], v[220:223], v[30:33]
	v_mfma_f32_16x16x32_bf16 v[26:29], v[180:183], v[220:223], v[26:29]
	v_mfma_f32_16x16x32_bf16 v[14:17], v[172:175], v[228:231], v[14:17]
	v_mfma_f32_16x16x32_bf16 v[10:13], v[180:183], v[228:231], v[10:13]
	v_mfma_f32_16x16x32_bf16 v[54:57], v[184:187], v[200:203], v[54:57]
	v_mfma_f32_16x16x32_bf16 v[50:53], v[192:195], v[200:203], v[50:53]
	v_mfma_f32_16x16x32_bf16 v[38:41], v[184:187], v[208:211], v[38:41]
	v_mfma_f32_16x16x32_bf16 v[34:37], v[192:195], v[208:211], v[34:37]
	v_mfma_f32_16x16x32_bf16 v[22:25], v[184:187], v[216:219], v[22:25]
	v_mfma_f32_16x16x32_bf16 v[18:21], v[192:195], v[216:219], v[18:21]
	v_mfma_f32_16x16x32_bf16 v[6:9], v[184:187], v[224:227], v[6:9]
	v_mfma_f32_16x16x32_bf16 v[2:5], v[192:195], v[224:227], v[2:5]
	v_mfma_f32_16x16x32_bf16 v[54:57], v[188:191], v[204:207], v[54:57]
	v_mfma_f32_16x16x32_bf16 v[50:53], v[196:199], v[204:207], v[50:53]
	v_mfma_f32_16x16x32_bf16 v[38:41], v[188:191], v[212:215], v[38:41]
	v_mfma_f32_16x16x32_bf16 v[34:37], v[196:199], v[212:215], v[34:37]
	v_mfma_f32_16x16x32_bf16 v[22:25], v[188:191], v[220:223], v[22:25]
	v_mfma_f32_16x16x32_bf16 v[18:21], v[196:199], v[220:223], v[18:21]
	v_mfma_f32_16x16x32_bf16 v[6:9], v[188:191], v[228:231], v[6:9]
	v_mfma_f32_16x16x32_bf16 v[2:5], v[196:199], v[228:231], v[2:5]
	s_setprio 0
	s_add_u32 s86, s86, 0x100
	s_addc_u32 s87, s87, 0
	s_add_u32 s36, s36, 0x100
	s_addc_u32 s37, s37, 0
	s_cmp_ge_i32 s88, s52
	s_mov_b32 s38, s88
	s_barrier
	s_cbranch_scc0 .LBB0_1518
	v_readlane_b32 s74, v244, 3
	v_readlane_b32 s88, v244, 5
	v_readlane_b32 s75, v244, 4
	v_readlane_b32 s90, v244, 7
	v_readlane_b32 s91, v244, 8
	v_readlane_b32 s92, v244, 9
	v_readlane_b32 s93, v244, 10
	v_readlane_b32 s94, v244, 11
	v_readlane_b32 s95, v244, 12
	v_readlane_b32 s89, v244, 6

; #define PG8_STAGE(bufoff, gbase, voff) do { _Pragma("unroll") for (int _i = 0; _i < 2; ++_i) \
;         __builtin_amdgcn_global_load_lds((const unsigned*)((const char*)(gbase) + (voff)[_i]), (PG8_LAS unsigned*)(lds + (bufoff) + ldsw + _i * 8192), 16, 0, 0); } while (0)
; #define PG8_LDA(dst, b, h) do { _Pragma("unroll") for (int m = 0; m < 4; ++m) _Pragma("unroll") for (int k = 0; k < 2; ++k) dst[m][k] = *(const PG8_LAS bf16x8*)(lds + PG8_SA(b, h) + aoff + m * 2048 + k * 1024); } while (0)
; #define PG8_LDB(dst, b, h) do { _Pragma("unroll") for (int n = 0; n < 2; ++n) _Pragma("unroll") for (int k = 0; k < 2; ++k) dst[n][k] = *(const PG8_LAS bf16x8*)(lds + PG8_SB(b, h) + boff + n * 2048 + k * 1024); } while (0)
; #define PG8_MMA(ai, bj, At, Bt) do { __builtin_amdgcn_s_setprio(1); _Pragma("unroll") for (int m = 0; m < 4; ++m) _Pragma("unroll") for (int n = 0; n < 2; ++n) _Pragma("unroll") for (int k = 0; k < 2; ++k) \
;         acc[ai][bj][m][n] = __builtin_amdgcn_mfma_f32_16x16x32_bf16(Bt[n][k], At[m][k], acc[ai][bj][m][n], 0, 0, 0); __builtin_amdgcn_s_setprio(0); } while (0)
; #define PG8_WAIT_V(n) asm volatile("s_waitcnt vmcnt(" #n ")" ::: "memory")
; #define PG8_WAIT_L(n) asm volatile("s_waitcnt lgkmcnt(" #n ")" ::: "memory")
; template <class Epi, class Sched, bool ALIGN_EPI = false, bool SP2 = false>
; __device__ __forceinline__ void gemm_phase(PG8_LAS unsigned char* lds, const Gemm g, const Sched& S, const Epi& E) {
;     ...
;             const bool last = (t == nt - 2);
;             const char* a1 = cA + (size_t)(t + 1) * kstep;
;             const char* a2 = last ? nA : cA + (size_t)(t + 2) * kstep; const char* b2 = last ? nB : cB + (size_t)(t + 2) * kstep;
;             const char* a3 = a2 + kstep; const char* b3 = b2 + kstep;
;             if (last && has_next) S.a_ready(nxt);
;             if constexpr (SP2) {
;             PG8_LDB(B0, 0, 0); PG8_LDB(B1, 0, 1); PG8_SCHED; PG8_LDA(At, 0, 0); PG8_STAGE(PG8_SA(1, 1), a1 + hstep, voffA);
;             PG8_WAIT_V(8); PG8_WAIT_L(0); PG8_BAR; PG8_MMA(0, 0, At, B0); PG8_MMA(0, 1, At, B1); PG8_BAR; PG8_SCHED;
;             PG8_LDA(At, 0, 1); PG8_STAGE(PG8_SB(0, 0), b2, voffB); PG8_STAGE(PG8_SB(0, 1), b2 + hstep, voffB); PG8_STAGE(PG8_SA(0, 0), a2, voffA);
;             PG8_WAIT_V(8); PG8_WAIT_L(0); PG8_BAR; PG8_MMA(1, 0, At, B0); PG8_MMA(1, 1, At, B1); PG8_BAR; PG8_SCHED;
.LBB0_1548:
	ds_read_b128 v[146:149], v1
	ds_read_b128 v[162:165], v1 offset:1024
	ds_read_b128 v[166:169], v1 offset:2048
	ds_read_b128 v[170:173], v1 offset:3072
	ds_read_b128 v[174:177], v152
	ds_read_b128 v[178:181], v152 offset:1024
	ds_read_b128 v[182:185], v152 offset:2048
	ds_read_b128 v[186:189], v152 offset:3072
	s_add_i32 s68, s28, 2
	s_add_u32 s69, s26, 0x80
	s_addc_u32 s29, s27, 0
	s_cmp_eq_u32 s45, s28
	s_cselect_b32 s28, s4, s69
	s_cselect_b32 s29, s5, s29
	s_cselect_b32 s71, s9, s57
	s_cselect_b32 s70, s8, s56
	v_lshl_add_u64 v[150:151], s[26:27], 0, v[140:141]
	s_add_i32 m0, s37, 0xc000
	ds_read_b128 v[190:193], v153
	ds_read_b128 v[194:197], v153 offset:1024
	ds_read_b128 v[198:201], v153 offset:2048
	ds_read_b128 v[202:205], v153 offset:3072
	ds_read_b128 v[206:209], v153 offset:4096
	ds_read_b128 v[210:213], v153 offset:5120
	ds_read_b128 v[214:217], v153 offset:6144
	ds_read_b128 v[218:221], v153 offset:7168
	global_load_lds_dwordx4 v[150:151], off
	v_lshl_add_u64 v[150:151], s[26:27], 0, v[138:139]
	s_add_i32 m0, s37, 0xe000
	s_nop 0
	global_load_lds_dwordx4 v[150:151], off
	s_waitcnt vmcnt(8)
	s_waitcnt lgkmcnt(0)
	s_barrier
	s_setprio 1
	v_mfma_f32_16x16x32_bf16 v[122:125], v[146:149], v[190:193], v[122:125]
	v_mfma_f32_16x16x32_bf16 v[126:129], v[166:169], v[190:193], v[126:129]
	v_mfma_f32_16x16x32_bf16 v[110:113], v[146:149], v[198:201], v[110:113]
	v_mfma_f32_16x16x32_bf16 v[106:109], v[166:169], v[198:201], v[106:109]
	v_mfma_f32_16x16x32_bf16 v[94:97], v[146:149], v[206:209], v[94:97]
	v_mfma_f32_16x16x32_bf16 v[90:93], v[166:169], v[206:209], v[90:93]
	v_mfma_f32_16x16x32_bf16 v[78:81], v[146:149], v[214:217], v[78:81]
	v_mfma_f32_16x16x32_bf16 v[74:77], v[166:169], v[214:217], v[74:77]
	v_mfma_f32_16x16x32_bf16 v[122:125], v[162:165], v[194:197], v[122:125]
	v_mfma_f32_16x16x32_bf16 v[126:129], v[170:173], v[194:197], v[126:129]
	v_mfma_f32_16x16x32_bf16 v[110:113], v[162:165], v[202:205], v[110:113]
	v_mfma_f32_16x16x32_bf16 v[106:109], v[170:173], v[202:205], v[106:109]
	v_mfma_f32_16x16x32_bf16 v[94:97], v[162:165], v[210:213], v[94:97]
	v_mfma_f32_16x16x32_bf16 v[90:93], v[170:173], v[210:213], v[90:93]
	v_mfma_f32_16x16x32_bf16 v[78:81], v[162:165], v[218:221], v[78:81]
	v_mfma_f32_16x16x32_bf16 v[74:77], v[170:173], v[218:221], v[74:77]
	v_mfma_f32_16x16x32_bf16 v[118:121], v[174:177], v[190:193], v[118:121]
	v_mfma_f32_16x16x32_bf16 v[114:117], v[182:185], v[190:193], v[114:117]
	v_mfma_f32_16x16x32_bf16 v[102:105], v[174:177], v[198:201], v[102:105]
	v_mfma_f32_16x16x32_bf16 v[98:101], v[182:185], v[198:201], v[98:101]
	v_mfma_f32_16x16x32_bf16 v[86:89], v[174:177], v[206:209], v[86:89]
	v_mfma_f32_16x16x32_bf16 v[82:85], v[182:185], v[206:209], v[82:85]
	v_mfma_f32_16x16x32_bf16 v[70:73], v[174:177], v[214:217], v[70:73]
	v_mfma_f32_16x16x32_bf16 v[66:69], v[182:185], v[214:217], v[66:69]
	v_mfma_f32_16x16x32_bf16 v[118:121], v[178:181], v[194:197], v[118:121]
	v_mfma_f32_16x16x32_bf16 v[114:117], v[186:189], v[194:197], v[114:117]
	v_mfma_f32_16x16x32_bf16 v[102:105], v[178:181], v[202:205], v[102:105]
	v_mfma_f32_16x16x32_bf16 v[98:101], v[186:189], v[202:205], v[98:101]
	v_mfma_f32_16x16x32_bf16 v[86:89], v[178:181], v[210:213], v[86:89]
	v_mfma_f32_16x16x32_bf16 v[82:85], v[186:189], v[210:213], v[82:85]
	v_mfma_f32_16x16x32_bf16 v[70:73], v[178:181], v[218:221], v[70:73]
	v_mfma_f32_16x16x32_bf16 v[66:69], v[186:189], v[218:221], v[66:69]
	s_setprio 0
	s_barrier
	s_add_i32 s69, s48, s36
	v_lshl_add_u64 v[150:151], s[70:71], 0, v[132:133]
	s_mov_b32 m0, s69
	ds_read_b128 v[190:193], v153 offset:16384
	ds_read_b128 v[194:197], v153 offset:17408
	ds_read_b128 v[198:201], v153 offset:18432
	ds_read_b128 v[202:205], v153 offset:19456
	ds_read_b128 v[206:209], v153 offset:20480
	ds_read_b128 v[210:213], v153 offset:21504
	ds_read_b128 v[214:217], v153 offset:22528
	ds_read_b128 v[218:221], v153 offset:23552
	global_load_lds_dwordx4 v[150:151], off
	s_add_i32 m0, s69, 0x2000
	v_lshl_add_u64 v[158:159], s[70:71], 0, v[136:137]
	s_add_u32 s70, s70, s10
	s_addc_u32 s71, s71, s11
	s_add_i32 s69, s49, s36
	global_load_lds_dwordx4 v[158:159], off
	v_lshl_add_u64 v[222:223], s[70:71], 0, v[132:133]
	s_mov_b32 m0, s69
	v_lshl_add_u64 v[224:225], s[70:71], 0, v[136:137]
	global_load_lds_dwordx4 v[222:223], off
	s_add_i32 m0, s69, 0x2000
	v_lshl_add_u64 v[226:227], s[28:29], 0, v[130:131]
	global_load_lds_dwordx4 v[224:225], off
	s_mov_b32 m0, s37
	v_lshl_add_u64 v[228:229], s[28:29], 0, v[134:135]
	global_load_lds_dwordx4 v[226:227], off
	s_mov_b32 m0, s38
	s_nop 0
	global_load_lds_dwordx4 v[228:229], off
	s_waitcnt vmcnt(8)
	s_waitcnt lgkmcnt(0)
	s_barrier
; #define PG8_STAGE(bufoff, gbase, voff) do { _Pragma("unroll") for (int _i = 0; _i < 2; ++_i) \
;         __builtin_amdgcn_global_load_lds((const unsigned*)((const char*)(gbase) + (voff)[_i]), (PG8_LAS unsigned*)(lds + (bufoff) + ldsw + _i * 8192), 16, 0, 0); } while (0)
; #define PG8_LDA(dst, b, h) do { _Pragma("unroll") for (int m = 0; m < 4; ++m) _Pragma("unroll") for (int k = 0; k < 2; ++k) dst[m][k] = *(const PG8_LAS bf16x8*)(lds + PG8_SA(b, h) + aoff + m * 2048 + k * 1024); } while (0)
; #define PG8_LDB(dst, b, h) do { _Pragma("unroll") for (int n = 0; n < 2; ++n) _Pragma("unroll") for (int k = 0; k < 2; ++k) dst[n][k] = *(const PG8_LAS bf16x8*)(lds + PG8_SB(b, h) + boff + n * 2048 + k * 1024); } while (0)
; #define PG8_MMA(ai, bj, At, Bt) do { __builtin_amdgcn_s_setprio(1); _Pragma("unroll") for (int m = 0; m < 4; ++m) _Pragma("unroll") for (int n = 0; n < 2; ++n) _Pragma("unroll") for (int k = 0; k < 2; ++k) \
;         acc[ai][bj][m][n] = __builtin_amdgcn_mfma_f32_16x16x32_bf16(Bt[n][k], At[m][k], acc[ai][bj][m][n], 0, 0, 0); __builtin_amdgcn_s_setprio(0); } while (0)
; #define PG8_WAIT_V(n) asm volatile("s_waitcnt vmcnt(" #n ")" ::: "memory")
; #define PG8_WAIT_L(n) asm volatile("s_waitcnt lgkmcnt(" #n ")" ::: "memory")
; #define PG8_BAR __builtin_amdgcn_s_barrier()
; #define PG8_SCHED __builtin_amdgcn_sched_barrier(0)
; template <class Epi, class Sched, bool ALIGN_EPI = false, bool SP2 = false>
; __device__ __forceinline__ void gemm_phase(PG8_LAS unsigned char* lds, const Gemm g, const Sched& S, const Epi& E) {
;     ...
;             PG8_WAIT_V(8); PG8_WAIT_L(0); PG8_BAR; PG8_MMA(1, 0, At, B0); PG8_MMA(1, 1, At, B1); PG8_BAR; PG8_SCHED;
;             PG8_LDB(B0, 1, 0); PG8_LDB(B1, 1, 1); PG8_SCHED; PG8_LDA(At, 1, 0); PG8_STAGE(PG8_SA(0, 1), a2 + hstep, voffA);
;             PG8_WAIT_V(8); PG8_WAIT_L(0); PG8_BAR; PG8_MMA(0, 0, At, B0); PG8_MMA(0, 1, At, B1); PG8_BAR; PG8_SCHED;
	s_setprio 1
	v_mfma_f32_16x16x32_bf16 v[62:65], v[146:149], v[190:193], v[62:65]
	v_mfma_f32_16x16x32_bf16 v[58:61], v[166:169], v[190:193], v[58:61]
	v_mfma_f32_16x16x32_bf16 v[46:49], v[146:149], v[198:201], v[46:49]
	v_mfma_f32_16x16x32_bf16 v[42:45], v[166:169], v[198:201], v[42:45]
	v_mfma_f32_16x16x32_bf16 v[30:33], v[146:149], v[206:209], v[30:33]
	v_mfma_f32_16x16x32_bf16 v[26:29], v[166:169], v[206:209], v[26:29]
	v_mfma_f32_16x16x32_bf16 v[14:17], v[146:149], v[214:217], v[14:17]
	v_mfma_f32_16x16x32_bf16 v[10:13], v[166:169], v[214:217], v[10:13]
	v_mfma_f32_16x16x32_bf16 v[62:65], v[162:165], v[194:197], v[62:65]
	v_mfma_f32_16x16x32_bf16 v[58:61], v[170:173], v[194:197], v[58:61]
	v_mfma_f32_16x16x32_bf16 v[46:49], v[162:165], v[202:205], v[46:49]
	v_mfma_f32_16x16x32_bf16 v[42:45], v[170:173], v[202:205], v[42:45]
	v_mfma_f32_16x16x32_bf16 v[30:33], v[162:165], v[210:213], v[30:33]
	v_mfma_f32_16x16x32_bf16 v[26:29], v[170:173], v[210:213], v[26:29]
	v_mfma_f32_16x16x32_bf16 v[14:17], v[162:165], v[218:221], v[14:17]
	v_mfma_f32_16x16x32_bf16 v[10:13], v[170:173], v[218:221], v[10:13]
	v_mfma_f32_16x16x32_bf16 v[54:57], v[174:177], v[190:193], v[54:57]
	v_mfma_f32_16x16x32_bf16 v[50:53], v[182:185], v[190:193], v[50:53]
	v_mfma_f32_16x16x32_bf16 v[38:41], v[174:177], v[198:201], v[38:41]
	v_mfma_f32_16x16x32_bf16 v[34:37], v[182:185], v[198:201], v[34:37]
	v_mfma_f32_16x16x32_bf16 v[22:25], v[174:177], v[206:209], v[22:25]
	v_mfma_f32_16x16x32_bf16 v[18:21], v[182:185], v[206:209], v[18:21]
	v_mfma_f32_16x16x32_bf16 v[6:9], v[174:177], v[214:217], v[6:9]
	v_mfma_f32_16x16x32_bf16 v[2:5], v[182:185], v[214:217], v[2:5]
	v_mfma_f32_16x16x32_bf16 v[54:57], v[178:181], v[194:197], v[54:57]
	v_mfma_f32_16x16x32_bf16 v[50:53], v[186:189], v[194:197], v[50:53]
	v_mfma_f32_16x16x32_bf16 v[38:41], v[178:181], v[202:205], v[38:41]
	v_mfma_f32_16x16x32_bf16 v[34:37], v[186:189], v[202:205], v[34:37]
	v_mfma_f32_16x16x32_bf16 v[22:25], v[178:181], v[210:213], v[22:25]
	v_mfma_f32_16x16x32_bf16 v[18:21], v[186:189], v[210:213], v[18:21]
	v_mfma_f32_16x16x32_bf16 v[6:9], v[178:181], v[218:221], v[6:9]
	v_mfma_f32_16x16x32_bf16 v[2:5], v[186:189], v[218:221], v[2:5]
	s_setprio 0
	s_barrier
	s_add_i32 s69, 0, 0x18000
	v_add_u32_e32 v154, s69, v156
	s_add_i32 s70, 0, 0x1c000
	ds_read_b128 v[146:149], v154
	ds_read_b128 v[162:165], v154 offset:1024
	ds_read_b128 v[166:169], v154 offset:2048
	ds_read_b128 v[170:173], v154 offset:3072
	v_add_u32_e32 v154, s70, v156
	ds_read_b128 v[174:177], v154
	ds_read_b128 v[178:181], v154 offset:1024
	ds_read_b128 v[182:185], v154 offset:2048
	ds_read_b128 v[186:189], v154 offset:3072
	s_add_u32 s28, s28, s10
	s_addc_u32 s29, s29, s11
	s_mov_b32 m0, s39
	v_lshl_add_u64 v[230:231], s[28:29], 0, v[130:131]
	ds_read_b128 v[190:193], v153 offset:32768
	ds_read_b128 v[194:197], v153 offset:33792
	ds_read_b128 v[198:201], v153 offset:34816
	ds_read_b128 v[202:205], v153 offset:35840
	ds_read_b128 v[206:209], v153 offset:36864
	ds_read_b128 v[210:213], v153 offset:37888
	ds_read_b128 v[214:217], v153 offset:38912
	ds_read_b128 v[218:221], v153 offset:39936
	global_load_lds_dwordx4 v[230:231], off
	v_lshl_add_u64 v[230:231], s[28:29], 0, v[134:135]
	s_mov_b32 m0, s40
	s_nop 0
	global_load_lds_dwordx4 v[230:231], off
	s_waitcnt vmcnt(8)
	s_waitcnt lgkmcnt(0)
	s_barrier
	s_setprio 1
	v_mfma_f32_16x16x32_bf16 v[122:125], v[146:149], v[190:193], v[122:125]
	v_mfma_f32_16x16x32_bf16 v[126:129], v[166:169], v[190:193], v[126:129]
	v_mfma_f32_16x16x32_bf16 v[110:113], v[146:149], v[198:201], v[110:113]
	v_mfma_f32_16x16x32_bf16 v[106:109], v[166:169], v[198:201], v[106:109]
	v_mfma_f32_16x16x32_bf16 v[94:97], v[146:149], v[206:209], v[94:97]
	v_mfma_f32_16x16x32_bf16 v[90:93], v[166:169], v[206:209], v[90:93]
	v_mfma_f32_16x16x32_bf16 v[78:81], v[146:149], v[214:217], v[78:81]
	v_mfma_f32_16x16x32_bf16 v[74:77], v[166:169], v[214:217], v[74:77]
	v_mfma_f32_16x16x32_bf16 v[122:125], v[162:165], v[194:197], v[122:125]
	v_mfma_f32_16x16x32_bf16 v[126:129], v[170:173], v[194:197], v[126:129]
	v_mfma_f32_16x16x32_bf16 v[110:113], v[162:165], v[202:205], v[110:113]
	v_mfma_f32_16x16x32_bf16 v[106:109], v[170:173], v[202:205], v[106:109]
	v_mfma_f32_16x16x32_bf16 v[94:97], v[162:165], v[210:213], v[94:97]
	v_mfma_f32_16x16x32_bf16 v[90:93], v[170:173], v[210:213], v[90:93]
	v_mfma_f32_16x16x32_bf16 v[78:81], v[162:165], v[218:221], v[78:81]
	v_mfma_f32_16x16x32_bf16 v[74:77], v[170:173], v[218:221], v[74:77]
	v_mfma_f32_16x16x32_bf16 v[118:121], v[174:177], v[190:193], v[118:121]
	v_mfma_f32_16x16x32_bf16 v[114:117], v[182:185], v[190:193], v[114:117]
	v_mfma_f32_16x16x32_bf16 v[102:105], v[174:177], v[198:201], v[102:105]
	v_mfma_f32_16x16x32_bf16 v[98:101], v[182:185], v[198:201], v[98:101]
	v_mfma_f32_16x16x32_bf16 v[86:89], v[174:177], v[206:209], v[86:89]
	v_mfma_f32_16x16x32_bf16 v[82:85], v[182:185], v[206:209], v[82:85]
	v_mfma_f32_16x16x32_bf16 v[70:73], v[174:177], v[214:217], v[70:73]
	v_mfma_f32_16x16x32_bf16 v[66:69], v[182:185], v[214:217], v[66:69]
	v_mfma_f32_16x16x32_bf16 v[118:121], v[178:181], v[194:197], v[118:121]
	v_mfma_f32_16x16x32_bf16 v[114:117], v[186:189], v[194:197], v[114:117]
	v_mfma_f32_16x16x32_bf16 v[102:105], v[178:181], v[202:205], v[102:105]
	v_mfma_f32_16x16x32_bf16 v[98:101], v[186:189], v[202:205], v[98:101]
	v_mfma_f32_16x16x32_bf16 v[86:89], v[178:181], v[210:213], v[86:89]
	v_mfma_f32_16x16x32_bf16 v[82:85], v[186:189], v[210:213], v[82:85]
	v_mfma_f32_16x16x32_bf16 v[70:73], v[178:181], v[218:221], v[70:73]
	v_mfma_f32_16x16x32_bf16 v[66:69], v[186:189], v[218:221], v[66:69]
	s_setprio 0
	s_barrier
; #define PG8_STAGE(bufoff, gbase, voff) do { _Pragma("unroll") for (int _i = 0; _i < 2; ++_i) \
;         __builtin_amdgcn_global_load_lds((const unsigned*)((const char*)(gbase) + (voff)[_i]), (PG8_LAS unsigned*)(lds + (bufoff) + ldsw + _i * 8192), 16, 0, 0); } while (0)
; #define PG8_LDA(dst, b, h) do { _Pragma("unroll") for (int m = 0; m < 4; ++m) _Pragma("unroll") for (int k = 0; k < 2; ++k) dst[m][k] = *(const PG8_LAS bf16x8*)(lds + PG8_SA(b, h) + aoff + m * 2048 + k * 1024); } while (0)
; #define PG8_MMA(ai, bj, At, Bt) do { __builtin_amdgcn_s_setprio(1); _Pragma("unroll") for (int m = 0; m < 4; ++m) _Pragma("unroll") for (int n = 0; n < 2; ++n) _Pragma("unroll") for (int k = 0; k < 2; ++k) \
;         acc[ai][bj][m][n] = __builtin_amdgcn_mfma_f32_16x16x32_bf16(Bt[n][k], At[m][k], acc[ai][bj][m][n], 0, 0, 0); __builtin_amdgcn_s_setprio(0); } while (0)
; #define PG8_WAIT_V(n) asm volatile("s_waitcnt vmcnt(" #n ")" ::: "memory")
; #define PG8_WAIT_L(n) asm volatile("s_waitcnt lgkmcnt(" #n ")" ::: "memory")
; #define PG8_BAR __builtin_amdgcn_s_barrier()
; #define PG8_SCHED __builtin_amdgcn_sched_barrier(0)
; template <class Epi, class Sched, bool ALIGN_EPI = false, bool SP2 = false>
; __device__ __forceinline__ void gemm_phase(PG8_LAS unsigned char* lds, const Gemm g, const Sched& S, const Epi& E) {
;     ...
;         for (int t = 0; t < nt; t += 2) {
;             const bool last = (t == nt - 2);
;             const char* a1 = cA + (size_t)(t + 1) * kstep;
;             const char* a2 = last ? nA : cA + (size_t)(t + 2) * kstep; const char* b2 = last ? nB : cB + (size_t)(t + 2) * kstep;
;             const char* a3 = a2 + kstep; const char* b3 = b2 + kstep;
;     ...
;             PG8_LDA(At, 1, 1); PG8_STAGE(PG8_SB(1, 0), b3, voffB); PG8_STAGE(PG8_SB(1, 1), b3 + hstep, voffB); PG8_STAGE(PG8_SA(1, 0), a3, voffA);
;             PG8_WAIT_V(8); PG8_WAIT_L(0); PG8_BAR; PG8_MMA(1, 0, At, B0); PG8_MMA(1, 1, At, B1); PG8_BAR; PG8_SCHED;
	s_add_i32 s28, s69, s36
	v_lshl_add_u64 v[150:151], v[150:151], 0, s[20:21]
	s_mov_b32 m0, s28
	ds_read_b128 v[190:193], v153 offset:49152
	ds_read_b128 v[194:197], v153 offset:50176
	ds_read_b128 v[198:201], v153 offset:51200
	ds_read_b128 v[202:205], v153 offset:52224
	ds_read_b128 v[206:209], v153 offset:53248
	ds_read_b128 v[210:213], v153 offset:54272
	ds_read_b128 v[214:217], v153 offset:55296
	ds_read_b128 v[218:221], v153 offset:56320
	global_load_lds_dwordx4 v[150:151], off
	v_lshl_add_u64 v[150:151], v[158:159], 0, s[20:21]
	s_add_i32 m0, s28, 0x2000
	s_add_i32 s28, s70, s36
	global_load_lds_dwordx4 v[150:151], off
	v_lshl_add_u64 v[150:151], v[222:223], 0, s[20:21]
	s_mov_b32 m0, s28
	s_nop 0
	global_load_lds_dwordx4 v[150:151], off
	v_lshl_add_u64 v[150:151], v[224:225], 0, s[20:21]
	s_add_i32 m0, s28, 0x2000
	s_nop 0
	global_load_lds_dwordx4 v[150:151], off
	v_lshl_add_u64 v[150:151], v[226:227], 0, s[20:21]
	s_mov_b32 m0, s42
	s_nop 0
	global_load_lds_dwordx4 v[150:151], off
	v_lshl_add_u64 v[150:151], v[228:229], 0, s[20:21]
	s_mov_b32 m0, s43
	s_nop 0
	global_load_lds_dwordx4 v[150:151], off
	s_waitcnt vmcnt(8)
	s_waitcnt lgkmcnt(0)
	s_barrier
	s_setprio 1
	v_mfma_f32_16x16x32_bf16 v[62:65], v[146:149], v[190:193], v[62:65]
	v_mfma_f32_16x16x32_bf16 v[58:61], v[166:169], v[190:193], v[58:61]
	v_mfma_f32_16x16x32_bf16 v[46:49], v[146:149], v[198:201], v[46:49]
	v_mfma_f32_16x16x32_bf16 v[42:45], v[166:169], v[198:201], v[42:45]
	v_mfma_f32_16x16x32_bf16 v[30:33], v[146:149], v[206:209], v[30:33]
	v_mfma_f32_16x16x32_bf16 v[26:29], v[166:169], v[206:209], v[26:29]
	v_mfma_f32_16x16x32_bf16 v[14:17], v[146:149], v[214:217], v[14:17]
	v_mfma_f32_16x16x32_bf16 v[10:13], v[166:169], v[214:217], v[10:13]
	v_mfma_f32_16x16x32_bf16 v[62:65], v[162:165], v[194:197], v[62:65]
	v_mfma_f32_16x16x32_bf16 v[58:61], v[170:173], v[194:197], v[58:61]
	v_mfma_f32_16x16x32_bf16 v[46:49], v[162:165], v[202:205], v[46:49]
	v_mfma_f32_16x16x32_bf16 v[42:45], v[170:173], v[202:205], v[42:45]
	v_mfma_f32_16x16x32_bf16 v[30:33], v[162:165], v[210:213], v[30:33]
	v_mfma_f32_16x16x32_bf16 v[26:29], v[170:173], v[210:213], v[26:29]
	v_mfma_f32_16x16x32_bf16 v[14:17], v[162:165], v[218:221], v[14:17]
	v_mfma_f32_16x16x32_bf16 v[10:13], v[170:173], v[218:221], v[10:13]
	v_mfma_f32_16x16x32_bf16 v[54:57], v[174:177], v[190:193], v[54:57]
	v_mfma_f32_16x16x32_bf16 v[50:53], v[182:185], v[190:193], v[50:53]
	v_mfma_f32_16x16x32_bf16 v[38:41], v[174:177], v[198:201], v[38:41]
	v_mfma_f32_16x16x32_bf16 v[34:37], v[182:185], v[198:201], v[34:37]
	v_mfma_f32_16x16x32_bf16 v[22:25], v[174:177], v[206:209], v[22:25]
	v_mfma_f32_16x16x32_bf16 v[18:21], v[182:185], v[206:209], v[18:21]
	v_mfma_f32_16x16x32_bf16 v[6:9], v[174:177], v[214:217], v[6:9]
	v_mfma_f32_16x16x32_bf16 v[2:5], v[182:185], v[214:217], v[2:5]
	v_mfma_f32_16x16x32_bf16 v[54:57], v[178:181], v[194:197], v[54:57]
	v_mfma_f32_16x16x32_bf16 v[50:53], v[186:189], v[194:197], v[50:53]
	v_mfma_f32_16x16x32_bf16 v[38:41], v[178:181], v[202:205], v[38:41]
	v_mfma_f32_16x16x32_bf16 v[34:37], v[186:189], v[202:205], v[34:37]
	v_mfma_f32_16x16x32_bf16 v[22:25], v[178:181], v[210:213], v[22:25]
	v_mfma_f32_16x16x32_bf16 v[18:21], v[186:189], v[210:213], v[18:21]
	v_mfma_f32_16x16x32_bf16 v[6:9], v[178:181], v[218:221], v[6:9]
	v_mfma_f32_16x16x32_bf16 v[2:5], v[186:189], v[218:221], v[2:5]
	s_setprio 0
	s_add_u32 s56, s56, 0x100
	s_addc_u32 s57, s57, 0
	s_add_u32 s26, s26, 0x100
	s_addc_u32 s27, s27, 0
	s_cmp_ge_i32 s68, s44
	s_mov_b32 s28, s68
	s_barrier
	s_cbranch_scc0 .LBB0_1548

; #define PG8_STAGE(bufoff, gbase, voff) do { _Pragma("unroll") for (int _i = 0; _i < 2; ++_i) \
;         __builtin_amdgcn_global_load_lds((const unsigned*)((const char*)(gbase) + (voff)[_i]), (PG8_LAS unsigned*)(lds + (bufoff) + ldsw + _i * 8192), 16, 0, 0); } while (0)
; #define PG8_LDA(dst, b, h) do { _Pragma("unroll") for (int m = 0; m < 4; ++m) _Pragma("unroll") for (int k = 0; k < 2; ++k) dst[m][k] = *(const PG8_LAS bf16x8*)(lds + PG8_SA(b, h) + aoff + m * 2048 + k * 1024); } while (0)
; #define PG8_LDB(dst, b, h) do { _Pragma("unroll") for (int n = 0; n < 2; ++n) _Pragma("unroll") for (int k = 0; k < 2; ++k) dst[n][k] = *(const PG8_LAS bf16x8*)(lds + PG8_SB(b, h) + boff + n * 2048 + k * 1024); } while (0)
; #define PG8_MMA(ai, bj, At, Bt) do { __builtin_amdgcn_s_setprio(1); _Pragma("unroll") for (int m = 0; m < 4; ++m) _Pragma("unroll") for (int n = 0; n < 2; ++n) _Pragma("unroll") for (int k = 0; k < 2; ++k) \
;         acc[ai][bj][m][n] = __builtin_amdgcn_mfma_f32_16x16x32_bf16(Bt[n][k], At[m][k], acc[ai][bj][m][n], 0, 0, 0); __builtin_amdgcn_s_setprio(0); } while (0)
; #define PG8_WAIT_V(n) asm volatile("s_waitcnt vmcnt(" #n ")" ::: "memory")
; #define PG8_WAIT_L(n) asm volatile("s_waitcnt lgkmcnt(" #n ")" ::: "memory")
; template <class Epi, class Sched, bool ALIGN_EPI = false, bool SP2 = false>
; __device__ __forceinline__ void gemm_phase(PG8_LAS unsigned char* lds, const Gemm g, const Sched& S, const Epi& E) {
;     ...
;             const bool last = (t == nt - 2);
;             const char* a1 = cA + (size_t)(t + 1) * kstep;
;             const char* a2 = last ? nA : cA + (size_t)(t + 2) * kstep; const char* b2 = last ? nB : cB + (size_t)(t + 2) * kstep;
;             const char* a3 = a2 + kstep; const char* b3 = b2 + kstep;
;             if (last && has_next) S.a_ready(nxt);
;             if constexpr (SP2) {
;             PG8_LDB(B0, 0, 0); PG8_LDB(B1, 0, 1); PG8_SCHED; PG8_LDA(At, 0, 0); PG8_STAGE(PG8_SA(1, 1), a1 + hstep, voffA);
;             PG8_WAIT_V(8); PG8_WAIT_L(0); PG8_BAR; PG8_MMA(0, 0, At, B0); PG8_MMA(0, 1, At, B1); PG8_BAR; PG8_SCHED;
;             PG8_LDA(At, 0, 1); PG8_STAGE(PG8_SB(0, 0), b2, voffB); PG8_STAGE(PG8_SB(0, 1), b2 + hstep, voffB); PG8_STAGE(PG8_SA(0, 0), a2, voffA);
;             PG8_WAIT_V(8); PG8_WAIT_L(0); PG8_BAR; PG8_MMA(1, 0, At, B0); PG8_MMA(1, 1, At, B1); PG8_BAR; PG8_SCHED;
.LBB0_1724:
	ds_read_b128 v[148:151], v157
	ds_read_b128 v[152:155], v157 offset:1024
	ds_read_b128 v[160:163], v157 offset:2048
	ds_read_b128 v[164:167], v157 offset:3072
	ds_read_b128 v[168:171], v158
	ds_read_b128 v[172:175], v158 offset:1024
	ds_read_b128 v[176:179], v158 offset:2048
	ds_read_b128 v[180:183], v158 offset:3072
	s_add_i32 s80, s38, 2
	s_add_u32 s70, s36, 0x80
	s_addc_u32 s39, s37, 0
	s_cmp_eq_u32 s59, s38
	s_cselect_b32 s38, s4, s70
	s_cselect_b32 s39, s5, s39
	s_cselect_b32 s71, s35, s45
	s_cselect_b32 s70, s34, s44
	v_lshl_add_u64 v[216:217], s[36:37], 0, v[142:143]
	s_add_i32 m0, s48, 0xc000
	ds_read_b128 v[184:187], v159
	ds_read_b128 v[188:191], v159 offset:1024
	ds_read_b128 v[192:195], v159 offset:2048
	ds_read_b128 v[196:199], v159 offset:3072
	ds_read_b128 v[200:203], v159 offset:4096
	ds_read_b128 v[204:207], v159 offset:5120
	ds_read_b128 v[208:211], v159 offset:6144
	ds_read_b128 v[212:215], v159 offset:7168
	global_load_lds_dwordx4 v[216:217], off
	v_lshl_add_u64 v[216:217], s[36:37], 0, v[140:141]
	s_add_i32 m0, s48, 0xe000
	s_nop 0
	global_load_lds_dwordx4 v[216:217], off
	s_waitcnt vmcnt(8)
	s_waitcnt lgkmcnt(0)
	s_barrier
	s_setprio 1
	v_mfma_f32_16x16x32_bf16 v[122:125], v[148:151], v[184:187], v[122:125]
	v_mfma_f32_16x16x32_bf16 v[126:129], v[160:163], v[184:187], v[126:129]
	v_mfma_f32_16x16x32_bf16 v[110:113], v[148:151], v[192:195], v[110:113]
	v_mfma_f32_16x16x32_bf16 v[106:109], v[160:163], v[192:195], v[106:109]
	v_mfma_f32_16x16x32_bf16 v[94:97], v[148:151], v[200:203], v[94:97]
	v_mfma_f32_16x16x32_bf16 v[90:93], v[160:163], v[200:203], v[90:93]
	v_mfma_f32_16x16x32_bf16 v[78:81], v[148:151], v[208:211], v[78:81]
	v_mfma_f32_16x16x32_bf16 v[74:77], v[160:163], v[208:211], v[74:77]
	v_mfma_f32_16x16x32_bf16 v[122:125], v[152:155], v[188:191], v[122:125]
	v_mfma_f32_16x16x32_bf16 v[126:129], v[164:167], v[188:191], v[126:129]
	v_mfma_f32_16x16x32_bf16 v[110:113], v[152:155], v[196:199], v[110:113]
	v_mfma_f32_16x16x32_bf16 v[106:109], v[164:167], v[196:199], v[106:109]
	v_mfma_f32_16x16x32_bf16 v[94:97], v[152:155], v[204:207], v[94:97]
	v_mfma_f32_16x16x32_bf16 v[90:93], v[164:167], v[204:207], v[90:93]
	v_mfma_f32_16x16x32_bf16 v[78:81], v[152:155], v[212:215], v[78:81]
	v_mfma_f32_16x16x32_bf16 v[74:77], v[164:167], v[212:215], v[74:77]
	v_mfma_f32_16x16x32_bf16 v[118:121], v[168:171], v[184:187], v[118:121]
	v_mfma_f32_16x16x32_bf16 v[114:117], v[176:179], v[184:187], v[114:117]
	v_mfma_f32_16x16x32_bf16 v[102:105], v[168:171], v[192:195], v[102:105]
	v_mfma_f32_16x16x32_bf16 v[98:101], v[176:179], v[192:195], v[98:101]
	v_mfma_f32_16x16x32_bf16 v[86:89], v[168:171], v[200:203], v[86:89]
	v_mfma_f32_16x16x32_bf16 v[82:85], v[176:179], v[200:203], v[82:85]
	v_mfma_f32_16x16x32_bf16 v[70:73], v[168:171], v[208:211], v[70:73]
	v_mfma_f32_16x16x32_bf16 v[66:69], v[176:179], v[208:211], v[66:69]
	v_mfma_f32_16x16x32_bf16 v[118:121], v[172:175], v[188:191], v[118:121]
	v_mfma_f32_16x16x32_bf16 v[114:117], v[180:183], v[188:191], v[114:117]
	v_mfma_f32_16x16x32_bf16 v[102:105], v[172:175], v[196:199], v[102:105]
	v_mfma_f32_16x16x32_bf16 v[98:101], v[180:183], v[196:199], v[98:101]
	v_mfma_f32_16x16x32_bf16 v[86:89], v[172:175], v[204:207], v[86:89]
	v_mfma_f32_16x16x32_bf16 v[82:85], v[180:183], v[204:207], v[82:85]
	v_mfma_f32_16x16x32_bf16 v[70:73], v[172:175], v[212:215], v[70:73]
	v_mfma_f32_16x16x32_bf16 v[66:69], v[180:183], v[212:215], v[66:69]
	s_setprio 0
	s_barrier
	s_add_i32 s72, s62, s47
	v_lshl_add_u64 v[216:217], s[70:71], 0, v[134:135]
	s_mov_b32 m0, s72
	ds_read_b128 v[184:187], v159 offset:16384
	ds_read_b128 v[188:191], v159 offset:17408
	ds_read_b128 v[192:195], v159 offset:18432
	ds_read_b128 v[196:199], v159 offset:19456
	ds_read_b128 v[200:203], v159 offset:20480
	ds_read_b128 v[204:207], v159 offset:21504
	ds_read_b128 v[208:211], v159 offset:22528
	ds_read_b128 v[212:215], v159 offset:23552
	global_load_lds_dwordx4 v[216:217], off
	s_add_i32 m0, s72, 0x2000
	v_lshl_add_u64 v[218:219], s[70:71], 0, v[138:139]
	s_add_u32 s70, s70, s8
	s_addc_u32 s71, s71, s9
	s_add_i32 s72, s63, s47
	global_load_lds_dwordx4 v[218:219], off
	v_lshl_add_u64 v[220:221], s[70:71], 0, v[134:135]
	s_mov_b32 m0, s72
	v_lshl_add_u64 v[222:223], s[70:71], 0, v[138:139]
	global_load_lds_dwordx4 v[220:221], off
	s_add_i32 m0, s72, 0x2000
	v_lshl_add_u64 v[224:225], s[38:39], 0, v[132:133]
	global_load_lds_dwordx4 v[222:223], off
	s_mov_b32 m0, s48
	v_lshl_add_u64 v[226:227], s[38:39], 0, v[136:137]
	global_load_lds_dwordx4 v[224:225], off
	s_mov_b32 m0, s49
	s_nop 0
	global_load_lds_dwordx4 v[226:227], off
	s_waitcnt vmcnt(8)
	s_waitcnt lgkmcnt(0)
	s_barrier
; #define PG8_STAGE(bufoff, gbase, voff) do { _Pragma("unroll") for (int _i = 0; _i < 2; ++_i) \
;         __builtin_amdgcn_global_load_lds((const unsigned*)((const char*)(gbase) + (voff)[_i]), (PG8_LAS unsigned*)(lds + (bufoff) + ldsw + _i * 8192), 16, 0, 0); } while (0)
; #define PG8_LDA(dst, b, h) do { _Pragma("unroll") for (int m = 0; m < 4; ++m) _Pragma("unroll") for (int k = 0; k < 2; ++k) dst[m][k] = *(const PG8_LAS bf16x8*)(lds + PG8_SA(b, h) + aoff + m * 2048 + k * 1024); } while (0)
; #define PG8_LDB(dst, b, h) do { _Pragma("unroll") for (int n = 0; n < 2; ++n) _Pragma("unroll") for (int k = 0; k < 2; ++k) dst[n][k] = *(const PG8_LAS bf16x8*)(lds + PG8_SB(b, h) + boff + n * 2048 + k * 1024); } while (0)
; #define PG8_MMA(ai, bj, At, Bt) do { __builtin_amdgcn_s_setprio(1); _Pragma("unroll") for (int m = 0; m < 4; ++m) _Pragma("unroll") for (int n = 0; n < 2; ++n) _Pragma("unroll") for (int k = 0; k < 2; ++k) \
;         acc[ai][bj][m][n] = __builtin_amdgcn_mfma_f32_16x16x32_bf16(Bt[n][k], At[m][k], acc[ai][bj][m][n], 0, 0, 0); __builtin_amdgcn_s_setprio(0); } while (0)
; #define PG8_WAIT_V(n) asm volatile("s_waitcnt vmcnt(" #n ")" ::: "memory")
; #define PG8_WAIT_L(n) asm volatile("s_waitcnt lgkmcnt(" #n ")" ::: "memory")
; #define PG8_BAR __builtin_amdgcn_s_barrier()
; #define PG8_SCHED __builtin_amdgcn_sched_barrier(0)
; template <class Epi, class Sched, bool ALIGN_EPI = false, bool SP2 = false>
; __device__ __forceinline__ void gemm_phase(PG8_LAS unsigned char* lds, const Gemm g, const Sched& S, const Epi& E) {
;     ...
;             PG8_WAIT_V(8); PG8_WAIT_L(0); PG8_BAR; PG8_MMA(1, 0, At, B0); PG8_MMA(1, 1, At, B1); PG8_BAR; PG8_SCHED;
;             PG8_LDB(B0, 1, 0); PG8_LDB(B1, 1, 1); PG8_SCHED; PG8_LDA(At, 1, 0); PG8_STAGE(PG8_SA(0, 1), a2 + hstep, voffA);
;             PG8_WAIT_V(8); PG8_WAIT_L(0); PG8_BAR; PG8_MMA(0, 0, At, B0); PG8_MMA(0, 1, At, B1); PG8_BAR; PG8_SCHED;
	s_setprio 1
	v_mfma_f32_16x16x32_bf16 v[62:65], v[148:151], v[184:187], v[62:65]
	v_mfma_f32_16x16x32_bf16 v[58:61], v[160:163], v[184:187], v[58:61]
	v_mfma_f32_16x16x32_bf16 v[46:49], v[148:151], v[192:195], v[46:49]
	v_mfma_f32_16x16x32_bf16 v[42:45], v[160:163], v[192:195], v[42:45]
	v_mfma_f32_16x16x32_bf16 v[30:33], v[148:151], v[200:203], v[30:33]
	v_mfma_f32_16x16x32_bf16 v[26:29], v[160:163], v[200:203], v[26:29]
	v_mfma_f32_16x16x32_bf16 v[14:17], v[148:151], v[208:211], v[14:17]
	v_mfma_f32_16x16x32_bf16 v[10:13], v[160:163], v[208:211], v[10:13]
	v_mfma_f32_16x16x32_bf16 v[62:65], v[152:155], v[188:191], v[62:65]
	v_mfma_f32_16x16x32_bf16 v[58:61], v[164:167], v[188:191], v[58:61]
	v_mfma_f32_16x16x32_bf16 v[46:49], v[152:155], v[196:199], v[46:49]
	v_mfma_f32_16x16x32_bf16 v[42:45], v[164:167], v[196:199], v[42:45]
	v_mfma_f32_16x16x32_bf16 v[30:33], v[152:155], v[204:207], v[30:33]
	v_mfma_f32_16x16x32_bf16 v[26:29], v[164:167], v[204:207], v[26:29]
	v_mfma_f32_16x16x32_bf16 v[14:17], v[152:155], v[212:215], v[14:17]
	v_mfma_f32_16x16x32_bf16 v[10:13], v[164:167], v[212:215], v[10:13]
	v_mfma_f32_16x16x32_bf16 v[54:57], v[168:171], v[184:187], v[54:57]
	v_mfma_f32_16x16x32_bf16 v[50:53], v[176:179], v[184:187], v[50:53]
	v_mfma_f32_16x16x32_bf16 v[38:41], v[168:171], v[192:195], v[38:41]
	v_mfma_f32_16x16x32_bf16 v[34:37], v[176:179], v[192:195], v[34:37]
	v_mfma_f32_16x16x32_bf16 v[22:25], v[168:171], v[200:203], v[22:25]
	v_mfma_f32_16x16x32_bf16 v[18:21], v[176:179], v[200:203], v[18:21]
	v_mfma_f32_16x16x32_bf16 v[6:9], v[168:171], v[208:211], v[6:9]
	v_mfma_f32_16x16x32_bf16 v[2:5], v[176:179], v[208:211], v[2:5]
	v_mfma_f32_16x16x32_bf16 v[54:57], v[172:175], v[188:191], v[54:57]
	v_mfma_f32_16x16x32_bf16 v[50:53], v[180:183], v[188:191], v[50:53]
	v_mfma_f32_16x16x32_bf16 v[38:41], v[172:175], v[196:199], v[38:41]
	v_mfma_f32_16x16x32_bf16 v[34:37], v[180:183], v[196:199], v[34:37]
	v_mfma_f32_16x16x32_bf16 v[22:25], v[172:175], v[204:207], v[22:25]
	v_mfma_f32_16x16x32_bf16 v[18:21], v[180:183], v[204:207], v[18:21]
	v_mfma_f32_16x16x32_bf16 v[6:9], v[172:175], v[212:215], v[6:9]
	v_mfma_f32_16x16x32_bf16 v[2:5], v[180:183], v[212:215], v[2:5]
	s_setprio 0
	s_barrier
	s_add_i32 s70, 0, 0x18000
	s_add_i32 s71, 0, 0x1c000
	v_add_u32_e32 v164, s70, v156
	v_add_u32_e32 v180, s71, v156
	ds_read_b128 v[148:151], v164
	ds_read_b128 v[152:155], v164 offset:1024
	ds_read_b128 v[160:163], v164 offset:2048
	ds_read_b128 v[164:167], v164 offset:3072
	ds_read_b128 v[168:171], v180
	ds_read_b128 v[172:175], v180 offset:1024
	ds_read_b128 v[176:179], v180 offset:2048
	ds_read_b128 v[180:183], v180 offset:3072
	s_add_u32 s38, s38, s8
	s_addc_u32 s39, s39, s9
	s_mov_b32 m0, s52
	v_lshl_add_u64 v[228:229], s[38:39], 0, v[132:133]
	ds_read_b128 v[184:187], v159 offset:32768
	ds_read_b128 v[188:191], v159 offset:33792
	ds_read_b128 v[192:195], v159 offset:34816
	ds_read_b128 v[196:199], v159 offset:35840
	ds_read_b128 v[200:203], v159 offset:36864
	ds_read_b128 v[204:207], v159 offset:37888
	ds_read_b128 v[208:211], v159 offset:38912
	ds_read_b128 v[212:215], v159 offset:39936
	global_load_lds_dwordx4 v[228:229], off
	v_lshl_add_u64 v[228:229], s[38:39], 0, v[136:137]
	s_mov_b32 m0, s53
	s_nop 0
	global_load_lds_dwordx4 v[228:229], off
	s_waitcnt vmcnt(8)
	s_waitcnt lgkmcnt(0)
	s_barrier
	s_setprio 1
	v_mfma_f32_16x16x32_bf16 v[122:125], v[148:151], v[184:187], v[122:125]
	v_mfma_f32_16x16x32_bf16 v[126:129], v[160:163], v[184:187], v[126:129]
	v_mfma_f32_16x16x32_bf16 v[110:113], v[148:151], v[192:195], v[110:113]
	v_mfma_f32_16x16x32_bf16 v[106:109], v[160:163], v[192:195], v[106:109]
	v_mfma_f32_16x16x32_bf16 v[94:97], v[148:151], v[200:203], v[94:97]
	v_mfma_f32_16x16x32_bf16 v[90:93], v[160:163], v[200:203], v[90:93]
	v_mfma_f32_16x16x32_bf16 v[78:81], v[148:151], v[208:211], v[78:81]
	v_mfma_f32_16x16x32_bf16 v[74:77], v[160:163], v[208:211], v[74:77]
	v_mfma_f32_16x16x32_bf16 v[122:125], v[152:155], v[188:191], v[122:125]
	v_mfma_f32_16x16x32_bf16 v[126:129], v[164:167], v[188:191], v[126:129]
	v_mfma_f32_16x16x32_bf16 v[110:113], v[152:155], v[196:199], v[110:113]
	v_mfma_f32_16x16x32_bf16 v[106:109], v[164:167], v[196:199], v[106:109]
	v_mfma_f32_16x16x32_bf16 v[94:97], v[152:155], v[204:207], v[94:97]
	v_mfma_f32_16x16x32_bf16 v[90:93], v[164:167], v[204:207], v[90:93]
	v_mfma_f32_16x16x32_bf16 v[78:81], v[152:155], v[212:215], v[78:81]
	v_mfma_f32_16x16x32_bf16 v[74:77], v[164:167], v[212:215], v[74:77]
	v_mfma_f32_16x16x32_bf16 v[118:121], v[168:171], v[184:187], v[118:121]
	v_mfma_f32_16x16x32_bf16 v[114:117], v[176:179], v[184:187], v[114:117]
	v_mfma_f32_16x16x32_bf16 v[102:105], v[168:171], v[192:195], v[102:105]
	v_mfma_f32_16x16x32_bf16 v[98:101], v[176:179], v[192:195], v[98:101]
	v_mfma_f32_16x16x32_bf16 v[86:89], v[168:171], v[200:203], v[86:89]
	v_mfma_f32_16x16x32_bf16 v[82:85], v[176:179], v[200:203], v[82:85]
	v_mfma_f32_16x16x32_bf16 v[70:73], v[168:171], v[208:211], v[70:73]
	v_mfma_f32_16x16x32_bf16 v[66:69], v[176:179], v[208:211], v[66:69]
	v_mfma_f32_16x16x32_bf16 v[118:121], v[172:175], v[188:191], v[118:121]
	v_mfma_f32_16x16x32_bf16 v[114:117], v[180:183], v[188:191], v[114:117]
	v_mfma_f32_16x16x32_bf16 v[102:105], v[172:175], v[196:199], v[102:105]
	v_mfma_f32_16x16x32_bf16 v[98:101], v[180:183], v[196:199], v[98:101]
	v_mfma_f32_16x16x32_bf16 v[86:89], v[172:175], v[204:207], v[86:89]
	v_mfma_f32_16x16x32_bf16 v[82:85], v[180:183], v[204:207], v[82:85]
	v_mfma_f32_16x16x32_bf16 v[70:73], v[172:175], v[212:215], v[70:73]
	v_mfma_f32_16x16x32_bf16 v[66:69], v[180:183], v[212:215], v[66:69]
	s_setprio 0
	s_barrier
; #define PG8_STAGE(bufoff, gbase, voff) do { _Pragma("unroll") for (int _i = 0; _i < 2; ++_i) \
;         __builtin_amdgcn_global_load_lds((const unsigned*)((const char*)(gbase) + (voff)[_i]), (PG8_LAS unsigned*)(lds + (bufoff) + ldsw + _i * 8192), 16, 0, 0); } while (0)
; #define PG8_LDA(dst, b, h) do { _Pragma("unroll") for (int m = 0; m < 4; ++m) _Pragma("unroll") for (int k = 0; k < 2; ++k) dst[m][k] = *(const PG8_LAS bf16x8*)(lds + PG8_SA(b, h) + aoff + m * 2048 + k * 1024); } while (0)
; #define PG8_MMA(ai, bj, At, Bt) do { __builtin_amdgcn_s_setprio(1); _Pragma("unroll") for (int m = 0; m < 4; ++m) _Pragma("unroll") for (int n = 0; n < 2; ++n) _Pragma("unroll") for (int k = 0; k < 2; ++k) \
;         acc[ai][bj][m][n] = __builtin_amdgcn_mfma_f32_16x16x32_bf16(Bt[n][k], At[m][k], acc[ai][bj][m][n], 0, 0, 0); __builtin_amdgcn_s_setprio(0); } while (0)
; #define PG8_WAIT_V(n) asm volatile("s_waitcnt vmcnt(" #n ")" ::: "memory")
; #define PG8_WAIT_L(n) asm volatile("s_waitcnt lgkmcnt(" #n ")" ::: "memory")
; #define PG8_BAR __builtin_amdgcn_s_barrier()
; #define PG8_SCHED __builtin_amdgcn_sched_barrier(0)
; template <class Epi, class Sched, bool ALIGN_EPI = false, bool SP2 = false>
; __device__ __forceinline__ void gemm_phase(PG8_LAS unsigned char* lds, const Gemm g, const Sched& S, const Epi& E) {
;     ...
;         for (int t = 0; t < nt; t += 2) {
;             const bool last = (t == nt - 2);
;             const char* a1 = cA + (size_t)(t + 1) * kstep;
;             const char* a2 = last ? nA : cA + (size_t)(t + 2) * kstep; const char* b2 = last ? nB : cB + (size_t)(t + 2) * kstep;
;             const char* a3 = a2 + kstep; const char* b3 = b2 + kstep;
;     ...
;             PG8_LDA(At, 1, 1); PG8_STAGE(PG8_SB(1, 0), b3, voffB); PG8_STAGE(PG8_SB(1, 1), b3 + hstep, voffB); PG8_STAGE(PG8_SA(1, 0), a3, voffA);
;             PG8_WAIT_V(8); PG8_WAIT_L(0); PG8_BAR; PG8_MMA(1, 0, At, B0); PG8_MMA(1, 1, At, B1); PG8_BAR; PG8_SCHED;
	s_add_i32 s38, s70, s47
	v_lshl_add_u64 v[216:217], v[216:217], 0, s[24:25]
	s_mov_b32 m0, s38
	ds_read_b128 v[184:187], v159 offset:49152
	ds_read_b128 v[188:191], v159 offset:50176
	ds_read_b128 v[192:195], v159 offset:51200
	ds_read_b128 v[196:199], v159 offset:52224
	ds_read_b128 v[200:203], v159 offset:53248
	ds_read_b128 v[204:207], v159 offset:54272
	ds_read_b128 v[208:211], v159 offset:55296
	ds_read_b128 v[212:215], v159 offset:56320
	global_load_lds_dwordx4 v[216:217], off
	v_lshl_add_u64 v[216:217], v[218:219], 0, s[24:25]
	s_add_i32 m0, s38, 0x2000
	s_add_i32 s38, s71, s47
	global_load_lds_dwordx4 v[216:217], off
	v_lshl_add_u64 v[216:217], v[220:221], 0, s[24:25]
	s_mov_b32 m0, s38
	s_nop 0
	global_load_lds_dwordx4 v[216:217], off
	v_lshl_add_u64 v[216:217], v[222:223], 0, s[24:25]
	s_add_i32 m0, s38, 0x2000
	s_nop 0
	global_load_lds_dwordx4 v[216:217], off
	v_lshl_add_u64 v[216:217], v[224:225], 0, s[24:25]
	s_mov_b32 m0, s55
	s_nop 0
	global_load_lds_dwordx4 v[216:217], off
	v_lshl_add_u64 v[216:217], v[226:227], 0, s[24:25]
	s_mov_b32 m0, s56
	s_nop 0
	global_load_lds_dwordx4 v[216:217], off
	s_waitcnt vmcnt(8)
	s_waitcnt lgkmcnt(0)
	s_barrier
	s_setprio 1
	v_mfma_f32_16x16x32_bf16 v[62:65], v[148:151], v[184:187], v[62:65]
	v_mfma_f32_16x16x32_bf16 v[58:61], v[160:163], v[184:187], v[58:61]
	v_mfma_f32_16x16x32_bf16 v[46:49], v[148:151], v[192:195], v[46:49]
	v_mfma_f32_16x16x32_bf16 v[42:45], v[160:163], v[192:195], v[42:45]
	v_mfma_f32_16x16x32_bf16 v[30:33], v[148:151], v[200:203], v[30:33]
	v_mfma_f32_16x16x32_bf16 v[26:29], v[160:163], v[200:203], v[26:29]
	v_mfma_f32_16x16x32_bf16 v[14:17], v[148:151], v[208:211], v[14:17]
	v_mfma_f32_16x16x32_bf16 v[10:13], v[160:163], v[208:211], v[10:13]
	v_mfma_f32_16x16x32_bf16 v[62:65], v[152:155], v[188:191], v[62:65]
	v_mfma_f32_16x16x32_bf16 v[58:61], v[164:167], v[188:191], v[58:61]
	v_mfma_f32_16x16x32_bf16 v[46:49], v[152:155], v[196:199], v[46:49]
	v_mfma_f32_16x16x32_bf16 v[42:45], v[164:167], v[196:199], v[42:45]
	v_mfma_f32_16x16x32_bf16 v[30:33], v[152:155], v[204:207], v[30:33]
	v_mfma_f32_16x16x32_bf16 v[26:29], v[164:167], v[204:207], v[26:29]
	v_mfma_f32_16x16x32_bf16 v[14:17], v[152:155], v[212:215], v[14:17]
	v_mfma_f32_16x16x32_bf16 v[10:13], v[164:167], v[212:215], v[10:13]
	v_mfma_f32_16x16x32_bf16 v[54:57], v[168:171], v[184:187], v[54:57]
	v_mfma_f32_16x16x32_bf16 v[50:53], v[176:179], v[184:187], v[50:53]
	v_mfma_f32_16x16x32_bf16 v[38:41], v[168:171], v[192:195], v[38:41]
	v_mfma_f32_16x16x32_bf16 v[34:37], v[176:179], v[192:195], v[34:37]
	v_mfma_f32_16x16x32_bf16 v[22:25], v[168:171], v[200:203], v[22:25]
	v_mfma_f32_16x16x32_bf16 v[18:21], v[176:179], v[200:203], v[18:21]
	v_mfma_f32_16x16x32_bf16 v[6:9], v[168:171], v[208:211], v[6:9]
	v_mfma_f32_16x16x32_bf16 v[2:5], v[176:179], v[208:211], v[2:5]
	v_mfma_f32_16x16x32_bf16 v[54:57], v[172:175], v[188:191], v[54:57]
	v_mfma_f32_16x16x32_bf16 v[50:53], v[180:183], v[188:191], v[50:53]
	v_mfma_f32_16x16x32_bf16 v[38:41], v[172:175], v[196:199], v[38:41]
	v_mfma_f32_16x16x32_bf16 v[34:37], v[180:183], v[196:199], v[34:37]
	v_mfma_f32_16x16x32_bf16 v[22:25], v[172:175], v[204:207], v[22:25]
	v_mfma_f32_16x16x32_bf16 v[18:21], v[180:183], v[204:207], v[18:21]
	v_mfma_f32_16x16x32_bf16 v[6:9], v[172:175], v[212:215], v[6:9]
	v_mfma_f32_16x16x32_bf16 v[2:5], v[180:183], v[212:215], v[2:5]
	s_setprio 0
	s_add_u32 s44, s44, 0x100
	s_addc_u32 s45, s45, 0
	s_add_u32 s36, s36, 0x100
	s_addc_u32 s37, s37, 0
	s_cmp_ge_i32 s80, s57
	s_mov_b32 s38, s80
	s_barrier
	s_cbranch_scc0 .LBB0_1724

; #define PG8_STAGE(bufoff, gbase, voff) do { _Pragma("unroll") for (int _i = 0; _i < 2; ++_i) \
;         __builtin_amdgcn_global_load_lds((const unsigned*)((const char*)(gbase) + (voff)[_i]), (PG8_LAS unsigned*)(lds + (bufoff) + ldsw + _i * 8192), 16, 0, 0); } while (0)
; #define PG8_LDA(dst, b, h) do { _Pragma("unroll") for (int m = 0; m < 4; ++m) _Pragma("unroll") for (int k = 0; k < 2; ++k) dst[m][k] = *(const PG8_LAS bf16x8*)(lds + PG8_SA(b, h) + aoff + m * 2048 + k * 1024); } while (0)
; #define PG8_LDB(dst, b, h) do { _Pragma("unroll") for (int n = 0; n < 2; ++n) _Pragma("unroll") for (int k = 0; k < 2; ++k) dst[n][k] = *(const PG8_LAS bf16x8*)(lds + PG8_SB(b, h) + boff + n * 2048 + k * 1024); } while (0)
; #define PG8_MMA(ai, bj, At, Bt) do { __builtin_amdgcn_s_setprio(1); _Pragma("unroll") for (int m = 0; m < 4; ++m) _Pragma("unroll") for (int n = 0; n < 2; ++n) _Pragma("unroll") for (int k = 0; k < 2; ++k) \
;         acc[ai][bj][m][n] = __builtin_amdgcn_mfma_f32_16x16x32_bf16(Bt[n][k], At[m][k], acc[ai][bj][m][n], 0, 0, 0); __builtin_amdgcn_s_setprio(0); } while (0)
; #define PG8_WAIT_V(n) asm volatile("s_waitcnt vmcnt(" #n ")" ::: "memory")
; #define PG8_WAIT_L(n) asm volatile("s_waitcnt lgkmcnt(" #n ")" ::: "memory")
; template <class Epi, class Sched, bool ALIGN_EPI = false, bool SP2 = false>
; __device__ __forceinline__ void gemm_phase(PG8_LAS unsigned char* lds, const Gemm g, const Sched& S, const Epi& E) {
;     ...
;             const bool last = (t == nt - 2);
;             const char* a1 = cA + (size_t)(t + 1) * kstep;
;             const char* a2 = last ? nA : cA + (size_t)(t + 2) * kstep; const char* b2 = last ? nB : cB + (size_t)(t + 2) * kstep;
;             const char* a3 = a2 + kstep; const char* b3 = b2 + kstep;
;             if (last && has_next) S.a_ready(nxt);
;             if constexpr (SP2) {
;             PG8_LDB(B0, 0, 0); PG8_LDB(B1, 0, 1); PG8_SCHED; PG8_LDA(At, 0, 0); PG8_STAGE(PG8_SA(1, 1), a1 + hstep, voffA);
;             PG8_WAIT_V(8); PG8_WAIT_L(0); PG8_BAR; PG8_MMA(0, 0, At, B0); PG8_MMA(0, 1, At, B1); PG8_BAR; PG8_SCHED;
;             PG8_LDA(At, 0, 1); PG8_STAGE(PG8_SB(0, 0), b2, voffB); PG8_STAGE(PG8_SB(0, 1), b2 + hstep, voffB); PG8_STAGE(PG8_SA(0, 0), a2, voffA);
;             PG8_WAIT_V(8); PG8_WAIT_L(0); PG8_BAR; PG8_MMA(1, 0, At, B0); PG8_MMA(1, 1, At, B1); PG8_BAR; PG8_SCHED;
.LBB0_1809:
	ds_read_b128 v[152:155], v148
	ds_read_b128 v[156:159], v148 offset:1024
	ds_read_b128 v[160:163], v148 offset:2048
	ds_read_b128 v[164:167], v148 offset:3072
	ds_read_b128 v[168:171], v149
	ds_read_b128 v[172:175], v149 offset:1024
	ds_read_b128 v[176:179], v149 offset:2048
	ds_read_b128 v[180:183], v149 offset:3072
	s_add_i32 s56, s26, 2
	s_add_u32 s57, s24, 0x80
	s_addc_u32 s27, s25, 0
	s_cmp_eq_u32 s43, s26
	s_cselect_b32 s26, s4, s57
	s_cselect_b32 s27, s5, s27
	s_cselect_b32 s59, s23, s55
	s_cselect_b32 s58, s22, s54
	v_lshl_add_u64 v[216:217], s[24:25], 0, v[140:141]
	s_add_i32 m0, s35, 0xc000
	ds_read_b128 v[184:187], v150
	ds_read_b128 v[188:191], v150 offset:1024
	ds_read_b128 v[192:195], v150 offset:2048
	ds_read_b128 v[196:199], v150 offset:3072
	ds_read_b128 v[200:203], v150 offset:4096
	ds_read_b128 v[204:207], v150 offset:5120
	ds_read_b128 v[208:211], v150 offset:6144
	ds_read_b128 v[212:215], v150 offset:7168
	global_load_lds_dwordx4 v[216:217], off
	v_lshl_add_u64 v[216:217], s[24:25], 0, v[138:139]
	s_add_i32 m0, s35, 0xe000
	s_nop 0
	global_load_lds_dwordx4 v[216:217], off
	s_waitcnt vmcnt(8)
	s_waitcnt lgkmcnt(0)
	s_barrier
	s_setprio 1
	v_mfma_f32_16x16x32_bf16 v[122:125], v[152:155], v[184:187], v[122:125]
	v_mfma_f32_16x16x32_bf16 v[126:129], v[160:163], v[184:187], v[126:129]
	v_mfma_f32_16x16x32_bf16 v[110:113], v[152:155], v[192:195], v[110:113]
	v_mfma_f32_16x16x32_bf16 v[106:109], v[160:163], v[192:195], v[106:109]
	v_mfma_f32_16x16x32_bf16 v[94:97], v[152:155], v[200:203], v[94:97]
	v_mfma_f32_16x16x32_bf16 v[90:93], v[160:163], v[200:203], v[90:93]
	v_mfma_f32_16x16x32_bf16 v[78:81], v[152:155], v[208:211], v[78:81]
	v_mfma_f32_16x16x32_bf16 v[74:77], v[160:163], v[208:211], v[74:77]
	v_mfma_f32_16x16x32_bf16 v[122:125], v[156:159], v[188:191], v[122:125]
	v_mfma_f32_16x16x32_bf16 v[126:129], v[164:167], v[188:191], v[126:129]
	v_mfma_f32_16x16x32_bf16 v[110:113], v[156:159], v[196:199], v[110:113]
	v_mfma_f32_16x16x32_bf16 v[106:109], v[164:167], v[196:199], v[106:109]
	v_mfma_f32_16x16x32_bf16 v[94:97], v[156:159], v[204:207], v[94:97]
	v_mfma_f32_16x16x32_bf16 v[90:93], v[164:167], v[204:207], v[90:93]
	v_mfma_f32_16x16x32_bf16 v[78:81], v[156:159], v[212:215], v[78:81]
	v_mfma_f32_16x16x32_bf16 v[74:77], v[164:167], v[212:215], v[74:77]
	v_mfma_f32_16x16x32_bf16 v[118:121], v[168:171], v[184:187], v[118:121]
	v_mfma_f32_16x16x32_bf16 v[114:117], v[176:179], v[184:187], v[114:117]
	v_mfma_f32_16x16x32_bf16 v[102:105], v[168:171], v[192:195], v[102:105]
	v_mfma_f32_16x16x32_bf16 v[98:101], v[176:179], v[192:195], v[98:101]
	v_mfma_f32_16x16x32_bf16 v[86:89], v[168:171], v[200:203], v[86:89]
	v_mfma_f32_16x16x32_bf16 v[82:85], v[176:179], v[200:203], v[82:85]
	v_mfma_f32_16x16x32_bf16 v[70:73], v[168:171], v[208:211], v[70:73]
	v_mfma_f32_16x16x32_bf16 v[66:69], v[176:179], v[208:211], v[66:69]
	v_mfma_f32_16x16x32_bf16 v[118:121], v[172:175], v[188:191], v[118:121]
	v_mfma_f32_16x16x32_bf16 v[114:117], v[180:183], v[188:191], v[114:117]
	v_mfma_f32_16x16x32_bf16 v[102:105], v[172:175], v[196:199], v[102:105]
	v_mfma_f32_16x16x32_bf16 v[98:101], v[180:183], v[196:199], v[98:101]
	v_mfma_f32_16x16x32_bf16 v[86:89], v[172:175], v[204:207], v[86:89]
	v_mfma_f32_16x16x32_bf16 v[82:85], v[180:183], v[204:207], v[82:85]
	v_mfma_f32_16x16x32_bf16 v[70:73], v[172:175], v[212:215], v[70:73]
	v_mfma_f32_16x16x32_bf16 v[66:69], v[180:183], v[212:215], v[66:69]
	s_setprio 0
	s_barrier
	s_add_i32 s57, s46, s34
	v_lshl_add_u64 v[216:217], s[58:59], 0, v[132:133]
	s_mov_b32 m0, s57
	ds_read_b128 v[184:187], v150 offset:16384
	ds_read_b128 v[188:191], v150 offset:17408
	ds_read_b128 v[192:195], v150 offset:18432
	ds_read_b128 v[196:199], v150 offset:19456
	ds_read_b128 v[200:203], v150 offset:20480
	ds_read_b128 v[204:207], v150 offset:21504
	ds_read_b128 v[208:211], v150 offset:22528
	ds_read_b128 v[212:215], v150 offset:23552
	global_load_lds_dwordx4 v[216:217], off
	s_add_i32 m0, s57, 0x2000
	v_lshl_add_u64 v[218:219], s[58:59], 0, v[136:137]
	s_add_u32 s58, s58, s8
	s_addc_u32 s59, s59, s9
	s_add_i32 s57, s47, s34
	global_load_lds_dwordx4 v[218:219], off
	v_lshl_add_u64 v[220:221], s[58:59], 0, v[132:133]
	s_mov_b32 m0, s57
	v_lshl_add_u64 v[222:223], s[58:59], 0, v[136:137]
	global_load_lds_dwordx4 v[220:221], off
	s_add_i32 m0, s57, 0x2000
	v_lshl_add_u64 v[224:225], s[26:27], 0, v[130:131]
	global_load_lds_dwordx4 v[222:223], off
	s_mov_b32 m0, s35
	v_lshl_add_u64 v[226:227], s[26:27], 0, v[134:135]
	global_load_lds_dwordx4 v[224:225], off
	s_mov_b32 m0, s36
	s_nop 0
	global_load_lds_dwordx4 v[226:227], off
	s_waitcnt vmcnt(8)
	s_waitcnt lgkmcnt(0)
	s_barrier
; #define PG8_STAGE(bufoff, gbase, voff) do { _Pragma("unroll") for (int _i = 0; _i < 2; ++_i) \
;         __builtin_amdgcn_global_load_lds((const unsigned*)((const char*)(gbase) + (voff)[_i]), (PG8_LAS unsigned*)(lds + (bufoff) + ldsw + _i * 8192), 16, 0, 0); } while (0)
; #define PG8_LDA(dst, b, h) do { _Pragma("unroll") for (int m = 0; m < 4; ++m) _Pragma("unroll") for (int k = 0; k < 2; ++k) dst[m][k] = *(const PG8_LAS bf16x8*)(lds + PG8_SA(b, h) + aoff + m * 2048 + k * 1024); } while (0)
; #define PG8_LDB(dst, b, h) do { _Pragma("unroll") for (int n = 0; n < 2; ++n) _Pragma("unroll") for (int k = 0; k < 2; ++k) dst[n][k] = *(const PG8_LAS bf16x8*)(lds + PG8_SB(b, h) + boff + n * 2048 + k * 1024); } while (0)
; #define PG8_MMA(ai, bj, At, Bt) do { __builtin_amdgcn_s_setprio(1); _Pragma("unroll") for (int m = 0; m < 4; ++m) _Pragma("unroll") for (int n = 0; n < 2; ++n) _Pragma("unroll") for (int k = 0; k < 2; ++k) \
;         acc[ai][bj][m][n] = __builtin_amdgcn_mfma_f32_16x16x32_bf16(Bt[n][k], At[m][k], acc[ai][bj][m][n], 0, 0, 0); __builtin_amdgcn_s_setprio(0); } while (0)
; #define PG8_WAIT_V(n) asm volatile("s_waitcnt vmcnt(" #n ")" ::: "memory")
; #define PG8_WAIT_L(n) asm volatile("s_waitcnt lgkmcnt(" #n ")" ::: "memory")
; #define PG8_BAR __builtin_amdgcn_s_barrier()
; #define PG8_SCHED __builtin_amdgcn_sched_barrier(0)
; template <class Epi, class Sched, bool ALIGN_EPI = false, bool SP2 = false>
; __device__ __forceinline__ void gemm_phase(PG8_LAS unsigned char* lds, const Gemm g, const Sched& S, const Epi& E) {
;     ...
;             PG8_WAIT_V(8); PG8_WAIT_L(0); PG8_BAR; PG8_MMA(1, 0, At, B0); PG8_MMA(1, 1, At, B1); PG8_BAR; PG8_SCHED;
;             PG8_LDB(B0, 1, 0); PG8_LDB(B1, 1, 1); PG8_SCHED; PG8_LDA(At, 1, 0); PG8_STAGE(PG8_SA(0, 1), a2 + hstep, voffA);
;             PG8_WAIT_V(8); PG8_WAIT_L(0); PG8_BAR; PG8_MMA(0, 0, At, B0); PG8_MMA(0, 1, At, B1); PG8_BAR; PG8_SCHED;
	s_setprio 1
	v_mfma_f32_16x16x32_bf16 v[62:65], v[152:155], v[184:187], v[62:65]
	v_mfma_f32_16x16x32_bf16 v[58:61], v[160:163], v[184:187], v[58:61]
	v_mfma_f32_16x16x32_bf16 v[46:49], v[152:155], v[192:195], v[46:49]
	v_mfma_f32_16x16x32_bf16 v[42:45], v[160:163], v[192:195], v[42:45]
	v_mfma_f32_16x16x32_bf16 v[30:33], v[152:155], v[200:203], v[30:33]
	v_mfma_f32_16x16x32_bf16 v[26:29], v[160:163], v[200:203], v[26:29]
	v_mfma_f32_16x16x32_bf16 v[14:17], v[152:155], v[208:211], v[14:17]
	v_mfma_f32_16x16x32_bf16 v[10:13], v[160:163], v[208:211], v[10:13]
	v_mfma_f32_16x16x32_bf16 v[62:65], v[156:159], v[188:191], v[62:65]
	v_mfma_f32_16x16x32_bf16 v[58:61], v[164:167], v[188:191], v[58:61]
	v_mfma_f32_16x16x32_bf16 v[46:49], v[156:159], v[196:199], v[46:49]
	v_mfma_f32_16x16x32_bf16 v[42:45], v[164:167], v[196:199], v[42:45]
	v_mfma_f32_16x16x32_bf16 v[30:33], v[156:159], v[204:207], v[30:33]
	v_mfma_f32_16x16x32_bf16 v[26:29], v[164:167], v[204:207], v[26:29]
	v_mfma_f32_16x16x32_bf16 v[14:17], v[156:159], v[212:215], v[14:17]
	v_mfma_f32_16x16x32_bf16 v[10:13], v[164:167], v[212:215], v[10:13]
	v_mfma_f32_16x16x32_bf16 v[54:57], v[168:171], v[184:187], v[54:57]
	v_mfma_f32_16x16x32_bf16 v[50:53], v[176:179], v[184:187], v[50:53]
	v_mfma_f32_16x16x32_bf16 v[38:41], v[168:171], v[192:195], v[38:41]
	v_mfma_f32_16x16x32_bf16 v[34:37], v[176:179], v[192:195], v[34:37]
	v_mfma_f32_16x16x32_bf16 v[22:25], v[168:171], v[200:203], v[22:25]
	v_mfma_f32_16x16x32_bf16 v[18:21], v[176:179], v[200:203], v[18:21]
	v_mfma_f32_16x16x32_bf16 v[6:9], v[168:171], v[208:211], v[6:9]
	v_mfma_f32_16x16x32_bf16 v[2:5], v[176:179], v[208:211], v[2:5]
	v_mfma_f32_16x16x32_bf16 v[54:57], v[172:175], v[188:191], v[54:57]
	v_mfma_f32_16x16x32_bf16 v[50:53], v[180:183], v[188:191], v[50:53]
	v_mfma_f32_16x16x32_bf16 v[38:41], v[172:175], v[196:199], v[38:41]
	v_mfma_f32_16x16x32_bf16 v[34:37], v[180:183], v[196:199], v[34:37]
	v_mfma_f32_16x16x32_bf16 v[22:25], v[172:175], v[204:207], v[22:25]
	v_mfma_f32_16x16x32_bf16 v[18:21], v[180:183], v[204:207], v[18:21]
	v_mfma_f32_16x16x32_bf16 v[6:9], v[172:175], v[212:215], v[6:9]
	v_mfma_f32_16x16x32_bf16 v[2:5], v[180:183], v[212:215], v[2:5]
	s_setprio 0
	s_barrier
	s_add_i32 s57, 0, 0x18000
	v_add_u32_e32 v151, s57, v146
	s_add_i32 s58, 0, 0x1c000
	ds_read_b128 v[152:155], v151
	ds_read_b128 v[156:159], v151 offset:1024
	ds_read_b128 v[160:163], v151 offset:2048
	ds_read_b128 v[164:167], v151 offset:3072
	v_add_u32_e32 v151, s58, v146
	ds_read_b128 v[168:171], v151
	ds_read_b128 v[172:175], v151 offset:1024
	ds_read_b128 v[176:179], v151 offset:2048
	ds_read_b128 v[180:183], v151 offset:3072
	s_add_u32 s26, s26, s8
	s_addc_u32 s27, s27, s9
	s_mov_b32 m0, s37
	v_lshl_add_u64 v[228:229], s[26:27], 0, v[130:131]
	ds_read_b128 v[184:187], v150 offset:32768
	ds_read_b128 v[188:191], v150 offset:33792
	ds_read_b128 v[192:195], v150 offset:34816
	ds_read_b128 v[196:199], v150 offset:35840
	ds_read_b128 v[200:203], v150 offset:36864
	ds_read_b128 v[204:207], v150 offset:37888
	ds_read_b128 v[208:211], v150 offset:38912
	ds_read_b128 v[212:215], v150 offset:39936
	global_load_lds_dwordx4 v[228:229], off
	v_lshl_add_u64 v[228:229], s[26:27], 0, v[134:135]
	s_mov_b32 m0, s38
	s_nop 0
	global_load_lds_dwordx4 v[228:229], off
	s_waitcnt vmcnt(8)
	s_waitcnt lgkmcnt(0)
	s_barrier
	s_setprio 1
	v_mfma_f32_16x16x32_bf16 v[122:125], v[152:155], v[184:187], v[122:125]
	v_mfma_f32_16x16x32_bf16 v[126:129], v[160:163], v[184:187], v[126:129]
	v_mfma_f32_16x16x32_bf16 v[110:113], v[152:155], v[192:195], v[110:113]
	v_mfma_f32_16x16x32_bf16 v[106:109], v[160:163], v[192:195], v[106:109]
	v_mfma_f32_16x16x32_bf16 v[94:97], v[152:155], v[200:203], v[94:97]
	v_mfma_f32_16x16x32_bf16 v[90:93], v[160:163], v[200:203], v[90:93]
	v_mfma_f32_16x16x32_bf16 v[78:81], v[152:155], v[208:211], v[78:81]
	v_mfma_f32_16x16x32_bf16 v[74:77], v[160:163], v[208:211], v[74:77]
	v_mfma_f32_16x16x32_bf16 v[122:125], v[156:159], v[188:191], v[122:125]
	v_mfma_f32_16x16x32_bf16 v[126:129], v[164:167], v[188:191], v[126:129]
	v_mfma_f32_16x16x32_bf16 v[110:113], v[156:159], v[196:199], v[110:113]
	v_mfma_f32_16x16x32_bf16 v[106:109], v[164:167], v[196:199], v[106:109]
	v_mfma_f32_16x16x32_bf16 v[94:97], v[156:159], v[204:207], v[94:97]
	v_mfma_f32_16x16x32_bf16 v[90:93], v[164:167], v[204:207], v[90:93]
	v_mfma_f32_16x16x32_bf16 v[78:81], v[156:159], v[212:215], v[78:81]
	v_mfma_f32_16x16x32_bf16 v[74:77], v[164:167], v[212:215], v[74:77]
	v_mfma_f32_16x16x32_bf16 v[118:121], v[168:171], v[184:187], v[118:121]
	v_mfma_f32_16x16x32_bf16 v[114:117], v[176:179], v[184:187], v[114:117]
	v_mfma_f32_16x16x32_bf16 v[102:105], v[168:171], v[192:195], v[102:105]
	v_mfma_f32_16x16x32_bf16 v[98:101], v[176:179], v[192:195], v[98:101]
	v_mfma_f32_16x16x32_bf16 v[86:89], v[168:171], v[200:203], v[86:89]
	v_mfma_f32_16x16x32_bf16 v[82:85], v[176:179], v[200:203], v[82:85]
	v_mfma_f32_16x16x32_bf16 v[70:73], v[168:171], v[208:211], v[70:73]
	v_mfma_f32_16x16x32_bf16 v[66:69], v[176:179], v[208:211], v[66:69]
	v_mfma_f32_16x16x32_bf16 v[118:121], v[172:175], v[188:191], v[118:121]
	v_mfma_f32_16x16x32_bf16 v[114:117], v[180:183], v[188:191], v[114:117]
	v_mfma_f32_16x16x32_bf16 v[102:105], v[172:175], v[196:199], v[102:105]
	v_mfma_f32_16x16x32_bf16 v[98:101], v[180:183], v[196:199], v[98:101]
	v_mfma_f32_16x16x32_bf16 v[86:89], v[172:175], v[204:207], v[86:89]
	v_mfma_f32_16x16x32_bf16 v[82:85], v[180:183], v[204:207], v[82:85]
	v_mfma_f32_16x16x32_bf16 v[70:73], v[172:175], v[212:215], v[70:73]
	v_mfma_f32_16x16x32_bf16 v[66:69], v[180:183], v[212:215], v[66:69]
	s_setprio 0
	s_barrier
; #define PG8_STAGE(bufoff, gbase, voff) do { _Pragma("unroll") for (int _i = 0; _i < 2; ++_i) \
;         __builtin_amdgcn_global_load_lds((const unsigned*)((const char*)(gbase) + (voff)[_i]), (PG8_LAS unsigned*)(lds + (bufoff) + ldsw + _i * 8192), 16, 0, 0); } while (0)
; #define PG8_LDA(dst, b, h) do { _Pragma("unroll") for (int m = 0; m < 4; ++m) _Pragma("unroll") for (int k = 0; k < 2; ++k) dst[m][k] = *(const PG8_LAS bf16x8*)(lds + PG8_SA(b, h) + aoff + m * 2048 + k * 1024); } while (0)
; #define PG8_MMA(ai, bj, At, Bt) do { __builtin_amdgcn_s_setprio(1); _Pragma("unroll") for (int m = 0; m < 4; ++m) _Pragma("unroll") for (int n = 0; n < 2; ++n) _Pragma("unroll") for (int k = 0; k < 2; ++k) \
;         acc[ai][bj][m][n] = __builtin_amdgcn_mfma_f32_16x16x32_bf16(Bt[n][k], At[m][k], acc[ai][bj][m][n], 0, 0, 0); __builtin_amdgcn_s_setprio(0); } while (0)
; #define PG8_WAIT_V(n) asm volatile("s_waitcnt vmcnt(" #n ")" ::: "memory")
; #define PG8_WAIT_L(n) asm volatile("s_waitcnt lgkmcnt(" #n ")" ::: "memory")
; #define PG8_BAR __builtin_amdgcn_s_barrier()
; #define PG8_SCHED __builtin_amdgcn_sched_barrier(0)
; template <class Epi, class Sched, bool ALIGN_EPI = false, bool SP2 = false>
; __device__ __forceinline__ void gemm_phase(PG8_LAS unsigned char* lds, const Gemm g, const Sched& S, const Epi& E) {
;     ...
;         for (int t = 0; t < nt; t += 2) {
;             const bool last = (t == nt - 2);
;             const char* a1 = cA + (size_t)(t + 1) * kstep;
;             const char* a2 = last ? nA : cA + (size_t)(t + 2) * kstep; const char* b2 = last ? nB : cB + (size_t)(t + 2) * kstep;
;             const char* a3 = a2 + kstep; const char* b3 = b2 + kstep;
;     ...
;             PG8_LDA(At, 1, 1); PG8_STAGE(PG8_SB(1, 0), b3, voffB); PG8_STAGE(PG8_SB(1, 1), b3 + hstep, voffB); PG8_STAGE(PG8_SA(1, 0), a3, voffA);
;             PG8_WAIT_V(8); PG8_WAIT_L(0); PG8_BAR; PG8_MMA(1, 0, At, B0); PG8_MMA(1, 1, At, B1); PG8_BAR; PG8_SCHED;
	s_add_i32 s26, s57, s34
	v_lshl_add_u64 v[216:217], v[216:217], 0, s[16:17]
	s_mov_b32 m0, s26
	ds_read_b128 v[184:187], v150 offset:49152
	ds_read_b128 v[188:191], v150 offset:50176
	ds_read_b128 v[192:195], v150 offset:51200
	ds_read_b128 v[196:199], v150 offset:52224
	ds_read_b128 v[200:203], v150 offset:53248
	ds_read_b128 v[204:207], v150 offset:54272
	ds_read_b128 v[208:211], v150 offset:55296
	ds_read_b128 v[212:215], v150 offset:56320
	global_load_lds_dwordx4 v[216:217], off
	v_lshl_add_u64 v[216:217], v[218:219], 0, s[16:17]
	s_add_i32 m0, s26, 0x2000
	s_add_i32 s26, s58, s34
	global_load_lds_dwordx4 v[216:217], off
	v_lshl_add_u64 v[216:217], v[220:221], 0, s[16:17]
	s_mov_b32 m0, s26
	s_nop 0
	global_load_lds_dwordx4 v[216:217], off
	v_lshl_add_u64 v[216:217], v[222:223], 0, s[16:17]
	s_add_i32 m0, s26, 0x2000
	s_nop 0
	global_load_lds_dwordx4 v[216:217], off
	v_lshl_add_u64 v[216:217], v[224:225], 0, s[16:17]
	s_mov_b32 m0, s40
	s_nop 0
	global_load_lds_dwordx4 v[216:217], off
	v_lshl_add_u64 v[216:217], v[226:227], 0, s[16:17]
	s_mov_b32 m0, s41
	s_nop 0
	global_load_lds_dwordx4 v[216:217], off
	s_waitcnt vmcnt(8)
	s_waitcnt lgkmcnt(0)
	s_barrier
	s_setprio 1
	v_mfma_f32_16x16x32_bf16 v[62:65], v[152:155], v[184:187], v[62:65]
	v_mfma_f32_16x16x32_bf16 v[58:61], v[160:163], v[184:187], v[58:61]
	v_mfma_f32_16x16x32_bf16 v[46:49], v[152:155], v[192:195], v[46:49]
	v_mfma_f32_16x16x32_bf16 v[42:45], v[160:163], v[192:195], v[42:45]
	v_mfma_f32_16x16x32_bf16 v[30:33], v[152:155], v[200:203], v[30:33]
	v_mfma_f32_16x16x32_bf16 v[26:29], v[160:163], v[200:203], v[26:29]
	v_mfma_f32_16x16x32_bf16 v[14:17], v[152:155], v[208:211], v[14:17]
	v_mfma_f32_16x16x32_bf16 v[10:13], v[160:163], v[208:211], v[10:13]
	v_mfma_f32_16x16x32_bf16 v[62:65], v[156:159], v[188:191], v[62:65]
	v_mfma_f32_16x16x32_bf16 v[58:61], v[164:167], v[188:191], v[58:61]
	v_mfma_f32_16x16x32_bf16 v[46:49], v[156:159], v[196:199], v[46:49]
	v_mfma_f32_16x16x32_bf16 v[42:45], v[164:167], v[196:199], v[42:45]
	v_mfma_f32_16x16x32_bf16 v[30:33], v[156:159], v[204:207], v[30:33]
	v_mfma_f32_16x16x32_bf16 v[26:29], v[164:167], v[204:207], v[26:29]
	v_mfma_f32_16x16x32_bf16 v[14:17], v[156:159], v[212:215], v[14:17]
	v_mfma_f32_16x16x32_bf16 v[10:13], v[164:167], v[212:215], v[10:13]
	v_mfma_f32_16x16x32_bf16 v[54:57], v[168:171], v[184:187], v[54:57]
	v_mfma_f32_16x16x32_bf16 v[50:53], v[176:179], v[184:187], v[50:53]
	v_mfma_f32_16x16x32_bf16 v[38:41], v[168:171], v[192:195], v[38:41]
	v_mfma_f32_16x16x32_bf16 v[34:37], v[176:179], v[192:195], v[34:37]
	v_mfma_f32_16x16x32_bf16 v[22:25], v[168:171], v[200:203], v[22:25]
	v_mfma_f32_16x16x32_bf16 v[18:21], v[176:179], v[200:203], v[18:21]
	v_mfma_f32_16x16x32_bf16 v[6:9], v[168:171], v[208:211], v[6:9]
	v_mfma_f32_16x16x32_bf16 v[2:5], v[176:179], v[208:211], v[2:5]
	v_mfma_f32_16x16x32_bf16 v[54:57], v[172:175], v[188:191], v[54:57]
	v_mfma_f32_16x16x32_bf16 v[50:53], v[180:183], v[188:191], v[50:53]
	v_mfma_f32_16x16x32_bf16 v[38:41], v[172:175], v[196:199], v[38:41]
	v_mfma_f32_16x16x32_bf16 v[34:37], v[180:183], v[196:199], v[34:37]
	v_mfma_f32_16x16x32_bf16 v[22:25], v[172:175], v[204:207], v[22:25]
	v_mfma_f32_16x16x32_bf16 v[18:21], v[180:183], v[204:207], v[18:21]
	v_mfma_f32_16x16x32_bf16 v[6:9], v[172:175], v[212:215], v[6:9]
	v_mfma_f32_16x16x32_bf16 v[2:5], v[180:183], v[212:215], v[2:5]
	s_setprio 0
	s_add_u32 s54, s54, 0x100
	s_addc_u32 s55, s55, 0
	s_add_u32 s24, s24, 0x100
	s_addc_u32 s25, s25, 0
	s_cmp_ge_i32 s56, s42
	s_mov_b32 s26, s56
	s_barrier
	s_cbranch_scc0 .LBB0_1809

; #define PG8_STAGE(bufoff, gbase, voff) do { _Pragma("unroll") for (int _i = 0; _i < 2; ++_i) \
;         __builtin_amdgcn_global_load_lds((const unsigned*)((const char*)(gbase) + (voff)[_i]), (PG8_LAS unsigned*)(lds + (bufoff) + ldsw + _i * 8192), 16, 0, 0); } while (0)
; #define PG8_LDA(dst, b, h) do { _Pragma("unroll") for (int m = 0; m < 4; ++m) _Pragma("unroll") for (int k = 0; k < 2; ++k) dst[m][k] = *(const PG8_LAS bf16x8*)(lds + PG8_SA(b, h) + aoff + m * 2048 + k * 1024); } while (0)
; #define PG8_LDB(dst, b, h) do { _Pragma("unroll") for (int n = 0; n < 2; ++n) _Pragma("unroll") for (int k = 0; k < 2; ++k) dst[n][k] = *(const PG8_LAS bf16x8*)(lds + PG8_SB(b, h) + boff + n * 2048 + k * 1024); } while (0)
; #define PG8_MMA(ai, bj, At, Bt) do { __builtin_amdgcn_s_setprio(1); _Pragma("unroll") for (int m = 0; m < 4; ++m) _Pragma("unroll") for (int n = 0; n < 2; ++n) _Pragma("unroll") for (int k = 0; k < 2; ++k) \
;         acc[ai][bj][m][n] = __builtin_amdgcn_mfma_f32_16x16x32_bf16(Bt[n][k], At[m][k], acc[ai][bj][m][n], 0, 0, 0); __builtin_amdgcn_s_setprio(0); } while (0)
; #define PG8_WAIT_V(n) asm volatile("s_waitcnt vmcnt(" #n ")" ::: "memory")
; #define PG8_WAIT_L(n) asm volatile("s_waitcnt lgkmcnt(" #n ")" ::: "memory")
; template <class Epi, class Sched, bool ALIGN_EPI = false, bool SP2 = false>
; __device__ __forceinline__ void gemm_phase(PG8_LAS unsigned char* lds, const Gemm g, const Sched& S, const Epi& E) {
;     ...
;             const bool last = (t == nt - 2);
;             const char* a1 = cA + (size_t)(t + 1) * kstep;
;             const char* a2 = last ? nA : cA + (size_t)(t + 2) * kstep; const char* b2 = last ? nB : cB + (size_t)(t + 2) * kstep;
;             const char* a3 = a2 + kstep; const char* b3 = b2 + kstep;
;             if (last && has_next) S.a_ready(nxt);
;             if constexpr (SP2) {
;             PG8_LDB(B0, 0, 0); PG8_LDB(B1, 0, 1); PG8_SCHED; PG8_LDA(At, 0, 0); PG8_STAGE(PG8_SA(1, 1), a1 + hstep, voffA);
;             PG8_WAIT_V(8); PG8_WAIT_L(0); PG8_BAR; PG8_MMA(0, 0, At, B0); PG8_MMA(0, 1, At, B1); PG8_BAR; PG8_SCHED;
;             PG8_LDA(At, 0, 1); PG8_STAGE(PG8_SB(0, 0), b2, voffB); PG8_STAGE(PG8_SB(0, 1), b2 + hstep, voffB); PG8_STAGE(PG8_SA(0, 0), a2, voffA);
;             PG8_WAIT_V(8); PG8_WAIT_L(0); PG8_BAR; PG8_MMA(1, 0, At, B0); PG8_MMA(1, 1, At, B1); PG8_BAR; PG8_SCHED;
.LBB0_1976:
	ds_read_b128 v[152:155], v148
	ds_read_b128 v[156:159], v148 offset:1024
	ds_read_b128 v[160:163], v148 offset:2048
	ds_read_b128 v[164:167], v148 offset:3072
	ds_read_b128 v[168:171], v149
	ds_read_b128 v[172:175], v149 offset:1024
	ds_read_b128 v[176:179], v149 offset:2048
	ds_read_b128 v[180:183], v149 offset:3072
	s_add_i32 s58, s26, 2
	s_add_u32 s59, s24, 0x80
	s_addc_u32 s27, s25, 0
	s_cmp_eq_u32 s44, s26
	s_cselect_b32 s26, s4, s59
	s_cselect_b32 s27, s5, s27
	s_cselect_b32 s61, s23, s57
	s_cselect_b32 s60, s22, s56
	v_lshl_add_u64 v[216:217], s[24:25], 0, v[140:141]
	s_add_i32 m0, s36, 0xc000
	ds_read_b128 v[184:187], v150
	ds_read_b128 v[188:191], v150 offset:1024
	ds_read_b128 v[192:195], v150 offset:2048
	ds_read_b128 v[196:199], v150 offset:3072
	ds_read_b128 v[200:203], v150 offset:4096
	ds_read_b128 v[204:207], v150 offset:5120
	ds_read_b128 v[208:211], v150 offset:6144
	ds_read_b128 v[212:215], v150 offset:7168
	global_load_lds_dwordx4 v[216:217], off
	v_lshl_add_u64 v[216:217], s[24:25], 0, v[138:139]
	s_add_i32 m0, s36, 0xe000
	s_nop 0
	global_load_lds_dwordx4 v[216:217], off
	s_waitcnt vmcnt(8)
	s_waitcnt lgkmcnt(0)
	s_barrier
	s_setprio 1
	v_mfma_f32_16x16x32_bf16 v[122:125], v[152:155], v[184:187], v[122:125]
	v_mfma_f32_16x16x32_bf16 v[118:121], v[160:163], v[184:187], v[118:121]
	v_mfma_f32_16x16x32_bf16 v[110:113], v[152:155], v[192:195], v[110:113]
	v_mfma_f32_16x16x32_bf16 v[102:105], v[160:163], v[192:195], v[102:105]
	v_mfma_f32_16x16x32_bf16 v[94:97], v[152:155], v[200:203], v[94:97]
	v_mfma_f32_16x16x32_bf16 v[86:89], v[160:163], v[200:203], v[86:89]
	v_mfma_f32_16x16x32_bf16 v[78:81], v[152:155], v[208:211], v[78:81]
	v_mfma_f32_16x16x32_bf16 v[70:73], v[160:163], v[208:211], v[70:73]
	v_mfma_f32_16x16x32_bf16 v[122:125], v[156:159], v[188:191], v[122:125]
	v_mfma_f32_16x16x32_bf16 v[118:121], v[164:167], v[188:191], v[118:121]
	v_mfma_f32_16x16x32_bf16 v[110:113], v[156:159], v[196:199], v[110:113]
	v_mfma_f32_16x16x32_bf16 v[102:105], v[164:167], v[196:199], v[102:105]
	v_mfma_f32_16x16x32_bf16 v[94:97], v[156:159], v[204:207], v[94:97]
	v_mfma_f32_16x16x32_bf16 v[86:89], v[164:167], v[204:207], v[86:89]
	v_mfma_f32_16x16x32_bf16 v[78:81], v[156:159], v[212:215], v[78:81]
	v_mfma_f32_16x16x32_bf16 v[70:73], v[164:167], v[212:215], v[70:73]
	v_mfma_f32_16x16x32_bf16 v[126:129], v[168:171], v[184:187], v[126:129]
	v_mfma_f32_16x16x32_bf16 v[114:117], v[176:179], v[184:187], v[114:117]
	v_mfma_f32_16x16x32_bf16 v[106:109], v[168:171], v[192:195], v[106:109]
	v_mfma_f32_16x16x32_bf16 v[98:101], v[176:179], v[192:195], v[98:101]
	v_mfma_f32_16x16x32_bf16 v[90:93], v[168:171], v[200:203], v[90:93]
	v_mfma_f32_16x16x32_bf16 v[82:85], v[176:179], v[200:203], v[82:85]
	v_mfma_f32_16x16x32_bf16 v[74:77], v[168:171], v[208:211], v[74:77]
	v_mfma_f32_16x16x32_bf16 v[66:69], v[176:179], v[208:211], v[66:69]
	v_mfma_f32_16x16x32_bf16 v[126:129], v[172:175], v[188:191], v[126:129]
	v_mfma_f32_16x16x32_bf16 v[114:117], v[180:183], v[188:191], v[114:117]
	v_mfma_f32_16x16x32_bf16 v[106:109], v[172:175], v[196:199], v[106:109]
	v_mfma_f32_16x16x32_bf16 v[98:101], v[180:183], v[196:199], v[98:101]
	v_mfma_f32_16x16x32_bf16 v[90:93], v[172:175], v[204:207], v[90:93]
	v_mfma_f32_16x16x32_bf16 v[82:85], v[180:183], v[204:207], v[82:85]
	v_mfma_f32_16x16x32_bf16 v[74:77], v[172:175], v[212:215], v[74:77]
	v_mfma_f32_16x16x32_bf16 v[66:69], v[180:183], v[212:215], v[66:69]
	s_setprio 0
	s_barrier
	s_add_i32 s59, s47, s31
	v_lshl_add_u64 v[216:217], s[60:61], 0, v[134:135]
	s_mov_b32 m0, s59
	ds_read_b128 v[184:187], v150 offset:16384
	ds_read_b128 v[188:191], v150 offset:17408
	ds_read_b128 v[192:195], v150 offset:18432
	ds_read_b128 v[196:199], v150 offset:19456
	ds_read_b128 v[200:203], v150 offset:20480
	ds_read_b128 v[204:207], v150 offset:21504
	ds_read_b128 v[208:211], v150 offset:22528
	ds_read_b128 v[212:215], v150 offset:23552
	global_load_lds_dwordx4 v[216:217], off
	s_add_i32 m0, s59, 0x2000
	v_lshl_add_u64 v[218:219], s[60:61], 0, v[130:131]
	s_add_u32 s60, s60, s8
	s_addc_u32 s61, s61, s9
	s_add_i32 s59, s48, s31
	global_load_lds_dwordx4 v[218:219], off
	v_lshl_add_u64 v[220:221], s[60:61], 0, v[134:135]
	s_mov_b32 m0, s59
	v_lshl_add_u64 v[222:223], s[60:61], 0, v[130:131]
	global_load_lds_dwordx4 v[220:221], off
	s_add_i32 m0, s59, 0x2000
	v_lshl_add_u64 v[224:225], s[26:27], 0, v[136:137]
	global_load_lds_dwordx4 v[222:223], off
	s_mov_b32 m0, s36
	v_lshl_add_u64 v[226:227], s[26:27], 0, v[132:133]
	global_load_lds_dwordx4 v[224:225], off
	s_mov_b32 m0, s37
	s_nop 0
	global_load_lds_dwordx4 v[226:227], off
	s_waitcnt vmcnt(8)
	s_waitcnt lgkmcnt(0)
	s_barrier
; #define PG8_STAGE(bufoff, gbase, voff) do { _Pragma("unroll") for (int _i = 0; _i < 2; ++_i) \
;         __builtin_amdgcn_global_load_lds((const unsigned*)((const char*)(gbase) + (voff)[_i]), (PG8_LAS unsigned*)(lds + (bufoff) + ldsw + _i * 8192), 16, 0, 0); } while (0)
; #define PG8_LDA(dst, b, h) do { _Pragma("unroll") for (int m = 0; m < 4; ++m) _Pragma("unroll") for (int k = 0; k < 2; ++k) dst[m][k] = *(const PG8_LAS bf16x8*)(lds + PG8_SA(b, h) + aoff + m * 2048 + k * 1024); } while (0)
; #define PG8_LDB(dst, b, h) do { _Pragma("unroll") for (int n = 0; n < 2; ++n) _Pragma("unroll") for (int k = 0; k < 2; ++k) dst[n][k] = *(const PG8_LAS bf16x8*)(lds + PG8_SB(b, h) + boff + n * 2048 + k * 1024); } while (0)
; #define PG8_MMA(ai, bj, At, Bt) do { __builtin_amdgcn_s_setprio(1); _Pragma("unroll") for (int m = 0; m < 4; ++m) _Pragma("unroll") for (int n = 0; n < 2; ++n) _Pragma("unroll") for (int k = 0; k < 2; ++k) \
;         acc[ai][bj][m][n] = __builtin_amdgcn_mfma_f32_16x16x32_bf16(Bt[n][k], At[m][k], acc[ai][bj][m][n], 0, 0, 0); __builtin_amdgcn_s_setprio(0); } while (0)
; #define PG8_WAIT_V(n) asm volatile("s_waitcnt vmcnt(" #n ")" ::: "memory")
; #define PG8_WAIT_L(n) asm volatile("s_waitcnt lgkmcnt(" #n ")" ::: "memory")
; #define PG8_BAR __builtin_amdgcn_s_barrier()
; #define PG8_SCHED __builtin_amdgcn_sched_barrier(0)
; template <class Epi, class Sched, bool ALIGN_EPI = false, bool SP2 = false>
; __device__ __forceinline__ void gemm_phase(PG8_LAS unsigned char* lds, const Gemm g, const Sched& S, const Epi& E) {
;     ...
;             PG8_WAIT_V(8); PG8_WAIT_L(0); PG8_BAR; PG8_MMA(1, 0, At, B0); PG8_MMA(1, 1, At, B1); PG8_BAR; PG8_SCHED;
;             PG8_LDB(B0, 1, 0); PG8_LDB(B1, 1, 1); PG8_SCHED; PG8_LDA(At, 1, 0); PG8_STAGE(PG8_SA(0, 1), a2 + hstep, voffA);
;             PG8_WAIT_V(8); PG8_WAIT_L(0); PG8_BAR; PG8_MMA(0, 0, At, B0); PG8_MMA(0, 1, At, B1); PG8_BAR; PG8_SCHED;
	s_setprio 1
	v_mfma_f32_16x16x32_bf16 v[62:65], v[152:155], v[184:187], v[62:65]
	v_mfma_f32_16x16x32_bf16 v[54:57], v[160:163], v[184:187], v[54:57]
	v_mfma_f32_16x16x32_bf16 v[46:49], v[152:155], v[192:195], v[46:49]
	v_mfma_f32_16x16x32_bf16 v[38:41], v[160:163], v[192:195], v[38:41]
	v_mfma_f32_16x16x32_bf16 v[30:33], v[152:155], v[200:203], v[30:33]
	v_mfma_f32_16x16x32_bf16 v[22:25], v[160:163], v[200:203], v[22:25]
	v_mfma_f32_16x16x32_bf16 v[14:17], v[152:155], v[208:211], v[14:17]
	v_mfma_f32_16x16x32_bf16 v[6:9], v[160:163], v[208:211], v[6:9]
	v_mfma_f32_16x16x32_bf16 v[62:65], v[156:159], v[188:191], v[62:65]
	v_mfma_f32_16x16x32_bf16 v[54:57], v[164:167], v[188:191], v[54:57]
	v_mfma_f32_16x16x32_bf16 v[46:49], v[156:159], v[196:199], v[46:49]
	v_mfma_f32_16x16x32_bf16 v[38:41], v[164:167], v[196:199], v[38:41]
	v_mfma_f32_16x16x32_bf16 v[30:33], v[156:159], v[204:207], v[30:33]
	v_mfma_f32_16x16x32_bf16 v[22:25], v[164:167], v[204:207], v[22:25]
	v_mfma_f32_16x16x32_bf16 v[14:17], v[156:159], v[212:215], v[14:17]
	v_mfma_f32_16x16x32_bf16 v[6:9], v[164:167], v[212:215], v[6:9]
	v_mfma_f32_16x16x32_bf16 v[58:61], v[168:171], v[184:187], v[58:61]
	v_mfma_f32_16x16x32_bf16 v[50:53], v[176:179], v[184:187], v[50:53]
	v_mfma_f32_16x16x32_bf16 v[42:45], v[168:171], v[192:195], v[42:45]
	v_mfma_f32_16x16x32_bf16 v[34:37], v[176:179], v[192:195], v[34:37]
	v_mfma_f32_16x16x32_bf16 v[26:29], v[168:171], v[200:203], v[26:29]
	v_mfma_f32_16x16x32_bf16 v[18:21], v[176:179], v[200:203], v[18:21]
	v_mfma_f32_16x16x32_bf16 v[10:13], v[168:171], v[208:211], v[10:13]
	v_mfma_f32_16x16x32_bf16 v[2:5], v[176:179], v[208:211], v[2:5]
	v_mfma_f32_16x16x32_bf16 v[58:61], v[172:175], v[188:191], v[58:61]
	v_mfma_f32_16x16x32_bf16 v[50:53], v[180:183], v[188:191], v[50:53]
	v_mfma_f32_16x16x32_bf16 v[42:45], v[172:175], v[196:199], v[42:45]
	v_mfma_f32_16x16x32_bf16 v[34:37], v[180:183], v[196:199], v[34:37]
	v_mfma_f32_16x16x32_bf16 v[26:29], v[172:175], v[204:207], v[26:29]
	v_mfma_f32_16x16x32_bf16 v[18:21], v[180:183], v[204:207], v[18:21]
	v_mfma_f32_16x16x32_bf16 v[10:13], v[172:175], v[212:215], v[10:13]
	v_mfma_f32_16x16x32_bf16 v[2:5], v[180:183], v[212:215], v[2:5]
	s_setprio 0
	s_barrier
	s_add_i32 s59, 0, 0x18000
	v_add_u32_e32 v151, s59, v146
	s_add_i32 s60, 0, 0x1c000
	ds_read_b128 v[152:155], v151
	ds_read_b128 v[156:159], v151 offset:1024
	ds_read_b128 v[160:163], v151 offset:2048
	ds_read_b128 v[164:167], v151 offset:3072
	v_add_u32_e32 v151, s60, v146
	ds_read_b128 v[168:171], v151
	ds_read_b128 v[172:175], v151 offset:1024
	ds_read_b128 v[176:179], v151 offset:2048
	ds_read_b128 v[180:183], v151 offset:3072
	s_add_u32 s26, s26, s8
	s_addc_u32 s27, s27, s9
	s_mov_b32 m0, s38
	v_lshl_add_u64 v[228:229], s[26:27], 0, v[136:137]
	ds_read_b128 v[184:187], v150 offset:32768
	ds_read_b128 v[188:191], v150 offset:33792
	ds_read_b128 v[192:195], v150 offset:34816
	ds_read_b128 v[196:199], v150 offset:35840
	ds_read_b128 v[200:203], v150 offset:36864
	ds_read_b128 v[204:207], v150 offset:37888
	ds_read_b128 v[208:211], v150 offset:38912
	ds_read_b128 v[212:215], v150 offset:39936
	global_load_lds_dwordx4 v[228:229], off
	v_lshl_add_u64 v[228:229], s[26:27], 0, v[132:133]
	s_mov_b32 m0, s39
	s_nop 0
	global_load_lds_dwordx4 v[228:229], off
	s_waitcnt vmcnt(8)
	s_waitcnt lgkmcnt(0)
	s_barrier
	s_setprio 1
	v_mfma_f32_16x16x32_bf16 v[122:125], v[152:155], v[184:187], v[122:125]
	v_mfma_f32_16x16x32_bf16 v[118:121], v[160:163], v[184:187], v[118:121]
	v_mfma_f32_16x16x32_bf16 v[110:113], v[152:155], v[192:195], v[110:113]
	v_mfma_f32_16x16x32_bf16 v[102:105], v[160:163], v[192:195], v[102:105]
	v_mfma_f32_16x16x32_bf16 v[94:97], v[152:155], v[200:203], v[94:97]
	v_mfma_f32_16x16x32_bf16 v[86:89], v[160:163], v[200:203], v[86:89]
	v_mfma_f32_16x16x32_bf16 v[78:81], v[152:155], v[208:211], v[78:81]
	v_mfma_f32_16x16x32_bf16 v[70:73], v[160:163], v[208:211], v[70:73]
	v_mfma_f32_16x16x32_bf16 v[122:125], v[156:159], v[188:191], v[122:125]
	v_mfma_f32_16x16x32_bf16 v[118:121], v[164:167], v[188:191], v[118:121]
	v_mfma_f32_16x16x32_bf16 v[110:113], v[156:159], v[196:199], v[110:113]
	v_mfma_f32_16x16x32_bf16 v[102:105], v[164:167], v[196:199], v[102:105]
	v_mfma_f32_16x16x32_bf16 v[94:97], v[156:159], v[204:207], v[94:97]
	v_mfma_f32_16x16x32_bf16 v[86:89], v[164:167], v[204:207], v[86:89]
	v_mfma_f32_16x16x32_bf16 v[78:81], v[156:159], v[212:215], v[78:81]
	v_mfma_f32_16x16x32_bf16 v[70:73], v[164:167], v[212:215], v[70:73]
	v_mfma_f32_16x16x32_bf16 v[126:129], v[168:171], v[184:187], v[126:129]
	v_mfma_f32_16x16x32_bf16 v[114:117], v[176:179], v[184:187], v[114:117]
	v_mfma_f32_16x16x32_bf16 v[106:109], v[168:171], v[192:195], v[106:109]
	v_mfma_f32_16x16x32_bf16 v[98:101], v[176:179], v[192:195], v[98:101]
	v_mfma_f32_16x16x32_bf16 v[90:93], v[168:171], v[200:203], v[90:93]
	v_mfma_f32_16x16x32_bf16 v[82:85], v[176:179], v[200:203], v[82:85]
	v_mfma_f32_16x16x32_bf16 v[74:77], v[168:171], v[208:211], v[74:77]
	v_mfma_f32_16x16x32_bf16 v[66:69], v[176:179], v[208:211], v[66:69]
	v_mfma_f32_16x16x32_bf16 v[126:129], v[172:175], v[188:191], v[126:129]
	v_mfma_f32_16x16x32_bf16 v[114:117], v[180:183], v[188:191], v[114:117]
	v_mfma_f32_16x16x32_bf16 v[106:109], v[172:175], v[196:199], v[106:109]
	v_mfma_f32_16x16x32_bf16 v[98:101], v[180:183], v[196:199], v[98:101]
	v_mfma_f32_16x16x32_bf16 v[90:93], v[172:175], v[204:207], v[90:93]
	v_mfma_f32_16x16x32_bf16 v[82:85], v[180:183], v[204:207], v[82:85]
	v_mfma_f32_16x16x32_bf16 v[74:77], v[172:175], v[212:215], v[74:77]
	v_mfma_f32_16x16x32_bf16 v[66:69], v[180:183], v[212:215], v[66:69]
	s_setprio 0
	s_barrier
; #define PG8_STAGE(bufoff, gbase, voff) do { _Pragma("unroll") for (int _i = 0; _i < 2; ++_i) \
;         __builtin_amdgcn_global_load_lds((const unsigned*)((const char*)(gbase) + (voff)[_i]), (PG8_LAS unsigned*)(lds + (bufoff) + ldsw + _i * 8192), 16, 0, 0); } while (0)
; #define PG8_LDA(dst, b, h) do { _Pragma("unroll") for (int m = 0; m < 4; ++m) _Pragma("unroll") for (int k = 0; k < 2; ++k) dst[m][k] = *(const PG8_LAS bf16x8*)(lds + PG8_SA(b, h) + aoff + m * 2048 + k * 1024); } while (0)
; #define PG8_MMA(ai, bj, At, Bt) do { __builtin_amdgcn_s_setprio(1); _Pragma("unroll") for (int m = 0; m < 4; ++m) _Pragma("unroll") for (int n = 0; n < 2; ++n) _Pragma("unroll") for (int k = 0; k < 2; ++k) \
;         acc[ai][bj][m][n] = __builtin_amdgcn_mfma_f32_16x16x32_bf16(Bt[n][k], At[m][k], acc[ai][bj][m][n], 0, 0, 0); __builtin_amdgcn_s_setprio(0); } while (0)
; #define PG8_WAIT_V(n) asm volatile("s_waitcnt vmcnt(" #n ")" ::: "memory")
; #define PG8_WAIT_L(n) asm volatile("s_waitcnt lgkmcnt(" #n ")" ::: "memory")
; #define PG8_BAR __builtin_amdgcn_s_barrier()
; #define PG8_SCHED __builtin_amdgcn_sched_barrier(0)
; template <class Epi, class Sched, bool ALIGN_EPI = false, bool SP2 = false>
; __device__ __forceinline__ void gemm_phase(PG8_LAS unsigned char* lds, const Gemm g, const Sched& S, const Epi& E) {
;     ...
;         for (int t = 0; t < nt; t += 2) {
;             const bool last = (t == nt - 2);
;             const char* a1 = cA + (size_t)(t + 1) * kstep;
;             const char* a2 = last ? nA : cA + (size_t)(t + 2) * kstep; const char* b2 = last ? nB : cB + (size_t)(t + 2) * kstep;
;             const char* a3 = a2 + kstep; const char* b3 = b2 + kstep;
;     ...
;             PG8_LDA(At, 1, 1); PG8_STAGE(PG8_SB(1, 0), b3, voffB); PG8_STAGE(PG8_SB(1, 1), b3 + hstep, voffB); PG8_STAGE(PG8_SA(1, 0), a3, voffA);
;             PG8_WAIT_V(8); PG8_WAIT_L(0); PG8_BAR; PG8_MMA(1, 0, At, B0); PG8_MMA(1, 1, At, B1); PG8_BAR; PG8_SCHED;
	s_add_i32 s26, s59, s31
	v_lshl_add_u64 v[216:217], v[216:217], 0, s[16:17]
	s_mov_b32 m0, s26
	ds_read_b128 v[184:187], v150 offset:49152
	ds_read_b128 v[188:191], v150 offset:50176
	ds_read_b128 v[192:195], v150 offset:51200
	ds_read_b128 v[196:199], v150 offset:52224
	ds_read_b128 v[200:203], v150 offset:53248
	ds_read_b128 v[204:207], v150 offset:54272
	ds_read_b128 v[208:211], v150 offset:55296
	ds_read_b128 v[212:215], v150 offset:56320
	global_load_lds_dwordx4 v[216:217], off
	v_lshl_add_u64 v[216:217], v[218:219], 0, s[16:17]
	s_add_i32 m0, s26, 0x2000
	s_add_i32 s26, s60, s31
	global_load_lds_dwordx4 v[216:217], off
	v_lshl_add_u64 v[216:217], v[220:221], 0, s[16:17]
	s_mov_b32 m0, s26
	s_nop 0
	global_load_lds_dwordx4 v[216:217], off
	v_lshl_add_u64 v[216:217], v[222:223], 0, s[16:17]
	s_add_i32 m0, s26, 0x2000
	s_nop 0
	global_load_lds_dwordx4 v[216:217], off
	v_lshl_add_u64 v[216:217], v[224:225], 0, s[16:17]
	s_mov_b32 m0, s41
	s_nop 0
	global_load_lds_dwordx4 v[216:217], off
	v_lshl_add_u64 v[216:217], v[226:227], 0, s[16:17]
	s_mov_b32 m0, s42
	s_nop 0
	global_load_lds_dwordx4 v[216:217], off
	s_waitcnt vmcnt(8)
	s_waitcnt lgkmcnt(0)
	s_barrier
	s_setprio 1
	v_mfma_f32_16x16x32_bf16 v[62:65], v[152:155], v[184:187], v[62:65]
	v_mfma_f32_16x16x32_bf16 v[54:57], v[160:163], v[184:187], v[54:57]
	v_mfma_f32_16x16x32_bf16 v[46:49], v[152:155], v[192:195], v[46:49]
	v_mfma_f32_16x16x32_bf16 v[38:41], v[160:163], v[192:195], v[38:41]
	v_mfma_f32_16x16x32_bf16 v[30:33], v[152:155], v[200:203], v[30:33]
	v_mfma_f32_16x16x32_bf16 v[22:25], v[160:163], v[200:203], v[22:25]
	v_mfma_f32_16x16x32_bf16 v[14:17], v[152:155], v[208:211], v[14:17]
	v_mfma_f32_16x16x32_bf16 v[6:9], v[160:163], v[208:211], v[6:9]
	v_mfma_f32_16x16x32_bf16 v[62:65], v[156:159], v[188:191], v[62:65]
	v_mfma_f32_16x16x32_bf16 v[54:57], v[164:167], v[188:191], v[54:57]
	v_mfma_f32_16x16x32_bf16 v[46:49], v[156:159], v[196:199], v[46:49]
	v_mfma_f32_16x16x32_bf16 v[38:41], v[164:167], v[196:199], v[38:41]
	v_mfma_f32_16x16x32_bf16 v[30:33], v[156:159], v[204:207], v[30:33]
	v_mfma_f32_16x16x32_bf16 v[22:25], v[164:167], v[204:207], v[22:25]
	v_mfma_f32_16x16x32_bf16 v[14:17], v[156:159], v[212:215], v[14:17]
	v_mfma_f32_16x16x32_bf16 v[6:9], v[164:167], v[212:215], v[6:9]
	v_mfma_f32_16x16x32_bf16 v[58:61], v[168:171], v[184:187], v[58:61]
	v_mfma_f32_16x16x32_bf16 v[50:53], v[176:179], v[184:187], v[50:53]
	v_mfma_f32_16x16x32_bf16 v[42:45], v[168:171], v[192:195], v[42:45]
	v_mfma_f32_16x16x32_bf16 v[34:37], v[176:179], v[192:195], v[34:37]
	v_mfma_f32_16x16x32_bf16 v[26:29], v[168:171], v[200:203], v[26:29]
	v_mfma_f32_16x16x32_bf16 v[18:21], v[176:179], v[200:203], v[18:21]
	v_mfma_f32_16x16x32_bf16 v[10:13], v[168:171], v[208:211], v[10:13]
	v_mfma_f32_16x16x32_bf16 v[2:5], v[176:179], v[208:211], v[2:5]
	v_mfma_f32_16x16x32_bf16 v[58:61], v[172:175], v[188:191], v[58:61]
	v_mfma_f32_16x16x32_bf16 v[50:53], v[180:183], v[188:191], v[50:53]
	v_mfma_f32_16x16x32_bf16 v[42:45], v[172:175], v[196:199], v[42:45]
	v_mfma_f32_16x16x32_bf16 v[34:37], v[180:183], v[196:199], v[34:37]
	v_mfma_f32_16x16x32_bf16 v[26:29], v[172:175], v[204:207], v[26:29]
	v_mfma_f32_16x16x32_bf16 v[18:21], v[180:183], v[204:207], v[18:21]
	v_mfma_f32_16x16x32_bf16 v[10:13], v[172:175], v[212:215], v[10:13]
	v_mfma_f32_16x16x32_bf16 v[2:5], v[180:183], v[212:215], v[2:5]
	s_setprio 0
	s_add_u32 s56, s56, 0x100
	s_addc_u32 s57, s57, 0
	s_add_u32 s24, s24, 0x100
	s_addc_u32 s25, s25, 0
	s_cmp_ge_i32 s58, s43
	s_mov_b32 s26, s58
	s_barrier
	s_cbranch_scc0 .LBB0_1976
